# K-loop MFMAs reordered in snake order (consecutive MFMAs share one operand fragment)
# speedup vs baseline: 1.0025x; 1.0025x over previous
; #define PG8_STAGE(bufoff, gbase, voff) do { const int so_ = (int)(unsigned)((const char*)(gbase) - base_##voff); _Pragma("unroll") for (int _i = 0; _i < 2; ++_i) \
;         __builtin_amdgcn_raw_ptr_buffer_load_lds(rs_##voff, (PG8_LAS unsigned*)(lds + (bufoff) + ldsw + _i * 8192), 16, (int)(voff)[_i], so_, 0, 0); } while (0)
; #define PG8_LDA(dst, b, h) do { _Pragma("unroll") for (int m = 0; m < 4; ++m) _Pragma("unroll") for (int k = 0; k < 2; ++k) dst[m][k] = *(const PG8_LAS bf16x8*)(lds + PG8_SA(b, h) + aoff + m * 2048 + k * 1024); } while (0)
; #define PG8_LDB(dst, b, h) do { _Pragma("unroll") for (int n = 0; n < 2; ++n) _Pragma("unroll") for (int k = 0; k < 2; ++k) dst[n][k] = *(const PG8_LAS bf16x8*)(lds + PG8_SB(b, h) + boff + n * 2048 + k * 1024); } while (0)
; #define PG8_MMA(ai, bj, At, Bt) do { __builtin_amdgcn_s_setprio(1); _Pragma("unroll") for (int m = 0; m < 4; ++m) _Pragma("unroll") for (int n = 0; n < 2; ++n) _Pragma("unroll") for (int k = 0; k < 2; ++k) \
;         acc[ai][bj][m][n] = __builtin_amdgcn_mfma_f32_16x16x32_bf16(Bt[n][k], At[m][k], acc[ai][bj][m][n], 0, 0, 0); __builtin_amdgcn_s_setprio(0); } while (0)
; #define PG8_WAIT_V(n) asm volatile("s_waitcnt vmcnt(" #n ")" ::: "memory")
; #define PG8_WAIT_L(n) asm volatile("s_waitcnt lgkmcnt(" #n ")" ::: "memory")
; #define PG8_BAR __builtin_amdgcn_s_barrier()
; #define PG8_SCHED __builtin_amdgcn_sched_barrier(0)
; template <class Epi, class Sched, bool ALIGN_EPI = false, bool SP2 = false>
; __device__ __forceinline__ void gemm_phase(PG8_LAS unsigned char* lds, const Gemm g, const Sched& S, const Epi& E, int tid_in) {
;     ...
;             PG8_LDB(B0, 0, 0); PG8_LDB(B1, 0, 1); PG8_SCHED; PG8_LDA(At, 0, 0); PG8_STAGE(PG8_SA(1, 1), a1 + hstepA, voffA);
;             PG8_WAIT_V(8); PG8_WAIT_L(0); PG8_BAR; PG8_MMA(0, 0, At, B0); PG8_MMA(0, 1, At, B1); PG8_BAR; PG8_SCHED;
;             PG8_LDA(At, 0, 1); PG8_STAGE(PG8_SB(0, 0), b2, voffB); PG8_STAGE(PG8_SB(0, 1), b2 + hstepB, voffB); PG8_STAGE(PG8_SA(0, 0), a2, voffA);
;             PG8_WAIT_V(8); PG8_WAIT_L(0); PG8_BAR; PG8_MMA(1, 0, At, B0); PG8_MMA(1, 1, At, B1); PG8_BAR; PG8_SCHED;
.LBB0_312:
	v_add_u32_e32 v0, 0x10000, v237
	ds_read_b128 v[130:133], v0
	ds_read_b128 v[134:137], v0 offset:1024
	ds_read_b128 v[138:141], v0 offset:2048
	ds_read_b128 v[142:145], v0 offset:3072
	v_add_u32_e32 v0, 0x14000, v237
	ds_read_b128 v[146:149], v0
	ds_read_b128 v[150:153], v0 offset:1024
	ds_read_b128 v[154:157], v0 offset:2048
	ds_read_b128 v[158:161], v0 offset:3072
	s_add_u32 s16, s12, 0x100
	s_addc_u32 s17, s13, 0
	s_sub_i32 s12, s12, s4
	s_add_i32 s12, s12, 0x80080
	s_cmp_eq_u32 s23, 28
	s_cselect_b32 s13, s19, s16
	s_mov_b32 m0, s69
	ds_read_b128 v[162:165], v238
	ds_read_b128 v[166:169], v238 offset:1024
	ds_read_b128 v[170:173], v238 offset:2048
	ds_read_b128 v[174:177], v238 offset:3072
	ds_read_b128 v[178:181], v238 offset:4096
	ds_read_b128 v[182:185], v238 offset:5120
	ds_read_b128 v[186:189], v238 offset:6144
	ds_read_b128 v[190:193], v238 offset:7168
	buffer_load_dwordx4 v195, s[4:7], s12 offen lds
	s_mov_b32 m0, s67
	s_nop 0
	buffer_load_dwordx4 v211, s[4:7], s12 offen lds
	s_waitcnt vmcnt(8)
	s_waitcnt lgkmcnt(0)
	s_barrier
	s_setprio 1
	s_waitcnt lgkmcnt(0)
	v_mfma_f32_16x16x32_bf16 v[126:129], v[130:133], v[162:165], v[126:129]
	v_mfma_f32_16x16x32_bf16 v[122:125], v[138:141], v[162:165], v[122:125]
	v_mfma_f32_16x16x32_bf16 v[106:109], v[138:141], v[170:173], v[106:109]
	v_mfma_f32_16x16x32_bf16 v[110:113], v[130:133], v[170:173], v[110:113]
	v_mfma_f32_16x16x32_bf16 v[94:97], v[130:133], v[178:181], v[94:97]
	v_mfma_f32_16x16x32_bf16 v[90:93], v[138:141], v[178:181], v[90:93]
	v_mfma_f32_16x16x32_bf16 v[74:77], v[138:141], v[186:189], v[74:77]
	v_mfma_f32_16x16x32_bf16 v[78:81], v[130:133], v[186:189], v[78:81]
	v_mfma_f32_16x16x32_bf16 v[126:129], v[134:137], v[166:169], v[126:129]
	v_mfma_f32_16x16x32_bf16 v[122:125], v[142:145], v[166:169], v[122:125]
	v_mfma_f32_16x16x32_bf16 v[106:109], v[142:145], v[174:177], v[106:109]
	v_mfma_f32_16x16x32_bf16 v[110:113], v[134:137], v[174:177], v[110:113]
	v_mfma_f32_16x16x32_bf16 v[94:97], v[134:137], v[182:185], v[94:97]
	v_mfma_f32_16x16x32_bf16 v[90:93], v[142:145], v[182:185], v[90:93]
	v_mfma_f32_16x16x32_bf16 v[74:77], v[142:145], v[190:193], v[74:77]
	v_mfma_f32_16x16x32_bf16 v[78:81], v[134:137], v[190:193], v[78:81]
	s_setprio 0
	s_setprio 1
	v_mfma_f32_16x16x32_bf16 v[118:121], v[146:149], v[162:165], v[118:121]
	v_mfma_f32_16x16x32_bf16 v[114:117], v[154:157], v[162:165], v[114:117]
	v_mfma_f32_16x16x32_bf16 v[98:101], v[154:157], v[170:173], v[98:101]
	v_mfma_f32_16x16x32_bf16 v[102:105], v[146:149], v[170:173], v[102:105]
	v_mfma_f32_16x16x32_bf16 v[86:89], v[146:149], v[178:181], v[86:89]
	v_mfma_f32_16x16x32_bf16 v[82:85], v[154:157], v[178:181], v[82:85]
	v_mfma_f32_16x16x32_bf16 v[66:69], v[154:157], v[186:189], v[66:69]
	v_mfma_f32_16x16x32_bf16 v[70:73], v[146:149], v[186:189], v[70:73]
	v_mfma_f32_16x16x32_bf16 v[118:121], v[150:153], v[166:169], v[118:121]
	v_mfma_f32_16x16x32_bf16 v[114:117], v[158:161], v[166:169], v[114:117]
	v_mfma_f32_16x16x32_bf16 v[98:101], v[158:161], v[174:177], v[98:101]
	v_mfma_f32_16x16x32_bf16 v[102:105], v[150:153], v[174:177], v[102:105]
	v_mfma_f32_16x16x32_bf16 v[86:89], v[150:153], v[182:185], v[86:89]
	v_mfma_f32_16x16x32_bf16 v[82:85], v[158:161], v[182:185], v[82:85]
	v_mfma_f32_16x16x32_bf16 v[66:69], v[158:161], v[190:193], v[66:69]
	v_mfma_f32_16x16x32_bf16 v[70:73], v[150:153], v[190:193], v[70:73]
	s_setprio 0
	s_barrier
	s_cselect_b32 s12, s15, s20
	s_mov_b32 m0, s61
	s_mov_b32 s42, s6
	s_mov_b32 s43, s7
	s_sub_i32 s12, s12, s40
	ds_read_b128 v[162:165], v238 offset:16384
	ds_read_b128 v[166:169], v238 offset:17408
	ds_read_b128 v[170:173], v238 offset:18432
	ds_read_b128 v[174:177], v238 offset:19456
	ds_read_b128 v[178:181], v238 offset:20480
	ds_read_b128 v[182:185], v238 offset:21504
	ds_read_b128 v[186:189], v238 offset:22528
	ds_read_b128 v[190:193], v238 offset:23552
	buffer_load_dwordx4 v207, s[40:43], s12 offen lds
	s_mov_b32 m0, s62
	s_add_i32 s36, s12, 0x80000
	buffer_load_dwordx4 v224, s[40:43], s12 offen lds
	s_mov_b32 m0, s63
	s_sub_i32 s13, s13, s4
	buffer_load_dwordx4 v207, s[40:43], s36 offen lds
	s_mov_b32 m0, s71
	s_nop 0
	buffer_load_dwordx4 v224, s[40:43], s36 offen lds
	s_mov_b32 m0, s53
	s_nop 0
	buffer_load_dwordx4 v195, s[4:7], s13 offen lds
	s_mov_b32 m0, s72
	s_nop 0
	buffer_load_dwordx4 v211, s[4:7], s13 offen lds
	s_waitcnt vmcnt(8)
	s_waitcnt lgkmcnt(0)
	s_barrier
	s_setprio 1
	s_waitcnt lgkmcnt(0)
	v_mfma_f32_16x16x32_bf16 v[62:65], v[130:133], v[162:165], v[62:65]
	v_mfma_f32_16x16x32_bf16 v[58:61], v[138:141], v[162:165], v[58:61]
	v_mfma_f32_16x16x32_bf16 v[42:45], v[138:141], v[170:173], v[42:45]
	v_mfma_f32_16x16x32_bf16 v[46:49], v[130:133], v[170:173], v[46:49]
	v_mfma_f32_16x16x32_bf16 v[30:33], v[130:133], v[178:181], v[30:33]
	v_mfma_f32_16x16x32_bf16 v[26:29], v[138:141], v[178:181], v[26:29]
	v_mfma_f32_16x16x32_bf16 v[10:13], v[138:141], v[186:189], v[10:13]
	v_mfma_f32_16x16x32_bf16 v[14:17], v[130:133], v[186:189], v[14:17]
	v_mfma_f32_16x16x32_bf16 v[62:65], v[134:137], v[166:169], v[62:65]
	v_mfma_f32_16x16x32_bf16 v[58:61], v[142:145], v[166:169], v[58:61]
	v_mfma_f32_16x16x32_bf16 v[42:45], v[142:145], v[174:177], v[42:45]
	v_mfma_f32_16x16x32_bf16 v[46:49], v[134:137], v[174:177], v[46:49]
	v_mfma_f32_16x16x32_bf16 v[30:33], v[134:137], v[182:185], v[30:33]
	v_mfma_f32_16x16x32_bf16 v[26:29], v[142:145], v[182:185], v[26:29]
	v_mfma_f32_16x16x32_bf16 v[10:13], v[142:145], v[190:193], v[10:13]
	v_mfma_f32_16x16x32_bf16 v[14:17], v[134:137], v[190:193], v[14:17]
	s_setprio 0
	s_setprio 1
	v_mfma_f32_16x16x32_bf16 v[54:57], v[146:149], v[162:165], v[54:57]
	v_mfma_f32_16x16x32_bf16 v[50:53], v[154:157], v[162:165], v[50:53]
	v_mfma_f32_16x16x32_bf16 v[34:37], v[154:157], v[170:173], v[34:37]
	v_mfma_f32_16x16x32_bf16 v[38:41], v[146:149], v[170:173], v[38:41]
	v_mfma_f32_16x16x32_bf16 v[22:25], v[146:149], v[178:181], v[22:25]
	v_mfma_f32_16x16x32_bf16 v[18:21], v[154:157], v[178:181], v[18:21]
	v_mfma_f32_16x16x32_bf16 v[2:5], v[154:157], v[186:189], v[2:5]
	v_mfma_f32_16x16x32_bf16 v[6:9], v[146:149], v[186:189], v[6:9]
	v_mfma_f32_16x16x32_bf16 v[54:57], v[150:153], v[166:169], v[54:57]
	v_mfma_f32_16x16x32_bf16 v[50:53], v[158:161], v[166:169], v[50:53]
	v_mfma_f32_16x16x32_bf16 v[34:37], v[158:161], v[174:177], v[34:37]
	v_mfma_f32_16x16x32_bf16 v[38:41], v[150:153], v[174:177], v[38:41]
	v_mfma_f32_16x16x32_bf16 v[22:25], v[150:153], v[182:185], v[22:25]
	v_mfma_f32_16x16x32_bf16 v[18:21], v[158:161], v[182:185], v[18:21]
	v_mfma_f32_16x16x32_bf16 v[2:5], v[158:161], v[190:193], v[2:5]
	v_mfma_f32_16x16x32_bf16 v[6:9], v[150:153], v[190:193], v[6:9]
	s_setprio 0
	s_barrier
; #define PG8_STAGE(bufoff, gbase, voff) do { const int so_ = (int)(unsigned)((const char*)(gbase) - base_##voff); _Pragma("unroll") for (int _i = 0; _i < 2; ++_i) \
;         __builtin_amdgcn_raw_ptr_buffer_load_lds(rs_##voff, (PG8_LAS unsigned*)(lds + (bufoff) + ldsw + _i * 8192), 16, (int)(voff)[_i], so_, 0, 0); } while (0)
; #define PG8_LDA(dst, b, h) do { _Pragma("unroll") for (int m = 0; m < 4; ++m) _Pragma("unroll") for (int k = 0; k < 2; ++k) dst[m][k] = *(const PG8_LAS bf16x8*)(lds + PG8_SA(b, h) + aoff + m * 2048 + k * 1024); } while (0)
; #define PG8_LDB(dst, b, h) do { _Pragma("unroll") for (int n = 0; n < 2; ++n) _Pragma("unroll") for (int k = 0; k < 2; ++k) dst[n][k] = *(const PG8_LAS bf16x8*)(lds + PG8_SB(b, h) + boff + n * 2048 + k * 1024); } while (0)
; #define PG8_MMA(ai, bj, At, Bt) do { __builtin_amdgcn_s_setprio(1); _Pragma("unroll") for (int m = 0; m < 4; ++m) _Pragma("unroll") for (int n = 0; n < 2; ++n) _Pragma("unroll") for (int k = 0; k < 2; ++k) \
;         acc[ai][bj][m][n] = __builtin_amdgcn_mfma_f32_16x16x32_bf16(Bt[n][k], At[m][k], acc[ai][bj][m][n], 0, 0, 0); __builtin_amdgcn_s_setprio(0); } while (0)
; #define PG8_WAIT_V(n) asm volatile("s_waitcnt vmcnt(" #n ")" ::: "memory")
; #define PG8_WAIT_L(n) asm volatile("s_waitcnt lgkmcnt(" #n ")" ::: "memory")
; #define PG8_BAR __builtin_amdgcn_s_barrier()
; #define PG8_SCHED __builtin_amdgcn_sched_barrier(0)
; template <class Epi, class Sched, bool ALIGN_EPI = false, bool SP2 = false>
; __device__ __forceinline__ void gemm_phase(PG8_LAS unsigned char* lds, const Gemm g, const Sched& S, const Epi& E, int tid_in) {
;     ...
;         for (int t = 0; t < nt; t += 2) {
;     ...
;             PG8_LDB(B0, 1, 0); PG8_LDB(B1, 1, 1); PG8_SCHED; PG8_LDA(At, 1, 0); PG8_STAGE(PG8_SA(0, 1), a2 + hstepA, voffA);
;             PG8_WAIT_V(8); PG8_WAIT_L(0); PG8_BAR; PG8_MMA(0, 0, At, B0); PG8_MMA(0, 1, At, B1); PG8_BAR; PG8_SCHED;
;             PG8_LDA(At, 1, 1); PG8_STAGE(PG8_SB(1, 0), b3, voffB); PG8_STAGE(PG8_SB(1, 1), b3 + hstepB, voffB); PG8_STAGE(PG8_SA(1, 0), a3, voffA);
;             PG8_WAIT_V(8); PG8_WAIT_L(0); PG8_BAR; PG8_MMA(1, 0, At, B0); PG8_MMA(1, 1, At, B1); PG8_BAR; PG8_SCHED;
	v_add_u32_e32 v0, 0x18000, v237
	ds_read_b128 v[130:133], v0
	ds_read_b128 v[134:137], v0 offset:1024
	ds_read_b128 v[138:141], v0 offset:2048
	ds_read_b128 v[142:145], v0 offset:3072
	v_add_u32_e32 v0, 0x1c000, v237
	ds_read_b128 v[146:149], v0
	ds_read_b128 v[150:153], v0 offset:1024
	ds_read_b128 v[154:157], v0 offset:2048
	ds_read_b128 v[158:161], v0 offset:3072
	s_add_i32 s36, s13, 0x80000
	s_mov_b32 m0, s73
	ds_read_b128 v[162:165], v238 offset:32768
	ds_read_b128 v[166:169], v238 offset:33792
	ds_read_b128 v[170:173], v238 offset:34816
	ds_read_b128 v[174:177], v238 offset:35840
	ds_read_b128 v[178:181], v238 offset:36864
	ds_read_b128 v[182:185], v238 offset:37888
	ds_read_b128 v[186:189], v238 offset:38912
	ds_read_b128 v[190:193], v238 offset:39936
	buffer_load_dwordx4 v195, s[4:7], s36 offen lds
	s_mov_b32 m0, s74
	s_nop 0
	buffer_load_dwordx4 v211, s[4:7], s36 offen lds
	s_waitcnt vmcnt(8)
	s_waitcnt lgkmcnt(0)
	s_barrier
	s_setprio 1
	s_waitcnt lgkmcnt(0)
	v_mfma_f32_16x16x32_bf16 v[126:129], v[130:133], v[162:165], v[126:129]
	v_mfma_f32_16x16x32_bf16 v[122:125], v[138:141], v[162:165], v[122:125]
	v_mfma_f32_16x16x32_bf16 v[106:109], v[138:141], v[170:173], v[106:109]
	v_mfma_f32_16x16x32_bf16 v[110:113], v[130:133], v[170:173], v[110:113]
	v_mfma_f32_16x16x32_bf16 v[94:97], v[130:133], v[178:181], v[94:97]
	v_mfma_f32_16x16x32_bf16 v[90:93], v[138:141], v[178:181], v[90:93]
	v_mfma_f32_16x16x32_bf16 v[74:77], v[138:141], v[186:189], v[74:77]
	v_mfma_f32_16x16x32_bf16 v[78:81], v[130:133], v[186:189], v[78:81]
	v_mfma_f32_16x16x32_bf16 v[126:129], v[134:137], v[166:169], v[126:129]
	v_mfma_f32_16x16x32_bf16 v[122:125], v[142:145], v[166:169], v[122:125]
	v_mfma_f32_16x16x32_bf16 v[106:109], v[142:145], v[174:177], v[106:109]
	v_mfma_f32_16x16x32_bf16 v[110:113], v[134:137], v[174:177], v[110:113]
	v_mfma_f32_16x16x32_bf16 v[94:97], v[134:137], v[182:185], v[94:97]
	v_mfma_f32_16x16x32_bf16 v[90:93], v[142:145], v[182:185], v[90:93]
	v_mfma_f32_16x16x32_bf16 v[74:77], v[142:145], v[190:193], v[74:77]
	v_mfma_f32_16x16x32_bf16 v[78:81], v[134:137], v[190:193], v[78:81]
	s_setprio 0
	s_setprio 1
	v_mfma_f32_16x16x32_bf16 v[118:121], v[146:149], v[162:165], v[118:121]
	v_mfma_f32_16x16x32_bf16 v[114:117], v[154:157], v[162:165], v[114:117]
	v_mfma_f32_16x16x32_bf16 v[98:101], v[154:157], v[170:173], v[98:101]
	v_mfma_f32_16x16x32_bf16 v[102:105], v[146:149], v[170:173], v[102:105]
	v_mfma_f32_16x16x32_bf16 v[86:89], v[146:149], v[178:181], v[86:89]
	v_mfma_f32_16x16x32_bf16 v[82:85], v[154:157], v[178:181], v[82:85]
	v_mfma_f32_16x16x32_bf16 v[66:69], v[154:157], v[186:189], v[66:69]
	v_mfma_f32_16x16x32_bf16 v[70:73], v[146:149], v[186:189], v[70:73]
	v_mfma_f32_16x16x32_bf16 v[118:121], v[150:153], v[166:169], v[118:121]
	v_mfma_f32_16x16x32_bf16 v[114:117], v[158:161], v[166:169], v[114:117]
	v_mfma_f32_16x16x32_bf16 v[98:101], v[158:161], v[174:177], v[98:101]
	v_mfma_f32_16x16x32_bf16 v[102:105], v[150:153], v[174:177], v[102:105]
	v_mfma_f32_16x16x32_bf16 v[86:89], v[150:153], v[182:185], v[86:89]
	v_mfma_f32_16x16x32_bf16 v[82:85], v[158:161], v[182:185], v[82:85]
	v_mfma_f32_16x16x32_bf16 v[66:69], v[158:161], v[190:193], v[66:69]
	v_mfma_f32_16x16x32_bf16 v[70:73], v[150:153], v[190:193], v[70:73]
	s_setprio 0
	s_barrier
	s_mov_b32 m0, s75
	s_add_i32 s36, s12, 0x80
	ds_read_b128 v[162:165], v238 offset:49152
	ds_read_b128 v[166:169], v238 offset:50176
	ds_read_b128 v[170:173], v238 offset:51200
	ds_read_b128 v[174:177], v238 offset:52224
	ds_read_b128 v[178:181], v238 offset:53248
	ds_read_b128 v[182:185], v238 offset:54272
	ds_read_b128 v[186:189], v238 offset:55296
	ds_read_b128 v[190:193], v238 offset:56320
	buffer_load_dwordx4 v207, s[40:43], s36 offen lds
	s_mov_b32 m0, s76
	s_add_i32 s12, s12, 0x80080
	buffer_load_dwordx4 v224, s[40:43], s36 offen lds
	s_mov_b32 m0, s79
	s_addk_i32 s13, 0x80
	buffer_load_dwordx4 v207, s[40:43], s12 offen lds
	s_mov_b32 m0, s68
	s_nop 0
	buffer_load_dwordx4 v224, s[40:43], s12 offen lds
	s_mov_b32 m0, s77
	s_nop 0
	buffer_load_dwordx4 v195, s[4:7], s13 offen lds
	s_mov_b32 m0, s78
	s_nop 0
	buffer_load_dwordx4 v211, s[4:7], s13 offen lds
	s_waitcnt vmcnt(8)
	s_waitcnt lgkmcnt(0)
	s_barrier
	s_setprio 1
	s_waitcnt lgkmcnt(0)
	v_mfma_f32_16x16x32_bf16 v[62:65], v[130:133], v[162:165], v[62:65]
	v_mfma_f32_16x16x32_bf16 v[58:61], v[138:141], v[162:165], v[58:61]
	v_mfma_f32_16x16x32_bf16 v[42:45], v[138:141], v[170:173], v[42:45]
	v_mfma_f32_16x16x32_bf16 v[46:49], v[130:133], v[170:173], v[46:49]
	v_mfma_f32_16x16x32_bf16 v[30:33], v[130:133], v[178:181], v[30:33]
	v_mfma_f32_16x16x32_bf16 v[26:29], v[138:141], v[178:181], v[26:29]
	v_mfma_f32_16x16x32_bf16 v[10:13], v[138:141], v[186:189], v[10:13]
	v_mfma_f32_16x16x32_bf16 v[14:17], v[130:133], v[186:189], v[14:17]
	v_mfma_f32_16x16x32_bf16 v[62:65], v[134:137], v[166:169], v[62:65]
	v_mfma_f32_16x16x32_bf16 v[58:61], v[142:145], v[166:169], v[58:61]
	v_mfma_f32_16x16x32_bf16 v[42:45], v[142:145], v[174:177], v[42:45]
	v_mfma_f32_16x16x32_bf16 v[46:49], v[134:137], v[174:177], v[46:49]
	v_mfma_f32_16x16x32_bf16 v[30:33], v[134:137], v[182:185], v[30:33]
	v_mfma_f32_16x16x32_bf16 v[26:29], v[142:145], v[182:185], v[26:29]
	v_mfma_f32_16x16x32_bf16 v[10:13], v[142:145], v[190:193], v[10:13]
	v_mfma_f32_16x16x32_bf16 v[14:17], v[134:137], v[190:193], v[14:17]
	s_setprio 0
	s_setprio 1
	v_mfma_f32_16x16x32_bf16 v[54:57], v[146:149], v[162:165], v[54:57]
	v_mfma_f32_16x16x32_bf16 v[50:53], v[154:157], v[162:165], v[50:53]
	v_mfma_f32_16x16x32_bf16 v[34:37], v[154:157], v[170:173], v[34:37]
	v_mfma_f32_16x16x32_bf16 v[38:41], v[146:149], v[170:173], v[38:41]
	v_mfma_f32_16x16x32_bf16 v[22:25], v[146:149], v[178:181], v[22:25]
	v_mfma_f32_16x16x32_bf16 v[18:21], v[154:157], v[178:181], v[18:21]
	v_mfma_f32_16x16x32_bf16 v[2:5], v[154:157], v[186:189], v[2:5]
	v_mfma_f32_16x16x32_bf16 v[6:9], v[146:149], v[186:189], v[6:9]
	v_mfma_f32_16x16x32_bf16 v[54:57], v[150:153], v[166:169], v[54:57]
	v_mfma_f32_16x16x32_bf16 v[50:53], v[158:161], v[166:169], v[50:53]
	v_mfma_f32_16x16x32_bf16 v[34:37], v[158:161], v[174:177], v[34:37]
	v_mfma_f32_16x16x32_bf16 v[38:41], v[150:153], v[174:177], v[38:41]
	v_mfma_f32_16x16x32_bf16 v[22:25], v[150:153], v[182:185], v[22:25]
	v_mfma_f32_16x16x32_bf16 v[18:21], v[158:161], v[182:185], v[18:21]
	v_mfma_f32_16x16x32_bf16 v[2:5], v[158:161], v[190:193], v[2:5]
	v_mfma_f32_16x16x32_bf16 v[6:9], v[150:153], v[190:193], v[6:9]
	s_setprio 0
	s_barrier
	s_add_i32 s23, s23, 2
	s_add_u32 s20, s20, 0x100
	s_addc_u32 s21, s21, 0
	s_cmp_gt_u32 s23, 29
	s_mov_b64 s[12:13], s[16:17]
	s_cbranch_scc0 .LBB0_312
	s_and_b64 vcc, exec, s[48:49]
	s_cbranch_vccz .LBB0_315
	s_barrier

; #define LAS __attribute__((address_space(3)))
; __device__ __forceinline__ unsigned pk2(float lo, float hi) { return pg8::cvt_pk_bf16(lo, hi); }
; __device__ __forceinline__ float bflo(unsigned w) { return __uint_as_float(w << 16); }
; __device__ __forceinline__ float bfhi(unsigned w) { return __uint_as_float(w & 0xffff0000u); }
; __device__ __forceinline__ float log_sigmoid(float x) { return -softplus(-x); }
; __device__ __forceinline__ void ret_kv_unit(LAS unsigned char* lds, const bf16* P, bf16* KV, const float* dec, int u, int tid) {
;     ...
;     const float lgf = log_sigmoid(dcf), lgb = log_sigmoid(dcb);
; #pragma unroll
;     for (int eh = 0; eh < 2; ++eh) {
;         if (eh) __syncthreads();
;         {
; #pragma unroll
;           for (int k = 0; k < 4; ++k) { const int idx = tid + k * NTHR, r = idx >> 4, c8 = idx & 15; const u32x4 v = eh ? vvb[k] : vva[k];
;             const float sf = __expf((float)(127 - r) * lgf), sb = __expf((float)r * lgb);
;             u32x4 of, ob;
;             of.x = pk2(bflo(v.x) * sf, bfhi(v.x) * sf); of.y = pk2(bflo(v.y) * sf, bfhi(v.y) * sf); of.z = pk2(bflo(v.z) * sf, bfhi(v.z) * sf); of.w = pk2(bflo(v.w) * sf, bfhi(v.w) * sf);
;             ob.x = pk2(bflo(v.x) * sb, bfhi(v.x) * sb); ob.y = pk2(bflo(v.y) * sb, bfhi(v.y) * sb); ob.z = pk2(bflo(v.z) * sb, bfhi(v.z) * sb); ob.w = pk2(bflo(v.w) * sb, bfhi(v.w) * sb);
;             *(LAS u32x4*)(Vf + r * RSV + c8 * 16) = of; *(LAS u32x4*)(Vb + r * RSV + c8 * 16) = ob; } }
;         __syncthreads();
.LBB0_570:
	s_or_b64 exec, exec, s[16:17]
	v_max_f32_e64 v0, -v0, -v0
	v_max_f32_e32 v0, 0, v0
	v_max_f32_e64 v34, -v34, -v34
	v_add_f32_e32 v51, v0, v42
	v_and_b32_e32 v0, 0xf0, v37
	v_max_f32_e32 v34, 0, v34
	v_add_u32_e32 v52, s50, v0
	v_add_u32_e32 v53, s95, v0
	v_ashrrev_i32_e32 v0, 1, v36
	v_add_f32_e32 v50, v34, v38
	v_and_b32_e32 v34, 0xffffffe0, v0
	v_lshrrev_b32_e32 v0, 1, v36
	v_lshrrev_b32_e32 v37, 2, v36
	v_and_b32_e32 v0, 24, v0
	v_ashrrev_i32_e32 v54, 4, v36
	v_and_or_b32 v38, v37, 3, v0
	v_lshlrev_b32_e32 v37, 2, v36
	v_sub_u32_e32 v42, 0x7f, v54
	v_and_b32_e32 v37, 12, v37
	v_cvt_f32_i32_e32 v42, v42
	v_or_b32_e32 v41, v37, v34
	v_lshlrev_b32_e32 v55, 1, v41
	v_cvt_f32_i32_e32 v41, v54
	v_mul_f32_e64 v42, v42, -v50
	v_mul_f32_e32 v42, 0x3fb8aa3b, v42
	v_exp_f32_e32 v84, v42
	v_mul_f32_e64 v41, v41, -v51
	v_mul_f32_e32 v41, 0x3fb8aa3b, v41
	v_exp_f32_e32 v82, v41
	v_lshlrev_b32_e32 v42, 16, v30
	v_and_b32_e32 v43, 0xffff0000, v30
	v_pk_mul_f32 v[44:45], v[84:85], v[42:43] op_sel_hi:[0,1]
	v_cvt_pk_bf16_f32 v30, v44, v45
	v_lshlrev_b32_e32 v44, 16, v31
	v_and_b32_e32 v45, 0xffff0000, v31
	v_pk_mul_f32 v[42:43], v[82:83], v[42:43] op_sel_hi:[0,1]
	v_pk_mul_f32 v[46:47], v[84:85], v[44:45] op_sel_hi:[0,1]
	v_pk_mul_f32 v[44:45], v[82:83], v[44:45] op_sel_hi:[0,1]
	v_cvt_pk_bf16_f32 v42, v42, v43
	v_cvt_pk_bf16_f32 v43, v44, v45
	v_lshlrev_b32_e32 v44, 16, v32
	v_and_b32_e32 v45, 0xffff0000, v32
	v_cvt_pk_bf16_f32 v31, v46, v47
	v_pk_mul_f32 v[46:47], v[84:85], v[44:45] op_sel_hi:[0,1]
	v_cvt_pk_bf16_f32 v32, v46, v47
	v_lshlrev_b32_e32 v46, 16, v33
	v_and_b32_e32 v47, 0xffff0000, v33
	v_pk_mul_f32 v[44:45], v[82:83], v[44:45] op_sel_hi:[0,1]
	v_pk_mul_f32 v[48:49], v[84:85], v[46:47] op_sel_hi:[0,1]
	v_pk_mul_f32 v[46:47], v[82:83], v[46:47] op_sel_hi:[0,1]
	v_mul_lo_u32 v41, v54, s56
	v_cvt_pk_bf16_f32 v44, v44, v45
	v_cvt_pk_bf16_f32 v33, v48, v49
	v_cvt_pk_bf16_f32 v45, v46, v47
	v_add_u32_e32 v114, v52, v41
	v_ashrrev_i32_e32 v46, 4, v40
	ds_write_b128 v114, v[30:33]
	v_sub_u32_e32 v30, 0x7f, v46
	v_cvt_f32_i32_e32 v30, v30
	v_cvt_f32_i32_e32 v31, v46
	v_add_u32_e32 v116, v53, v41
	ds_write_b128 v116, v[42:45]
	v_mul_f32_e64 v30, v30, -v50
	v_mul_f32_e32 v30, 0x3fb8aa3b, v30
	v_exp_f32_e32 v88, v30
	v_mul_f32_e64 v30, v31, -v51
	v_mul_f32_e32 v30, 0x3fb8aa3b, v30
	v_exp_f32_e32 v86, v30
	v_lshlrev_b32_e32 v30, 16, v26
	v_and_b32_e32 v31, 0xffff0000, v26
	v_pk_mul_f32 v[32:33], v[88:89], v[30:31] op_sel_hi:[0,1]
	v_cvt_pk_bf16_f32 v26, v32, v33
	v_lshlrev_b32_e32 v32, 16, v27
	v_and_b32_e32 v33, 0xffff0000, v27
	v_pk_mul_f32 v[30:31], v[86:87], v[30:31] op_sel_hi:[0,1]
	v_pk_mul_f32 v[40:41], v[88:89], v[32:33] op_sel_hi:[0,1]
	v_pk_mul_f32 v[32:33], v[86:87], v[32:33] op_sel_hi:[0,1]
	v_cvt_pk_bf16_f32 v30, v30, v31
	v_cvt_pk_bf16_f32 v31, v32, v33
	v_lshlrev_b32_e32 v32, 16, v28
	v_and_b32_e32 v33, 0xffff0000, v28
	v_cvt_pk_bf16_f32 v27, v40, v41
	v_pk_mul_f32 v[40:41], v[88:89], v[32:33] op_sel_hi:[0,1]
	v_cvt_pk_bf16_f32 v28, v40, v41
	v_lshlrev_b32_e32 v40, 16, v29
	v_and_b32_e32 v41, 0xffff0000, v29
	v_pk_mul_f32 v[32:33], v[86:87], v[32:33] op_sel_hi:[0,1]
	v_pk_mul_f32 v[42:43], v[88:89], v[40:41] op_sel_hi:[0,1]
	v_pk_mul_f32 v[40:41], v[86:87], v[40:41] op_sel_hi:[0,1]
	v_cvt_pk_bf16_f32 v32, v32, v33
	v_cvt_pk_bf16_f32 v33, v40, v41
	v_mul_lo_u32 v40, v46, s56
	v_cvt_pk_bf16_f32 v29, v42, v43
	v_add_u32_e32 v117, v52, v40
	v_ashrrev_i32_e32 v39, 4, v39
	ds_write_b128 v117, v[26:29]
	v_sub_u32_e32 v26, 0x7f, v39
	v_cvt_f32_i32_e32 v26, v26
	v_cvt_f32_i32_e32 v27, v39
	v_add_u32_e32 v118, v53, v40
	ds_write_b128 v118, v[30:33]
	v_mul_f32_e64 v26, v26, -v50
	v_mul_f32_e32 v26, 0x3fb8aa3b, v26
	v_exp_f32_e32 v94, v26
	v_mul_f32_e64 v26, v27, -v51
	v_mul_f32_e32 v26, 0x3fb8aa3b, v26
	v_exp_f32_e32 v90, v26
	v_lshlrev_b32_e32 v26, 16, v22
	v_and_b32_e32 v27, 0xffff0000, v22
	v_pk_mul_f32 v[28:29], v[94:95], v[26:27] op_sel_hi:[0,1]
	v_cvt_pk_bf16_f32 v22, v28, v29
	v_lshlrev_b32_e32 v28, 16, v23
	v_and_b32_e32 v29, 0xffff0000, v23
	v_pk_mul_f32 v[26:27], v[90:91], v[26:27] op_sel_hi:[0,1]
	v_pk_mul_f32 v[30:31], v[94:95], v[28:29] op_sel_hi:[0,1]
	v_pk_mul_f32 v[28:29], v[90:91], v[28:29] op_sel_hi:[0,1]
	v_cvt_pk_bf16_f32 v26, v26, v27
	v_cvt_pk_bf16_f32 v27, v28, v29
	v_lshlrev_b32_e32 v28, 16, v24
	v_and_b32_e32 v29, 0xffff0000, v24
	v_cvt_pk_bf16_f32 v23, v30, v31
	v_pk_mul_f32 v[30:31], v[94:95], v[28:29] op_sel_hi:[0,1]
	v_cvt_pk_bf16_f32 v24, v30, v31
	v_lshlrev_b32_e32 v30, 16, v25
	v_and_b32_e32 v31, 0xffff0000, v25
	v_pk_mul_f32 v[28:29], v[90:91], v[28:29] op_sel_hi:[0,1]
	v_pk_mul_f32 v[32:33], v[94:95], v[30:31] op_sel_hi:[0,1]
	v_pk_mul_f32 v[30:31], v[90:91], v[30:31] op_sel_hi:[0,1]
	v_cvt_pk_bf16_f32 v28, v28, v29
	v_cvt_pk_bf16_f32 v29, v30, v31
	v_mul_lo_u32 v30, v39, s56
	v_cvt_pk_bf16_f32 v25, v32, v33
	v_add_u32_e32 v119, v52, v30
	v_ashrrev_i32_e32 v31, 4, v35
	ds_write_b128 v119, v[22:25]
	v_sub_u32_e32 v22, 0x7f, v31
	v_cvt_f32_i32_e32 v22, v22
	v_cvt_f32_i32_e32 v23, v31
	v_add_u32_e32 v120, v53, v30
	ds_write_b128 v120, v[26:29]
	v_mul_f32_e64 v22, v22, -v50
	v_mul_f32_e32 v22, 0x3fb8aa3b, v22
	v_exp_f32_e32 v98, v22
	v_mul_f32_e64 v22, v23, -v51
	v_mul_f32_e32 v22, 0x3fb8aa3b, v22
	v_exp_f32_e32 v96, v22
	v_lshlrev_b32_e32 v22, 16, v18
	v_and_b32_e32 v23, 0xffff0000, v18
	v_pk_mul_f32 v[24:25], v[98:99], v[22:23] op_sel_hi:[0,1]
	v_cvt_pk_bf16_f32 v18, v24, v25
	v_lshlrev_b32_e32 v24, 16, v19
	v_and_b32_e32 v25, 0xffff0000, v19
	v_pk_mul_f32 v[22:23], v[96:97], v[22:23] op_sel_hi:[0,1]
	v_pk_mul_f32 v[26:27], v[98:99], v[24:25] op_sel_hi:[0,1]
	v_pk_mul_f32 v[24:25], v[96:97], v[24:25] op_sel_hi:[0,1]
	v_cvt_pk_bf16_f32 v22, v22, v23
	v_cvt_pk_bf16_f32 v23, v24, v25
	v_lshlrev_b32_e32 v24, 16, v20
	v_and_b32_e32 v25, 0xffff0000, v20
	v_cvt_pk_bf16_f32 v19, v26, v27
	v_pk_mul_f32 v[26:27], v[98:99], v[24:25] op_sel_hi:[0,1]
	v_cvt_pk_bf16_f32 v20, v26, v27
	v_lshlrev_b32_e32 v26, 16, v21
	v_and_b32_e32 v27, 0xffff0000, v21
	v_pk_mul_f32 v[24:25], v[96:97], v[24:25] op_sel_hi:[0,1]
	v_pk_mul_f32 v[28:29], v[98:99], v[26:27] op_sel_hi:[0,1]
	v_pk_mul_f32 v[26:27], v[96:97], v[26:27] op_sel_hi:[0,1]
	v_cvt_pk_bf16_f32 v24, v24, v25
	v_cvt_pk_bf16_f32 v25, v26, v27
	v_mul_lo_u32 v26, v31, s56
	v_lshlrev_b32_e32 v37, 1, v37
	v_cvt_pk_bf16_f32 v21, v28, v29
	v_add_u32_e32 v121, v52, v26
	ds_write_b128 v121, v[18:21]
	v_add_u32_e32 v20, s50, v37
	v_mul_u32_u24_e32 v18, 0x210, v38
	v_add_u32_e32 v122, v53, v26
	v_add3_u32 v83, 0, v18, v55
	v_mad_u32_u24 v115, v38, s56, v20
	ds_write_b128 v122, v[22:25]
	s_waitcnt lgkmcnt(0)
	s_barrier
; #define LAS __attribute__((address_space(3)))
; __device__ __forceinline__ f32x4 mfma16(bf16x8 a, bf16x8 b, f32x4 c) { return __builtin_amdgcn_mfma_f32_16x16x32_bf16(a, b, c, 0, 0, 0); }
; __device__ __forceinline__ void ret_kv_unit(LAS unsigned char* lds, const bf16* P, bf16* KV, const float* dec, int u, int tid) {
;     ...
;         for (int dir = 0; dir < 2; ++dir) {
;             const LAS unsigned char* Vd = dir ? Vb : Vf;
;             f32x4 acc[8][2];
; #pragma unroll
;             for (int mt = 0; mt < 8; ++mt) { acc[mt][0] = (f32x4){0.f, 0.f, 0.f, 0.f}; acc[mt][1] = (f32x4){0.f, 0.f, 0.f, 0.f}; }
; #pragma unroll
;             for (int ks = 0; ks < 4; ++ks) {
;                 const bf16x8 kf0 = ldtr(Kt, RSK, 32 * ks, 32 * w, lane), kf1 = ldtr(Kt, RSK, 32 * ks, 32 * w + 16, lane);
; #pragma unroll
;                 for (int mt = 0; mt < 8; ++mt) { const bf16x8 vf = ldtr(Vd, RSV, 32 * ks, 16 * mt, lane); acc[mt][0] = mfma16(kf0, vf, acc[mt][0]); acc[mt][1] = mfma16(kf1, vf, acc[mt][1]); }
;                 __builtin_amdgcn_sched_barrier(0);
;             }
	ds_read_b64_tr_b16 v[24:25], v83 offset:2112
	ds_read_b64_tr_b16 v[22:23], v83
	ds_read_b64_tr_b16 v[28:29], v83 offset:2144
	ds_read_b64_tr_b16 v[26:27], v83 offset:32
	ds_read_b64_tr_b16 v[32:33], v115 offset:1088
	ds_read_b64_tr_b16 v[30:31], v115
	ds_read_b64_tr_b16 v[40:41], v115 offset:32
	ds_read_b64_tr_b16 v[44:45], v115 offset:64
	ds_read_b64_tr_b16 v[48:49], v115 offset:96
	ds_read_b64_tr_b16 v[42:43], v115 offset:1120
	ds_read_b64_tr_b16 v[46:47], v115 offset:1152
	ds_read_b64_tr_b16 v[50:51], v115 offset:1184
	ds_read_b64_tr_b16 v[70:71], v115 offset:1216
	ds_read_b64_tr_b16 v[68:69], v115 offset:128
	ds_read_b64_tr_b16 v[72:73], v115 offset:160
	ds_read_b64_tr_b16 v[76:77], v115 offset:192
	ds_read_b64_tr_b16 v[100:101], v115 offset:224
	ds_read_b64_tr_b16 v[74:75], v115 offset:1248
	ds_read_b64_tr_b16 v[78:79], v115 offset:1280
	ds_read_b64_tr_b16 v[102:103], v115 offset:1312
	v_ashrrev_i32_e32 v35, 31, v34
	v_lshl_add_u64 v[18:19], v[34:35], 1, s[10:11]
	s_waitcnt lgkmcnt(14)
	v_mfma_f32_16x16x32_bf16 v[52:55], v[22:25], v[30:33], 0
	s_lshl_b32 s26, s18, 18
	v_lshl_add_u64 v[18:19], v[18:19], 0, v[0:1]
	v_mfma_f32_16x16x32_bf16 v[30:33], v[26:29], v[30:33], 0
	s_waitcnt lgkmcnt(10)
	v_mfma_f32_16x16x32_bf16 v[56:59], v[22:25], v[40:43], 0
	v_mfma_f32_16x16x32_bf16 v[40:43], v[26:29], v[40:43], 0
	s_waitcnt lgkmcnt(9)
	v_mfma_f32_16x16x32_bf16 v[60:63], v[22:25], v[44:47], 0
	v_mfma_f32_16x16x32_bf16 v[44:47], v[26:29], v[44:47], 0
	s_waitcnt lgkmcnt(8)
	v_mfma_f32_16x16x32_bf16 v[64:67], v[22:25], v[48:51], 0
	v_mfma_f32_16x16x32_bf16 v[48:51], v[26:29], v[48:51], 0
	s_waitcnt lgkmcnt(6)
	v_mfma_f32_16x16x32_bf16 v[104:107], v[22:25], v[68:71], 0
	v_mfma_f32_16x16x32_bf16 v[68:71], v[26:29], v[68:71], 0
	s_waitcnt lgkmcnt(2)
	v_mfma_f32_16x16x32_bf16 v[108:111], v[22:25], v[72:75], 0
	v_mfma_f32_16x16x32_bf16 v[72:75], v[26:29], v[72:75], 0
	s_waitcnt lgkmcnt(1)
	v_mfma_f32_16x16x32_bf16 v[124:127], v[22:25], v[76:79], 0
	v_mfma_f32_16x16x32_bf16 v[76:79], v[26:29], v[76:79], 0
	s_waitcnt lgkmcnt(0)
	v_mfma_f32_16x16x32_bf16 v[22:25], v[22:25], v[100:103], 0
	v_mfma_f32_16x16x32_bf16 v[26:29], v[26:29], v[100:103], 0
	v_mad_u32_u24 v95, v38, s56, v234
	ds_read_b64_tr_b16 v[102:103], v83 offset:19008
	ds_read_b64_tr_b16 v[100:101], v83 offset:16896
	ds_read_b64_tr_b16 v[128:129], v83 offset:16928
	ds_read_b64_tr_b16 v[130:131], v83 offset:19040
	v_add_u32_e32 v87, v20, v95
	ds_read_b64_tr_b16 v[134:135], v87 offset:1088
	ds_read_b64_tr_b16 v[132:133], v87
	ds_read_b64_tr_b16 v[136:137], v87 offset:32
	ds_read_b64_tr_b16 v[138:139], v87 offset:1120
	s_waitcnt lgkmcnt(2)
	v_mfma_f32_16x16x32_bf16 v[52:55], v[100:103], v[132:135], v[52:55]
	v_mfma_f32_16x16x32_bf16 v[30:33], v[128:131], v[132:135], v[30:33]
	ds_read_b64_tr_b16 v[132:133], v87 offset:64
	ds_read_b64_tr_b16 v[134:135], v87 offset:1152
	s_waitcnt lgkmcnt(0)
	v_mfma_f32_16x16x32_bf16 v[60:63], v[100:103], v[132:135], v[60:63]
	v_mfma_f32_16x16x32_bf16 v[44:47], v[128:131], v[132:135], v[44:47]
	ds_read_b64_tr_b16 v[132:133], v87 offset:96
	ds_read_b64_tr_b16 v[134:135], v87 offset:1184
	s_waitcnt lgkmcnt(0)
	v_mfma_f32_16x16x32_bf16 v[64:67], v[100:103], v[132:135], v[64:67]
	v_mfma_f32_16x16x32_bf16 v[48:51], v[128:131], v[132:135], v[48:51]
	ds_read_b64_tr_b16 v[132:133], v87 offset:128
	ds_read_b64_tr_b16 v[134:135], v87 offset:1216
	s_waitcnt lgkmcnt(0)
	v_mfma_f32_16x16x32_bf16 v[104:107], v[100:103], v[132:135], v[104:107]
	v_mfma_f32_16x16x32_bf16 v[68:71], v[128:131], v[132:135], v[68:71]
	ds_read_b64_tr_b16 v[132:133], v87 offset:160
	ds_read_b64_tr_b16 v[134:135], v87 offset:1248
	s_waitcnt lgkmcnt(0)
	v_mfma_f32_16x16x32_bf16 v[108:111], v[100:103], v[132:135], v[108:111]
	v_mfma_f32_16x16x32_bf16 v[72:75], v[128:131], v[132:135], v[72:75]
	ds_read_b64_tr_b16 v[132:133], v87 offset:192
	ds_read_b64_tr_b16 v[134:135], v87 offset:1280
	s_waitcnt lgkmcnt(0)
	v_mfma_f32_16x16x32_bf16 v[124:127], v[100:103], v[132:135], v[124:127]
	v_mfma_f32_16x16x32_bf16 v[76:79], v[128:131], v[132:135], v[76:79]
	ds_read_b64_tr_b16 v[132:133], v87 offset:224
	ds_read_b64_tr_b16 v[134:135], v87 offset:1312
	v_mfma_f32_16x16x32_bf16 v[56:59], v[100:103], v[136:139], v[56:59]
	v_mfma_f32_16x16x32_bf16 v[40:43], v[128:131], v[136:139], v[40:43]
	s_waitcnt lgkmcnt(0)
	v_mfma_f32_16x16x32_bf16 v[22:25], v[100:103], v[132:135], v[22:25]
	v_mfma_f32_16x16x32_bf16 v[26:29], v[128:131], v[132:135], v[26:29]
	v_mad_u32_u24 v97, v38, s56, v233
	ds_read_b64_tr_b16 v[102:103], v83 offset:35904
	ds_read_b64_tr_b16 v[100:101], v83 offset:33792
	ds_read_b64_tr_b16 v[128:129], v83 offset:33824
	ds_read_b64_tr_b16 v[130:131], v83 offset:35936
	v_add_u32_e32 v89, v20, v97
	ds_read_b64_tr_b16 v[134:135], v89 offset:1088
	ds_read_b64_tr_b16 v[132:133], v89
	ds_read_b64_tr_b16 v[136:137], v89 offset:32
	ds_read_b64_tr_b16 v[138:139], v89 offset:1120
	s_waitcnt lgkmcnt(2)
	v_mfma_f32_16x16x32_bf16 v[52:55], v[100:103], v[132:135], v[52:55]
	v_mfma_f32_16x16x32_bf16 v[30:33], v[128:131], v[132:135], v[30:33]
	ds_read_b64_tr_b16 v[132:133], v89 offset:64
	ds_read_b64_tr_b16 v[134:135], v89 offset:1152
	s_waitcnt lgkmcnt(0)
	v_mfma_f32_16x16x32_bf16 v[60:63], v[100:103], v[132:135], v[60:63]
	v_mfma_f32_16x16x32_bf16 v[44:47], v[128:131], v[132:135], v[44:47]
	ds_read_b64_tr_b16 v[132:133], v89 offset:96
	ds_read_b64_tr_b16 v[134:135], v89 offset:1184
	s_waitcnt lgkmcnt(0)
	v_mfma_f32_16x16x32_bf16 v[64:67], v[100:103], v[132:135], v[64:67]
	v_mfma_f32_16x16x32_bf16 v[48:51], v[128:131], v[132:135], v[48:51]
	ds_read_b64_tr_b16 v[132:133], v89 offset:128
	ds_read_b64_tr_b16 v[134:135], v89 offset:1216
	s_waitcnt lgkmcnt(0)
; #define LAS __attribute__((address_space(3)))
; __device__ __forceinline__ unsigned pk2(float lo, float hi) { return pg8::cvt_pk_bf16(lo, hi); }
; __device__ __forceinline__ f32x4 mfma16(bf16x8 a, bf16x8 b, f32x4 c) { return __builtin_amdgcn_mfma_f32_16x16x32_bf16(a, b, c, 0, 0, 0); }
; __device__ __forceinline__ void ret_kv_unit(LAS unsigned char* lds, const bf16* P, bf16* KV, const float* dec, int u, int tid) {
;     ...
;         for (int dir = 0; dir < 2; ++dir) {
;             const LAS unsigned char* Vd = dir ? Vb : Vf;
;             f32x4 acc[8][2];
; #pragma unroll
;             for (int mt = 0; mt < 8; ++mt) { acc[mt][0] = (f32x4){0.f, 0.f, 0.f, 0.f}; acc[mt][1] = (f32x4){0.f, 0.f, 0.f, 0.f}; }
; #pragma unroll
;             for (int ks = 0; ks < 4; ++ks) {
;                 const bf16x8 kf0 = ldtr(Kt, RSK, 32 * ks, 32 * w, lane), kf1 = ldtr(Kt, RSK, 32 * ks, 32 * w + 16, lane);
; #pragma unroll
;                 for (int mt = 0; mt < 8; ++mt) { const bf16x8 vf = ldtr(Vd, RSV, 32 * ks, 16 * mt, lane); acc[mt][0] = mfma16(kf0, vf, acc[mt][0]); acc[mt][1] = mfma16(kf1, vf, acc[mt][1]); }
;                 __builtin_amdgcn_sched_barrier(0);
;             }
;             bf16* dst = KV + ((size_t)n * 8 + h * 2 + dir) * 65536;
; #pragma unroll
;             for (int mt = 0; mt < 8; ++mt)
; #pragma unroll
;                 for (int nt = 0; nt < 2; ++nt) { u32x2 wv; wv.x = pk2(acc[mt][nt][0], acc[mt][nt][1]); wv.y = pk2(acc[mt][nt][2], acc[mt][nt][3]);
;                     *(u32x2*)(dst + (size_t)(eh * 128 + 16 * mt + i) * 256 + 32 * w + 16 * nt + 4 * g) = wv; }
	v_mfma_f32_16x16x32_bf16 v[104:107], v[100:103], v[132:135], v[104:107]
	v_mfma_f32_16x16x32_bf16 v[68:71], v[128:131], v[132:135], v[68:71]
	ds_read_b64_tr_b16 v[132:133], v89 offset:160
	ds_read_b64_tr_b16 v[134:135], v89 offset:1248
	s_waitcnt lgkmcnt(0)
	v_mfma_f32_16x16x32_bf16 v[108:111], v[100:103], v[132:135], v[108:111]
	v_mfma_f32_16x16x32_bf16 v[72:75], v[128:131], v[132:135], v[72:75]
	ds_read_b64_tr_b16 v[132:133], v89 offset:192
	ds_read_b64_tr_b16 v[134:135], v89 offset:1280
	s_waitcnt lgkmcnt(0)
	v_mfma_f32_16x16x32_bf16 v[124:127], v[100:103], v[132:135], v[124:127]
	v_mfma_f32_16x16x32_bf16 v[76:79], v[128:131], v[132:135], v[76:79]
	ds_read_b64_tr_b16 v[132:133], v89 offset:224
	ds_read_b64_tr_b16 v[134:135], v89 offset:1312
	v_mfma_f32_16x16x32_bf16 v[56:59], v[100:103], v[136:139], v[56:59]
	v_mfma_f32_16x16x32_bf16 v[40:43], v[128:131], v[136:139], v[40:43]
	s_waitcnt lgkmcnt(0)
	v_mfma_f32_16x16x32_bf16 v[22:25], v[100:103], v[132:135], v[22:25]
	v_mfma_f32_16x16x32_bf16 v[26:29], v[128:131], v[132:135], v[26:29]
	v_mad_u32_u24 v99, v38, s56, v204
	ds_read_b64_tr_b16 v[102:103], v83 offset:52800
	ds_read_b64_tr_b16 v[100:101], v83 offset:50688
	ds_read_b64_tr_b16 v[128:129], v83 offset:50720
	ds_read_b64_tr_b16 v[130:131], v83 offset:52832
	v_add_u32_e32 v91, v20, v99
	ds_read_b64_tr_b16 v[134:135], v91 offset:1088
	ds_read_b64_tr_b16 v[132:133], v91
	ds_read_b64_tr_b16 v[136:137], v91 offset:32
	ds_read_b64_tr_b16 v[138:139], v91 offset:1120
	s_waitcnt lgkmcnt(2)
	v_mfma_f32_16x16x32_bf16 v[52:55], v[100:103], v[132:135], v[52:55]
	v_mfma_f32_16x16x32_bf16 v[30:33], v[128:131], v[132:135], v[30:33]
	ds_read_b64_tr_b16 v[132:133], v91 offset:64
	ds_read_b64_tr_b16 v[134:135], v91 offset:1152
	s_waitcnt lgkmcnt(0)
	v_mfma_f32_16x16x32_bf16 v[60:63], v[100:103], v[132:135], v[60:63]
	v_mfma_f32_16x16x32_bf16 v[44:47], v[128:131], v[132:135], v[44:47]
	ds_read_b64_tr_b16 v[132:133], v91 offset:96
	ds_read_b64_tr_b16 v[134:135], v91 offset:1184
	s_waitcnt lgkmcnt(0)
	v_mfma_f32_16x16x32_bf16 v[64:67], v[100:103], v[132:135], v[64:67]
	v_mfma_f32_16x16x32_bf16 v[48:51], v[128:131], v[132:135], v[48:51]
	ds_read_b64_tr_b16 v[132:133], v91 offset:128
	ds_read_b64_tr_b16 v[134:135], v91 offset:1216
	s_waitcnt lgkmcnt(0)
	v_mfma_f32_16x16x32_bf16 v[104:107], v[100:103], v[132:135], v[104:107]
	v_mfma_f32_16x16x32_bf16 v[68:71], v[128:131], v[132:135], v[68:71]
	ds_read_b64_tr_b16 v[132:133], v91 offset:160
	ds_read_b64_tr_b16 v[134:135], v91 offset:1248
	v_mfma_f32_16x16x32_bf16 v[56:59], v[100:103], v[136:139], v[56:59]
	v_mfma_f32_16x16x32_bf16 v[40:43], v[128:131], v[136:139], v[40:43]
	s_waitcnt lgkmcnt(0)
	v_mfma_f32_16x16x32_bf16 v[136:139], v[100:103], v[132:135], v[108:111]
	s_nop 2
	ds_read_b64_tr_b16 v[108:109], v91 offset:192
	ds_read_b64_tr_b16 v[110:111], v91 offset:1280
	s_waitcnt lgkmcnt(0)
	v_mfma_f32_16x16x32_bf16 v[124:127], v[100:103], v[108:111], v[124:127]
	v_mfma_f32_16x16x32_bf16 v[76:79], v[128:131], v[108:111], v[76:79]
	ds_read_b64_tr_b16 v[108:109], v91 offset:224
	ds_read_b64_tr_b16 v[110:111], v91 offset:1312
	v_mfma_f32_16x16x32_bf16 v[72:75], v[128:131], v[132:135], v[72:75]
	s_waitcnt lgkmcnt(0)
	v_mfma_f32_16x16x32_bf16 v[20:23], v[100:103], v[108:111], v[22:25]
	v_mfma_f32_16x16x32_bf16 v[24:27], v[128:131], v[108:111], v[26:29]
	s_lshl_b64 s[12:13], s[12:13], 20
	v_lshl_add_u64 v[18:19], v[18:19], 0, s[12:13]
	v_lshlrev_b32_e32 v0, 9, v36
	v_lshl_add_u64 v[92:93], v[18:19], 0, s[26:27]
	v_and_b32_e32 v0, 0x1e00, v0
	v_lshl_add_u64 v[18:19], v[92:93], 0, v[0:1]
	v_cvt_pk_bf16_f32 v28, v52, v53
	v_cvt_pk_bf16_f32 v29, v54, v55
	global_store_dwordx2 v[18:19], v[28:29], off
	v_cvt_pk_bf16_f32 v28, v30, v31
	v_cvt_pk_bf16_f32 v29, v32, v33
	v_or_b32_e32 v102, 0x2000, v0
	v_mov_b32_e32 v103, v1
	global_store_dwordx2 v[18:19], v[28:29], off offset:32
	v_lshl_add_u64 v[18:19], v[92:93], 0, v[102:103]
	v_cvt_pk_bf16_f32 v28, v56, v57
	v_cvt_pk_bf16_f32 v29, v58, v59
	global_store_dwordx2 v[18:19], v[28:29], off
	v_cvt_pk_bf16_f32 v28, v40, v41
	v_cvt_pk_bf16_f32 v29, v42, v43
	v_or_b32_e32 v108, 0x4000, v0
	v_mov_b32_e32 v109, v1
	global_store_dwordx2 v[18:19], v[28:29], off offset:32
	v_lshl_add_u64 v[18:19], v[92:93], 0, v[108:109]
	v_cvt_pk_bf16_f32 v28, v60, v61
	v_cvt_pk_bf16_f32 v29, v62, v63
	global_store_dwordx2 v[18:19], v[28:29], off
	v_cvt_pk_bf16_f32 v28, v44, v45
	v_cvt_pk_bf16_f32 v29, v46, v47
	v_or_b32_e32 v112, 0x6000, v0
	v_mov_b32_e32 v113, v1
	global_store_dwordx2 v[18:19], v[28:29], off offset:32
	v_lshl_add_u64 v[18:19], v[92:93], 0, v[112:113]
	v_cvt_pk_bf16_f32 v28, v64, v65
	v_cvt_pk_bf16_f32 v29, v66, v67
	global_store_dwordx2 v[18:19], v[28:29], off
	v_cvt_pk_bf16_f32 v28, v48, v49
	v_cvt_pk_bf16_f32 v29, v50, v51
	v_or_b32_e32 v110, 0x8000, v0
	v_mov_b32_e32 v111, v1
	global_store_dwordx2 v[18:19], v[28:29], off offset:32
	v_lshl_add_u64 v[18:19], v[92:93], 0, v[110:111]
	v_cvt_pk_bf16_f32 v28, v104, v105
	v_cvt_pk_bf16_f32 v29, v106, v107
	global_store_dwordx2 v[18:19], v[28:29], off
	v_cvt_pk_bf16_f32 v28, v68, v69
	v_cvt_pk_bf16_f32 v29, v70, v71
	v_or_b32_e32 v106, 0xa000, v0
	v_mov_b32_e32 v107, v1
	global_store_dwordx2 v[18:19], v[28:29], off offset:32
	v_lshl_add_u64 v[18:19], v[92:93], 0, v[106:107]
	v_cvt_pk_bf16_f32 v28, v136, v137
	v_cvt_pk_bf16_f32 v29, v138, v139
	global_store_dwordx2 v[18:19], v[28:29], off
	v_cvt_pk_bf16_f32 v28, v72, v73
	v_cvt_pk_bf16_f32 v29, v74, v75
	v_or_b32_e32 v104, 0xc000, v0
	v_mov_b32_e32 v105, v1
	global_store_dwordx2 v[18:19], v[28:29], off offset:32
	v_lshl_add_u64 v[18:19], v[92:93], 0, v[104:105]
	v_cvt_pk_bf16_f32 v28, v124, v125
; #define LAS __attribute__((address_space(3)))
; __device__ __forceinline__ unsigned pk2(float lo, float hi) { return pg8::cvt_pk_bf16(lo, hi); }
; __device__ __forceinline__ f32x4 mfma16(bf16x8 a, bf16x8 b, f32x4 c) { return __builtin_amdgcn_mfma_f32_16x16x32_bf16(a, b, c, 0, 0, 0); }
; __device__ __forceinline__ void ret_kv_unit(LAS unsigned char* lds, const bf16* P, bf16* KV, const float* dec, int u, int tid) {
;     ...
;         for (int dir = 0; dir < 2; ++dir) {
;             const LAS unsigned char* Vd = dir ? Vb : Vf;
;             f32x4 acc[8][2];
; #pragma unroll
;             for (int mt = 0; mt < 8; ++mt) { acc[mt][0] = (f32x4){0.f, 0.f, 0.f, 0.f}; acc[mt][1] = (f32x4){0.f, 0.f, 0.f, 0.f}; }
; #pragma unroll
;             for (int ks = 0; ks < 4; ++ks) {
;                 const bf16x8 kf0 = ldtr(Kt, RSK, 32 * ks, 32 * w, lane), kf1 = ldtr(Kt, RSK, 32 * ks, 32 * w + 16, lane);
; #pragma unroll
;                 for (int mt = 0; mt < 8; ++mt) { const bf16x8 vf = ldtr(Vd, RSV, 32 * ks, 16 * mt, lane); acc[mt][0] = mfma16(kf0, vf, acc[mt][0]); acc[mt][1] = mfma16(kf1, vf, acc[mt][1]); }
;                 __builtin_amdgcn_sched_barrier(0);
;             }
;             bf16* dst = KV + ((size_t)n * 8 + h * 2 + dir) * 65536;
; #pragma unroll
;             for (int mt = 0; mt < 8; ++mt)
; #pragma unroll
;                 for (int nt = 0; nt < 2; ++nt) { u32x2 wv; wv.x = pk2(acc[mt][nt][0], acc[mt][nt][1]); wv.y = pk2(acc[mt][nt][2], acc[mt][nt][3]);
;                     *(u32x2*)(dst + (size_t)(eh * 128 + 16 * mt + i) * 256 + 32 * w + 16 * nt + 4 * g) = wv; }
	v_cvt_pk_bf16_f32 v29, v126, v127
	global_store_dwordx2 v[18:19], v[28:29], off
	v_cvt_pk_bf16_f32 v28, v76, v77
	v_cvt_pk_bf16_f32 v29, v78, v79
	v_or_b32_e32 v100, 0xe000, v0
	v_mov_b32_e32 v101, v1
	global_store_dwordx2 v[18:19], v[28:29], off offset:32
	v_lshl_add_u64 v[18:19], v[92:93], 0, v[100:101]
	v_cvt_pk_bf16_f32 v20, v20, v21
	v_cvt_pk_bf16_f32 v21, v22, v23
	global_store_dwordx2 v[18:19], v[20:21], off
	v_cvt_pk_bf16_f32 v20, v24, v25
	v_cvt_pk_bf16_f32 v21, v26, v27
	v_add_u32_e32 v123, s95, v37
	global_store_dwordx2 v[18:19], v[20:21], off offset:32
	v_mad_u32_u24 v85, v38, s56, v123
	ds_read_b64_tr_b16 v[48:49], v83 offset:2112
	ds_read_b64_tr_b16 v[46:47], v83
	ds_read_b64_tr_b16 v[34:35], v83 offset:32
	ds_read_b64_tr_b16 v[36:37], v83 offset:2144
	ds_read_b64_tr_b16 v[24:25], v85 offset:1088
	ds_read_b64_tr_b16 v[22:23], v85
	ds_read_b64_tr_b16 v[30:31], v85 offset:32
	ds_read_b64_tr_b16 v[32:33], v85 offset:1120
	ds_read_b64_tr_b16 v[42:43], v85 offset:64
	ds_read_b64_tr_b16 v[44:45], v85 offset:1152
	ds_read_b64_tr_b16 v[54:55], v85 offset:96
	ds_read_b64_tr_b16 v[56:57], v85 offset:1184
	ds_read_b64_tr_b16 v[62:63], v85 offset:128
	ds_read_b64_tr_b16 v[64:65], v85 offset:1216
	ds_read_b64_tr_b16 v[70:71], v85 offset:160
	ds_read_b64_tr_b16 v[72:73], v85 offset:1248
	ds_read_b64_tr_b16 v[78:79], v85 offset:192
	ds_read_b64_tr_b16 v[80:81], v85 offset:1280
	ds_read_b64_tr_b16 v[124:125], v85 offset:224
	ds_read_b64_tr_b16 v[126:127], v85 offset:1312
	s_waitcnt lgkmcnt(14)
	v_mfma_f32_16x16x32_bf16 v[18:21], v[46:49], v[22:25], 0
	v_mfma_f32_16x16x32_bf16 v[22:25], v[34:37], v[22:25], 0
	s_waitcnt lgkmcnt(12)
	v_mfma_f32_16x16x32_bf16 v[26:29], v[46:49], v[30:33], 0
	v_mfma_f32_16x16x32_bf16 v[30:33], v[34:37], v[30:33], 0
	s_waitcnt lgkmcnt(10)
	v_mfma_f32_16x16x32_bf16 v[38:41], v[46:49], v[42:45], 0
	v_mfma_f32_16x16x32_bf16 v[42:45], v[34:37], v[42:45], 0
	s_waitcnt lgkmcnt(8)
	v_mfma_f32_16x16x32_bf16 v[50:53], v[46:49], v[54:57], 0
	v_mfma_f32_16x16x32_bf16 v[54:57], v[34:37], v[54:57], 0
	s_waitcnt lgkmcnt(6)
	v_mfma_f32_16x16x32_bf16 v[58:61], v[46:49], v[62:65], 0
	v_mfma_f32_16x16x32_bf16 v[62:65], v[34:37], v[62:65], 0
	s_waitcnt lgkmcnt(4)
	v_mfma_f32_16x16x32_bf16 v[66:69], v[46:49], v[70:73], 0
	v_mfma_f32_16x16x32_bf16 v[70:73], v[34:37], v[70:73], 0
	s_waitcnt lgkmcnt(2)
	v_mfma_f32_16x16x32_bf16 v[74:77], v[46:49], v[78:81], 0
	v_mfma_f32_16x16x32_bf16 v[78:81], v[34:37], v[78:81], 0
	s_waitcnt lgkmcnt(0)
	v_mfma_f32_16x16x32_bf16 v[46:49], v[46:49], v[124:127], 0
	v_mfma_f32_16x16x32_bf16 v[34:37], v[34:37], v[124:127], 0
	ds_read_b64_tr_b16 v[126:127], v83 offset:19008
	ds_read_b64_tr_b16 v[124:125], v83 offset:16896
	ds_read_b64_tr_b16 v[128:129], v83 offset:16928
	ds_read_b64_tr_b16 v[130:131], v83 offset:19040
	v_add_u32_e32 v95, v123, v95
	ds_read_b64_tr_b16 v[134:135], v95 offset:1088
	ds_read_b64_tr_b16 v[132:133], v95
	ds_read_b64_tr_b16 v[136:137], v95 offset:32
	ds_read_b64_tr_b16 v[138:139], v95 offset:1120
	s_waitcnt lgkmcnt(2)
	v_mfma_f32_16x16x32_bf16 v[18:21], v[124:127], v[132:135], v[18:21]
	v_mfma_f32_16x16x32_bf16 v[22:25], v[128:131], v[132:135], v[22:25]
	ds_read_b64_tr_b16 v[132:133], v95 offset:64
	ds_read_b64_tr_b16 v[134:135], v95 offset:1152
	s_waitcnt lgkmcnt(0)
	v_mfma_f32_16x16x32_bf16 v[38:41], v[124:127], v[132:135], v[38:41]
	v_mfma_f32_16x16x32_bf16 v[42:45], v[128:131], v[132:135], v[42:45]
	ds_read_b64_tr_b16 v[132:133], v95 offset:96
	ds_read_b64_tr_b16 v[134:135], v95 offset:1184
	s_waitcnt lgkmcnt(0)
	v_mfma_f32_16x16x32_bf16 v[50:53], v[124:127], v[132:135], v[50:53]
	v_mfma_f32_16x16x32_bf16 v[54:57], v[128:131], v[132:135], v[54:57]
	ds_read_b64_tr_b16 v[132:133], v95 offset:128
	ds_read_b64_tr_b16 v[134:135], v95 offset:1216
	s_waitcnt lgkmcnt(0)
	v_mfma_f32_16x16x32_bf16 v[58:61], v[124:127], v[132:135], v[58:61]
	v_mfma_f32_16x16x32_bf16 v[62:65], v[128:131], v[132:135], v[62:65]
	ds_read_b64_tr_b16 v[132:133], v95 offset:160
	ds_read_b64_tr_b16 v[134:135], v95 offset:1248
	s_waitcnt lgkmcnt(0)
	v_mfma_f32_16x16x32_bf16 v[66:69], v[124:127], v[132:135], v[66:69]
	v_mfma_f32_16x16x32_bf16 v[70:73], v[128:131], v[132:135], v[70:73]
	ds_read_b64_tr_b16 v[132:133], v95 offset:192
	ds_read_b64_tr_b16 v[134:135], v95 offset:1280
	s_waitcnt lgkmcnt(0)
	v_mfma_f32_16x16x32_bf16 v[74:77], v[124:127], v[132:135], v[74:77]
	v_mfma_f32_16x16x32_bf16 v[78:81], v[128:131], v[132:135], v[78:81]
	ds_read_b64_tr_b16 v[132:133], v95 offset:224
	ds_read_b64_tr_b16 v[134:135], v95 offset:1312
	v_mfma_f32_16x16x32_bf16 v[26:29], v[124:127], v[136:139], v[26:29]
	v_mfma_f32_16x16x32_bf16 v[30:33], v[128:131], v[136:139], v[30:33]
	s_waitcnt lgkmcnt(0)
	v_mfma_f32_16x16x32_bf16 v[46:49], v[124:127], v[132:135], v[46:49]
	v_mfma_f32_16x16x32_bf16 v[34:37], v[128:131], v[132:135], v[34:37]
	ds_read_b64_tr_b16 v[126:127], v83 offset:35904
	ds_read_b64_tr_b16 v[124:125], v83 offset:33792
	ds_read_b64_tr_b16 v[128:129], v83 offset:33824
	ds_read_b64_tr_b16 v[130:131], v83 offset:35936
	v_add_u32_e32 v97, v123, v97
	ds_read_b64_tr_b16 v[134:135], v97 offset:1088
	ds_read_b64_tr_b16 v[132:133], v97
	ds_read_b64_tr_b16 v[136:137], v97 offset:32
	ds_read_b64_tr_b16 v[138:139], v97 offset:1120
	s_waitcnt lgkmcnt(2)
	v_mfma_f32_16x16x32_bf16 v[18:21], v[124:127], v[132:135], v[18:21]
	v_mfma_f32_16x16x32_bf16 v[22:25], v[128:131], v[132:135], v[22:25]
	ds_read_b64_tr_b16 v[132:133], v97 offset:64
	ds_read_b64_tr_b16 v[134:135], v97 offset:1152
	s_waitcnt lgkmcnt(0)
; #define LAS __attribute__((address_space(3)))
; __device__ __forceinline__ unsigned pk2(float lo, float hi) { return pg8::cvt_pk_bf16(lo, hi); }
; __device__ __forceinline__ f32x4 mfma16(bf16x8 a, bf16x8 b, f32x4 c) { return __builtin_amdgcn_mfma_f32_16x16x32_bf16(a, b, c, 0, 0, 0); }
; __device__ __forceinline__ void ret_kv_unit(LAS unsigned char* lds, const bf16* P, bf16* KV, const float* dec, int u, int tid) {
;     ...
;         for (int dir = 0; dir < 2; ++dir) {
;             const LAS unsigned char* Vd = dir ? Vb : Vf;
;             f32x4 acc[8][2];
; #pragma unroll
;             for (int mt = 0; mt < 8; ++mt) { acc[mt][0] = (f32x4){0.f, 0.f, 0.f, 0.f}; acc[mt][1] = (f32x4){0.f, 0.f, 0.f, 0.f}; }
; #pragma unroll
;             for (int ks = 0; ks < 4; ++ks) {
;                 const bf16x8 kf0 = ldtr(Kt, RSK, 32 * ks, 32 * w, lane), kf1 = ldtr(Kt, RSK, 32 * ks, 32 * w + 16, lane);
; #pragma unroll
;                 for (int mt = 0; mt < 8; ++mt) { const bf16x8 vf = ldtr(Vd, RSV, 32 * ks, 16 * mt, lane); acc[mt][0] = mfma16(kf0, vf, acc[mt][0]); acc[mt][1] = mfma16(kf1, vf, acc[mt][1]); }
;                 __builtin_amdgcn_sched_barrier(0);
;             }
;             bf16* dst = KV + ((size_t)n * 8 + h * 2 + dir) * 65536;
; #pragma unroll
;             for (int mt = 0; mt < 8; ++mt)
; #pragma unroll
;                 for (int nt = 0; nt < 2; ++nt) { u32x2 wv; wv.x = pk2(acc[mt][nt][0], acc[mt][nt][1]); wv.y = pk2(acc[mt][nt][2], acc[mt][nt][3]);
;                     *(u32x2*)(dst + (size_t)(eh * 128 + 16 * mt + i) * 256 + 32 * w + 16 * nt + 4 * g) = wv; }
	v_mfma_f32_16x16x32_bf16 v[38:41], v[124:127], v[132:135], v[38:41]
	v_mfma_f32_16x16x32_bf16 v[42:45], v[128:131], v[132:135], v[42:45]
	ds_read_b64_tr_b16 v[132:133], v97 offset:96
	ds_read_b64_tr_b16 v[134:135], v97 offset:1184
	s_waitcnt lgkmcnt(0)
	v_mfma_f32_16x16x32_bf16 v[50:53], v[124:127], v[132:135], v[50:53]
	v_mfma_f32_16x16x32_bf16 v[54:57], v[128:131], v[132:135], v[54:57]
	ds_read_b64_tr_b16 v[132:133], v97 offset:128
	ds_read_b64_tr_b16 v[134:135], v97 offset:1216
	s_waitcnt lgkmcnt(0)
	v_mfma_f32_16x16x32_bf16 v[58:61], v[124:127], v[132:135], v[58:61]
	v_mfma_f32_16x16x32_bf16 v[62:65], v[128:131], v[132:135], v[62:65]
	ds_read_b64_tr_b16 v[132:133], v97 offset:160
	ds_read_b64_tr_b16 v[134:135], v97 offset:1248
	s_waitcnt lgkmcnt(0)
	v_mfma_f32_16x16x32_bf16 v[66:69], v[124:127], v[132:135], v[66:69]
	v_mfma_f32_16x16x32_bf16 v[70:73], v[128:131], v[132:135], v[70:73]
	ds_read_b64_tr_b16 v[132:133], v97 offset:192
	ds_read_b64_tr_b16 v[134:135], v97 offset:1280
	s_waitcnt lgkmcnt(0)
	v_mfma_f32_16x16x32_bf16 v[74:77], v[124:127], v[132:135], v[74:77]
	v_mfma_f32_16x16x32_bf16 v[78:81], v[128:131], v[132:135], v[78:81]
	ds_read_b64_tr_b16 v[132:133], v97 offset:224
	ds_read_b64_tr_b16 v[134:135], v97 offset:1312
	v_mfma_f32_16x16x32_bf16 v[26:29], v[124:127], v[136:139], v[26:29]
	v_mfma_f32_16x16x32_bf16 v[30:33], v[128:131], v[136:139], v[30:33]
	s_waitcnt lgkmcnt(0)
	v_mfma_f32_16x16x32_bf16 v[46:49], v[124:127], v[132:135], v[46:49]
	v_mfma_f32_16x16x32_bf16 v[34:37], v[128:131], v[132:135], v[34:37]
	ds_read_b64_tr_b16 v[126:127], v83 offset:52800
	ds_read_b64_tr_b16 v[124:125], v83 offset:50688
	ds_read_b64_tr_b16 v[128:129], v83 offset:50720
	ds_read_b64_tr_b16 v[130:131], v83 offset:52832
	v_add_u32_e32 v99, v123, v99
	ds_read_b64_tr_b16 v[134:135], v99 offset:1088
	ds_read_b64_tr_b16 v[132:133], v99
	ds_read_b64_tr_b16 v[136:137], v99 offset:32
	ds_read_b64_tr_b16 v[138:139], v99 offset:1120
	s_waitcnt lgkmcnt(2)
	v_mfma_f32_16x16x32_bf16 v[18:21], v[124:127], v[132:135], v[18:21]
	v_mfma_f32_16x16x32_bf16 v[22:25], v[128:131], v[132:135], v[22:25]
	ds_read_b64_tr_b16 v[132:133], v99 offset:64
	ds_read_b64_tr_b16 v[134:135], v99 offset:1152
	s_waitcnt lgkmcnt(0)
	v_mfma_f32_16x16x32_bf16 v[38:41], v[124:127], v[132:135], v[38:41]
	v_mfma_f32_16x16x32_bf16 v[42:45], v[128:131], v[132:135], v[42:45]
	ds_read_b64_tr_b16 v[132:133], v99 offset:96
	ds_read_b64_tr_b16 v[134:135], v99 offset:1184
	s_waitcnt lgkmcnt(0)
	v_mfma_f32_16x16x32_bf16 v[50:53], v[124:127], v[132:135], v[50:53]
	v_mfma_f32_16x16x32_bf16 v[54:57], v[128:131], v[132:135], v[54:57]
	ds_read_b64_tr_b16 v[132:133], v99 offset:128
	ds_read_b64_tr_b16 v[134:135], v99 offset:1216
	s_waitcnt lgkmcnt(0)
	v_mfma_f32_16x16x32_bf16 v[58:61], v[124:127], v[132:135], v[58:61]
	v_mfma_f32_16x16x32_bf16 v[62:65], v[128:131], v[132:135], v[62:65]
	ds_read_b64_tr_b16 v[132:133], v99 offset:160
	ds_read_b64_tr_b16 v[134:135], v99 offset:1248
	v_mfma_f32_16x16x32_bf16 v[26:29], v[124:127], v[136:139], v[26:29]
	v_mfma_f32_16x16x32_bf16 v[30:33], v[128:131], v[136:139], v[30:33]
	s_waitcnt lgkmcnt(0)
	v_mfma_f32_16x16x32_bf16 v[136:139], v[124:127], v[132:135], v[66:69]
	v_mfma_f32_16x16x32_bf16 v[68:71], v[128:131], v[132:135], v[70:73]
	ds_read_b64_tr_b16 v[132:133], v99 offset:192
	ds_read_b64_tr_b16 v[134:135], v99 offset:1280
	s_waitcnt lgkmcnt(0)
	v_mfma_f32_16x16x32_bf16 v[72:75], v[124:127], v[132:135], v[74:77]
	v_mfma_f32_16x16x32_bf16 v[76:79], v[128:131], v[132:135], v[78:81]
	ds_read_b64_tr_b16 v[132:133], v99 offset:224
	ds_read_b64_tr_b16 v[134:135], v99 offset:1312
	s_waitcnt lgkmcnt(0)
	v_mfma_f32_16x16x32_bf16 v[46:49], v[124:127], v[132:135], v[46:49]
	v_mfma_f32_16x16x32_bf16 v[34:37], v[128:131], v[132:135], v[34:37]
	s_mov_b64 s[12:13], 0x20000
	v_lshl_add_u64 v[66:67], v[92:93], 0, s[12:13]
	v_lshl_add_u64 v[80:81], v[66:67], 0, v[0:1]
	v_cvt_pk_bf16_f32 v18, v18, v19
	v_cvt_pk_bf16_f32 v19, v20, v21
	global_store_dwordx2 v[80:81], v[18:19], off
	v_cvt_pk_bf16_f32 v18, v22, v23
	v_cvt_pk_bf16_f32 v19, v24, v25
	global_store_dwordx2 v[80:81], v[18:19], off offset:32
	v_lshl_add_u64 v[18:19], v[66:67], 0, v[102:103]
	v_cvt_pk_bf16_f32 v20, v26, v27
	v_cvt_pk_bf16_f32 v21, v28, v29
	global_store_dwordx2 v[18:19], v[20:21], off
	v_cvt_pk_bf16_f32 v20, v30, v31
	v_cvt_pk_bf16_f32 v21, v32, v33
	global_store_dwordx2 v[18:19], v[20:21], off offset:32
	v_lshl_add_u64 v[18:19], v[66:67], 0, v[108:109]
	v_cvt_pk_bf16_f32 v20, v38, v39
	v_cvt_pk_bf16_f32 v21, v40, v41
	global_store_dwordx2 v[18:19], v[20:21], off
	v_cvt_pk_bf16_f32 v20, v42, v43
	v_cvt_pk_bf16_f32 v21, v44, v45
	global_store_dwordx2 v[18:19], v[20:21], off offset:32
	v_lshl_add_u64 v[18:19], v[66:67], 0, v[112:113]
	v_cvt_pk_bf16_f32 v20, v50, v51
	v_cvt_pk_bf16_f32 v21, v52, v53
	global_store_dwordx2 v[18:19], v[20:21], off
	v_cvt_pk_bf16_f32 v20, v54, v55
	v_cvt_pk_bf16_f32 v21, v56, v57
	global_store_dwordx2 v[18:19], v[20:21], off offset:32
	v_lshl_add_u64 v[18:19], v[66:67], 0, v[110:111]
	v_cvt_pk_bf16_f32 v20, v58, v59
	v_cvt_pk_bf16_f32 v21, v60, v61
	global_store_dwordx2 v[18:19], v[20:21], off
	v_cvt_pk_bf16_f32 v20, v62, v63
	v_cvt_pk_bf16_f32 v21, v64, v65
	global_store_dwordx2 v[18:19], v[20:21], off offset:32
	v_lshl_add_u64 v[18:19], v[66:67], 0, v[106:107]
	v_cvt_pk_bf16_f32 v20, v136, v137
	v_cvt_pk_bf16_f32 v21, v138, v139
	global_store_dwordx2 v[18:19], v[20:21], off
	v_cvt_pk_bf16_f32 v20, v68, v69
	v_cvt_pk_bf16_f32 v21, v70, v71
	global_store_dwordx2 v[18:19], v[20:21], off offset:32
	v_lshl_add_u64 v[18:19], v[66:67], 0, v[104:105]
	v_cvt_pk_bf16_f32 v20, v72, v73
; #define LAS __attribute__((address_space(3)))
; __device__ __forceinline__ unsigned pk2(float lo, float hi) { return pg8::cvt_pk_bf16(lo, hi); }
; __device__ __forceinline__ float bflo(unsigned w) { return __uint_as_float(w << 16); }
; __device__ __forceinline__ float bfhi(unsigned w) { return __uint_as_float(w & 0xffff0000u); }
; __device__ __forceinline__ void ret_kv_unit(LAS unsigned char* lds, const bf16* P, bf16* KV, const float* dec, int u, int tid) {
;     ...
;         if (eh) __syncthreads();
;         {
; #pragma unroll
;           for (int k = 0; k < 4; ++k) { const int idx = tid + k * NTHR, r = idx >> 4, c8 = idx & 15; const u32x4 v = eh ? vvb[k] : vva[k];
;             const float sf = __expf((float)(127 - r) * lgf), sb = __expf((float)r * lgb);
;             u32x4 of, ob;
;             of.x = pk2(bflo(v.x) * sf, bfhi(v.x) * sf); of.y = pk2(bflo(v.y) * sf, bfhi(v.y) * sf); of.z = pk2(bflo(v.z) * sf, bfhi(v.z) * sf); of.w = pk2(bflo(v.w) * sf, bfhi(v.w) * sf);
;             ob.x = pk2(bflo(v.x) * sb, bfhi(v.x) * sb); ob.y = pk2(bflo(v.y) * sb, bfhi(v.y) * sb); ob.z = pk2(bflo(v.z) * sb, bfhi(v.z) * sb); ob.w = pk2(bflo(v.w) * sb, bfhi(v.w) * sb);
;             *(LAS u32x4*)(Vf + r * RSV + c8 * 16) = of; *(LAS u32x4*)(Vb + r * RSV + c8 * 16) = ob; } }
;         __syncthreads();
;     ...
;             bf16* dst = KV + ((size_t)n * 8 + h * 2 + dir) * 65536;
; #pragma unroll
;             for (int mt = 0; mt < 8; ++mt)
; #pragma unroll
;                 for (int nt = 0; nt < 2; ++nt) { u32x2 wv; wv.x = pk2(acc[mt][nt][0], acc[mt][nt][1]); wv.y = pk2(acc[mt][nt][2], acc[mt][nt][3]);
;                     *(u32x2*)(dst + (size_t)(eh * 128 + 16 * mt + i) * 256 + 32 * w + 16 * nt + 4 * g) = wv; }
	v_cvt_pk_bf16_f32 v21, v74, v75
	global_store_dwordx2 v[18:19], v[20:21], off
	v_cvt_pk_bf16_f32 v20, v76, v77
	v_cvt_pk_bf16_f32 v21, v78, v79
	global_store_dwordx2 v[18:19], v[20:21], off offset:32
	v_lshl_add_u64 v[18:19], v[66:67], 0, v[100:101]
	v_cvt_pk_bf16_f32 v20, v46, v47
	v_cvt_pk_bf16_f32 v21, v48, v49
	global_store_dwordx2 v[18:19], v[20:21], off
	v_cvt_pk_bf16_f32 v20, v34, v35
	v_cvt_pk_bf16_f32 v21, v36, v37
	global_store_dwordx2 v[18:19], v[20:21], off offset:32
	v_lshlrev_b32_e32 v18, 16, v14
	v_and_b32_e32 v19, 0xffff0000, v14
	v_pk_mul_f32 v[20:21], v[84:85], v[18:19] op_sel_hi:[0,1]
	v_cvt_pk_bf16_f32 v14, v20, v21
	v_lshlrev_b32_e32 v20, 16, v15
	v_and_b32_e32 v21, 0xffff0000, v15
	v_pk_mul_f32 v[18:19], v[82:83], v[18:19] op_sel_hi:[0,1]
	v_pk_mul_f32 v[22:23], v[84:85], v[20:21] op_sel_hi:[0,1]
	v_pk_mul_f32 v[20:21], v[82:83], v[20:21] op_sel_hi:[0,1]
	v_cvt_pk_bf16_f32 v18, v18, v19
	v_cvt_pk_bf16_f32 v19, v20, v21
	v_lshlrev_b32_e32 v20, 16, v16
	v_and_b32_e32 v21, 0xffff0000, v16
	v_cvt_pk_bf16_f32 v15, v22, v23
	v_pk_mul_f32 v[22:23], v[84:85], v[20:21] op_sel_hi:[0,1]
	v_cvt_pk_bf16_f32 v16, v22, v23
	v_lshlrev_b32_e32 v22, 16, v17
	v_and_b32_e32 v23, 0xffff0000, v17
	v_pk_mul_f32 v[24:25], v[84:85], v[22:23] op_sel_hi:[0,1]
	v_pk_mul_f32 v[20:21], v[82:83], v[20:21] op_sel_hi:[0,1]
	v_cvt_pk_bf16_f32 v17, v24, v25
	v_pk_mul_f32 v[22:23], v[82:83], v[22:23] op_sel_hi:[0,1]
	s_barrier
	v_cvt_pk_bf16_f32 v20, v20, v21
	v_cvt_pk_bf16_f32 v21, v22, v23
	ds_write_b128 v114, v[14:17]
	ds_write_b128 v116, v[18:21]
	v_lshlrev_b32_e32 v14, 16, v10
	v_and_b32_e32 v15, 0xffff0000, v10
	v_pk_mul_f32 v[16:17], v[88:89], v[14:15] op_sel_hi:[0,1]
	v_cvt_pk_bf16_f32 v10, v16, v17
	v_lshlrev_b32_e32 v16, 16, v11
	v_and_b32_e32 v17, 0xffff0000, v11
	v_pk_mul_f32 v[14:15], v[86:87], v[14:15] op_sel_hi:[0,1]
	v_pk_mul_f32 v[18:19], v[88:89], v[16:17] op_sel_hi:[0,1]
	v_pk_mul_f32 v[16:17], v[86:87], v[16:17] op_sel_hi:[0,1]
	v_cvt_pk_bf16_f32 v14, v14, v15
	v_cvt_pk_bf16_f32 v15, v16, v17
	v_lshlrev_b32_e32 v16, 16, v12
	v_and_b32_e32 v17, 0xffff0000, v12
	v_cvt_pk_bf16_f32 v11, v18, v19
	v_pk_mul_f32 v[18:19], v[88:89], v[16:17] op_sel_hi:[0,1]
	v_cvt_pk_bf16_f32 v12, v18, v19
	v_lshlrev_b32_e32 v18, 16, v13
	v_and_b32_e32 v19, 0xffff0000, v13
	v_pk_mul_f32 v[20:21], v[88:89], v[18:19] op_sel_hi:[0,1]
	v_pk_mul_f32 v[16:17], v[86:87], v[16:17] op_sel_hi:[0,1]
	v_cvt_pk_bf16_f32 v13, v20, v21
	v_pk_mul_f32 v[18:19], v[86:87], v[18:19] op_sel_hi:[0,1]
	v_cvt_pk_bf16_f32 v16, v16, v17
	v_cvt_pk_bf16_f32 v17, v18, v19
	ds_write_b128 v117, v[10:13]
	ds_write_b128 v118, v[14:17]
	v_lshlrev_b32_e32 v10, 16, v6
	v_and_b32_e32 v11, 0xffff0000, v6
	v_pk_mul_f32 v[12:13], v[94:95], v[10:11] op_sel_hi:[0,1]
	v_cvt_pk_bf16_f32 v6, v12, v13
	v_lshlrev_b32_e32 v12, 16, v7
	v_and_b32_e32 v13, 0xffff0000, v7
	v_pk_mul_f32 v[10:11], v[90:91], v[10:11] op_sel_hi:[0,1]
	v_pk_mul_f32 v[14:15], v[94:95], v[12:13] op_sel_hi:[0,1]
	v_pk_mul_f32 v[12:13], v[90:91], v[12:13] op_sel_hi:[0,1]
	v_cvt_pk_bf16_f32 v10, v10, v11
	v_cvt_pk_bf16_f32 v11, v12, v13
	v_lshlrev_b32_e32 v12, 16, v8
	v_and_b32_e32 v13, 0xffff0000, v8
	v_cvt_pk_bf16_f32 v7, v14, v15
	v_pk_mul_f32 v[14:15], v[94:95], v[12:13] op_sel_hi:[0,1]
	v_cvt_pk_bf16_f32 v8, v14, v15
	v_lshlrev_b32_e32 v14, 16, v9
	v_and_b32_e32 v15, 0xffff0000, v9
	v_pk_mul_f32 v[16:17], v[94:95], v[14:15] op_sel_hi:[0,1]
	v_pk_mul_f32 v[12:13], v[90:91], v[12:13] op_sel_hi:[0,1]
	v_cvt_pk_bf16_f32 v9, v16, v17
	v_pk_mul_f32 v[14:15], v[90:91], v[14:15] op_sel_hi:[0,1]
	v_cvt_pk_bf16_f32 v12, v12, v13
	v_cvt_pk_bf16_f32 v13, v14, v15
	ds_write_b128 v119, v[6:9]
	ds_write_b128 v120, v[10:13]
	v_lshlrev_b32_e32 v6, 16, v2
	v_and_b32_e32 v7, 0xffff0000, v2
	v_pk_mul_f32 v[8:9], v[98:99], v[6:7] op_sel_hi:[0,1]
	v_cvt_pk_bf16_f32 v2, v8, v9
	v_lshlrev_b32_e32 v8, 16, v3
	v_and_b32_e32 v9, 0xffff0000, v3
	v_pk_mul_f32 v[6:7], v[96:97], v[6:7] op_sel_hi:[0,1]
	v_pk_mul_f32 v[10:11], v[98:99], v[8:9] op_sel_hi:[0,1]
	v_pk_mul_f32 v[8:9], v[96:97], v[8:9] op_sel_hi:[0,1]
	v_cvt_pk_bf16_f32 v6, v6, v7
	v_cvt_pk_bf16_f32 v7, v8, v9
	v_lshlrev_b32_e32 v8, 16, v4
	v_and_b32_e32 v9, 0xffff0000, v4
	v_cvt_pk_bf16_f32 v3, v10, v11
	v_pk_mul_f32 v[10:11], v[98:99], v[8:9] op_sel_hi:[0,1]
	v_cvt_pk_bf16_f32 v4, v10, v11
	v_lshlrev_b32_e32 v10, 16, v5
	v_and_b32_e32 v11, 0xffff0000, v5
	v_pk_mul_f32 v[8:9], v[96:97], v[8:9] op_sel_hi:[0,1]
	v_pk_mul_f32 v[12:13], v[98:99], v[10:11] op_sel_hi:[0,1]
	v_pk_mul_f32 v[10:11], v[96:97], v[10:11] op_sel_hi:[0,1]
	v_cvt_pk_bf16_f32 v8, v8, v9
	v_cvt_pk_bf16_f32 v5, v12, v13
	v_cvt_pk_bf16_f32 v9, v10, v11
	ds_write_b128 v121, v[2:5]
	ds_write_b128 v122, v[6:9]
	s_waitcnt lgkmcnt(0)
	s_barrier
; #define LAS __attribute__((address_space(3)))
; __device__ __forceinline__ unsigned pk2(float lo, float hi) { return pg8::cvt_pk_bf16(lo, hi); }
; __device__ __forceinline__ f32x4 mfma16(bf16x8 a, bf16x8 b, f32x4 c) { return __builtin_amdgcn_mfma_f32_16x16x32_bf16(a, b, c, 0, 0, 0); }
; __device__ __forceinline__ void ret_kv_unit(LAS unsigned char* lds, const bf16* P, bf16* KV, const float* dec, int u, int tid) {
;     ...
;         for (int dir = 0; dir < 2; ++dir) {
;             const LAS unsigned char* Vd = dir ? Vb : Vf;
;             f32x4 acc[8][2];
; #pragma unroll
;             for (int mt = 0; mt < 8; ++mt) { acc[mt][0] = (f32x4){0.f, 0.f, 0.f, 0.f}; acc[mt][1] = (f32x4){0.f, 0.f, 0.f, 0.f}; }
; #pragma unroll
;             for (int ks = 0; ks < 4; ++ks) {
;                 const bf16x8 kf0 = ldtr(Kt, RSK, 32 * ks, 32 * w, lane), kf1 = ldtr(Kt, RSK, 32 * ks, 32 * w + 16, lane);
; #pragma unroll
;                 for (int mt = 0; mt < 8; ++mt) { const bf16x8 vf = ldtr(Vd, RSV, 32 * ks, 16 * mt, lane); acc[mt][0] = mfma16(kf0, vf, acc[mt][0]); acc[mt][1] = mfma16(kf1, vf, acc[mt][1]); }
;                 __builtin_amdgcn_sched_barrier(0);
;             }
;             bf16* dst = KV + ((size_t)n * 8 + h * 2 + dir) * 65536;
; #pragma unroll
;             for (int mt = 0; mt < 8; ++mt)
; #pragma unroll
;                 for (int nt = 0; nt < 2; ++nt) { u32x2 wv; wv.x = pk2(acc[mt][nt][0], acc[mt][nt][1]); wv.y = pk2(acc[mt][nt][2], acc[mt][nt][3]);
;                     *(u32x2*)(dst + (size_t)(eh * 128 + 16 * mt + i) * 256 + 32 * w + 16 * nt + 4 * g) = wv; }
	ds_read_b64_tr_b16 v[4:5], v83 offset:2112
	ds_read_b64_tr_b16 v[2:3], v83
	ds_read_b64_tr_b16 v[8:9], v83 offset:2144
	ds_read_b64_tr_b16 v[6:7], v83 offset:32
	ds_read_b64_tr_b16 v[12:13], v115 offset:1088
	ds_read_b64_tr_b16 v[10:11], v115
	ds_read_b64_tr_b16 v[14:15], v115 offset:32
	ds_read_b64_tr_b16 v[18:19], v115 offset:64
	ds_read_b64_tr_b16 v[22:23], v115 offset:96
	ds_read_b64_tr_b16 v[16:17], v115 offset:1120
	ds_read_b64_tr_b16 v[20:21], v115 offset:1152
	ds_read_b64_tr_b16 v[24:25], v115 offset:1184
	ds_read_b64_tr_b16 v[44:45], v115 offset:1216
	ds_read_b64_tr_b16 v[42:43], v115 offset:128
	ds_read_b64_tr_b16 v[46:47], v115 offset:160
	ds_read_b64_tr_b16 v[50:51], v115 offset:192
	ds_read_b64_tr_b16 v[54:55], v115 offset:224
	ds_read_b64_tr_b16 v[48:49], v115 offset:1248
	ds_read_b64_tr_b16 v[52:53], v115 offset:1280
	ds_read_b64_tr_b16 v[56:57], v115 offset:1312
	s_waitcnt lgkmcnt(14)
	v_mfma_f32_16x16x32_bf16 v[26:29], v[2:5], v[10:13], 0
	v_mfma_f32_16x16x32_bf16 v[10:13], v[6:9], v[10:13], 0
	s_waitcnt lgkmcnt(10)
	v_mfma_f32_16x16x32_bf16 v[30:33], v[2:5], v[14:17], 0
	v_mfma_f32_16x16x32_bf16 v[14:17], v[6:9], v[14:17], 0
	s_waitcnt lgkmcnt(9)
	v_mfma_f32_16x16x32_bf16 v[34:37], v[2:5], v[18:21], 0
	v_mfma_f32_16x16x32_bf16 v[18:21], v[6:9], v[18:21], 0
	s_waitcnt lgkmcnt(8)
	v_mfma_f32_16x16x32_bf16 v[38:41], v[2:5], v[22:25], 0
	v_mfma_f32_16x16x32_bf16 v[22:25], v[6:9], v[22:25], 0
	s_waitcnt lgkmcnt(6)
	v_mfma_f32_16x16x32_bf16 v[58:61], v[2:5], v[42:45], 0
	v_mfma_f32_16x16x32_bf16 v[42:45], v[6:9], v[42:45], 0
	s_waitcnt lgkmcnt(2)
	v_mfma_f32_16x16x32_bf16 v[62:65], v[2:5], v[46:49], 0
	v_mfma_f32_16x16x32_bf16 v[46:49], v[6:9], v[46:49], 0
	s_waitcnt lgkmcnt(1)
	v_mfma_f32_16x16x32_bf16 v[68:71], v[2:5], v[50:53], 0
	v_mfma_f32_16x16x32_bf16 v[50:53], v[6:9], v[50:53], 0
	s_waitcnt lgkmcnt(0)
	v_mfma_f32_16x16x32_bf16 v[2:5], v[2:5], v[54:57], 0
	v_mfma_f32_16x16x32_bf16 v[6:9], v[6:9], v[54:57], 0
	ds_read_b64_tr_b16 v[56:57], v83 offset:19008
	ds_read_b64_tr_b16 v[54:55], v83 offset:16896
	ds_read_b64_tr_b16 v[72:73], v83 offset:16928
	ds_read_b64_tr_b16 v[74:75], v83 offset:19040
	ds_read_b64_tr_b16 v[78:79], v87 offset:1088
	ds_read_b64_tr_b16 v[76:77], v87
	ds_read_b64_tr_b16 v[100:101], v87 offset:32
	ds_read_b64_tr_b16 v[102:103], v87 offset:1120
	s_waitcnt lgkmcnt(2)
	v_mfma_f32_16x16x32_bf16 v[26:29], v[54:57], v[76:79], v[26:29]
	v_mfma_f32_16x16x32_bf16 v[10:13], v[72:75], v[76:79], v[10:13]
	ds_read_b64_tr_b16 v[76:77], v87 offset:64
	ds_read_b64_tr_b16 v[78:79], v87 offset:1152
	s_waitcnt lgkmcnt(0)
	v_mfma_f32_16x16x32_bf16 v[34:37], v[54:57], v[76:79], v[34:37]
	v_mfma_f32_16x16x32_bf16 v[18:21], v[72:75], v[76:79], v[18:21]
	ds_read_b64_tr_b16 v[76:77], v87 offset:96
	ds_read_b64_tr_b16 v[78:79], v87 offset:1184
	s_waitcnt lgkmcnt(0)
	v_mfma_f32_16x16x32_bf16 v[38:41], v[54:57], v[76:79], v[38:41]
	v_mfma_f32_16x16x32_bf16 v[22:25], v[72:75], v[76:79], v[22:25]
	ds_read_b64_tr_b16 v[76:77], v87 offset:128
	ds_read_b64_tr_b16 v[78:79], v87 offset:1216
	s_waitcnt lgkmcnt(0)
	v_mfma_f32_16x16x32_bf16 v[58:61], v[54:57], v[76:79], v[58:61]
	v_mfma_f32_16x16x32_bf16 v[42:45], v[72:75], v[76:79], v[42:45]
	ds_read_b64_tr_b16 v[76:77], v87 offset:160
	ds_read_b64_tr_b16 v[78:79], v87 offset:1248
	s_waitcnt lgkmcnt(0)
	v_mfma_f32_16x16x32_bf16 v[62:65], v[54:57], v[76:79], v[62:65]
	v_mfma_f32_16x16x32_bf16 v[46:49], v[72:75], v[76:79], v[46:49]
	ds_read_b64_tr_b16 v[76:77], v87 offset:192
	ds_read_b64_tr_b16 v[78:79], v87 offset:1280
	s_waitcnt lgkmcnt(0)
	v_mfma_f32_16x16x32_bf16 v[68:71], v[54:57], v[76:79], v[68:71]
	v_mfma_f32_16x16x32_bf16 v[50:53], v[72:75], v[76:79], v[50:53]
	ds_read_b64_tr_b16 v[76:77], v87 offset:224
	ds_read_b64_tr_b16 v[78:79], v87 offset:1312
	v_mfma_f32_16x16x32_bf16 v[30:33], v[54:57], v[100:103], v[30:33]
	v_mfma_f32_16x16x32_bf16 v[14:17], v[72:75], v[100:103], v[14:17]
	s_waitcnt lgkmcnt(0)
	v_mfma_f32_16x16x32_bf16 v[2:5], v[54:57], v[76:79], v[2:5]
	v_mfma_f32_16x16x32_bf16 v[6:9], v[72:75], v[76:79], v[6:9]
	ds_read_b64_tr_b16 v[56:57], v83 offset:35904
	ds_read_b64_tr_b16 v[54:55], v83 offset:33792
	ds_read_b64_tr_b16 v[72:73], v83 offset:33824
	ds_read_b64_tr_b16 v[74:75], v83 offset:35936
	ds_read_b64_tr_b16 v[78:79], v89 offset:1088
	ds_read_b64_tr_b16 v[76:77], v89
	ds_read_b64_tr_b16 v[100:101], v89 offset:32
	ds_read_b64_tr_b16 v[102:103], v89 offset:1120
	s_waitcnt lgkmcnt(2)
	v_mfma_f32_16x16x32_bf16 v[26:29], v[54:57], v[76:79], v[26:29]
	v_mfma_f32_16x16x32_bf16 v[10:13], v[72:75], v[76:79], v[10:13]
	ds_read_b64_tr_b16 v[76:77], v89 offset:64
	ds_read_b64_tr_b16 v[78:79], v89 offset:1152
	s_waitcnt lgkmcnt(0)
	v_mfma_f32_16x16x32_bf16 v[34:37], v[54:57], v[76:79], v[34:37]
	v_mfma_f32_16x16x32_bf16 v[18:21], v[72:75], v[76:79], v[18:21]
	ds_read_b64_tr_b16 v[76:77], v89 offset:96
	ds_read_b64_tr_b16 v[78:79], v89 offset:1184
	s_waitcnt lgkmcnt(0)
	v_mfma_f32_16x16x32_bf16 v[38:41], v[54:57], v[76:79], v[38:41]
	v_mfma_f32_16x16x32_bf16 v[22:25], v[72:75], v[76:79], v[22:25]
	ds_read_b64_tr_b16 v[76:77], v89 offset:128
	ds_read_b64_tr_b16 v[78:79], v89 offset:1216
	s_waitcnt lgkmcnt(0)
	v_mfma_f32_16x16x32_bf16 v[58:61], v[54:57], v[76:79], v[58:61]
	v_mfma_f32_16x16x32_bf16 v[42:45], v[72:75], v[76:79], v[42:45]
	ds_read_b64_tr_b16 v[76:77], v89 offset:160
	ds_read_b64_tr_b16 v[78:79], v89 offset:1248
	s_waitcnt lgkmcnt(0)
	v_mfma_f32_16x16x32_bf16 v[62:65], v[54:57], v[76:79], v[62:65]
	v_mfma_f32_16x16x32_bf16 v[46:49], v[72:75], v[76:79], v[46:49]
	ds_read_b64_tr_b16 v[76:77], v89 offset:192
	ds_read_b64_tr_b16 v[78:79], v89 offset:1280
	s_waitcnt lgkmcnt(0)
; #define LAS __attribute__((address_space(3)))
; __device__ __forceinline__ unsigned pk2(float lo, float hi) { return pg8::cvt_pk_bf16(lo, hi); }
; __device__ __forceinline__ f32x4 mfma16(bf16x8 a, bf16x8 b, f32x4 c) { return __builtin_amdgcn_mfma_f32_16x16x32_bf16(a, b, c, 0, 0, 0); }
; __device__ __forceinline__ void ret_kv_unit(LAS unsigned char* lds, const bf16* P, bf16* KV, const float* dec, int u, int tid) {
;     ...
;         for (int dir = 0; dir < 2; ++dir) {
;             const LAS unsigned char* Vd = dir ? Vb : Vf;
;             f32x4 acc[8][2];
; #pragma unroll
;             for (int mt = 0; mt < 8; ++mt) { acc[mt][0] = (f32x4){0.f, 0.f, 0.f, 0.f}; acc[mt][1] = (f32x4){0.f, 0.f, 0.f, 0.f}; }
; #pragma unroll
;             for (int ks = 0; ks < 4; ++ks) {
;                 const bf16x8 kf0 = ldtr(Kt, RSK, 32 * ks, 32 * w, lane), kf1 = ldtr(Kt, RSK, 32 * ks, 32 * w + 16, lane);
; #pragma unroll
;                 for (int mt = 0; mt < 8; ++mt) { const bf16x8 vf = ldtr(Vd, RSV, 32 * ks, 16 * mt, lane); acc[mt][0] = mfma16(kf0, vf, acc[mt][0]); acc[mt][1] = mfma16(kf1, vf, acc[mt][1]); }
;                 __builtin_amdgcn_sched_barrier(0);
;             }
;             bf16* dst = KV + ((size_t)n * 8 + h * 2 + dir) * 65536;
; #pragma unroll
;             for (int mt = 0; mt < 8; ++mt)
; #pragma unroll
;                 for (int nt = 0; nt < 2; ++nt) { u32x2 wv; wv.x = pk2(acc[mt][nt][0], acc[mt][nt][1]); wv.y = pk2(acc[mt][nt][2], acc[mt][nt][3]);
;                     *(u32x2*)(dst + (size_t)(eh * 128 + 16 * mt + i) * 256 + 32 * w + 16 * nt + 4 * g) = wv; }
	v_mfma_f32_16x16x32_bf16 v[68:71], v[54:57], v[76:79], v[68:71]
	v_mfma_f32_16x16x32_bf16 v[50:53], v[72:75], v[76:79], v[50:53]
	ds_read_b64_tr_b16 v[76:77], v89 offset:224
	ds_read_b64_tr_b16 v[78:79], v89 offset:1312
	v_mfma_f32_16x16x32_bf16 v[30:33], v[54:57], v[100:103], v[30:33]
	v_mfma_f32_16x16x32_bf16 v[14:17], v[72:75], v[100:103], v[14:17]
	s_waitcnt lgkmcnt(0)
	v_mfma_f32_16x16x32_bf16 v[2:5], v[54:57], v[76:79], v[2:5]
	v_mfma_f32_16x16x32_bf16 v[6:9], v[72:75], v[76:79], v[6:9]
	ds_read_b64_tr_b16 v[56:57], v83 offset:52800
	ds_read_b64_tr_b16 v[54:55], v83 offset:50688
	ds_read_b64_tr_b16 v[72:73], v83 offset:50720
	ds_read_b64_tr_b16 v[74:75], v83 offset:52832
	ds_read_b64_tr_b16 v[78:79], v91 offset:1088
	ds_read_b64_tr_b16 v[76:77], v91
	ds_read_b64_tr_b16 v[86:87], v91 offset:32
	ds_read_b64_tr_b16 v[88:89], v91 offset:1120
	s_waitcnt lgkmcnt(2)
	v_mfma_f32_16x16x32_bf16 v[26:29], v[54:57], v[76:79], v[26:29]
	v_mfma_f32_16x16x32_bf16 v[10:13], v[72:75], v[76:79], v[10:13]
	ds_read_b64_tr_b16 v[76:77], v91 offset:64
	ds_read_b64_tr_b16 v[78:79], v91 offset:1152
	s_waitcnt lgkmcnt(0)
	v_mfma_f32_16x16x32_bf16 v[34:37], v[54:57], v[76:79], v[34:37]
	v_mfma_f32_16x16x32_bf16 v[18:21], v[72:75], v[76:79], v[18:21]
	ds_read_b64_tr_b16 v[76:77], v91 offset:96
	ds_read_b64_tr_b16 v[78:79], v91 offset:1184
	s_waitcnt lgkmcnt(0)
	v_mfma_f32_16x16x32_bf16 v[38:41], v[54:57], v[76:79], v[38:41]
	v_mfma_f32_16x16x32_bf16 v[22:25], v[72:75], v[76:79], v[22:25]
	ds_read_b64_tr_b16 v[76:77], v91 offset:128
	ds_read_b64_tr_b16 v[78:79], v91 offset:1216
	s_waitcnt lgkmcnt(0)
	v_mfma_f32_16x16x32_bf16 v[58:61], v[54:57], v[76:79], v[58:61]
	v_mfma_f32_16x16x32_bf16 v[42:45], v[72:75], v[76:79], v[42:45]
	ds_read_b64_tr_b16 v[76:77], v91 offset:160
	ds_read_b64_tr_b16 v[78:79], v91 offset:1248
	s_waitcnt lgkmcnt(0)
	v_mfma_f32_16x16x32_bf16 v[62:65], v[54:57], v[76:79], v[62:65]
	v_mfma_f32_16x16x32_bf16 v[46:49], v[72:75], v[76:79], v[46:49]
	ds_read_b64_tr_b16 v[76:77], v91 offset:192
	ds_read_b64_tr_b16 v[78:79], v91 offset:1280
	v_mfma_f32_16x16x32_bf16 v[30:33], v[54:57], v[86:89], v[30:33]
	v_mfma_f32_16x16x32_bf16 v[14:17], v[72:75], v[86:89], v[14:17]
	s_waitcnt lgkmcnt(0)
	v_mfma_f32_16x16x32_bf16 v[86:89], v[54:57], v[76:79], v[68:71]
	s_nop 2
	ds_read_b64_tr_b16 v[68:69], v91 offset:224
	ds_read_b64_tr_b16 v[70:71], v91 offset:1312
	v_mfma_f32_16x16x32_bf16 v[50:53], v[72:75], v[76:79], v[50:53]
	s_waitcnt lgkmcnt(0)
	v_mfma_f32_16x16x32_bf16 v[2:5], v[54:57], v[68:71], v[2:5]
	v_mfma_f32_16x16x32_bf16 v[6:9], v[72:75], v[68:71], v[6:9]
	v_or_b32_e32 v68, 0x10000, v0
	v_mov_b32_e32 v69, v1
	v_lshl_add_u64 v[54:55], v[92:93], 0, v[68:69]
	v_cvt_pk_bf16_f32 v10, v10, v11
	v_cvt_pk_bf16_f32 v11, v12, v13
	v_or_b32_e32 v70, 0x12000, v0
	v_mov_b32_e32 v71, v1
	global_store_dwordx2 v[54:55], v[10:11], off offset:32
	v_lshl_add_u64 v[10:11], v[92:93], 0, v[70:71]
	v_cvt_pk_bf16_f32 v12, v30, v31
	v_cvt_pk_bf16_f32 v13, v32, v33
	global_store_dwordx2 v[10:11], v[12:13], off
	v_cvt_pk_bf16_f32 v12, v14, v15
	v_cvt_pk_bf16_f32 v13, v16, v17
	v_or_b32_e32 v76, 0x14000, v0
	v_mov_b32_e32 v77, v1
	global_store_dwordx2 v[10:11], v[12:13], off offset:32
	v_lshl_add_u64 v[10:11], v[92:93], 0, v[76:77]
	v_cvt_pk_bf16_f32 v12, v34, v35
	v_cvt_pk_bf16_f32 v13, v36, v37
	global_store_dwordx2 v[10:11], v[12:13], off
	v_cvt_pk_bf16_f32 v12, v18, v19
	v_cvt_pk_bf16_f32 v13, v20, v21
	v_or_b32_e32 v80, 0x16000, v0
	v_mov_b32_e32 v81, v1
	global_store_dwordx2 v[10:11], v[12:13], off offset:32
	v_lshl_add_u64 v[10:11], v[92:93], 0, v[80:81]
	v_cvt_pk_bf16_f32 v12, v38, v39
	v_cvt_pk_bf16_f32 v13, v40, v41
	global_store_dwordx2 v[10:11], v[12:13], off
	v_cvt_pk_bf16_f32 v12, v22, v23
	v_cvt_pk_bf16_f32 v13, v24, v25
	v_or_b32_e32 v78, 0x18000, v0
	v_mov_b32_e32 v79, v1
	global_store_dwordx2 v[10:11], v[12:13], off offset:32
	v_lshl_add_u64 v[10:11], v[92:93], 0, v[78:79]
	v_cvt_pk_bf16_f32 v12, v58, v59
	v_cvt_pk_bf16_f32 v13, v60, v61
	global_store_dwordx2 v[10:11], v[12:13], off
	v_cvt_pk_bf16_f32 v12, v42, v43
	v_cvt_pk_bf16_f32 v13, v44, v45
	v_or_b32_e32 v74, 0x1a000, v0
	v_mov_b32_e32 v75, v1
	global_store_dwordx2 v[10:11], v[12:13], off offset:32
	v_lshl_add_u64 v[10:11], v[92:93], 0, v[74:75]
	v_cvt_pk_bf16_f32 v12, v62, v63
	v_cvt_pk_bf16_f32 v13, v64, v65
	global_store_dwordx2 v[10:11], v[12:13], off
	v_cvt_pk_bf16_f32 v12, v46, v47
	v_cvt_pk_bf16_f32 v13, v48, v49
	v_or_b32_e32 v72, 0x1c000, v0
	v_mov_b32_e32 v73, v1
	global_store_dwordx2 v[10:11], v[12:13], off offset:32
	v_lshl_add_u64 v[10:11], v[92:93], 0, v[72:73]
	v_cvt_pk_bf16_f32 v12, v86, v87
	v_cvt_pk_bf16_f32 v13, v88, v89
	global_store_dwordx2 v[10:11], v[12:13], off
	v_cvt_pk_bf16_f32 v12, v50, v51
	v_cvt_pk_bf16_f32 v13, v52, v53
	v_or_b32_e32 v0, 0x1e000, v0
	global_store_dwordx2 v[10:11], v[12:13], off offset:32
	v_lshl_add_u64 v[10:11], v[92:93], 0, v[0:1]
	v_cvt_pk_bf16_f32 v2, v2, v3
	v_cvt_pk_bf16_f32 v3, v4, v5
	v_cvt_pk_bf16_f32 v26, v26, v27
	v_cvt_pk_bf16_f32 v27, v28, v29
	global_store_dwordx2 v[10:11], v[2:3], off
	v_cvt_pk_bf16_f32 v2, v6, v7
	v_cvt_pk_bf16_f32 v3, v8, v9
	global_store_dwordx2 v[54:55], v[26:27], off
	global_store_dwordx2 v[10:11], v[2:3], off offset:32
	ds_read_b64_tr_b16 v[32:33], v83 offset:2112
	ds_read_b64_tr_b16 v[30:31], v83
	ds_read_b64_tr_b16 v[18:19], v83 offset:32
	ds_read_b64_tr_b16 v[20:21], v83 offset:2144
	ds_read_b64_tr_b16 v[8:9], v85 offset:1088
	ds_read_b64_tr_b16 v[6:7], v85
	ds_read_b64_tr_b16 v[14:15], v85 offset:32
	ds_read_b64_tr_b16 v[16:17], v85 offset:1120
	ds_read_b64_tr_b16 v[26:27], v85 offset:64
	ds_read_b64_tr_b16 v[28:29], v85 offset:1152
	ds_read_b64_tr_b16 v[38:39], v85 offset:96
	ds_read_b64_tr_b16 v[40:41], v85 offset:1184
	ds_read_b64_tr_b16 v[46:47], v85 offset:128
	ds_read_b64_tr_b16 v[48:49], v85 offset:1216
	ds_read_b64_tr_b16 v[54:55], v85 offset:160
	ds_read_b64_tr_b16 v[56:57], v85 offset:1248
	ds_read_b64_tr_b16 v[62:63], v85 offset:192
	ds_read_b64_tr_b16 v[64:65], v85 offset:1280
	ds_read_b64_tr_b16 v[86:87], v85 offset:224
	ds_read_b64_tr_b16 v[88:89], v85 offset:1312
	s_waitcnt lgkmcnt(14)
; #define LAS __attribute__((address_space(3)))
; __device__ __forceinline__ unsigned pk2(float lo, float hi) { return pg8::cvt_pk_bf16(lo, hi); }
; __device__ __forceinline__ f32x4 mfma16(bf16x8 a, bf16x8 b, f32x4 c) { return __builtin_amdgcn_mfma_f32_16x16x32_bf16(a, b, c, 0, 0, 0); }
; __device__ __forceinline__ void ret_kv_unit(LAS unsigned char* lds, const bf16* P, bf16* KV, const float* dec, int u, int tid) {
;     ...
;         for (int dir = 0; dir < 2; ++dir) {
;             const LAS unsigned char* Vd = dir ? Vb : Vf;
;             f32x4 acc[8][2];
; #pragma unroll
;             for (int mt = 0; mt < 8; ++mt) { acc[mt][0] = (f32x4){0.f, 0.f, 0.f, 0.f}; acc[mt][1] = (f32x4){0.f, 0.f, 0.f, 0.f}; }
; #pragma unroll
;             for (int ks = 0; ks < 4; ++ks) {
;                 const bf16x8 kf0 = ldtr(Kt, RSK, 32 * ks, 32 * w, lane), kf1 = ldtr(Kt, RSK, 32 * ks, 32 * w + 16, lane);
; #pragma unroll
;                 for (int mt = 0; mt < 8; ++mt) { const bf16x8 vf = ldtr(Vd, RSV, 32 * ks, 16 * mt, lane); acc[mt][0] = mfma16(kf0, vf, acc[mt][0]); acc[mt][1] = mfma16(kf1, vf, acc[mt][1]); }
;                 __builtin_amdgcn_sched_barrier(0);
;             }
;             bf16* dst = KV + ((size_t)n * 8 + h * 2 + dir) * 65536;
; #pragma unroll
;             for (int mt = 0; mt < 8; ++mt)
; #pragma unroll
;                 for (int nt = 0; nt < 2; ++nt) { u32x2 wv; wv.x = pk2(acc[mt][nt][0], acc[mt][nt][1]); wv.y = pk2(acc[mt][nt][2], acc[mt][nt][3]);
;                     *(u32x2*)(dst + (size_t)(eh * 128 + 16 * mt + i) * 256 + 32 * w + 16 * nt + 4 * g) = wv; }
	v_mfma_f32_16x16x32_bf16 v[2:5], v[30:33], v[6:9], 0
	v_mfma_f32_16x16x32_bf16 v[6:9], v[18:21], v[6:9], 0
	s_waitcnt lgkmcnt(12)
	v_mfma_f32_16x16x32_bf16 v[10:13], v[30:33], v[14:17], 0
	v_mfma_f32_16x16x32_bf16 v[14:17], v[18:21], v[14:17], 0
	s_waitcnt lgkmcnt(10)
	v_mfma_f32_16x16x32_bf16 v[22:25], v[30:33], v[26:29], 0
	v_mfma_f32_16x16x32_bf16 v[26:29], v[18:21], v[26:29], 0
	s_waitcnt lgkmcnt(8)
	v_mfma_f32_16x16x32_bf16 v[34:37], v[30:33], v[38:41], 0
	v_mfma_f32_16x16x32_bf16 v[38:41], v[18:21], v[38:41], 0
	s_waitcnt lgkmcnt(6)
	v_mfma_f32_16x16x32_bf16 v[42:45], v[30:33], v[46:49], 0
	v_mfma_f32_16x16x32_bf16 v[46:49], v[18:21], v[46:49], 0
	s_waitcnt lgkmcnt(4)
	v_mfma_f32_16x16x32_bf16 v[50:53], v[30:33], v[54:57], 0
	v_mfma_f32_16x16x32_bf16 v[54:57], v[18:21], v[54:57], 0
	s_waitcnt lgkmcnt(2)
	v_mfma_f32_16x16x32_bf16 v[58:61], v[30:33], v[62:65], 0
	v_mfma_f32_16x16x32_bf16 v[62:65], v[18:21], v[62:65], 0
	s_waitcnt lgkmcnt(0)
	v_mfma_f32_16x16x32_bf16 v[30:33], v[30:33], v[86:89], 0
	v_mfma_f32_16x16x32_bf16 v[18:21], v[18:21], v[86:89], 0
	ds_read_b64_tr_b16 v[86:87], v83 offset:19008
	ds_read_b64_tr_b16 v[84:85], v83 offset:16896
	ds_read_b64_tr_b16 v[88:89], v83 offset:16928
	ds_read_b64_tr_b16 v[90:91], v83 offset:19040
	ds_read_b64_tr_b16 v[102:103], v95 offset:1088
	ds_read_b64_tr_b16 v[100:101], v95
	ds_read_b64_tr_b16 v[104:105], v95 offset:32
	ds_read_b64_tr_b16 v[106:107], v95 offset:1120
	s_waitcnt lgkmcnt(2)
	v_mfma_f32_16x16x32_bf16 v[2:5], v[84:87], v[100:103], v[2:5]
	v_mfma_f32_16x16x32_bf16 v[6:9], v[88:91], v[100:103], v[6:9]
	ds_read_b64_tr_b16 v[100:101], v95 offset:64
	ds_read_b64_tr_b16 v[102:103], v95 offset:1152
	s_waitcnt lgkmcnt(0)
	v_mfma_f32_16x16x32_bf16 v[22:25], v[84:87], v[100:103], v[22:25]
	v_mfma_f32_16x16x32_bf16 v[26:29], v[88:91], v[100:103], v[26:29]
	ds_read_b64_tr_b16 v[100:101], v95 offset:96
	ds_read_b64_tr_b16 v[102:103], v95 offset:1184
	s_waitcnt lgkmcnt(0)
	v_mfma_f32_16x16x32_bf16 v[34:37], v[84:87], v[100:103], v[34:37]
	v_mfma_f32_16x16x32_bf16 v[38:41], v[88:91], v[100:103], v[38:41]
	ds_read_b64_tr_b16 v[100:101], v95 offset:128
	ds_read_b64_tr_b16 v[102:103], v95 offset:1216
	s_waitcnt lgkmcnt(0)
	v_mfma_f32_16x16x32_bf16 v[42:45], v[84:87], v[100:103], v[42:45]
	v_mfma_f32_16x16x32_bf16 v[46:49], v[88:91], v[100:103], v[46:49]
	ds_read_b64_tr_b16 v[100:101], v95 offset:160
	ds_read_b64_tr_b16 v[102:103], v95 offset:1248
	s_waitcnt lgkmcnt(0)
	v_mfma_f32_16x16x32_bf16 v[50:53], v[84:87], v[100:103], v[50:53]
	v_mfma_f32_16x16x32_bf16 v[54:57], v[88:91], v[100:103], v[54:57]
	ds_read_b64_tr_b16 v[100:101], v95 offset:192
	ds_read_b64_tr_b16 v[102:103], v95 offset:1280
	ds_read_b64_tr_b16 v[92:93], v95 offset:224
	ds_read_b64_tr_b16 v[94:95], v95 offset:1312
	v_mfma_f32_16x16x32_bf16 v[10:13], v[84:87], v[104:107], v[10:13]
	v_mfma_f32_16x16x32_bf16 v[14:17], v[88:91], v[104:107], v[14:17]
	s_waitcnt lgkmcnt(2)
	v_mfma_f32_16x16x32_bf16 v[58:61], v[84:87], v[100:103], v[58:61]
	v_mfma_f32_16x16x32_bf16 v[62:65], v[88:91], v[100:103], v[62:65]
	s_waitcnt lgkmcnt(0)
	v_mfma_f32_16x16x32_bf16 v[30:33], v[84:87], v[92:95], v[30:33]
	v_mfma_f32_16x16x32_bf16 v[18:21], v[88:91], v[92:95], v[18:21]
	ds_read_b64_tr_b16 v[86:87], v83 offset:35904
	ds_read_b64_tr_b16 v[84:85], v83 offset:33792
	ds_read_b64_tr_b16 v[88:89], v83 offset:33824
	ds_read_b64_tr_b16 v[90:91], v83 offset:35936
	ds_read_b64_tr_b16 v[94:95], v97 offset:1088
	ds_read_b64_tr_b16 v[92:93], v97
	ds_read_b64_tr_b16 v[100:101], v97 offset:32
	ds_read_b64_tr_b16 v[102:103], v97 offset:1120
	s_waitcnt lgkmcnt(2)
	v_mfma_f32_16x16x32_bf16 v[2:5], v[84:87], v[92:95], v[2:5]
	v_mfma_f32_16x16x32_bf16 v[6:9], v[88:91], v[92:95], v[6:9]
	ds_read_b64_tr_b16 v[92:93], v97 offset:64
	ds_read_b64_tr_b16 v[94:95], v97 offset:1152
	s_waitcnt lgkmcnt(0)
	v_mfma_f32_16x16x32_bf16 v[22:25], v[84:87], v[92:95], v[22:25]
	v_mfma_f32_16x16x32_bf16 v[26:29], v[88:91], v[92:95], v[26:29]
	ds_read_b64_tr_b16 v[92:93], v97 offset:96
	ds_read_b64_tr_b16 v[94:95], v97 offset:1184
	s_waitcnt lgkmcnt(0)
	v_mfma_f32_16x16x32_bf16 v[34:37], v[84:87], v[92:95], v[34:37]
	v_mfma_f32_16x16x32_bf16 v[38:41], v[88:91], v[92:95], v[38:41]
	ds_read_b64_tr_b16 v[92:93], v97 offset:128
	ds_read_b64_tr_b16 v[94:95], v97 offset:1216
	s_waitcnt lgkmcnt(0)
	v_mfma_f32_16x16x32_bf16 v[42:45], v[84:87], v[92:95], v[42:45]
	v_mfma_f32_16x16x32_bf16 v[46:49], v[88:91], v[92:95], v[46:49]
	ds_read_b64_tr_b16 v[92:93], v97 offset:160
	ds_read_b64_tr_b16 v[94:95], v97 offset:1248
	s_waitcnt lgkmcnt(0)
	v_mfma_f32_16x16x32_bf16 v[50:53], v[84:87], v[92:95], v[50:53]
	v_mfma_f32_16x16x32_bf16 v[54:57], v[88:91], v[92:95], v[54:57]
	ds_read_b64_tr_b16 v[92:93], v97 offset:192
	ds_read_b64_tr_b16 v[94:95], v97 offset:1280
	s_waitcnt lgkmcnt(0)
; #define LAS __attribute__((address_space(3)))
; __device__ __forceinline__ unsigned pk2(float lo, float hi) { return pg8::cvt_pk_bf16(lo, hi); }
; __device__ __forceinline__ f32x4 mfma16(bf16x8 a, bf16x8 b, f32x4 c) { return __builtin_amdgcn_mfma_f32_16x16x32_bf16(a, b, c, 0, 0, 0); }
; __device__ __forceinline__ void ret_kv_unit(LAS unsigned char* lds, const bf16* P, bf16* KV, const float* dec, int u, int tid) {
;     ...
;         for (int dir = 0; dir < 2; ++dir) {
;             const LAS unsigned char* Vd = dir ? Vb : Vf;
;             f32x4 acc[8][2];
; #pragma unroll
;             for (int mt = 0; mt < 8; ++mt) { acc[mt][0] = (f32x4){0.f, 0.f, 0.f, 0.f}; acc[mt][1] = (f32x4){0.f, 0.f, 0.f, 0.f}; }
; #pragma unroll
;             for (int ks = 0; ks < 4; ++ks) {
;                 const bf16x8 kf0 = ldtr(Kt, RSK, 32 * ks, 32 * w, lane), kf1 = ldtr(Kt, RSK, 32 * ks, 32 * w + 16, lane);
; #pragma unroll
;                 for (int mt = 0; mt < 8; ++mt) { const bf16x8 vf = ldtr(Vd, RSV, 32 * ks, 16 * mt, lane); acc[mt][0] = mfma16(kf0, vf, acc[mt][0]); acc[mt][1] = mfma16(kf1, vf, acc[mt][1]); }
;                 __builtin_amdgcn_sched_barrier(0);
;             }
;             bf16* dst = KV + ((size_t)n * 8 + h * 2 + dir) * 65536;
; #pragma unroll
;             for (int mt = 0; mt < 8; ++mt)
; #pragma unroll
;                 for (int nt = 0; nt < 2; ++nt) { u32x2 wv; wv.x = pk2(acc[mt][nt][0], acc[mt][nt][1]); wv.y = pk2(acc[mt][nt][2], acc[mt][nt][3]);
;                     *(u32x2*)(dst + (size_t)(eh * 128 + 16 * mt + i) * 256 + 32 * w + 16 * nt + 4 * g) = wv; }
;         }
;     }
;     __syncthreads();
	v_mfma_f32_16x16x32_bf16 v[58:61], v[84:87], v[92:95], v[58:61]
	v_mfma_f32_16x16x32_bf16 v[62:65], v[88:91], v[92:95], v[62:65]
	ds_read_b64_tr_b16 v[92:93], v97 offset:224
	ds_read_b64_tr_b16 v[94:95], v97 offset:1312
	v_mfma_f32_16x16x32_bf16 v[10:13], v[84:87], v[100:103], v[10:13]
	v_mfma_f32_16x16x32_bf16 v[14:17], v[88:91], v[100:103], v[14:17]
	s_waitcnt lgkmcnt(0)
	v_mfma_f32_16x16x32_bf16 v[30:33], v[84:87], v[92:95], v[30:33]
	v_mfma_f32_16x16x32_bf16 v[18:21], v[88:91], v[92:95], v[18:21]
	ds_read_b64_tr_b16 v[86:87], v83 offset:52800
	ds_read_b64_tr_b16 v[84:85], v83 offset:50688
	ds_read_b64_tr_b16 v[88:89], v83 offset:50720
	ds_read_b64_tr_b16 v[90:91], v83 offset:52832
	ds_read_b64_tr_b16 v[94:95], v99 offset:1088
	ds_read_b64_tr_b16 v[92:93], v99
	ds_read_b64_tr_b16 v[100:101], v99 offset:32
	ds_read_b64_tr_b16 v[102:103], v99 offset:1120
	s_waitcnt lgkmcnt(2)
	v_mfma_f32_16x16x32_bf16 v[2:5], v[84:87], v[92:95], v[2:5]
	v_mfma_f32_16x16x32_bf16 v[6:9], v[88:91], v[92:95], v[6:9]
	ds_read_b64_tr_b16 v[92:93], v99 offset:64
	ds_read_b64_tr_b16 v[94:95], v99 offset:1152
	s_waitcnt lgkmcnt(0)
	v_mfma_f32_16x16x32_bf16 v[22:25], v[84:87], v[92:95], v[22:25]
	v_mfma_f32_16x16x32_bf16 v[26:29], v[88:91], v[92:95], v[26:29]
	ds_read_b64_tr_b16 v[92:93], v99 offset:96
	ds_read_b64_tr_b16 v[94:95], v99 offset:1184
	s_waitcnt lgkmcnt(0)
	v_mfma_f32_16x16x32_bf16 v[34:37], v[84:87], v[92:95], v[34:37]
	v_mfma_f32_16x16x32_bf16 v[38:41], v[88:91], v[92:95], v[38:41]
	ds_read_b64_tr_b16 v[92:93], v99 offset:128
	ds_read_b64_tr_b16 v[94:95], v99 offset:1216
	s_waitcnt lgkmcnt(0)
	v_mfma_f32_16x16x32_bf16 v[42:45], v[84:87], v[92:95], v[42:45]
	v_mfma_f32_16x16x32_bf16 v[46:49], v[88:91], v[92:95], v[46:49]
	ds_read_b64_tr_b16 v[92:93], v99 offset:160
	ds_read_b64_tr_b16 v[94:95], v99 offset:1248
	s_waitcnt lgkmcnt(0)
	v_mfma_f32_16x16x32_bf16 v[50:53], v[84:87], v[92:95], v[50:53]
	v_mfma_f32_16x16x32_bf16 v[54:57], v[88:91], v[92:95], v[54:57]
	ds_read_b64_tr_b16 v[92:93], v99 offset:192
	ds_read_b64_tr_b16 v[94:95], v99 offset:1280
	s_waitcnt lgkmcnt(0)
	v_mfma_f32_16x16x32_bf16 v[58:61], v[84:87], v[92:95], v[58:61]
	v_mfma_f32_16x16x32_bf16 v[62:65], v[88:91], v[92:95], v[62:65]
	ds_read_b64_tr_b16 v[92:93], v99 offset:224
	ds_read_b64_tr_b16 v[94:95], v99 offset:1312
	v_mfma_f32_16x16x32_bf16 v[10:13], v[84:87], v[100:103], v[10:13]
	v_mfma_f32_16x16x32_bf16 v[14:17], v[88:91], v[100:103], v[14:17]
	s_waitcnt lgkmcnt(0)
	v_mfma_f32_16x16x32_bf16 v[30:33], v[84:87], v[92:95], v[30:33]
	v_mfma_f32_16x16x32_bf16 v[18:21], v[88:91], v[92:95], v[18:21]
	v_lshl_add_u64 v[68:69], v[66:67], 0, v[68:69]
	v_cvt_pk_bf16_f32 v2, v2, v3
	v_cvt_pk_bf16_f32 v3, v4, v5
	global_store_dwordx2 v[68:69], v[2:3], off
	v_cvt_pk_bf16_f32 v2, v6, v7
	v_cvt_pk_bf16_f32 v3, v8, v9
	global_store_dwordx2 v[68:69], v[2:3], off offset:32
	v_lshl_add_u64 v[2:3], v[66:67], 0, v[70:71]
	v_cvt_pk_bf16_f32 v4, v10, v11
	v_cvt_pk_bf16_f32 v5, v12, v13
	global_store_dwordx2 v[2:3], v[4:5], off
	v_cvt_pk_bf16_f32 v4, v14, v15
	v_cvt_pk_bf16_f32 v5, v16, v17
	global_store_dwordx2 v[2:3], v[4:5], off offset:32
	v_lshl_add_u64 v[2:3], v[66:67], 0, v[76:77]
	v_cvt_pk_bf16_f32 v4, v22, v23
	v_cvt_pk_bf16_f32 v5, v24, v25
	global_store_dwordx2 v[2:3], v[4:5], off
	v_cvt_pk_bf16_f32 v4, v26, v27
	v_cvt_pk_bf16_f32 v5, v28, v29
	global_store_dwordx2 v[2:3], v[4:5], off offset:32
	v_lshl_add_u64 v[2:3], v[66:67], 0, v[80:81]
	v_cvt_pk_bf16_f32 v4, v34, v35
	v_cvt_pk_bf16_f32 v5, v36, v37
	global_store_dwordx2 v[2:3], v[4:5], off
	v_cvt_pk_bf16_f32 v4, v38, v39
	v_cvt_pk_bf16_f32 v5, v40, v41
	global_store_dwordx2 v[2:3], v[4:5], off offset:32
	v_lshl_add_u64 v[2:3], v[66:67], 0, v[78:79]
	v_cvt_pk_bf16_f32 v4, v42, v43
	v_cvt_pk_bf16_f32 v5, v44, v45
	global_store_dwordx2 v[2:3], v[4:5], off
	v_cvt_pk_bf16_f32 v4, v46, v47
	v_cvt_pk_bf16_f32 v5, v48, v49
	global_store_dwordx2 v[2:3], v[4:5], off offset:32
	v_lshl_add_u64 v[2:3], v[66:67], 0, v[74:75]
	v_cvt_pk_bf16_f32 v4, v50, v51
	v_cvt_pk_bf16_f32 v5, v52, v53
	global_store_dwordx2 v[2:3], v[4:5], off
	v_cvt_pk_bf16_f32 v4, v54, v55
	v_cvt_pk_bf16_f32 v5, v56, v57
	global_store_dwordx2 v[2:3], v[4:5], off offset:32
	v_lshl_add_u64 v[2:3], v[66:67], 0, v[72:73]
	v_cvt_pk_bf16_f32 v4, v58, v59
	v_cvt_pk_bf16_f32 v5, v60, v61
	global_store_dwordx2 v[2:3], v[4:5], off
	v_cvt_pk_bf16_f32 v4, v62, v63
	v_cvt_pk_bf16_f32 v5, v64, v65
	global_store_dwordx2 v[2:3], v[4:5], off offset:32
	v_lshl_add_u64 v[2:3], v[66:67], 0, v[0:1]
	v_cvt_pk_bf16_f32 v4, v30, v31
	v_cvt_pk_bf16_f32 v5, v32, v33
	s_add_i32 s9, s9, s3
	global_store_dwordx2 v[2:3], v[4:5], off
	v_cvt_pk_bf16_f32 v4, v18, v19
	v_cvt_pk_bf16_f32 v5, v20, v21
	s_cmpk_gt_i32 s9, 0xff
	global_store_dwordx2 v[2:3], v[4:5], off offset:32
	s_waitcnt vmcnt(63) expcnt(7) lgkmcnt(15)
	s_barrier
	s_cbranch_scc1 .LBB0_579

; #define LAS __attribute__((address_space(3)))
; __device__ __forceinline__ f32x4 mfma16(bf16x8 a, bf16x8 b, f32x4 c) { return __builtin_amdgcn_mfma_f32_16x16x32_bf16(a, b, c, 0, 0, 0); }
; __device__ __forceinline__ void na_unit(LAS unsigned char* lds, const bf16* P, const float* rpb, bf16* BR, int u, int tid) {
;     ...
;     for (int k = 0; k < 4; ++k) { const int idx = tid + k * NTHR, uu = idx >> 10, rr = (idx >> 4) & 63, c8 = idx & 15; *(LAS u32x4*)(Qt + uu * ROWB + rr * RS + c8 * 16) = qv[k]; }
;     f32x4 s[8][2];
; #pragma unroll
;     for (int kr = 0; kr < 8; ++kr) { s[kr][0] = (f32x4){0.f, 0.f, 0.f, 0.f}; s[kr][1] = (f32x4){0.f, 0.f, 0.f, 0.f}; }
;     bf16x8 qf[4];
; #pragma unroll
;     for (int ub = 0; ub < 9; ub += 4) {
; #pragma unroll
;         for (int k = 2 * ub; k < 2 * ub + 8; ++k) if (k < 18) { const int idx = tid + (k - 2 * ub) * NTHR, uu = idx >> 10, rr = (idx >> 4) & 63, c8 = idx & 15; *(LAS u32x4*)(KA + uu * ROWB + rr * RS + c8 * 16) = kv[k < 18 ? k : 0]; }
;         __syncthreads();
;         if (ub == 0) {
; #pragma unroll
;             for (int ks = 0; ks < 4; ++ks) qf[ks] = ldrow(Qt + half * ROWB, RS, 16 * j, 32 * ks, lane); }
; #pragma unroll
;         for (int uu = 0; uu < 4; ++uu) { const int uo = ub + uu;
;             if (uo < 9) {
;                 const LAS unsigned char* kt = KA + uu * ROWB;
;                 if (dh == 0) { if (uo < 8) {
; #pragma unroll
;                     for (int mt = 0; mt < 2; ++mt)
; #pragma unroll
;                         for (int ks = 0; ks < 4; ++ks) { const bf16x8 kf = ldrow(kt, RS, ks0 + 16 * mt, 32 * ks, lane); s[uo < 8 ? uo : 0][mt] = mfma16(kf, qf[ks], s[uo < 8 ? uo : 0][mt]); } } }
.LBB0_652:
	s_or_b64 exec, exec, s[12:13]
	v_lshlrev_b32_e32 v90, 4, v140
	v_mul_i32_i24_e32 v182, 0x4400, v93
	v_mul_u32_u24_e32 v180, 0x110, v94
	v_and_b32_e32 v179, 0xf0, v90
	v_add3_u32 v90, 0, v182, v180
	v_add_u32_e32 v195, v90, v179
	v_mul_i32_i24_e32 v183, 0x4400, v95
	v_mul_u32_u24_e32 v184, 0x110, v96
	s_waitcnt vmcnt(21)
	ds_write_b128 v195, v[14:17]
	v_add3_u32 v14, 0, v183, v184
	v_add_u32_e32 v200, v14, v179
	v_mul_i32_i24_e32 v185, 0x4400, v97
	v_and_b32_e32 v194, 15, v140
	s_waitcnt vmcnt(20)
	ds_write_b128 v200, v[10:13]
	v_add3_u32 v10, 0, v185, v180
	v_mul_i32_i24_e32 v186, 0x4400, v98
	v_mul_u32_u24_e32 v187, 0x110, v99
	v_ashrrev_i32_e32 v138, 8, v140
	v_add_u32_e32 v90, v10, v179
	v_add3_u32 v10, 0, v186, v187
	s_movk_i32 s14, 0x4400
	v_lshl_or_b32 v141, v92, 4, v194
	v_add_u32_e32 v91, v10, v179
	v_and_b32_e32 v181, 48, v140
	v_mad_i32_i24 v10, v138, s14, 0
	v_mul_u32_u24_e32 v11, 0x110, v141
	v_mul_i32_i24_e32 v188, 0x4400, v100
	v_add3_u32 v10, v10, v11, v181
	v_add3_u32 v11, 0, v188, v180
	v_mul_i32_i24_e32 v189, 0x4400, v101
	v_mul_u32_u24_e32 v190, 0x110, v102
	v_add_u32_e32 v92, v11, v179
	v_add3_u32 v11, 0, v189, v190
	v_mul_i32_i24_e32 v191, 0x4400, v103
	v_add_u32_e32 v93, v11, v179
	v_add3_u32 v11, 0, v191, v180
	v_mul_i32_i24_e32 v192, 0x4400, v104
	v_mul_u32_u24_e32 v193, 0x110, v105
	v_add_u32_e32 v94, v11, v179
	v_add3_u32 v11, 0, v192, v193
	v_add_u32_e32 v95, v11, v179
	s_max_i32 s12, s9, 3
	s_waitcnt vmcnt(19)
	ds_write_b128 v90, v[22:25]
	s_waitcnt vmcnt(18)
	ds_write_b128 v91, v[18:21]
	s_waitcnt vmcnt(17)
	ds_write_b128 v195, v[58:61] offset:34816
	s_waitcnt vmcnt(16)
	ds_write_b128 v200, v[62:65] offset:34816
	s_waitcnt vmcnt(15)
	ds_write_b128 v90, v[66:69] offset:34816
	s_waitcnt vmcnt(14)
	ds_write_b128 v91, v[70:73] offset:34816
	s_waitcnt vmcnt(13)
	ds_write_b128 v92, v[78:81] offset:34816
	s_waitcnt vmcnt(12)
	ds_write_b128 v93, v[74:77] offset:34816
	s_waitcnt vmcnt(11)
	ds_write_b128 v94, v[86:89] offset:34816
	s_waitcnt vmcnt(10)
	ds_write_b128 v95, v[82:85] offset:34816
	s_waitcnt lgkmcnt(0)
	s_barrier
	ds_read_b128 v[22:25], v10
	ds_read_b128 v[18:21], v10 offset:64
	ds_read_b128 v[14:17], v10 offset:128
	ds_read_b128 v[10:13], v10 offset:192
	s_add_i32 s12, s12, -3
	s_min_u32 s20, s12, 0x78
	s_movk_i32 s12, 0x100
	s_cmp_eq_u32 s20, s18
	v_cmp_gt_u32_e32 vcc, s12, v140
	s_cselect_b64 s[12:13], -1, 0
	s_or_b64 s[12:13], vcc, s[12:13]
	v_add_u32_e32 v58, v139, v194
	s_xor_b64 s[14:15], s[12:13], -1
	v_mul_u32_u24_e32 v96, 0x110, v58
	s_and_saveexec_b64 s[16:17], s[14:15]
	s_xor_b64 s[16:17], exec, s[16:17]
	v_mul_u32_u24_e32 v96, 0x110, v58
	s_or_saveexec_b64 s[16:17], s[16:17]
	v_mov_b32_e32 v128, v1
	v_mov_b32_e32 v129, v1
	v_mov_b32_e32 v126, v1
	v_mov_b32_e32 v127, v1
	v_mov_b64_e32 v[132:133], v[128:129]
	v_mov_b64_e32 v[130:131], v[126:127]
	s_xor_b64 exec, exec, s[16:17]
	s_cbranch_execz .LBB0_656
	v_add3_u32 v66, 0, v181, v96
	ds_read_b128 v[58:61], v66 offset:34816
	ds_read_b128 v[62:65], v66 offset:34880
	s_waitcnt lgkmcnt(1)
	v_mfma_f32_16x16x32_bf16 v[58:61], v[58:61], v[22:25], 0
	s_waitcnt lgkmcnt(0)
	v_mfma_f32_16x16x32_bf16 v[58:61], v[62:65], v[18:21], v[58:61]
	ds_read_b128 v[62:65], v66 offset:34944
	s_waitcnt lgkmcnt(0)
	v_mfma_f32_16x16x32_bf16 v[58:61], v[62:65], v[14:17], v[58:61]
	ds_read_b128 v[62:65], v66 offset:35008
	s_waitcnt lgkmcnt(0)
	v_mfma_f32_16x16x32_bf16 v[126:129], v[62:65], v[10:13], v[58:61]
	s_nop 4
	ds_read_b128 v[58:61], v66 offset:39168
	ds_read_b128 v[62:65], v66 offset:39232
	s_waitcnt lgkmcnt(1)
	v_mfma_f32_16x16x32_bf16 v[58:61], v[58:61], v[22:25], 0
	s_waitcnt lgkmcnt(0)
	v_mfma_f32_16x16x32_bf16 v[58:61], v[62:65], v[18:21], v[58:61]
	ds_read_b128 v[62:65], v66 offset:39296
	s_waitcnt lgkmcnt(0)
	v_mfma_f32_16x16x32_bf16 v[58:61], v[62:65], v[14:17], v[58:61]
	ds_read_b128 v[62:65], v66 offset:39360
	s_waitcnt lgkmcnt(0)
	v_mfma_f32_16x16x32_bf16 v[130:133], v[62:65], v[10:13], v[58:61]

; #define LAS __attribute__((address_space(3)))
; __device__ __forceinline__ f32x4 mfma16(bf16x8 a, bf16x8 b, f32x4 c) { return __builtin_amdgcn_mfma_f32_16x16x32_bf16(a, b, c, 0, 0, 0); }
; __device__ __forceinline__ void na_unit(LAS unsigned char* lds, const bf16* P, const float* rpb, bf16* BR, int u, int tid) {
;     ...
;     for (int ub = 0; ub < 9; ub += 4) {
; #pragma unroll
;         for (int k = 2 * ub; k < 2 * ub + 8; ++k) if (k < 18) { const int idx = tid + (k - 2 * ub) * NTHR, uu = idx >> 10, rr = (idx >> 4) & 63, c8 = idx & 15; *(LAS u32x4*)(KA + uu * ROWB + rr * RS + c8 * 16) = kv[k < 18 ? k : 0]; }
;         __syncthreads();
;         if (ub == 0) {
; #pragma unroll
;             for (int ks = 0; ks < 4; ++ks) qf[ks] = ldrow(Qt + half * ROWB, RS, 16 * j, 32 * ks, lane); }
; #pragma unroll
;         for (int uu = 0; uu < 4; ++uu) { const int uo = ub + uu;
;             if (uo < 9) {
;                 const LAS unsigned char* kt = KA + uu * ROWB;
;                 if (dh == 0) { if (uo < 8) {
; #pragma unroll
;                     for (int mt = 0; mt < 2; ++mt)
; #pragma unroll
;                         for (int ks = 0; ks < 4; ++ks) { const bf16x8 kf = ldrow(kt, RS, ks0 + 16 * mt, 32 * ks, lane); s[uo < 8 ? uo : 0][mt] = mfma16(kf, qf[ks], s[uo < 8 ? uo : 0][mt]); } } }
;                 else { if (uo >= 1) {
; #pragma unroll
;                     for (int mt = 0; mt < 2; ++mt)
; #pragma unroll
;                         for (int ks = 0; ks < 4; ++ks) { const bf16x8 kf = ldrow(kt, RS, ks0 + 16 * mt, 32 * ks, lane); s[uo >= 1 ? uo - 1 : 0][mt] = mfma16(kf, qf[ks], s[uo >= 1 ? uo - 1 : 0][mt]); } } }
;             } }
.LBB0_684:
	s_or_b64 exec, exec, s[16:17]
	s_lshl_b32 s19, s19, 7
	s_waitcnt lgkmcnt(0)
	s_barrier
	s_waitcnt vmcnt(1)
	ds_write_b128 v195, v[2:5] offset:34816
	s_waitcnt vmcnt(0)
	ds_write_b128 v200, v[6:9] offset:34816
	s_waitcnt lgkmcnt(0)
	s_barrier
	s_and_saveexec_b64 s[16:17], s[14:15]
	s_cbranch_execz .LBB0_686
	ds_read_b128 v[2:5], v201 offset:34816
	ds_read_b128 v[6:9], v201 offset:34880
	s_waitcnt lgkmcnt(1)
	v_mfma_f32_16x16x32_bf16 v[2:5], v[2:5], v[22:25], v[82:85]
	s_waitcnt lgkmcnt(0)
	v_mfma_f32_16x16x32_bf16 v[2:5], v[6:9], v[18:21], v[2:5]
	ds_read_b128 v[6:9], v201 offset:34944
	s_waitcnt lgkmcnt(0)
	v_mfma_f32_16x16x32_bf16 v[2:5], v[6:9], v[14:17], v[2:5]
	ds_read_b128 v[6:9], v201 offset:35008
	s_waitcnt lgkmcnt(0)
	v_mfma_f32_16x16x32_bf16 v[82:85], v[6:9], v[10:13], v[2:5]
	s_nop 4
	ds_read_b128 v[2:5], v201 offset:39168
	ds_read_b128 v[6:9], v201 offset:39232
	s_waitcnt lgkmcnt(1)
	v_mfma_f32_16x16x32_bf16 v[2:5], v[2:5], v[22:25], v[74:77]
	s_waitcnt lgkmcnt(0)
	v_mfma_f32_16x16x32_bf16 v[2:5], v[6:9], v[18:21], v[2:5]
	ds_read_b128 v[6:9], v201 offset:39296
	s_waitcnt lgkmcnt(0)
	v_mfma_f32_16x16x32_bf16 v[2:5], v[6:9], v[14:17], v[2:5]
	ds_read_b128 v[6:9], v201 offset:39360
	s_waitcnt lgkmcnt(0)
	v_mfma_f32_16x16x32_bf16 v[74:77], v[6:9], v[10:13], v[2:5]

; #define LAS __attribute__((address_space(3)))
; __device__ __forceinline__ f32x4 mfma16(bf16x8 a, bf16x8 b, f32x4 c) { return __builtin_amdgcn_mfma_f32_16x16x32_bf16(a, b, c, 0, 0, 0); }
; __device__ __forceinline__ void na_unit(LAS unsigned char* lds, const bf16* P, const float* rpb, bf16* BR, int u, int tid) {
;     ...
;     for (int ub = 0; ub < 9; ub += 4) {
; #pragma unroll
;         for (int k = 2 * ub; k < 2 * ub + 8; ++k) if (k < 18) { const int idx = tid + (k - 2 * ub) * NTHR, uu = idx >> 10, rr = (idx >> 4) & 63, c8 = idx & 15; *(LAS u32x4*)(VB + uu * ROWB + rr * RS + c8 * 16) = vv[k < 18 ? k : 0]; }
;         __syncthreads();
; #pragma unroll
;         for (int uu = 0; uu < 4; ++uu) { const int uo = ub + uu;
;             if (uo < 9) {
;                 const LAS unsigned char* vt = VB + uu * ROWB;
;                 if (dh == 0) { if (uo < 8) { const bf16x8 pf = ldrow(Psc, RSP, 0, 32 * (uo < 8 ? uo : 0), lane);
; #pragma unroll
;                     for (int mt = 0; mt < 8; ++mt) { const bf16x8 vf = ldtr(vt, RS, ks0, 16 * mt, lane); o[mt] = mfma16(vf, pf, o[mt]); } } }
;                 else { if (uo >= 1) { const bf16x8 pf = ldrow(Psc, RSP, 0, 32 * (uo >= 1 ? uo - 1 : 0), lane);
; #pragma unroll
;                     for (int mt = 0; mt < 8; ++mt) { const bf16x8 vf = ldtr(vt, RS, ks0, 16 * mt, lane); o[mt] = mfma16(vf, pf, o[mt]); } } }
;             } }
.LBB0_820:
	s_or_b64 exec, exec, s[12:13]
	v_add3_u32 v113, s95, v114, v115
	s_and_saveexec_b64 s[12:13], s[14:15]
	s_xor_b64 s[12:13], exec, s[12:13]
	s_cbranch_execz .LBB0_822
	ds_read_b128 v[42:45], v112 offset:64
	ds_read_b64_tr_b16 v[72:73], v113 offset:1088
	ds_read_b64_tr_b16 v[70:71], v113
	ds_read_b64_tr_b16 v[74:75], v113 offset:32
	ds_read_b64_tr_b16 v[76:77], v113 offset:1120
	s_waitcnt lgkmcnt(2)
	v_mfma_f32_16x16x32_bf16 v[70:73], v[70:73], v[42:45], v[46:49]
	s_nop 2
	ds_read_b64_tr_b16 v[46:47], v113 offset:64
	ds_read_b64_tr_b16 v[48:49], v113 offset:1152
	s_waitcnt lgkmcnt(0)
	v_mfma_f32_16x16x32_bf16 v[78:81], v[46:49], v[42:45], v[58:61]
	ds_read_b64_tr_b16 v[46:47], v113 offset:96
	ds_read_b64_tr_b16 v[48:49], v113 offset:1184
	s_waitcnt lgkmcnt(0)
	v_mfma_f32_16x16x32_bf16 v[82:85], v[46:49], v[42:45], v[62:65]
	ds_read_b64_tr_b16 v[46:47], v113 offset:128
	ds_read_b64_tr_b16 v[48:49], v113 offset:1216
	s_waitcnt lgkmcnt(0)
	v_mfma_f32_16x16x32_bf16 v[86:89], v[46:49], v[42:45], v[66:69]
	ds_read_b64_tr_b16 v[46:47], v113 offset:160
	ds_read_b64_tr_b16 v[48:49], v113 offset:1248
	s_waitcnt lgkmcnt(0)
	v_mfma_f32_16x16x32_bf16 v[90:93], v[46:49], v[42:45], v[102:105]
	ds_read_b64_tr_b16 v[46:47], v113 offset:192
	ds_read_b64_tr_b16 v[48:49], v113 offset:1280
	s_waitcnt lgkmcnt(0)
	v_mfma_f32_16x16x32_bf16 v[94:97], v[46:49], v[42:45], v[106:109]
	ds_read_b64_tr_b16 v[46:47], v113 offset:224
	ds_read_b64_tr_b16 v[48:49], v113 offset:1312
	v_mfma_f32_16x16x32_bf16 v[74:77], v[74:77], v[42:45], v[54:57]
	s_waitcnt lgkmcnt(0)
	v_mfma_f32_16x16x32_bf16 v[98:101], v[46:49], v[42:45], v[50:53]
.LBB0_822:
	s_andn2_saveexec_b64 s[12:13], s[12:13]
	s_cbranch_execz .LBB0_824
	ds_read_b128 v[42:45], v112 offset:128
	ds_read_b64_tr_b16 v[72:73], v113 offset:1088
	ds_read_b64_tr_b16 v[70:71], v113
	s_nop 0
	ds_read_b64_tr_b16 v[74:75], v113 offset:32
	ds_read_b64_tr_b16 v[76:77], v113 offset:1120
	s_waitcnt lgkmcnt(2)
	v_mfma_f32_16x16x32_bf16 v[70:73], v[70:73], v[42:45], v[46:49]
	s_nop 2
	ds_read_b64_tr_b16 v[46:47], v113 offset:64
	ds_read_b64_tr_b16 v[48:49], v113 offset:1152
	s_waitcnt lgkmcnt(0)
	v_mfma_f32_16x16x32_bf16 v[78:81], v[46:49], v[42:45], v[58:61]
	ds_read_b64_tr_b16 v[46:47], v113 offset:96
	ds_read_b64_tr_b16 v[48:49], v113 offset:1184
	s_waitcnt lgkmcnt(0)
	v_mfma_f32_16x16x32_bf16 v[82:85], v[46:49], v[42:45], v[62:65]
	ds_read_b64_tr_b16 v[46:47], v113 offset:128
	ds_read_b64_tr_b16 v[48:49], v113 offset:1216
	s_waitcnt lgkmcnt(0)
	v_mfma_f32_16x16x32_bf16 v[86:89], v[46:49], v[42:45], v[66:69]
	ds_read_b64_tr_b16 v[46:47], v113 offset:160
	ds_read_b64_tr_b16 v[48:49], v113 offset:1248
	s_waitcnt lgkmcnt(0)
	v_mfma_f32_16x16x32_bf16 v[90:93], v[46:49], v[42:45], v[102:105]
	ds_read_b64_tr_b16 v[46:47], v113 offset:192
	ds_read_b64_tr_b16 v[48:49], v113 offset:1280
	s_waitcnt lgkmcnt(0)
	v_mfma_f32_16x16x32_bf16 v[94:97], v[46:49], v[42:45], v[106:109]
	ds_read_b64_tr_b16 v[46:47], v113 offset:224
	ds_read_b64_tr_b16 v[48:49], v113 offset:1312
	v_mfma_f32_16x16x32_bf16 v[74:77], v[74:77], v[42:45], v[54:57]
	s_waitcnt lgkmcnt(0)
	v_mfma_f32_16x16x32_bf16 v[98:101], v[46:49], v[42:45], v[50:53]
.LBB0_824:
	s_or_b64 exec, exec, s[12:13]
	v_readlane_b32 s9, v254, 62
	s_nop 1
	v_add3_u32 v106, s9, v114, v115
	s_and_saveexec_b64 s[12:13], s[14:15]
	s_xor_b64 s[12:13], exec, s[12:13]
	s_cbranch_execz .LBB0_826
	ds_read_b128 v[102:105], v112 offset:128
	ds_read_b64_tr_b16 v[44:45], v106 offset:1088
	ds_read_b64_tr_b16 v[42:43], v106
	ds_read_b64_tr_b16 v[46:47], v106 offset:32
	ds_read_b64_tr_b16 v[48:49], v106 offset:1120
	s_waitcnt lgkmcnt(2)
	v_mfma_f32_16x16x32_bf16 v[66:69], v[42:45], v[102:105], v[70:73]
	ds_read_b64_tr_b16 v[42:43], v106 offset:64
	ds_read_b64_tr_b16 v[44:45], v106 offset:1152
	s_waitcnt lgkmcnt(0)
	v_mfma_f32_16x16x32_bf16 v[62:65], v[42:45], v[102:105], v[78:81]
	ds_read_b64_tr_b16 v[42:43], v106 offset:96
	ds_read_b64_tr_b16 v[44:45], v106 offset:1184
	s_waitcnt lgkmcnt(0)
	v_mfma_f32_16x16x32_bf16 v[54:57], v[42:45], v[102:105], v[82:85]
	ds_read_b64_tr_b16 v[42:43], v106 offset:128
	ds_read_b64_tr_b16 v[44:45], v106 offset:1216
	s_waitcnt lgkmcnt(0)
	v_mfma_f32_16x16x32_bf16 v[50:53], v[42:45], v[102:105], v[86:89]
	ds_read_b64_tr_b16 v[42:43], v106 offset:160
	ds_read_b64_tr_b16 v[44:45], v106 offset:1248
	v_mfma_f32_16x16x32_bf16 v[58:61], v[46:49], v[102:105], v[74:77]
	s_waitcnt lgkmcnt(0)
	v_mfma_f32_16x16x32_bf16 v[46:49], v[42:45], v[102:105], v[90:93]
	ds_read_b64_tr_b16 v[42:43], v106 offset:192
	ds_read_b64_tr_b16 v[44:45], v106 offset:1280
	ds_read_b64_tr_b16 v[70:71], v106 offset:224
	ds_read_b64_tr_b16 v[72:73], v106 offset:1312
	s_waitcnt lgkmcnt(2)
	v_mfma_f32_16x16x32_bf16 v[42:45], v[42:45], v[102:105], v[94:97]
	s_waitcnt lgkmcnt(0)
	v_mfma_f32_16x16x32_bf16 v[102:105], v[70:73], v[102:105], v[98:101]
.LBB0_826:
	s_andn2_saveexec_b64 s[12:13], s[12:13]
	s_cbranch_execz .LBB0_828
	s_nop 5
	ds_read_b128 v[102:105], v112 offset:192
	ds_read_b64_tr_b16 v[44:45], v106 offset:1088
	ds_read_b64_tr_b16 v[42:43], v106
	ds_read_b64_tr_b16 v[46:47], v106 offset:32
	ds_read_b64_tr_b16 v[48:49], v106 offset:1120
	s_waitcnt lgkmcnt(2)
	v_mfma_f32_16x16x32_bf16 v[66:69], v[42:45], v[102:105], v[70:73]
	ds_read_b64_tr_b16 v[42:43], v106 offset:64
	ds_read_b64_tr_b16 v[44:45], v106 offset:1152
	s_waitcnt lgkmcnt(0)
	v_mfma_f32_16x16x32_bf16 v[62:65], v[42:45], v[102:105], v[78:81]
	ds_read_b64_tr_b16 v[42:43], v106 offset:96
	ds_read_b64_tr_b16 v[44:45], v106 offset:1184
	s_waitcnt lgkmcnt(0)
	v_mfma_f32_16x16x32_bf16 v[54:57], v[42:45], v[102:105], v[82:85]
	ds_read_b64_tr_b16 v[42:43], v106 offset:128
	ds_read_b64_tr_b16 v[44:45], v106 offset:1216
	s_waitcnt lgkmcnt(0)
	v_mfma_f32_16x16x32_bf16 v[50:53], v[42:45], v[102:105], v[86:89]
	ds_read_b64_tr_b16 v[42:43], v106 offset:160
	ds_read_b64_tr_b16 v[44:45], v106 offset:1248
	v_mfma_f32_16x16x32_bf16 v[58:61], v[46:49], v[102:105], v[74:77]
	s_waitcnt lgkmcnt(0)
	v_mfma_f32_16x16x32_bf16 v[46:49], v[42:45], v[102:105], v[90:93]
	ds_read_b64_tr_b16 v[42:43], v106 offset:192
	ds_read_b64_tr_b16 v[44:45], v106 offset:1280
	ds_read_b64_tr_b16 v[70:71], v106 offset:224
	ds_read_b64_tr_b16 v[72:73], v106 offset:1312
	s_waitcnt lgkmcnt(2)
	v_mfma_f32_16x16x32_bf16 v[42:45], v[42:45], v[102:105], v[94:97]
	s_waitcnt lgkmcnt(0)
	v_mfma_f32_16x16x32_bf16 v[102:105], v[70:73], v[102:105], v[98:101]
; #define LAS __attribute__((address_space(3)))
; __device__ __forceinline__ f32x4 mfma16(bf16x8 a, bf16x8 b, f32x4 c) { return __builtin_amdgcn_mfma_f32_16x16x32_bf16(a, b, c, 0, 0, 0); }
; __device__ __forceinline__ void na_unit(LAS unsigned char* lds, const bf16* P, const float* rpb, bf16* BR, int u, int tid) {
;     ...
;     for (int ub = 0; ub < 9; ub += 4) {
; #pragma unroll
;         for (int k = 2 * ub; k < 2 * ub + 8; ++k) if (k < 18) { const int idx = tid + (k - 2 * ub) * NTHR, uu = idx >> 10, rr = (idx >> 4) & 63, c8 = idx & 15; *(LAS u32x4*)(VB + uu * ROWB + rr * RS + c8 * 16) = vv[k < 18 ? k : 0]; }
;         __syncthreads();
; #pragma unroll
;         for (int uu = 0; uu < 4; ++uu) { const int uo = ub + uu;
;             if (uo < 9) {
;                 const LAS unsigned char* vt = VB + uu * ROWB;
;                 if (dh == 0) { if (uo < 8) { const bf16x8 pf = ldrow(Psc, RSP, 0, 32 * (uo < 8 ? uo : 0), lane);
; #pragma unroll
;                     for (int mt = 0; mt < 8; ++mt) { const bf16x8 vf = ldtr(vt, RS, ks0, 16 * mt, lane); o[mt] = mfma16(vf, pf, o[mt]); } } }
;                 else { if (uo >= 1) { const bf16x8 pf = ldrow(Psc, RSP, 0, 32 * (uo >= 1 ? uo - 1 : 0), lane);
; #pragma unroll
;                     for (int mt = 0; mt < 8; ++mt) { const bf16x8 vf = ldtr(vt, RS, ks0, 16 * mt, lane); o[mt] = mfma16(vf, pf, o[mt]); } } }
;             } }
.LBB0_828:
	s_or_b64 exec, exec, s[12:13]
	s_barrier
	s_waitcnt vmcnt(9)
	ds_write_b128 v110, v[10:13]
	s_waitcnt vmcnt(8)
	ds_write_b128 v111, v[14:17]
	s_waitcnt vmcnt(7)
	ds_write_b128 v116, v[18:21]
	s_waitcnt vmcnt(6)
	ds_write_b128 v117, v[22:25]
	s_waitcnt vmcnt(5)
	ds_write_b128 v118, v[26:29]
	s_waitcnt vmcnt(4)
	ds_write_b128 v119, v[30:33]
	s_waitcnt vmcnt(3)
	ds_write_b128 v120, v[34:37]
	s_waitcnt vmcnt(2)
	ds_write_b128 v121, v[38:41]
	v_add_u32_e32 v10, s50, v114
	v_add_u32_e32 v107, v10, v115
	s_waitcnt lgkmcnt(0)
	s_barrier
	s_and_saveexec_b64 s[12:13], s[14:15]
	s_xor_b64 s[12:13], exec, s[12:13]
	s_cbranch_execz .LBB0_830
	ds_read_b128 v[10:13], v112 offset:192
	ds_read_b64_tr_b16 v[16:17], v107 offset:1088
	ds_read_b64_tr_b16 v[14:15], v107
	ds_read_b64_tr_b16 v[18:19], v107 offset:32
	ds_read_b64_tr_b16 v[20:21], v107 offset:1120
	s_waitcnt lgkmcnt(2)
	v_mfma_f32_16x16x32_bf16 v[78:81], v[14:17], v[10:13], v[66:69]
	ds_read_b64_tr_b16 v[14:15], v107 offset:64
	ds_read_b64_tr_b16 v[16:17], v107 offset:1152
	s_waitcnt lgkmcnt(0)
	v_mfma_f32_16x16x32_bf16 v[74:77], v[14:17], v[10:13], v[62:65]
	ds_read_b64_tr_b16 v[14:15], v107 offset:96
	ds_read_b64_tr_b16 v[16:17], v107 offset:1184
	s_waitcnt lgkmcnt(0)
	v_mfma_f32_16x16x32_bf16 v[86:89], v[14:17], v[10:13], v[54:57]
	ds_read_b64_tr_b16 v[14:15], v107 offset:128
	ds_read_b64_tr_b16 v[16:17], v107 offset:1216
	s_waitcnt lgkmcnt(0)
	v_mfma_f32_16x16x32_bf16 v[90:93], v[14:17], v[10:13], v[50:53]
	ds_read_b64_tr_b16 v[14:15], v107 offset:160
	ds_read_b64_tr_b16 v[16:17], v107 offset:1248
	s_waitcnt lgkmcnt(0)
	v_mfma_f32_16x16x32_bf16 v[94:97], v[14:17], v[10:13], v[46:49]
	ds_read_b64_tr_b16 v[14:15], v107 offset:192
	ds_read_b64_tr_b16 v[16:17], v107 offset:1280
	s_waitcnt lgkmcnt(0)
	v_mfma_f32_16x16x32_bf16 v[98:101], v[14:17], v[10:13], v[42:45]
	ds_read_b64_tr_b16 v[14:15], v107 offset:224
	ds_read_b64_tr_b16 v[16:17], v107 offset:1312
	v_mfma_f32_16x16x32_bf16 v[82:85], v[18:21], v[10:13], v[58:61]
	s_waitcnt lgkmcnt(0)
	v_mfma_f32_16x16x32_bf16 v[10:13], v[14:17], v[10:13], v[102:105]
.LBB0_830:
	s_andn2_saveexec_b64 s[12:13], s[12:13]
	s_cbranch_execz .LBB0_832
	s_nop 5
	ds_read_b128 v[10:13], v112 offset:256
	ds_read_b64_tr_b16 v[16:17], v107 offset:1088
	ds_read_b64_tr_b16 v[14:15], v107
	ds_read_b64_tr_b16 v[18:19], v107 offset:32
	ds_read_b64_tr_b16 v[20:21], v107 offset:1120
	s_waitcnt lgkmcnt(2)
	v_mfma_f32_16x16x32_bf16 v[78:81], v[14:17], v[10:13], v[66:69]
	ds_read_b64_tr_b16 v[14:15], v107 offset:64
	ds_read_b64_tr_b16 v[16:17], v107 offset:1152
	s_waitcnt lgkmcnt(0)
	v_mfma_f32_16x16x32_bf16 v[74:77], v[14:17], v[10:13], v[62:65]
	ds_read_b64_tr_b16 v[14:15], v107 offset:96
	ds_read_b64_tr_b16 v[16:17], v107 offset:1184
	s_waitcnt lgkmcnt(0)
	v_mfma_f32_16x16x32_bf16 v[86:89], v[14:17], v[10:13], v[54:57]
	ds_read_b64_tr_b16 v[14:15], v107 offset:128
	ds_read_b64_tr_b16 v[16:17], v107 offset:1216
	s_waitcnt lgkmcnt(0)
	v_mfma_f32_16x16x32_bf16 v[90:93], v[14:17], v[10:13], v[50:53]
	ds_read_b64_tr_b16 v[14:15], v107 offset:160
	ds_read_b64_tr_b16 v[16:17], v107 offset:1248
	s_waitcnt lgkmcnt(0)
	v_mfma_f32_16x16x32_bf16 v[94:97], v[14:17], v[10:13], v[46:49]
	ds_read_b64_tr_b16 v[14:15], v107 offset:192
	ds_read_b64_tr_b16 v[16:17], v107 offset:1280
	s_waitcnt lgkmcnt(0)
	v_mfma_f32_16x16x32_bf16 v[98:101], v[14:17], v[10:13], v[42:45]
	ds_read_b64_tr_b16 v[14:15], v107 offset:224
	ds_read_b64_tr_b16 v[16:17], v107 offset:1312
	v_mfma_f32_16x16x32_bf16 v[82:85], v[18:21], v[10:13], v[58:61]
	s_waitcnt lgkmcnt(0)
	v_mfma_f32_16x16x32_bf16 v[10:13], v[14:17], v[10:13], v[102:105]
.LBB0_832:
	s_or_b64 exec, exec, s[12:13]
	v_readlane_b32 s9, v254, 61
	s_nop 1
	v_add_u32_e32 v14, s9, v114
	v_add_u32_e32 v42, v14, v115
	s_and_saveexec_b64 s[12:13], s[14:15]
	s_xor_b64 s[12:13], exec, s[12:13]
	s_cbranch_execz .LBB0_834
	ds_read_b128 v[14:17], v112 offset:256
	ds_read_b64_tr_b16 v[20:21], v42 offset:1088
	ds_read_b64_tr_b16 v[18:19], v42
	ds_read_b64_tr_b16 v[22:23], v42 offset:32
	ds_read_b64_tr_b16 v[24:25], v42 offset:1120
	s_waitcnt lgkmcnt(2)
	v_mfma_f32_16x16x32_bf16 v[70:73], v[18:21], v[14:17], v[78:81]
	ds_read_b64_tr_b16 v[18:19], v42 offset:64
	ds_read_b64_tr_b16 v[20:21], v42 offset:1152
	s_waitcnt lgkmcnt(0)
	v_mfma_f32_16x16x32_bf16 v[34:37], v[18:21], v[14:17], v[74:77]
	ds_read_b64_tr_b16 v[18:19], v42 offset:96
	ds_read_b64_tr_b16 v[20:21], v42 offset:1184
	s_waitcnt lgkmcnt(0)
	v_mfma_f32_16x16x32_bf16 v[30:33], v[18:21], v[14:17], v[86:89]
	ds_read_b64_tr_b16 v[18:19], v42 offset:128
	ds_read_b64_tr_b16 v[20:21], v42 offset:1216
	s_waitcnt lgkmcnt(0)
	v_mfma_f32_16x16x32_bf16 v[26:29], v[18:21], v[14:17], v[90:93]
	ds_read_b64_tr_b16 v[18:19], v42 offset:160
	ds_read_b64_tr_b16 v[20:21], v42 offset:1248
	v_mfma_f32_16x16x32_bf16 v[38:41], v[22:25], v[14:17], v[82:85]
	s_waitcnt lgkmcnt(0)
	v_mfma_f32_16x16x32_bf16 v[22:25], v[18:21], v[14:17], v[94:97]
	ds_read_b64_tr_b16 v[18:19], v42 offset:192
	ds_read_b64_tr_b16 v[20:21], v42 offset:1280
	ds_read_b64_tr_b16 v[44:45], v42 offset:224
	ds_read_b64_tr_b16 v[46:47], v42 offset:1312
	s_waitcnt lgkmcnt(2)
	v_mfma_f32_16x16x32_bf16 v[18:21], v[18:21], v[14:17], v[98:101]
	s_waitcnt lgkmcnt(0)
	v_mfma_f32_16x16x32_bf16 v[14:17], v[44:47], v[14:17], v[10:13]
	s_andn2_saveexec_b64 s[12:13], s[12:13]
	s_cbranch_execz .LBB0_836
	s_branch .LBB0_835

; #define LAS __attribute__((address_space(3)))
; __device__ __forceinline__ f32x4 mfma16(bf16x8 a, bf16x8 b, f32x4 c) { return __builtin_amdgcn_mfma_f32_16x16x32_bf16(a, b, c, 0, 0, 0); }
; __device__ __forceinline__ void na_unit(LAS unsigned char* lds, const bf16* P, const float* rpb, bf16* BR, int u, int tid) {
;     ...
;         for (int uu = 0; uu < 4; ++uu) { const int uo = ub + uu;
;             if (uo < 9) {
;                 const LAS unsigned char* vt = VB + uu * ROWB;
;                 if (dh == 0) { if (uo < 8) { const bf16x8 pf = ldrow(Psc, RSP, 0, 32 * (uo < 8 ? uo : 0), lane);
; #pragma unroll
;                     for (int mt = 0; mt < 8; ++mt) { const bf16x8 vf = ldtr(vt, RS, ks0, 16 * mt, lane); o[mt] = mfma16(vf, pf, o[mt]); } } }
;                 else { if (uo >= 1) { const bf16x8 pf = ldrow(Psc, RSP, 0, 32 * (uo >= 1 ? uo - 1 : 0), lane);
; #pragma unroll
;                     for (int mt = 0; mt < 8; ++mt) { const bf16x8 vf = ldtr(vt, RS, ks0, 16 * mt, lane); o[mt] = mfma16(vf, pf, o[mt]); } } }
;             } }
.LBB0_835:
	s_nop 4
	ds_read_b128 v[14:17], v112 offset:320
	ds_read_b64_tr_b16 v[20:21], v42 offset:1088
	ds_read_b64_tr_b16 v[18:19], v42
	ds_read_b64_tr_b16 v[22:23], v42 offset:32
	ds_read_b64_tr_b16 v[24:25], v42 offset:1120
	s_waitcnt lgkmcnt(2)
	v_mfma_f32_16x16x32_bf16 v[70:73], v[18:21], v[14:17], v[78:81]
	ds_read_b64_tr_b16 v[18:19], v42 offset:64
	ds_read_b64_tr_b16 v[20:21], v42 offset:1152
	s_waitcnt lgkmcnt(0)
	v_mfma_f32_16x16x32_bf16 v[34:37], v[18:21], v[14:17], v[74:77]
	ds_read_b64_tr_b16 v[18:19], v42 offset:96
	ds_read_b64_tr_b16 v[20:21], v42 offset:1184
	s_waitcnt lgkmcnt(0)
	v_mfma_f32_16x16x32_bf16 v[30:33], v[18:21], v[14:17], v[86:89]
	ds_read_b64_tr_b16 v[18:19], v42 offset:128
	ds_read_b64_tr_b16 v[20:21], v42 offset:1216
	s_waitcnt lgkmcnt(0)
	v_mfma_f32_16x16x32_bf16 v[26:29], v[18:21], v[14:17], v[90:93]
	ds_read_b64_tr_b16 v[18:19], v42 offset:160
	ds_read_b64_tr_b16 v[20:21], v42 offset:1248
	v_mfma_f32_16x16x32_bf16 v[38:41], v[22:25], v[14:17], v[82:85]
	s_waitcnt lgkmcnt(0)
	v_mfma_f32_16x16x32_bf16 v[22:25], v[18:21], v[14:17], v[94:97]
	ds_read_b64_tr_b16 v[18:19], v42 offset:192
	ds_read_b64_tr_b16 v[20:21], v42 offset:1280
	ds_read_b64_tr_b16 v[44:45], v42 offset:224
	ds_read_b64_tr_b16 v[46:47], v42 offset:1312
	s_waitcnt lgkmcnt(2)
	v_mfma_f32_16x16x32_bf16 v[18:21], v[18:21], v[14:17], v[98:101]
	s_waitcnt lgkmcnt(0)
	v_mfma_f32_16x16x32_bf16 v[14:17], v[44:47], v[14:17], v[10:13]
.LBB0_836:
	s_or_b64 exec, exec, s[12:13]
	s_and_saveexec_b64 s[12:13], s[14:15]
	s_xor_b64 s[12:13], exec, s[12:13]
	s_cbranch_execz .LBB0_838
	ds_read_b128 v[10:13], v112 offset:320
	ds_read_b64_tr_b16 v[44:45], v113 offset:1088
	ds_read_b64_tr_b16 v[42:43], v113
	ds_read_b64_tr_b16 v[46:47], v113 offset:32
	ds_read_b64_tr_b16 v[48:49], v113 offset:1120
	s_waitcnt lgkmcnt(2)
	v_mfma_f32_16x16x32_bf16 v[74:77], v[42:45], v[10:13], v[70:73]
	s_waitcnt lgkmcnt(0)
	v_mfma_f32_16x16x32_bf16 v[66:69], v[46:49], v[10:13], v[38:41]
	s_nop 2
	ds_read_b64_tr_b16 v[38:39], v113 offset:64
	ds_read_b64_tr_b16 v[40:41], v113 offset:1152
	s_waitcnt lgkmcnt(0)
	v_mfma_f32_16x16x32_bf16 v[62:65], v[38:41], v[10:13], v[34:37]
	s_nop 2
	ds_read_b64_tr_b16 v[34:35], v113 offset:96
	ds_read_b64_tr_b16 v[36:37], v113 offset:1184
	s_waitcnt lgkmcnt(0)
	v_mfma_f32_16x16x32_bf16 v[58:61], v[34:37], v[10:13], v[30:33]
	s_nop 2
	ds_read_b64_tr_b16 v[30:31], v113 offset:128
	ds_read_b64_tr_b16 v[32:33], v113 offset:1216
	s_waitcnt lgkmcnt(0)
	v_mfma_f32_16x16x32_bf16 v[54:57], v[30:33], v[10:13], v[26:29]
	s_nop 2
	ds_read_b64_tr_b16 v[26:27], v113 offset:160
	ds_read_b64_tr_b16 v[28:29], v113 offset:1248
	s_waitcnt lgkmcnt(0)
	v_mfma_f32_16x16x32_bf16 v[50:53], v[26:29], v[10:13], v[22:25]
	s_nop 2
	ds_read_b64_tr_b16 v[22:23], v113 offset:192
	ds_read_b64_tr_b16 v[24:25], v113 offset:1280
	s_waitcnt lgkmcnt(0)
	v_mfma_f32_16x16x32_bf16 v[46:49], v[22:25], v[10:13], v[18:21]
	s_nop 2
	ds_read_b64_tr_b16 v[18:19], v113 offset:224
	ds_read_b64_tr_b16 v[20:21], v113 offset:1312
	s_waitcnt lgkmcnt(0)
	v_mfma_f32_16x16x32_bf16 v[42:45], v[18:21], v[10:13], v[14:17]
	s_andn2_saveexec_b64 s[12:13], s[12:13]
	s_cbranch_execz .LBB0_840
	s_branch .LBB0_839

; #define LAS __attribute__((address_space(3)))
; __device__ __forceinline__ f32x4 mfma16(bf16x8 a, bf16x8 b, f32x4 c) { return __builtin_amdgcn_mfma_f32_16x16x32_bf16(a, b, c, 0, 0, 0); }
; __device__ __forceinline__ void na_unit(LAS unsigned char* lds, const bf16* P, const float* rpb, bf16* BR, int u, int tid) {
;     ...
;         for (int uu = 0; uu < 4; ++uu) { const int uo = ub + uu;
;             if (uo < 9) {
;                 const LAS unsigned char* vt = VB + uu * ROWB;
;                 if (dh == 0) { if (uo < 8) { const bf16x8 pf = ldrow(Psc, RSP, 0, 32 * (uo < 8 ? uo : 0), lane);
; #pragma unroll
;                     for (int mt = 0; mt < 8; ++mt) { const bf16x8 vf = ldtr(vt, RS, ks0, 16 * mt, lane); o[mt] = mfma16(vf, pf, o[mt]); } } }
;                 else { if (uo >= 1) { const bf16x8 pf = ldrow(Psc, RSP, 0, 32 * (uo >= 1 ? uo - 1 : 0), lane);
; #pragma unroll
;                     for (int mt = 0; mt < 8; ++mt) { const bf16x8 vf = ldtr(vt, RS, ks0, 16 * mt, lane); o[mt] = mfma16(vf, pf, o[mt]); } } }
;             } }
.LBB0_839:
	ds_read_b128 v[10:13], v112 offset:384
	s_nop 3
	ds_read_b64_tr_b16 v[44:45], v113 offset:1088
	ds_read_b64_tr_b16 v[42:43], v113
	ds_read_b64_tr_b16 v[46:47], v113 offset:32
	ds_read_b64_tr_b16 v[48:49], v113 offset:1120
	s_waitcnt lgkmcnt(2)
	v_mfma_f32_16x16x32_bf16 v[74:77], v[42:45], v[10:13], v[70:73]
	s_waitcnt lgkmcnt(0)
	v_mfma_f32_16x16x32_bf16 v[66:69], v[46:49], v[10:13], v[38:41]
	s_nop 2
	ds_read_b64_tr_b16 v[38:39], v113 offset:64
	ds_read_b64_tr_b16 v[40:41], v113 offset:1152
	s_waitcnt lgkmcnt(0)
	v_mfma_f32_16x16x32_bf16 v[62:65], v[38:41], v[10:13], v[34:37]
	s_nop 2
	ds_read_b64_tr_b16 v[34:35], v113 offset:96
	ds_read_b64_tr_b16 v[36:37], v113 offset:1184
	s_waitcnt lgkmcnt(0)
	v_mfma_f32_16x16x32_bf16 v[58:61], v[34:37], v[10:13], v[30:33]
	s_nop 2
	ds_read_b64_tr_b16 v[30:31], v113 offset:128
	ds_read_b64_tr_b16 v[32:33], v113 offset:1216
	s_waitcnt lgkmcnt(0)
	v_mfma_f32_16x16x32_bf16 v[54:57], v[30:33], v[10:13], v[26:29]
	s_nop 2
	ds_read_b64_tr_b16 v[26:27], v113 offset:160
	ds_read_b64_tr_b16 v[28:29], v113 offset:1248
	s_waitcnt lgkmcnt(0)
	v_mfma_f32_16x16x32_bf16 v[50:53], v[26:29], v[10:13], v[22:25]
	s_nop 2
	ds_read_b64_tr_b16 v[22:23], v113 offset:192
	ds_read_b64_tr_b16 v[24:25], v113 offset:1280
	s_waitcnt lgkmcnt(0)
	v_mfma_f32_16x16x32_bf16 v[46:49], v[22:25], v[10:13], v[18:21]
	s_nop 2
	ds_read_b64_tr_b16 v[18:19], v113 offset:224
	ds_read_b64_tr_b16 v[20:21], v113 offset:1312
	s_waitcnt lgkmcnt(0)
	v_mfma_f32_16x16x32_bf16 v[42:45], v[18:21], v[10:13], v[14:17]

; #define LAS __attribute__((address_space(3)))
; __device__ __forceinline__ f32x4 mfma16(bf16x8 a, bf16x8 b, f32x4 c) { return __builtin_amdgcn_mfma_f32_16x16x32_bf16(a, b, c, 0, 0, 0); }
; __device__ __forceinline__ void na_unit(LAS unsigned char* lds, const bf16* P, const float* rpb, bf16* BR, int u, int tid) {
;     ...
;     for (int ub = 0; ub < 9; ub += 4) {
; #pragma unroll
;         for (int k = 2 * ub; k < 2 * ub + 8; ++k) if (k < 18) { const int idx = tid + (k - 2 * ub) * NTHR, uu = idx >> 10, rr = (idx >> 4) & 63, c8 = idx & 15; *(LAS u32x4*)(VB + uu * ROWB + rr * RS + c8 * 16) = vv[k < 18 ? k : 0]; }
;         __syncthreads();
; #pragma unroll
;         for (int uu = 0; uu < 4; ++uu) { const int uo = ub + uu;
;             if (uo < 9) {
;                 const LAS unsigned char* vt = VB + uu * ROWB;
;                 if (dh == 0) { if (uo < 8) { const bf16x8 pf = ldrow(Psc, RSP, 0, 32 * (uo < 8 ? uo : 0), lane);
; #pragma unroll
;                     for (int mt = 0; mt < 8; ++mt) { const bf16x8 vf = ldtr(vt, RS, ks0, 16 * mt, lane); o[mt] = mfma16(vf, pf, o[mt]); } } }
;                 else { if (uo >= 1) { const bf16x8 pf = ldrow(Psc, RSP, 0, 32 * (uo >= 1 ? uo - 1 : 0), lane);
; #pragma unroll
;                     for (int mt = 0; mt < 8; ++mt) { const bf16x8 vf = ldtr(vt, RS, ks0, 16 * mt, lane); o[mt] = mfma16(vf, pf, o[mt]); } } }
;             } }
.LBB0_844:
	s_or_b64 exec, exec, s[12:13]
	s_barrier
	s_waitcnt vmcnt(1)
	ds_write_b128 v110, v[2:5]
	s_waitcnt vmcnt(0)
	ds_write_b128 v111, v[6:9]
	s_waitcnt lgkmcnt(0)
	s_barrier
	s_and_saveexec_b64 s[12:13], s[14:15]
	s_cbranch_execz .LBB0_637
	ds_read_b128 v[2:5], v112 offset:448
	ds_read_b64_tr_b16 v[8:9], v107 offset:1088
	ds_read_b64_tr_b16 v[6:7], v107
	ds_read_b64_tr_b16 v[42:43], v107 offset:32
	ds_read_b64_tr_b16 v[44:45], v107 offset:1120
	s_waitcnt lgkmcnt(2)
	v_mfma_f32_16x16x32_bf16 v[10:13], v[6:9], v[2:5], v[10:13]
	ds_read_b64_tr_b16 v[6:7], v107 offset:64
	ds_read_b64_tr_b16 v[8:9], v107 offset:1152
	s_waitcnt lgkmcnt(0)
	v_mfma_f32_16x16x32_bf16 v[18:21], v[6:9], v[2:5], v[18:21]
	ds_read_b64_tr_b16 v[6:7], v107 offset:96
	ds_read_b64_tr_b16 v[8:9], v107 offset:1184
	s_waitcnt lgkmcnt(0)
	v_mfma_f32_16x16x32_bf16 v[22:25], v[6:9], v[2:5], v[22:25]
	ds_read_b64_tr_b16 v[6:7], v107 offset:128
	ds_read_b64_tr_b16 v[8:9], v107 offset:1216
	s_waitcnt lgkmcnt(0)
	v_mfma_f32_16x16x32_bf16 v[26:29], v[6:9], v[2:5], v[26:29]
	ds_read_b64_tr_b16 v[6:7], v107 offset:160
	ds_read_b64_tr_b16 v[8:9], v107 offset:1248
	s_waitcnt lgkmcnt(0)
	v_mfma_f32_16x16x32_bf16 v[30:33], v[6:9], v[2:5], v[30:33]
	ds_read_b64_tr_b16 v[6:7], v107 offset:192
	ds_read_b64_tr_b16 v[8:9], v107 offset:1280
	s_waitcnt lgkmcnt(0)
	v_mfma_f32_16x16x32_bf16 v[34:37], v[6:9], v[2:5], v[34:37]
	ds_read_b64_tr_b16 v[6:7], v107 offset:224
	ds_read_b64_tr_b16 v[8:9], v107 offset:1312
	v_mfma_f32_16x16x32_bf16 v[14:17], v[42:45], v[2:5], v[14:17]
	s_waitcnt lgkmcnt(0)
	v_mfma_f32_16x16x32_bf16 v[38:41], v[6:9], v[2:5], v[38:41]
	s_branch .LBB0_637

; __device__ __forceinline__ float log_sigmoid(float x) { return -softplus(-x); }
; __device__ __forceinline__ f32x4 mfma16(bf16x8 a, bf16x8 b, f32x4 c) { return __builtin_amdgcn_mfma_f32_16x16x32_bf16(a, b, c, 0, 0, 0); }
; __device__ __forceinline__ void ret_apply_unit(LAS unsigned char* lds, const bf16* P, const bf16* PREV, bf16* BR, const float* dec, int u, int tid) {
;     ...
;     const float lgf2 = log_sigmoid(dcf) * 1.4426950408889634f, lgb2 = log_sigmoid(dcb) * 1.4426950408889634f;
;     tile_load<128, 32>(pr, PREV + ((size_t)n * 8 + h * 2) * 65536, 256, tid);
;     __syncthreads();
;     f32x4 s[8];
; #pragma unroll
;     for (int mt = 0; mt < 8; ++mt) s[mt] = (f32x4){0.f, 0.f, 0.f, 0.f};
; #pragma unroll
;     for (int ks = 0; ks < 8; ++ks) { const bf16x8 qf = ldrow(Qt, RSQ, 16 * w, 32 * ks, lane);
; #pragma unroll
;         for (int mt = 0; mt < 8; ++mt) { const bf16x8 kf = ldrow(Kt, RSQ, 16 * mt, 32 * ks, lane); s[mt] = mfma16(kf, qf, s[mt]); } }
.LBB0_961:
	s_or_b64 exec, exec, s[12:13]
	s_lshl_b32 s9, s9, 18
	s_lshl_b64 s[12:13], s[22:23], 20
	v_max_f32_e64 v50, -v50, -v50
	s_add_u32 s12, s16, s12
	v_max_f32_e32 v50, 0, v50
	s_addc_u32 s13, s17, s13
	v_ashrrev_i32_e32 v7, 31, v6
	v_ashrrev_i32_e32 v15, 31, v14
	v_ashrrev_i32_e32 v19, 31, v18
	v_ashrrev_i32_e32 v27, 31, v26
	v_ashrrev_i32_e32 v31, 31, v30
	v_ashrrev_i32_e32 v35, 31, v34
	v_ashrrev_i32_e32 v43, 31, v42
	v_ashrrev_i32_e32 v47, 31, v46
	v_add_f32_e32 v50, v50, v51
	s_add_u32 s24, s12, s9
	v_mul_f32_e32 v216, 0xbfb8aa3b, v50
	v_and_b32_e32 v50, 15, v94
	s_addc_u32 s25, s13, 0
	v_lshlrev_b64 v[164:165], 9, v[6:7]
	v_lshlrev_b64 v[168:169], 9, v[14:15]
	v_lshlrev_b64 v[172:173], 9, v[18:19]
	v_lshlrev_b64 v[176:177], 9, v[26:27]
	v_lshlrev_b64 v[180:181], 9, v[30:31]
	v_lshlrev_b64 v[184:185], 9, v[34:35]
	v_lshlrev_b64 v[188:189], 9, v[42:43]
	v_lshlrev_b64 v[192:193], 9, v[46:47]
	v_lshl_add_u64 v[6:7], s[24:25], 0, v[164:165]
	v_lshlrev_b64 v[166:167], 1, v[8:9]
	v_lshl_add_u64 v[14:15], s[24:25], 0, v[168:169]
	v_lshlrev_b64 v[170:171], 1, v[16:17]
	v_lshl_add_u64 v[18:19], s[24:25], 0, v[172:173]
	v_lshlrev_b64 v[174:175], 1, v[20:21]
	v_lshl_add_u64 v[26:27], s[24:25], 0, v[176:177]
	v_lshlrev_b64 v[178:179], 1, v[28:29]
	v_lshl_add_u64 v[30:31], s[24:25], 0, v[180:181]
	v_lshlrev_b64 v[182:183], 1, v[32:33]
	v_lshl_add_u64 v[34:35], s[24:25], 0, v[184:185]
	v_lshlrev_b64 v[186:187], 1, v[36:37]
	v_lshl_add_u64 v[42:43], s[24:25], 0, v[188:189]
	v_lshlrev_b64 v[190:191], 1, v[44:45]
	v_lshl_add_u64 v[46:47], s[24:25], 0, v[192:193]
	v_lshlrev_b64 v[194:195], 1, v[48:49]
	v_and_b32_e32 v104, 48, v94
	v_mul_u32_u24_e32 v54, 0x210, v50
	v_lshl_add_u64 v[6:7], v[6:7], 0, v[166:167]
	v_lshl_add_u64 v[14:15], v[14:15], 0, v[170:171]
	v_lshl_add_u64 v[18:19], v[18:19], 0, v[174:175]
	v_lshl_add_u64 v[26:27], v[26:27], 0, v[178:179]
	v_lshl_add_u64 v[30:31], v[30:31], 0, v[182:183]
	v_lshl_add_u64 v[34:35], v[34:35], 0, v[186:187]
	v_lshl_add_u64 v[42:43], v[42:43], 0, v[190:191]
	v_lshl_add_u64 v[46:47], v[46:47], 0, v[194:195]
	v_add3_u32 v207, s50, v104, v54
	global_load_dwordx4 v[6:9], v[6:7], off
	v_ashrrev_i32_e32 v51, 2, v94
	global_load_dwordx4 v[14:17], v[14:15], off
	v_bfi_b32 v162, -16, v51, v94
	global_load_dwordx4 v[18:21], v[18:19], off
	v_max_f32_e64 v0, -v0, -v0
	global_load_dwordx4 v[26:29], v[26:27], off
	v_mul_lo_u32 v51, v162, s55
	global_load_dwordx4 v[30:33], v[30:31], off
	v_max_f32_e32 v0, 0, v0
	global_load_dwordx4 v[34:37], v[34:35], off
	v_add3_u32 v208, 0, v51, v104
	global_load_dwordx4 v[42:45], v[42:43], off
	v_add_f32_e32 v0, v0, v52
	global_load_dwordx4 v[46:49], v[46:47], off
	s_waitcnt lgkmcnt(0)
	s_barrier
	ds_read_b128 v[54:57], v207
	ds_read_b128 v[58:61], v207 offset:8448
	ds_read_b128 v[62:65], v207 offset:16896
	ds_read_b128 v[82:85], v207 offset:25344
	ds_read_b128 v[86:89], v207 offset:33792
	ds_read_b128 v[90:93], v207 offset:42240
	ds_read_b128 v[108:111], v207 offset:50688
	ds_read_b128 v[112:115], v207 offset:59136
	ds_read_b128 v[50:53], v208
	s_waitcnt lgkmcnt(0)
	v_mfma_f32_16x16x32_bf16 v[54:57], v[54:57], v[50:53], 0
	v_bfe_u32 v107, v94, 4, 2
	v_mul_f32_e32 v217, 0xbfb8aa3b, v0
	v_mul_lo_u32 v0, v162, s56
	v_mfma_f32_16x16x32_bf16 v[58:61], v[58:61], v[50:53], 0
	v_add_u32_e32 v105, s50, v0
	v_lshlrev_b32_e32 v0, 3, v107
	v_lshlrev_b32_e32 v107, 2, v107
	v_mfma_f32_16x16x32_bf16 v[62:65], v[62:65], v[50:53], 0
	v_add_u32_e32 v106, v105, v0
	v_and_b32_e32 v206, 63, v94
	s_add_u32 s12, s24, 0x10000
	v_mfma_f32_16x16x32_bf16 v[82:85], v[82:85], v[50:53], 0
	s_addc_u32 s13, s25, 0
	s_mov_b32 s9, 0xf800000
	v_mfma_f32_16x16x32_bf16 v[86:89], v[86:89], v[50:53], 0
	v_mfma_f32_16x16x32_bf16 v[90:93], v[90:93], v[50:53], 0
	v_mfma_f32_16x16x32_bf16 v[108:111], v[108:111], v[50:53], 0
	v_mfma_f32_16x16x32_bf16 v[50:53], v[112:115], v[50:53], 0
	ds_read_b128 v[112:115], v208 offset:64
	ds_read_b128 v[116:119], v207 offset:64
	s_waitcnt lgkmcnt(0)
	v_mfma_f32_16x16x32_bf16 v[54:57], v[116:119], v[112:115], v[54:57]
	ds_read_b128 v[116:119], v207 offset:8512
	s_waitcnt lgkmcnt(0)
	v_mfma_f32_16x16x32_bf16 v[58:61], v[116:119], v[112:115], v[58:61]
	ds_read_b128 v[116:119], v207 offset:16960
	s_waitcnt lgkmcnt(0)
	v_mfma_f32_16x16x32_bf16 v[62:65], v[116:119], v[112:115], v[62:65]
	ds_read_b128 v[116:119], v207 offset:25408
	s_waitcnt lgkmcnt(0)
	v_mfma_f32_16x16x32_bf16 v[82:85], v[116:119], v[112:115], v[82:85]
	ds_read_b128 v[116:119], v207 offset:33856
	s_waitcnt lgkmcnt(0)
	v_mfma_f32_16x16x32_bf16 v[86:89], v[116:119], v[112:115], v[86:89]
	ds_read_b128 v[116:119], v207 offset:42304
	s_waitcnt lgkmcnt(0)
	v_mfma_f32_16x16x32_bf16 v[90:93], v[116:119], v[112:115], v[90:93]
	ds_read_b128 v[116:119], v207 offset:50752
	s_waitcnt lgkmcnt(0)
	v_mfma_f32_16x16x32_bf16 v[108:111], v[116:119], v[112:115], v[108:111]
	ds_read_b128 v[116:119], v207 offset:59200
	s_waitcnt lgkmcnt(0)
	v_mfma_f32_16x16x32_bf16 v[50:53], v[116:119], v[112:115], v[50:53]
	ds_read_b128 v[112:115], v208 offset:128
	ds_read_b128 v[116:119], v207 offset:128
	s_waitcnt lgkmcnt(0)
	v_mfma_f32_16x16x32_bf16 v[54:57], v[116:119], v[112:115], v[54:57]
	ds_read_b128 v[116:119], v207 offset:8576
	s_waitcnt lgkmcnt(0)
	v_mfma_f32_16x16x32_bf16 v[58:61], v[116:119], v[112:115], v[58:61]
	ds_read_b128 v[116:119], v207 offset:17024
	s_waitcnt lgkmcnt(0)
	v_mfma_f32_16x16x32_bf16 v[62:65], v[116:119], v[112:115], v[62:65]
	ds_read_b128 v[116:119], v207 offset:25472
	s_waitcnt lgkmcnt(0)
	v_mfma_f32_16x16x32_bf16 v[82:85], v[116:119], v[112:115], v[82:85]
	ds_read_b128 v[116:119], v207 offset:33920
	s_waitcnt lgkmcnt(0)
; __device__ __forceinline__ f32x4 mfma16(bf16x8 a, bf16x8 b, f32x4 c) { return __builtin_amdgcn_mfma_f32_16x16x32_bf16(a, b, c, 0, 0, 0); }
; __device__ __forceinline__ void ret_apply_unit(LAS unsigned char* lds, const bf16* P, const bf16* PREV, bf16* BR, const float* dec, int u, int tid) {
;     ...
; #pragma unroll
;     for (int ks = 0; ks < 8; ++ks) { const bf16x8 qf = ldrow(Qt, RSQ, 16 * w, 32 * ks, lane);
; #pragma unroll
;         for (int mt = 0; mt < 8; ++mt) { const bf16x8 kf = ldrow(Kt, RSQ, 16 * mt, 32 * ks, lane); s[mt] = mfma16(kf, qf, s[mt]); } }
	v_mfma_f32_16x16x32_bf16 v[86:89], v[116:119], v[112:115], v[86:89]
	ds_read_b128 v[116:119], v207 offset:42368
	s_waitcnt lgkmcnt(0)
	v_mfma_f32_16x16x32_bf16 v[90:93], v[116:119], v[112:115], v[90:93]
	ds_read_b128 v[116:119], v207 offset:50816
	s_waitcnt lgkmcnt(0)
	v_mfma_f32_16x16x32_bf16 v[108:111], v[116:119], v[112:115], v[108:111]
	ds_read_b128 v[116:119], v207 offset:59264
	s_waitcnt lgkmcnt(0)
	v_mfma_f32_16x16x32_bf16 v[50:53], v[116:119], v[112:115], v[50:53]
	ds_read_b128 v[112:115], v208 offset:192
	ds_read_b128 v[116:119], v207 offset:192
	s_waitcnt lgkmcnt(0)
	v_mfma_f32_16x16x32_bf16 v[54:57], v[116:119], v[112:115], v[54:57]
	ds_read_b128 v[116:119], v207 offset:8640
	s_waitcnt lgkmcnt(0)
	v_mfma_f32_16x16x32_bf16 v[58:61], v[116:119], v[112:115], v[58:61]
	ds_read_b128 v[116:119], v207 offset:17088
	s_waitcnt lgkmcnt(0)
	v_mfma_f32_16x16x32_bf16 v[62:65], v[116:119], v[112:115], v[62:65]
	ds_read_b128 v[116:119], v207 offset:25536
	s_waitcnt lgkmcnt(0)
	v_mfma_f32_16x16x32_bf16 v[82:85], v[116:119], v[112:115], v[82:85]
	ds_read_b128 v[116:119], v207 offset:33984
	s_waitcnt lgkmcnt(0)
	v_mfma_f32_16x16x32_bf16 v[86:89], v[116:119], v[112:115], v[86:89]
	ds_read_b128 v[116:119], v207 offset:42432
	s_waitcnt lgkmcnt(0)
	v_mfma_f32_16x16x32_bf16 v[90:93], v[116:119], v[112:115], v[90:93]
	ds_read_b128 v[116:119], v207 offset:50880
	s_waitcnt lgkmcnt(0)
	v_mfma_f32_16x16x32_bf16 v[108:111], v[116:119], v[112:115], v[108:111]
	ds_read_b128 v[116:119], v207 offset:59328
	s_waitcnt lgkmcnt(0)
	v_mfma_f32_16x16x32_bf16 v[50:53], v[116:119], v[112:115], v[50:53]
	ds_read_b128 v[112:115], v208 offset:256
	ds_read_b128 v[116:119], v207 offset:256
	s_waitcnt lgkmcnt(0)
	v_mfma_f32_16x16x32_bf16 v[54:57], v[116:119], v[112:115], v[54:57]
	ds_read_b128 v[116:119], v207 offset:8704
	s_waitcnt lgkmcnt(0)
	v_mfma_f32_16x16x32_bf16 v[58:61], v[116:119], v[112:115], v[58:61]
	ds_read_b128 v[116:119], v207 offset:17152
	s_waitcnt lgkmcnt(0)
	v_mfma_f32_16x16x32_bf16 v[62:65], v[116:119], v[112:115], v[62:65]
	ds_read_b128 v[116:119], v207 offset:25600
	s_waitcnt lgkmcnt(0)
	v_mfma_f32_16x16x32_bf16 v[82:85], v[116:119], v[112:115], v[82:85]
	ds_read_b128 v[116:119], v207 offset:34048
	s_waitcnt lgkmcnt(0)
	v_mfma_f32_16x16x32_bf16 v[86:89], v[116:119], v[112:115], v[86:89]
	ds_read_b128 v[116:119], v207 offset:42496
	s_waitcnt lgkmcnt(0)
	v_mfma_f32_16x16x32_bf16 v[90:93], v[116:119], v[112:115], v[90:93]
	ds_read_b128 v[116:119], v207 offset:50944
	s_waitcnt lgkmcnt(0)
	v_mfma_f32_16x16x32_bf16 v[108:111], v[116:119], v[112:115], v[108:111]
	ds_read_b128 v[116:119], v207 offset:59392
	s_waitcnt lgkmcnt(0)
	v_mfma_f32_16x16x32_bf16 v[50:53], v[116:119], v[112:115], v[50:53]
	ds_read_b128 v[112:115], v208 offset:320
	ds_read_b128 v[116:119], v207 offset:320
	s_waitcnt lgkmcnt(0)
	v_mfma_f32_16x16x32_bf16 v[54:57], v[116:119], v[112:115], v[54:57]
	ds_read_b128 v[116:119], v207 offset:8768
	s_waitcnt lgkmcnt(0)
	v_mfma_f32_16x16x32_bf16 v[58:61], v[116:119], v[112:115], v[58:61]
	ds_read_b128 v[116:119], v207 offset:17216
	s_waitcnt lgkmcnt(0)
	v_mfma_f32_16x16x32_bf16 v[62:65], v[116:119], v[112:115], v[62:65]
	ds_read_b128 v[116:119], v207 offset:25664
	s_waitcnt lgkmcnt(0)
	v_mfma_f32_16x16x32_bf16 v[82:85], v[116:119], v[112:115], v[82:85]
	ds_read_b128 v[116:119], v207 offset:34112
	s_waitcnt lgkmcnt(0)
	v_mfma_f32_16x16x32_bf16 v[86:89], v[116:119], v[112:115], v[86:89]
	ds_read_b128 v[116:119], v207 offset:42560
	s_waitcnt lgkmcnt(0)
	v_mfma_f32_16x16x32_bf16 v[90:93], v[116:119], v[112:115], v[90:93]
	ds_read_b128 v[116:119], v207 offset:51008
	s_waitcnt lgkmcnt(0)
	v_mfma_f32_16x16x32_bf16 v[108:111], v[116:119], v[112:115], v[108:111]
	ds_read_b128 v[116:119], v207 offset:59456
	s_waitcnt lgkmcnt(0)
	v_mfma_f32_16x16x32_bf16 v[50:53], v[116:119], v[112:115], v[50:53]
	ds_read_b128 v[112:115], v208 offset:384
	ds_read_b128 v[116:119], v207 offset:384
	s_waitcnt lgkmcnt(0)
	v_mfma_f32_16x16x32_bf16 v[54:57], v[116:119], v[112:115], v[54:57]
	ds_read_b128 v[116:119], v207 offset:8832
	s_waitcnt lgkmcnt(0)
	v_mfma_f32_16x16x32_bf16 v[58:61], v[116:119], v[112:115], v[58:61]
	ds_read_b128 v[116:119], v207 offset:17280
	s_waitcnt lgkmcnt(0)
	v_mfma_f32_16x16x32_bf16 v[62:65], v[116:119], v[112:115], v[62:65]
	ds_read_b128 v[116:119], v207 offset:25728
	s_waitcnt lgkmcnt(0)
	v_mfma_f32_16x16x32_bf16 v[82:85], v[116:119], v[112:115], v[82:85]
	ds_read_b128 v[116:119], v207 offset:34176
	s_waitcnt lgkmcnt(0)
	v_mfma_f32_16x16x32_bf16 v[116:119], v[116:119], v[112:115], v[86:89]
	s_nop 2
	ds_read_b128 v[86:89], v207 offset:42624
	s_waitcnt lgkmcnt(0)
	v_mfma_f32_16x16x32_bf16 v[120:123], v[86:89], v[112:115], v[90:93]
	ds_read_b128 v[86:89], v207 offset:51072
	s_waitcnt lgkmcnt(0)
	v_mfma_f32_16x16x32_bf16 v[108:111], v[86:89], v[112:115], v[108:111]
	ds_read_b128 v[86:89], v207 offset:59520
	s_waitcnt lgkmcnt(0)
	v_mfma_f32_16x16x32_bf16 v[50:53], v[86:89], v[112:115], v[50:53]
	ds_read_b128 v[112:115], v208 offset:448
	ds_read_b128 v[86:89], v207 offset:448
	s_waitcnt lgkmcnt(0)
	v_mfma_f32_16x16x32_bf16 v[124:127], v[86:89], v[112:115], v[54:57]
	s_nop 2
	ds_read_b128 v[54:57], v207 offset:8896
	s_waitcnt lgkmcnt(0)
	v_mfma_f32_16x16x32_bf16 v[90:93], v[54:57], v[112:115], v[58:61]
	ds_read_b128 v[54:57], v207 offset:17344
	s_waitcnt lgkmcnt(0)
	v_mfma_f32_16x16x32_bf16 v[86:89], v[54:57], v[112:115], v[62:65]
	ds_read_b128 v[54:57], v207 offset:25792
	s_waitcnt lgkmcnt(0)
	v_mfma_f32_16x16x32_bf16 v[82:85], v[54:57], v[112:115], v[82:85]
	ds_read_b128 v[54:57], v207 offset:34240
	s_waitcnt lgkmcnt(0)
	v_mfma_f32_16x16x32_bf16 v[62:65], v[54:57], v[112:115], v[116:119]
	ds_read_b128 v[54:57], v207 offset:42688
	s_waitcnt lgkmcnt(0)
	v_mfma_f32_16x16x32_bf16 v[58:61], v[54:57], v[112:115], v[120:123]
	ds_read_b128 v[54:57], v207 offset:51136
	s_waitcnt lgkmcnt(0)
	v_mfma_f32_16x16x32_bf16 v[54:57], v[54:57], v[112:115], v[108:111]
	s_nop 2
	ds_read_b128 v[108:111], v207 offset:59584
	s_waitcnt lgkmcnt(0)
	s_barrier
; #define LAS __attribute__((address_space(3)))
; __device__ __forceinline__ unsigned pk2(float lo, float hi) { return pg8::cvt_pk_bf16(lo, hi); }
; __device__ __forceinline__ void ret_apply_unit(LAS unsigned char* lds, const bf16* P, const bf16* PREV, bf16* BR, const float* dec, int u, int tid) {
;     ...
;     const int a = 16 * w + i;
; #pragma unroll
;     for (int mt = 0; mt < 8; ++mt) { float p[4];
; #pragma unroll
;         for (int r = 0; r < 4; ++r) { const int b = 16 * mt + 4 * g + r, df = a - b; const float D = __builtin_amdgcn_exp2f(df >= 0 ? (float)df * lgf2 : (float)(-df) * lgb2); p[r] = s[mt][r] * D; }
;         u32x2 wv; wv.x = pk2(p[0], p[1]); wv.y = pk2(p[2], p[3]);
;         *(LAS u32x2*)(Pl + a * RSP + (16 * mt + 4 * g) * 2) = wv; }
	v_mfma_f32_16x16x32_bf16 v[50:53], v[108:111], v[112:115], v[50:53]
	v_sub_u32_e32 v108, v162, v107
	v_sub_u32_e32 v109, 0, v108
	v_max_i32_e32 v109, v108, v109
	v_cvt_f32_u32_e32 v109, v109
	v_cmp_gt_i32_e32 vcc, 0, v108
	s_nop 1
	v_cndmask_b32_e32 v108, v216, v217, vcc
	v_mul_f32_e32 v108, v108, v109
	v_xad_u32 v109, v107, -1, v162
	v_sub_u32_e32 v110, 0, v109
	v_max_i32_e32 v110, v109, v110
	v_cvt_f32_u32_e32 v110, v110
	v_cmp_gt_i32_e32 vcc, 0, v109
	v_exp_f32_e32 v108, v108
	s_nop 0
	v_cndmask_b32_e32 v109, v216, v217, vcc
	v_mul_f32_e32 v109, v109, v110
	v_or_b32_e32 v110, 2, v107
	v_sub_u32_e32 v110, v162, v110
	v_sub_u32_e32 v111, 0, v110
	v_max_i32_e32 v111, v110, v111
	v_cvt_f32_u32_e32 v111, v111
	v_cmp_gt_i32_e32 vcc, 0, v110
	v_exp_f32_e32 v109, v109
	s_nop 0
	v_cndmask_b32_e32 v110, v216, v217, vcc
	v_mul_f32_e32 v110, v110, v111
	v_or_b32_e32 v111, 3, v107
	v_sub_u32_e32 v111, v162, v111
	v_sub_u32_e32 v112, 0, v111
	v_max_i32_e32 v112, v111, v112
	v_cvt_f32_u32_e32 v112, v112
	v_cmp_gt_i32_e32 vcc, 0, v111
	v_exp_f32_e32 v110, v110
	v_pk_mul_f32 v[108:109], v[108:109], v[124:125]
	v_cndmask_b32_e32 v111, v216, v217, vcc
	v_mul_f32_e32 v111, v111, v112
	v_exp_f32_e32 v111, v111
	v_cvt_pk_bf16_f32 v108, v108, v109
	v_pk_mul_f32 v[110:111], v[110:111], v[126:127]
	s_nop 0
	v_cvt_pk_bf16_f32 v109, v110, v111
	v_or_b32_e32 v110, 16, v107
	v_sub_u32_e32 v110, v162, v110
	v_sub_u32_e32 v111, 0, v110
	v_max_i32_e32 v111, v110, v111
	v_cvt_f32_u32_e32 v111, v111
	v_cmp_gt_i32_e32 vcc, 0, v110
	s_nop 1
	v_cndmask_b32_e32 v110, v216, v217, vcc
	v_mul_f32_e32 v110, v110, v111
	v_or_b32_e32 v111, 17, v107
	v_sub_u32_e32 v111, v162, v111
	v_sub_u32_e32 v112, 0, v111
	v_max_i32_e32 v112, v111, v112
	v_cvt_f32_u32_e32 v112, v112
	v_cmp_gt_i32_e32 vcc, 0, v111
	v_exp_f32_e32 v110, v110
	s_nop 0
	v_cndmask_b32_e32 v111, v216, v217, vcc
	v_mul_f32_e32 v111, v111, v112
	v_exp_f32_e32 v111, v111
	s_nop 0
	v_pk_mul_f32 v[90:91], v[110:111], v[90:91]
	v_or_b32_e32 v110, 18, v107
	v_sub_u32_e32 v110, v162, v110
	v_sub_u32_e32 v111, 0, v110
	v_max_i32_e32 v111, v110, v111
	v_cvt_f32_u32_e32 v111, v111
	v_cmp_gt_i32_e32 vcc, 0, v110
	v_cvt_pk_bf16_f32 v90, v90, v91
	s_nop 0
	v_cndmask_b32_e32 v110, v216, v217, vcc
	v_mul_f32_e32 v110, v110, v111
	v_or_b32_e32 v111, 19, v107
	v_sub_u32_e32 v111, v162, v111
	v_sub_u32_e32 v112, 0, v111
	v_max_i32_e32 v112, v111, v112
	v_cvt_f32_u32_e32 v112, v112
	v_cmp_gt_i32_e32 vcc, 0, v111
	v_exp_f32_e32 v110, v110
	s_nop 0
	v_cndmask_b32_e32 v111, v216, v217, vcc
	v_mul_f32_e32 v111, v111, v112
	v_exp_f32_e32 v111, v111
	s_nop 0
	v_pk_mul_f32 v[92:93], v[110:111], v[92:93]
	s_nop 0
	v_cvt_pk_bf16_f32 v91, v92, v93
	ds_write2_b64 v106, v[108:109], v[90:91] offset1:4
	v_or_b32_e32 v90, 32, v107
	v_sub_u32_e32 v90, v162, v90
	v_sub_u32_e32 v91, 0, v90
	v_max_i32_e32 v91, v90, v91
	v_cvt_f32_u32_e32 v91, v91
	v_cmp_gt_i32_e32 vcc, 0, v90
	s_nop 1
	v_cndmask_b32_e32 v90, v216, v217, vcc
	v_mul_f32_e32 v90, v90, v91
	v_or_b32_e32 v91, 33, v107
	v_sub_u32_e32 v91, v162, v91
	v_sub_u32_e32 v92, 0, v91
	v_max_i32_e32 v92, v91, v92
	v_cvt_f32_u32_e32 v92, v92
	v_cmp_gt_i32_e32 vcc, 0, v91
	v_exp_f32_e32 v90, v90
	s_nop 0
	v_cndmask_b32_e32 v91, v216, v217, vcc
	v_mul_f32_e32 v91, v91, v92
	v_exp_f32_e32 v91, v91
	s_nop 0
	v_pk_mul_f32 v[86:87], v[90:91], v[86:87]
	v_or_b32_e32 v90, 34, v107
	v_sub_u32_e32 v90, v162, v90
	v_sub_u32_e32 v91, 0, v90
	v_max_i32_e32 v91, v90, v91
	v_cvt_f32_u32_e32 v91, v91
	v_cmp_gt_i32_e32 vcc, 0, v90
	v_cvt_pk_bf16_f32 v86, v86, v87
	s_nop 0
	v_cndmask_b32_e32 v90, v216, v217, vcc
	v_mul_f32_e32 v90, v90, v91
	v_or_b32_e32 v91, 35, v107
	v_sub_u32_e32 v91, v162, v91
	v_sub_u32_e32 v92, 0, v91
	v_max_i32_e32 v92, v91, v92
	v_cvt_f32_u32_e32 v92, v92
	v_cmp_gt_i32_e32 vcc, 0, v91
	v_exp_f32_e32 v90, v90
	s_nop 0
	v_cndmask_b32_e32 v91, v216, v217, vcc
	v_mul_f32_e32 v91, v91, v92
	v_exp_f32_e32 v91, v91
	s_nop 0
	v_pk_mul_f32 v[88:89], v[90:91], v[88:89]
	s_nop 0
	v_cvt_pk_bf16_f32 v87, v88, v89
	v_or_b32_e32 v88, 48, v107
	v_sub_u32_e32 v88, v162, v88
	v_sub_u32_e32 v89, 0, v88
	v_max_i32_e32 v89, v88, v89
	v_cvt_f32_u32_e32 v89, v89
	v_cmp_gt_i32_e32 vcc, 0, v88
	s_nop 1
	v_cndmask_b32_e32 v88, v216, v217, vcc
	v_mul_f32_e32 v88, v88, v89
	v_or_b32_e32 v89, 49, v107
	v_sub_u32_e32 v89, v162, v89
	v_sub_u32_e32 v90, 0, v89
	v_max_i32_e32 v90, v89, v90
	v_cvt_f32_u32_e32 v90, v90
	v_cmp_gt_i32_e32 vcc, 0, v89
	v_exp_f32_e32 v88, v88
	s_nop 0
	v_cndmask_b32_e32 v89, v216, v217, vcc
	v_mul_f32_e32 v89, v89, v90
	v_exp_f32_e32 v89, v89
	s_nop 0
	v_pk_mul_f32 v[82:83], v[88:89], v[82:83]
	v_or_b32_e32 v88, 50, v107
	v_sub_u32_e32 v88, v162, v88
	v_sub_u32_e32 v89, 0, v88
	v_max_i32_e32 v89, v88, v89
	v_cvt_f32_u32_e32 v89, v89
	v_cmp_gt_i32_e32 vcc, 0, v88
	v_cvt_pk_bf16_f32 v82, v82, v83
	s_nop 0
	v_cndmask_b32_e32 v88, v216, v217, vcc
	v_mul_f32_e32 v88, v88, v89
	v_or_b32_e32 v89, 51, v107
	v_sub_u32_e32 v89, v162, v89
	v_sub_u32_e32 v90, 0, v89
	v_max_i32_e32 v90, v89, v90
	v_cvt_f32_u32_e32 v90, v90
	v_cmp_gt_i32_e32 vcc, 0, v89
	v_exp_f32_e32 v88, v88
	s_nop 0
	v_cndmask_b32_e32 v89, v216, v217, vcc
	v_mul_f32_e32 v89, v89, v90
	v_exp_f32_e32 v89, v89
	s_nop 0
	v_pk_mul_f32 v[84:85], v[88:89], v[84:85]
	s_nop 0
	v_cvt_pk_bf16_f32 v83, v84, v85
	ds_write2_b64 v106, v[86:87], v[82:83] offset0:8 offset1:12
	v_or_b32_e32 v82, 64, v107
	v_sub_u32_e32 v82, v162, v82
	v_sub_u32_e32 v83, 0, v82
	v_max_i32_e32 v83, v82, v83
	v_cvt_f32_u32_e32 v83, v83
	v_cmp_gt_i32_e32 vcc, 0, v82
	s_nop 1
	v_cndmask_b32_e32 v82, v216, v217, vcc
	v_mul_f32_e32 v82, v82, v83
	v_or_b32_e32 v83, 0x41, v107
; #define LAS __attribute__((address_space(3)))
; __device__ __forceinline__ unsigned pk2(float lo, float hi) { return pg8::cvt_pk_bf16(lo, hi); }
; __device__ __forceinline__ void ret_apply_unit(LAS unsigned char* lds, const bf16* P, const bf16* PREV, bf16* BR, const float* dec, int u, int tid) {
;     ...
;     const int a = 16 * w + i;
; #pragma unroll
;     for (int mt = 0; mt < 8; ++mt) { float p[4];
; #pragma unroll
;         for (int r = 0; r < 4; ++r) { const int b = 16 * mt + 4 * g + r, df = a - b; const float D = __builtin_amdgcn_exp2f(df >= 0 ? (float)df * lgf2 : (float)(-df) * lgb2); p[r] = s[mt][r] * D; }
;         u32x2 wv; wv.x = pk2(p[0], p[1]); wv.y = pk2(p[2], p[3]);
;         *(LAS u32x2*)(Pl + a * RSP + (16 * mt + 4 * g) * 2) = wv; }
;     f32x4 acc[16];
; #pragma unroll
;     for (int mt = 0; mt < 16; ++mt) acc[mt] = (f32x4){0.f, 0.f, 0.f, 0.f};
; #pragma unroll
;     for (int eh = 0; eh < 2; ++eh) {
;         if (eh == 0) tile_store<128, 16>(Vh, RSP, v0, tid); else tile_store<128, 16>(Vh, RSP, v1, tid);
	v_sub_u32_e32 v83, v162, v83
	v_sub_u32_e32 v84, 0, v83
	v_max_i32_e32 v84, v83, v84
	v_cvt_f32_u32_e32 v84, v84
	v_cmp_gt_i32_e32 vcc, 0, v83
	v_exp_f32_e32 v82, v82
	s_nop 0
	v_cndmask_b32_e32 v83, v216, v217, vcc
	v_mul_f32_e32 v83, v83, v84
	v_exp_f32_e32 v83, v83
	s_nop 0
	v_pk_mul_f32 v[62:63], v[82:83], v[62:63]
	v_or_b32_e32 v82, 0x42, v107
	v_sub_u32_e32 v82, v162, v82
	v_sub_u32_e32 v83, 0, v82
	v_max_i32_e32 v83, v82, v83
	v_cvt_f32_u32_e32 v83, v83
	v_cmp_gt_i32_e32 vcc, 0, v82
	v_cvt_pk_bf16_f32 v62, v62, v63
	s_nop 0
	v_cndmask_b32_e32 v82, v216, v217, vcc
	v_mul_f32_e32 v82, v82, v83
	v_or_b32_e32 v83, 0x43, v107
	v_sub_u32_e32 v83, v162, v83
	v_sub_u32_e32 v84, 0, v83
	v_max_i32_e32 v84, v83, v84
	v_cvt_f32_u32_e32 v84, v84
	v_cmp_gt_i32_e32 vcc, 0, v83
	v_exp_f32_e32 v82, v82
	s_nop 0
	v_cndmask_b32_e32 v83, v216, v217, vcc
	v_mul_f32_e32 v83, v83, v84
	v_exp_f32_e32 v83, v83
	s_nop 0
	v_pk_mul_f32 v[64:65], v[82:83], v[64:65]
	s_nop 0
	v_cvt_pk_bf16_f32 v63, v64, v65
	v_or_b32_e32 v64, 0x50, v107
	v_sub_u32_e32 v64, v162, v64
	v_sub_u32_e32 v65, 0, v64
	v_max_i32_e32 v65, v64, v65
	v_cvt_f32_u32_e32 v65, v65
	v_cmp_gt_i32_e32 vcc, 0, v64
	s_nop 1
	v_cndmask_b32_e32 v64, v216, v217, vcc
	v_mul_f32_e32 v64, v64, v65
	v_or_b32_e32 v65, 0x51, v107
	v_sub_u32_e32 v65, v162, v65
	v_sub_u32_e32 v82, 0, v65
	v_max_i32_e32 v82, v65, v82
	v_cvt_f32_u32_e32 v82, v82
	v_cmp_gt_i32_e32 vcc, 0, v65
	v_exp_f32_e32 v64, v64
	s_nop 0
	v_cndmask_b32_e32 v65, v216, v217, vcc
	v_mul_f32_e32 v65, v65, v82
	v_exp_f32_e32 v65, v65
	s_nop 0
	v_pk_mul_f32 v[58:59], v[64:65], v[58:59]
	v_or_b32_e32 v64, 0x52, v107
	v_sub_u32_e32 v64, v162, v64
	v_sub_u32_e32 v65, 0, v64
	v_max_i32_e32 v65, v64, v65
	v_cvt_f32_u32_e32 v65, v65
	v_cmp_gt_i32_e32 vcc, 0, v64
	v_cvt_pk_bf16_f32 v58, v58, v59
	s_nop 0
	v_cndmask_b32_e32 v64, v216, v217, vcc
	v_mul_f32_e32 v64, v64, v65
	v_or_b32_e32 v65, 0x53, v107
	v_sub_u32_e32 v65, v162, v65
	v_sub_u32_e32 v82, 0, v65
	v_max_i32_e32 v82, v65, v82
	v_cvt_f32_u32_e32 v82, v82
	v_cmp_gt_i32_e32 vcc, 0, v65
	v_exp_f32_e32 v64, v64
	s_nop 0
	v_cndmask_b32_e32 v65, v216, v217, vcc
	v_mul_f32_e32 v65, v65, v82
	v_exp_f32_e32 v65, v65
	v_add_u32_e32 v82, v105, v104
	v_pk_mul_f32 v[60:61], v[64:65], v[60:61]
	s_nop 0
	v_cvt_pk_bf16_f32 v59, v60, v61
	ds_write2_b64 v106, v[62:63], v[58:59] offset0:16 offset1:20
	v_or_b32_e32 v58, 0x60, v107
	v_sub_u32_e32 v58, v162, v58
	v_sub_u32_e32 v59, 0, v58
	v_max_i32_e32 v59, v58, v59
	v_cvt_f32_u32_e32 v59, v59
	v_cmp_gt_i32_e32 vcc, 0, v58
	s_nop 1
	v_cndmask_b32_e32 v58, v216, v217, vcc
	v_mul_f32_e32 v58, v58, v59
	v_or_b32_e32 v59, 0x61, v107
	v_sub_u32_e32 v59, v162, v59
	v_sub_u32_e32 v60, 0, v59
	v_max_i32_e32 v60, v59, v60
	v_cvt_f32_u32_e32 v60, v60
	v_cmp_gt_i32_e32 vcc, 0, v59
	v_exp_f32_e32 v58, v58
	s_nop 0
	v_cndmask_b32_e32 v59, v216, v217, vcc
	v_mul_f32_e32 v59, v59, v60
	v_exp_f32_e32 v59, v59
	s_nop 0
	v_pk_mul_f32 v[54:55], v[58:59], v[54:55]
	v_or_b32_e32 v58, 0x62, v107
	v_sub_u32_e32 v58, v162, v58
	v_sub_u32_e32 v59, 0, v58
	v_max_i32_e32 v59, v58, v59
	v_cvt_f32_u32_e32 v59, v59
	v_cmp_gt_i32_e32 vcc, 0, v58
	v_cvt_pk_bf16_f32 v54, v54, v55
	s_nop 0
	v_cndmask_b32_e32 v58, v216, v217, vcc
	v_mul_f32_e32 v58, v58, v59
	v_or_b32_e32 v59, 0x63, v107
	v_sub_u32_e32 v59, v162, v59
	v_sub_u32_e32 v60, 0, v59
	v_max_i32_e32 v60, v59, v60
	v_cvt_f32_u32_e32 v60, v60
	v_cmp_gt_i32_e32 vcc, 0, v59
	v_exp_f32_e32 v58, v58
	s_nop 0
	v_cndmask_b32_e32 v59, v216, v217, vcc
	v_mul_f32_e32 v59, v59, v60
	v_exp_f32_e32 v59, v59
	s_nop 0
	v_pk_mul_f32 v[56:57], v[58:59], v[56:57]
	s_nop 0
	v_cvt_pk_bf16_f32 v55, v56, v57
	v_or_b32_e32 v56, 0x70, v107
	v_sub_u32_e32 v56, v162, v56
	v_sub_u32_e32 v57, 0, v56
	v_max_i32_e32 v57, v56, v57
	v_cvt_f32_u32_e32 v57, v57
	v_cmp_gt_i32_e32 vcc, 0, v56
	s_nop 1
	v_cndmask_b32_e32 v56, v216, v217, vcc
	v_mul_f32_e32 v56, v56, v57
	v_or_b32_e32 v57, 0x71, v107
	v_sub_u32_e32 v57, v162, v57
	v_sub_u32_e32 v58, 0, v57
	v_max_i32_e32 v58, v57, v58
	v_cvt_f32_u32_e32 v58, v58
	v_cmp_gt_i32_e32 vcc, 0, v57
	v_exp_f32_e32 v56, v56
	s_nop 0
	v_cndmask_b32_e32 v57, v216, v217, vcc
	v_mul_f32_e32 v57, v57, v58
	v_exp_f32_e32 v57, v57
	s_nop 0
	v_pk_mul_f32 v[50:51], v[56:57], v[50:51]
	v_or_b32_e32 v56, 0x72, v107
	v_sub_u32_e32 v56, v162, v56
	v_sub_u32_e32 v57, 0, v56
	v_max_i32_e32 v57, v56, v57
	v_cvt_f32_u32_e32 v57, v57
	v_cmp_gt_i32_e32 vcc, 0, v56
	v_cvt_pk_bf16_f32 v50, v50, v51
	s_nop 0
	v_cndmask_b32_e32 v56, v216, v217, vcc
	v_mul_f32_e32 v56, v56, v57
	v_or_b32_e32 v57, 0x73, v107
	v_sub_u32_e32 v57, v162, v57
	v_sub_u32_e32 v58, 0, v57
	v_max_i32_e32 v58, v57, v58
	v_cvt_f32_u32_e32 v58, v58
	v_cmp_gt_i32_e32 vcc, 0, v57
	v_exp_f32_e32 v56, v56
	s_nop 0
	v_cndmask_b32_e32 v57, v216, v217, vcc
	v_mul_f32_e32 v57, v57, v58
	v_exp_f32_e32 v57, v57
	s_nop 0
	v_pk_mul_f32 v[52:53], v[56:57], v[52:53]
	s_nop 0
	v_cvt_pk_bf16_f32 v51, v52, v53
	v_lshlrev_b32_e32 v53, 8, v96
	v_mul_lo_u32 v52, v96, s56
	v_sub_u32_e32 v53, v100, v53
	v_add3_u32 v83, s95, v52, v53
	v_lshlrev_b32_e32 v53, 8, v97
	v_mul_lo_u32 v52, v97, s56
	v_sub_u32_e32 v53, v101, v53
	v_add3_u32 v84, s95, v52, v53
	v_lshlrev_b32_e32 v53, 8, v98
	v_mul_lo_u32 v52, v98, s56
	v_sub_u32_e32 v53, v102, v53
	ds_write2_b64 v106, v[54:55], v[50:51] offset0:24 offset1:28
	v_bfe_u32 v50, v94, 2, 2
	v_lshrrev_b32_e32 v51, 1, v94
	v_add3_u32 v85, s95, v52, v53
	v_lshlrev_b32_e32 v53, 8, v99
	v_and_or_b32 v50, v51, 24, v50
	v_mul_lo_u32 v52, v99, s56
	v_sub_u32_e32 v53, v103, v53
	v_and_b32_e32 v51, 24, v95
	v_add3_u32 v86, s95, v52, v53
	ds_write_b128 v83, v[2:5]
	ds_write_b128 v84, v[10:13]
	ds_write_b128 v85, v[22:25]
	ds_write_b128 v86, v[38:41]
	v_mul_u32_u24_e32 v10, 0x110, v50
	v_add3_u32 v94, s95, v51, v10
	s_waitcnt lgkmcnt(0)
	s_barrier
; __device__ __forceinline__ f32x4 mfma16(bf16x8 a, bf16x8 b, f32x4 c) { return __builtin_amdgcn_mfma_f32_16x16x32_bf16(a, b, c, 0, 0, 0); }
; __device__ __forceinline__ void ret_apply_unit(LAS unsigned char* lds, const bf16* P, const bf16* PREV, bf16* BR, const float* dec, int u, int tid) {
;     ...
;     for (int eh = 0; eh < 2; ++eh) {
;         if (eh == 0) tile_store<128, 16>(Vh, RSP, v0, tid); else tile_store<128, 16>(Vh, RSP, v1, tid);
;         __syncthreads();
; #pragma unroll
;         for (int ks = 0; ks < 4; ++ks) { const bf16x8 pf = ldrow(Pl, RSP, 16 * w, 32 * ks, lane);
; #pragma unroll
;             for (int mt = 0; mt < 8; ++mt) { const bf16x8 vf = ldtr(Vh, RSP, 32 * ks, 16 * mt, lane); acc[8 * eh + mt] = mfma16(vf, pf, acc[8 * eh + mt]); } }
	ds_read_b128 v[2:5], v82
	ds_read_b64_tr_b16 v[12:13], v94 offset:1088
	ds_read_b64_tr_b16 v[10:11], v94
	ds_read_b64_tr_b16 v[22:23], v94 offset:32
	ds_read_b64_tr_b16 v[24:25], v94 offset:1120
	ds_read_b64_tr_b16 v[38:39], v94 offset:64
	ds_read_b64_tr_b16 v[40:41], v94 offset:1152
	ds_read_b64_tr_b16 v[50:51], v94 offset:96
	ds_read_b64_tr_b16 v[52:53], v94 offset:1184
	ds_read_b64_tr_b16 v[54:55], v94 offset:128
	ds_read_b64_tr_b16 v[56:57], v94 offset:1216
	ds_read_b64_tr_b16 v[58:59], v94 offset:160
	ds_read_b64_tr_b16 v[60:61], v94 offset:1248
	ds_read_b64_tr_b16 v[62:63], v94 offset:192
	ds_read_b64_tr_b16 v[64:65], v94 offset:1280
	ds_read_b64_tr_b16 v[88:89], v94 offset:224
	ds_read_b64_tr_b16 v[90:91], v94 offset:1312
	s_waitcnt lgkmcnt(14)
	v_mfma_f32_16x16x32_bf16 v[10:13], v[10:13], v[2:5], 0
	s_waitcnt lgkmcnt(12)
	v_mfma_f32_16x16x32_bf16 v[22:25], v[22:25], v[2:5], 0
	s_waitcnt lgkmcnt(10)
	v_mfma_f32_16x16x32_bf16 v[38:41], v[38:41], v[2:5], 0
	s_waitcnt lgkmcnt(8)
	v_mfma_f32_16x16x32_bf16 v[50:53], v[50:53], v[2:5], 0
	s_waitcnt lgkmcnt(6)
	v_mfma_f32_16x16x32_bf16 v[54:57], v[54:57], v[2:5], 0
	s_waitcnt lgkmcnt(4)
	v_mfma_f32_16x16x32_bf16 v[58:61], v[58:61], v[2:5], 0
	s_waitcnt lgkmcnt(2)
	v_mfma_f32_16x16x32_bf16 v[62:65], v[62:65], v[2:5], 0
	s_waitcnt lgkmcnt(0)
	v_mfma_f32_16x16x32_bf16 v[2:5], v[88:91], v[2:5], 0
	ds_read_b128 v[88:91], v82 offset:64
	ds_read_b64_tr_b16 v[96:97], v94 offset:8704
	ds_read_b64_tr_b16 v[98:99], v94 offset:9792
	s_waitcnt lgkmcnt(0)
	v_mfma_f32_16x16x32_bf16 v[10:13], v[96:99], v[88:91], v[10:13]
	ds_read_b64_tr_b16 v[96:97], v94 offset:8736
	ds_read_b64_tr_b16 v[98:99], v94 offset:9824
	s_waitcnt lgkmcnt(0)
	v_mfma_f32_16x16x32_bf16 v[22:25], v[96:99], v[88:91], v[22:25]
	ds_read_b64_tr_b16 v[96:97], v94 offset:8768
	ds_read_b64_tr_b16 v[98:99], v94 offset:9856
	s_waitcnt lgkmcnt(0)
	v_mfma_f32_16x16x32_bf16 v[38:41], v[96:99], v[88:91], v[38:41]
	ds_read_b64_tr_b16 v[96:97], v94 offset:8800
	ds_read_b64_tr_b16 v[98:99], v94 offset:9888
	s_waitcnt lgkmcnt(0)
	v_mfma_f32_16x16x32_bf16 v[50:53], v[96:99], v[88:91], v[50:53]
	ds_read_b64_tr_b16 v[96:97], v94 offset:8832
	ds_read_b64_tr_b16 v[98:99], v94 offset:9920
	s_waitcnt lgkmcnt(0)
	v_mfma_f32_16x16x32_bf16 v[54:57], v[96:99], v[88:91], v[54:57]
	ds_read_b64_tr_b16 v[96:97], v94 offset:8864
	ds_read_b64_tr_b16 v[98:99], v94 offset:9952
	s_waitcnt lgkmcnt(0)
	v_mfma_f32_16x16x32_bf16 v[58:61], v[96:99], v[88:91], v[58:61]
	ds_read_b64_tr_b16 v[96:97], v94 offset:8896
	ds_read_b64_tr_b16 v[98:99], v94 offset:9984
	s_waitcnt lgkmcnt(0)
	v_mfma_f32_16x16x32_bf16 v[62:65], v[96:99], v[88:91], v[62:65]
	ds_read_b64_tr_b16 v[96:97], v94 offset:8928
	ds_read_b64_tr_b16 v[98:99], v94 offset:10016
	s_waitcnt lgkmcnt(0)
	v_mfma_f32_16x16x32_bf16 v[2:5], v[96:99], v[88:91], v[2:5]
	ds_read_b128 v[88:91], v82 offset:128
	ds_read_b64_tr_b16 v[96:97], v94 offset:17408
	ds_read_b64_tr_b16 v[98:99], v94 offset:18496
	s_waitcnt lgkmcnt(0)
	v_mfma_f32_16x16x32_bf16 v[10:13], v[96:99], v[88:91], v[10:13]
	ds_read_b64_tr_b16 v[96:97], v94 offset:17440
	ds_read_b64_tr_b16 v[98:99], v94 offset:18528
	s_waitcnt lgkmcnt(0)
	v_mfma_f32_16x16x32_bf16 v[22:25], v[96:99], v[88:91], v[22:25]
	ds_read_b64_tr_b16 v[96:97], v94 offset:17472
	ds_read_b64_tr_b16 v[98:99], v94 offset:18560
	s_waitcnt lgkmcnt(0)
	v_mfma_f32_16x16x32_bf16 v[38:41], v[96:99], v[88:91], v[38:41]
	ds_read_b64_tr_b16 v[96:97], v94 offset:17504
	ds_read_b64_tr_b16 v[98:99], v94 offset:18592
	s_waitcnt lgkmcnt(0)
	v_mfma_f32_16x16x32_bf16 v[50:53], v[96:99], v[88:91], v[50:53]
	ds_read_b64_tr_b16 v[96:97], v94 offset:17536
	ds_read_b64_tr_b16 v[98:99], v94 offset:18624
	s_waitcnt lgkmcnt(0)
	v_mfma_f32_16x16x32_bf16 v[54:57], v[96:99], v[88:91], v[54:57]
	ds_read_b64_tr_b16 v[96:97], v94 offset:17568
	ds_read_b64_tr_b16 v[98:99], v94 offset:18656
	s_waitcnt lgkmcnt(0)
	v_mfma_f32_16x16x32_bf16 v[58:61], v[96:99], v[88:91], v[58:61]
	ds_read_b64_tr_b16 v[96:97], v94 offset:17600
	ds_read_b64_tr_b16 v[98:99], v94 offset:18688
	s_waitcnt lgkmcnt(0)
	v_mfma_f32_16x16x32_bf16 v[62:65], v[96:99], v[88:91], v[62:65]
	ds_read_b64_tr_b16 v[96:97], v94 offset:17632
	ds_read_b64_tr_b16 v[98:99], v94 offset:18720
	s_waitcnt lgkmcnt(0)
	v_mfma_f32_16x16x32_bf16 v[88:91], v[96:99], v[88:91], v[2:5]
	ds_read_b128 v[96:99], v82 offset:192
	s_nop 1
	ds_read_b64_tr_b16 v[2:3], v94 offset:26112
	ds_read_b64_tr_b16 v[4:5], v94 offset:27200
	s_waitcnt lgkmcnt(0)
	v_mfma_f32_16x16x32_bf16 v[2:5], v[2:5], v[96:99], v[10:13]
	s_nop 2
	ds_read_b64_tr_b16 v[10:11], v94 offset:26144
	ds_read_b64_tr_b16 v[12:13], v94 offset:27232
	s_waitcnt lgkmcnt(0)
	v_mfma_f32_16x16x32_bf16 v[10:13], v[10:13], v[96:99], v[22:25]
	s_nop 2
	ds_read_b64_tr_b16 v[22:23], v94 offset:26176
	ds_read_b64_tr_b16 v[24:25], v94 offset:27264
	s_waitcnt lgkmcnt(0)
	v_mfma_f32_16x16x32_bf16 v[22:25], v[22:25], v[96:99], v[38:41]
	s_nop 2
	ds_read_b64_tr_b16 v[38:39], v94 offset:26208
	ds_read_b64_tr_b16 v[40:41], v94 offset:27296
	s_waitcnt lgkmcnt(0)
	v_mfma_f32_16x16x32_bf16 v[38:41], v[38:41], v[96:99], v[50:53]
	s_nop 2
	ds_read_b64_tr_b16 v[50:51], v94 offset:26240
	ds_read_b64_tr_b16 v[52:53], v94 offset:27328
	s_waitcnt lgkmcnt(0)
	v_mfma_f32_16x16x32_bf16 v[50:53], v[50:53], v[96:99], v[54:57]
	s_nop 2
	ds_read_b64_tr_b16 v[54:55], v94 offset:26272
	ds_read_b64_tr_b16 v[56:57], v94 offset:27360
	s_waitcnt lgkmcnt(0)
	v_mfma_f32_16x16x32_bf16 v[54:57], v[54:57], v[96:99], v[58:61]
	s_nop 2
	ds_read_b64_tr_b16 v[58:59], v94 offset:26304
	ds_read_b64_tr_b16 v[60:61], v94 offset:27392
	s_waitcnt lgkmcnt(0)
	v_mfma_f32_16x16x32_bf16 v[58:61], v[58:61], v[96:99], v[62:65]
	s_nop 2
	ds_read_b64_tr_b16 v[62:63], v94 offset:26336
	ds_read_b64_tr_b16 v[64:65], v94 offset:27424
	s_waitcnt lgkmcnt(0)
	s_barrier
; __device__ __forceinline__ f32x4 mfma16(bf16x8 a, bf16x8 b, f32x4 c) { return __builtin_amdgcn_mfma_f32_16x16x32_bf16(a, b, c, 0, 0, 0); }
; __device__ __forceinline__ void ret_apply_unit(LAS unsigned char* lds, const bf16* P, const bf16* PREV, bf16* BR, const float* dec, int u, int tid) {
;     ...
;     for (int eh = 0; eh < 2; ++eh) {
;         if (eh == 0) tile_store<128, 16>(Vh, RSP, v0, tid); else tile_store<128, 16>(Vh, RSP, v1, tid);
;         __syncthreads();
; #pragma unroll
;         for (int ks = 0; ks < 4; ++ks) { const bf16x8 pf = ldrow(Pl, RSP, 16 * w, 32 * ks, lane);
; #pragma unroll
;             for (int mt = 0; mt < 8; ++mt) { const bf16x8 vf = ldtr(Vh, RSP, 32 * ks, 16 * mt, lane); acc[8 * eh + mt] = mfma16(vf, pf, acc[8 * eh + mt]); } }
	ds_write_b128 v83, v[66:69]
	ds_write_b128 v84, v[70:73]
	ds_write_b128 v85, v[74:77]
	ds_write_b128 v86, v[78:81]
	s_waitcnt lgkmcnt(0)
	s_barrier
	ds_read_b128 v[66:69], v82
	ds_read_b64_tr_b16 v[72:73], v94 offset:1088
	ds_read_b64_tr_b16 v[70:71], v94
	ds_read_b64_tr_b16 v[74:75], v94 offset:32
	ds_read_b64_tr_b16 v[76:77], v94 offset:1120
	v_mfma_f32_16x16x32_bf16 v[62:65], v[62:65], v[96:99], v[88:91]
	ds_read_b64_tr_b16 v[78:79], v94 offset:64
	ds_read_b64_tr_b16 v[80:81], v94 offset:1152
	ds_read_b64_tr_b16 v[84:85], v94 offset:96
	ds_read_b64_tr_b16 v[86:87], v94 offset:1184
	ds_read_b64_tr_b16 v[88:89], v94 offset:128
	ds_read_b64_tr_b16 v[90:91], v94 offset:1216
	ds_read_b64_tr_b16 v[96:97], v94 offset:160
	ds_read_b64_tr_b16 v[98:99], v94 offset:1248
	ds_read_b64_tr_b16 v[100:101], v94 offset:192
	ds_read_b64_tr_b16 v[102:103], v94 offset:1280
	ds_read_b64_tr_b16 v[104:105], v94 offset:224
	ds_read_b64_tr_b16 v[106:107], v94 offset:1312
	s_waitcnt lgkmcnt(14)
	v_mfma_f32_16x16x32_bf16 v[70:73], v[70:73], v[66:69], 0
	s_waitcnt lgkmcnt(12)
	v_mfma_f32_16x16x32_bf16 v[74:77], v[74:77], v[66:69], 0
	s_waitcnt lgkmcnt(10)
	v_mfma_f32_16x16x32_bf16 v[78:81], v[78:81], v[66:69], 0
	s_waitcnt lgkmcnt(8)
	v_mfma_f32_16x16x32_bf16 v[84:87], v[84:87], v[66:69], 0
	s_waitcnt lgkmcnt(6)
	v_mfma_f32_16x16x32_bf16 v[88:91], v[88:91], v[66:69], 0
	s_waitcnt lgkmcnt(4)
	v_mfma_f32_16x16x32_bf16 v[96:99], v[96:99], v[66:69], 0
	s_waitcnt lgkmcnt(2)
	v_mfma_f32_16x16x32_bf16 v[100:103], v[100:103], v[66:69], 0
	s_waitcnt lgkmcnt(0)
	v_mfma_f32_16x16x32_bf16 v[66:69], v[104:107], v[66:69], 0
	ds_read_b128 v[104:107], v82 offset:64
	ds_read_b64_tr_b16 v[108:109], v94 offset:8704
	ds_read_b64_tr_b16 v[110:111], v94 offset:9792
	s_waitcnt lgkmcnt(0)
	v_mfma_f32_16x16x32_bf16 v[70:73], v[108:111], v[104:107], v[70:73]
	ds_read_b64_tr_b16 v[108:109], v94 offset:8736
	ds_read_b64_tr_b16 v[110:111], v94 offset:9824
	s_waitcnt lgkmcnt(0)
	v_mfma_f32_16x16x32_bf16 v[74:77], v[108:111], v[104:107], v[74:77]
	ds_read_b64_tr_b16 v[108:109], v94 offset:8768
	ds_read_b64_tr_b16 v[110:111], v94 offset:9856
	s_waitcnt lgkmcnt(0)
	v_mfma_f32_16x16x32_bf16 v[78:81], v[108:111], v[104:107], v[78:81]
	ds_read_b64_tr_b16 v[108:109], v94 offset:8800
	ds_read_b64_tr_b16 v[110:111], v94 offset:9888
	s_waitcnt lgkmcnt(0)
	v_mfma_f32_16x16x32_bf16 v[84:87], v[108:111], v[104:107], v[84:87]
	ds_read_b64_tr_b16 v[108:109], v94 offset:8832
	ds_read_b64_tr_b16 v[110:111], v94 offset:9920
	s_waitcnt lgkmcnt(0)
	v_mfma_f32_16x16x32_bf16 v[88:91], v[108:111], v[104:107], v[88:91]
	ds_read_b64_tr_b16 v[108:109], v94 offset:8864
	ds_read_b64_tr_b16 v[110:111], v94 offset:9952
	s_waitcnt lgkmcnt(0)
	v_mfma_f32_16x16x32_bf16 v[96:99], v[108:111], v[104:107], v[96:99]
	ds_read_b64_tr_b16 v[108:109], v94 offset:8896
	ds_read_b64_tr_b16 v[110:111], v94 offset:9984
	s_waitcnt lgkmcnt(0)
	v_mfma_f32_16x16x32_bf16 v[100:103], v[108:111], v[104:107], v[100:103]
	ds_read_b64_tr_b16 v[108:109], v94 offset:8928
	ds_read_b64_tr_b16 v[110:111], v94 offset:10016
	s_waitcnt lgkmcnt(0)
	v_mfma_f32_16x16x32_bf16 v[66:69], v[108:111], v[104:107], v[66:69]
	ds_read_b128 v[104:107], v82 offset:128
	ds_read_b64_tr_b16 v[108:109], v94 offset:17408
	ds_read_b64_tr_b16 v[110:111], v94 offset:18496
	s_waitcnt lgkmcnt(0)
	v_mfma_f32_16x16x32_bf16 v[70:73], v[108:111], v[104:107], v[70:73]
	ds_read_b64_tr_b16 v[108:109], v94 offset:17440
	ds_read_b64_tr_b16 v[110:111], v94 offset:18528
	s_waitcnt lgkmcnt(0)
	v_mfma_f32_16x16x32_bf16 v[74:77], v[108:111], v[104:107], v[74:77]
	ds_read_b64_tr_b16 v[108:109], v94 offset:17472
	ds_read_b64_tr_b16 v[110:111], v94 offset:18560
	s_waitcnt lgkmcnt(0)
	v_mfma_f32_16x16x32_bf16 v[78:81], v[108:111], v[104:107], v[78:81]
	ds_read_b64_tr_b16 v[108:109], v94 offset:17504
	ds_read_b64_tr_b16 v[110:111], v94 offset:18592
	s_waitcnt lgkmcnt(0)
	v_mfma_f32_16x16x32_bf16 v[84:87], v[108:111], v[104:107], v[84:87]
	ds_read_b64_tr_b16 v[108:109], v94 offset:17536
	ds_read_b64_tr_b16 v[110:111], v94 offset:18624
	s_waitcnt lgkmcnt(0)
	v_mfma_f32_16x16x32_bf16 v[88:91], v[108:111], v[104:107], v[88:91]
	ds_read_b64_tr_b16 v[108:109], v94 offset:17568
	ds_read_b64_tr_b16 v[110:111], v94 offset:18656
	s_waitcnt lgkmcnt(0)
	v_mfma_f32_16x16x32_bf16 v[96:99], v[108:111], v[104:107], v[96:99]
	ds_read_b64_tr_b16 v[108:109], v94 offset:17600
	ds_read_b64_tr_b16 v[110:111], v94 offset:18688
	s_waitcnt lgkmcnt(0)
	v_mfma_f32_16x16x32_bf16 v[100:103], v[108:111], v[104:107], v[100:103]
	ds_read_b64_tr_b16 v[108:109], v94 offset:17632
	ds_read_b64_tr_b16 v[110:111], v94 offset:18720
	s_waitcnt lgkmcnt(0)
	v_mfma_f32_16x16x32_bf16 v[104:107], v[108:111], v[104:107], v[66:69]
	ds_read_b128 v[108:111], v82 offset:192
	s_nop 1
	ds_read_b64_tr_b16 v[66:67], v94 offset:26112
	ds_read_b64_tr_b16 v[68:69], v94 offset:27200
	s_waitcnt lgkmcnt(0)
	v_mfma_f32_16x16x32_bf16 v[66:69], v[66:69], v[108:111], v[70:73]
	s_nop 2
	ds_read_b64_tr_b16 v[70:71], v94 offset:26144
	ds_read_b64_tr_b16 v[72:73], v94 offset:27232
	s_waitcnt lgkmcnt(0)
	v_mfma_f32_16x16x32_bf16 v[70:73], v[70:73], v[108:111], v[74:77]
	s_nop 2
	ds_read_b64_tr_b16 v[74:75], v94 offset:26176
	ds_read_b64_tr_b16 v[76:77], v94 offset:27264
	s_waitcnt lgkmcnt(0)
	v_mfma_f32_16x16x32_bf16 v[74:77], v[74:77], v[108:111], v[78:81]
	s_nop 2
	ds_read_b64_tr_b16 v[78:79], v94 offset:26208
	ds_read_b64_tr_b16 v[80:81], v94 offset:27296
	s_waitcnt lgkmcnt(0)
	v_mfma_f32_16x16x32_bf16 v[78:81], v[78:81], v[108:111], v[84:87]
	ds_read_b64_tr_b16 v[82:83], v94 offset:26240
	s_nop 1
	ds_read_b64_tr_b16 v[84:85], v94 offset:27328
	s_waitcnt lgkmcnt(0)
	v_mfma_f32_16x16x32_bf16 v[82:85], v[82:85], v[108:111], v[88:91]
	ds_read_b64_tr_b16 v[86:87], v94 offset:26272
	s_nop 1
	ds_read_b64_tr_b16 v[88:89], v94 offset:27360
	ds_read_b64_tr_b16 v[90:91], v94 offset:26304
	ds_read_b64_tr_b16 v[92:93], v94 offset:27392
	s_waitcnt lgkmcnt(2)
	v_mfma_f32_16x16x32_bf16 v[86:89], v[86:89], v[108:111], v[96:99]
	s_nop 2
	ds_read_b64_tr_b16 v[96:97], v94 offset:26336
	ds_read_b64_tr_b16 v[98:99], v94 offset:27424
	s_waitcnt lgkmcnt(0)
	s_barrier
; __device__ __forceinline__ f32x4 mfma16(bf16x8 a, bf16x8 b, f32x4 c) { return __builtin_amdgcn_mfma_f32_16x16x32_bf16(a, b, c, 0, 0, 0); }
; __device__ __forceinline__ void ret_apply_unit(LAS unsigned char* lds, const bf16* P, const bf16* PREV, bf16* BR, const float* dec, int u, int tid) {
;     ...
;             tile_store<128, 32>(Pc, RSQ, pr, tid);
;             if (dir * 2 + eh < 3) { const int nq = dir * 2 + eh + 1; tile_load<128, 32>(pr, PREV + ((size_t)n * 8 + h * 2 + (nq >> 1)) * 65536 + (size_t)(nq & 1) * 128 * 256, 256, tid); }
;             else {
; #pragma unroll
;                 for (int mt = 0; mt < 16; ++mt) gw[mt] = *(const u32x2*)(P + tok * INC + C_RG + h * 256 + 16 * mt + 4 * g); }
;             __syncthreads();
; #pragma unroll
;             for (int ks = 0; ks < 8; ++ks) { const bf16x8 qf = ldrow(Qt, RSQ, 16 * w, 32 * ks, lane);
; #pragma unroll
;                 for (int mt = 0; mt < 8; ++mt) { const bf16x8 pf = ldrow(Pc, RSQ, 16 * mt, 32 * ks, lane); X[mt] = mfma16(pf, qf, X[mt]); } }
;             __syncthreads();
	s_waitcnt vmcnt(7)
	ds_write_b128 v163, v[6:9]
	s_waitcnt vmcnt(6)
	ds_write_b128 v209, v[14:17]
	s_waitcnt vmcnt(5)
	ds_write_b128 v210, v[18:21]
	s_waitcnt vmcnt(4)
	ds_write_b128 v211, v[26:29]
	s_waitcnt vmcnt(3)
	ds_write_b128 v212, v[30:33]
	s_waitcnt vmcnt(2)
	ds_write_b128 v213, v[34:37]
	s_waitcnt vmcnt(1)
	ds_write_b128 v214, v[42:45]
	s_waitcnt vmcnt(0)
	ds_write_b128 v215, v[46:49]
	v_lshl_add_u64 v[6:7], s[12:13], 0, v[164:165]
	v_lshl_add_u64 v[6:7], v[6:7], 0, v[166:167]
	v_mfma_f32_16x16x32_bf16 v[90:93], v[90:93], v[108:111], v[100:103]
	v_mfma_f32_16x16x32_bf16 v[94:97], v[96:99], v[108:111], v[104:107]
	s_nop 1
	global_load_dwordx4 v[98:101], v[6:7], off
	v_lshl_add_u64 v[6:7], s[12:13], 0, v[168:169]
	v_lshl_add_u64 v[6:7], v[6:7], 0, v[170:171]
	global_load_dwordx4 v[102:105], v[6:7], off
	v_lshl_add_u64 v[6:7], s[12:13], 0, v[172:173]
	v_lshl_add_u64 v[6:7], v[6:7], 0, v[174:175]
	global_load_dwordx4 v[106:109], v[6:7], off
	v_lshl_add_u64 v[6:7], s[12:13], 0, v[176:177]
	v_lshl_add_u64 v[6:7], v[6:7], 0, v[178:179]
	global_load_dwordx4 v[110:113], v[6:7], off
	v_lshl_add_u64 v[6:7], s[12:13], 0, v[180:181]
	v_lshl_add_u64 v[6:7], v[6:7], 0, v[182:183]
	global_load_dwordx4 v[114:117], v[6:7], off
	v_lshl_add_u64 v[6:7], s[12:13], 0, v[184:185]
	v_lshl_add_u64 v[6:7], v[6:7], 0, v[186:187]
	global_load_dwordx4 v[118:121], v[6:7], off
	v_lshl_add_u64 v[6:7], s[12:13], 0, v[188:189]
	v_lshl_add_u64 v[6:7], v[6:7], 0, v[190:191]
	global_load_dwordx4 v[122:125], v[6:7], off
	v_lshl_add_u64 v[6:7], s[12:13], 0, v[192:193]
	v_lshl_add_u64 v[6:7], v[6:7], 0, v[194:195]
	global_load_dwordx4 v[126:129], v[6:7], off
	s_waitcnt lgkmcnt(0)
	s_barrier
	ds_read_b128 v[6:9], v208
	ds_read_b128 v[14:17], v207
	ds_read_b128 v[18:21], v207 offset:8448
	ds_read_b128 v[26:29], v207 offset:16896
	ds_read_b128 v[30:33], v207 offset:25344
	ds_read_b128 v[34:37], v207 offset:33792
	ds_read_b128 v[42:45], v207 offset:42240
	ds_read_b128 v[46:49], v207 offset:50688
	ds_read_b128 v[130:133], v207 offset:59136
	s_waitcnt lgkmcnt(7)
	v_mfma_f32_16x16x32_bf16 v[14:17], v[14:17], v[6:9], 0
	s_add_u32 s12, s24, 0x20000
	s_addc_u32 s13, s25, 0
	s_waitcnt lgkmcnt(6)
	v_mfma_f32_16x16x32_bf16 v[18:21], v[18:21], v[6:9], 0
	s_waitcnt lgkmcnt(5)
	v_mfma_f32_16x16x32_bf16 v[26:29], v[26:29], v[6:9], 0
	s_waitcnt lgkmcnt(4)
	v_mfma_f32_16x16x32_bf16 v[30:33], v[30:33], v[6:9], 0
	s_waitcnt lgkmcnt(3)
	v_mfma_f32_16x16x32_bf16 v[34:37], v[34:37], v[6:9], 0
	s_waitcnt lgkmcnt(2)
	v_mfma_f32_16x16x32_bf16 v[42:45], v[42:45], v[6:9], 0
	s_waitcnt lgkmcnt(1)
	v_mfma_f32_16x16x32_bf16 v[46:49], v[46:49], v[6:9], 0
	s_waitcnt lgkmcnt(0)
	v_mfma_f32_16x16x32_bf16 v[6:9], v[130:133], v[6:9], 0
	ds_read_b128 v[130:133], v208 offset:64
	ds_read_b128 v[134:137], v207 offset:64
	s_waitcnt lgkmcnt(0)
	v_mfma_f32_16x16x32_bf16 v[14:17], v[134:137], v[130:133], v[14:17]
	ds_read_b128 v[134:137], v207 offset:8512
	s_waitcnt lgkmcnt(0)
	v_mfma_f32_16x16x32_bf16 v[18:21], v[134:137], v[130:133], v[18:21]
	ds_read_b128 v[134:137], v207 offset:16960
	s_waitcnt lgkmcnt(0)
	v_mfma_f32_16x16x32_bf16 v[26:29], v[134:137], v[130:133], v[26:29]
	ds_read_b128 v[134:137], v207 offset:25408
	s_waitcnt lgkmcnt(0)
	v_mfma_f32_16x16x32_bf16 v[30:33], v[134:137], v[130:133], v[30:33]
	ds_read_b128 v[134:137], v207 offset:33856
	s_waitcnt lgkmcnt(0)
	v_mfma_f32_16x16x32_bf16 v[34:37], v[134:137], v[130:133], v[34:37]
	ds_read_b128 v[134:137], v207 offset:42304
	s_waitcnt lgkmcnt(0)
	v_mfma_f32_16x16x32_bf16 v[42:45], v[134:137], v[130:133], v[42:45]
	ds_read_b128 v[134:137], v207 offset:50752
	s_waitcnt lgkmcnt(0)
	v_mfma_f32_16x16x32_bf16 v[46:49], v[134:137], v[130:133], v[46:49]
	ds_read_b128 v[134:137], v207 offset:59200
	s_waitcnt lgkmcnt(0)
	v_mfma_f32_16x16x32_bf16 v[6:9], v[134:137], v[130:133], v[6:9]
	ds_read_b128 v[130:133], v208 offset:128
	ds_read_b128 v[134:137], v207 offset:128
	s_waitcnt lgkmcnt(0)
	v_mfma_f32_16x16x32_bf16 v[14:17], v[134:137], v[130:133], v[14:17]
	ds_read_b128 v[134:137], v207 offset:8576
	s_waitcnt lgkmcnt(0)
	v_mfma_f32_16x16x32_bf16 v[18:21], v[134:137], v[130:133], v[18:21]
	ds_read_b128 v[134:137], v207 offset:17024
	s_waitcnt lgkmcnt(0)
	v_mfma_f32_16x16x32_bf16 v[26:29], v[134:137], v[130:133], v[26:29]
	ds_read_b128 v[134:137], v207 offset:25472
	s_waitcnt lgkmcnt(0)
	v_mfma_f32_16x16x32_bf16 v[30:33], v[134:137], v[130:133], v[30:33]
	ds_read_b128 v[134:137], v207 offset:33920
	s_waitcnt lgkmcnt(0)
	v_mfma_f32_16x16x32_bf16 v[34:37], v[134:137], v[130:133], v[34:37]
	ds_read_b128 v[134:137], v207 offset:42368
	s_waitcnt lgkmcnt(0)
	v_mfma_f32_16x16x32_bf16 v[42:45], v[134:137], v[130:133], v[42:45]
	ds_read_b128 v[134:137], v207 offset:50816
	s_waitcnt lgkmcnt(0)
	v_mfma_f32_16x16x32_bf16 v[46:49], v[134:137], v[130:133], v[46:49]
	ds_read_b128 v[134:137], v207 offset:59264
	s_waitcnt lgkmcnt(0)
	v_mfma_f32_16x16x32_bf16 v[6:9], v[134:137], v[130:133], v[6:9]
	ds_read_b128 v[130:133], v208 offset:192
	ds_read_b128 v[134:137], v207 offset:192
	s_waitcnt lgkmcnt(0)
	v_mfma_f32_16x16x32_bf16 v[14:17], v[134:137], v[130:133], v[14:17]
	ds_read_b128 v[134:137], v207 offset:8640
	s_waitcnt lgkmcnt(0)
	v_mfma_f32_16x16x32_bf16 v[18:21], v[134:137], v[130:133], v[18:21]
	ds_read_b128 v[134:137], v207 offset:17088
	s_waitcnt lgkmcnt(0)
	v_mfma_f32_16x16x32_bf16 v[26:29], v[134:137], v[130:133], v[26:29]
	ds_read_b128 v[134:137], v207 offset:25536
	s_waitcnt lgkmcnt(0)
	v_mfma_f32_16x16x32_bf16 v[30:33], v[134:137], v[130:133], v[30:33]
	ds_read_b128 v[134:137], v207 offset:33984
	s_waitcnt lgkmcnt(0)
; __device__ __forceinline__ f32x4 mfma16(bf16x8 a, bf16x8 b, f32x4 c) { return __builtin_amdgcn_mfma_f32_16x16x32_bf16(a, b, c, 0, 0, 0); }
; __device__ __forceinline__ void ret_apply_unit(LAS unsigned char* lds, const bf16* P, const bf16* PREV, bf16* BR, const float* dec, int u, int tid) {
;     ...
;             for (int ks = 0; ks < 8; ++ks) { const bf16x8 qf = ldrow(Qt, RSQ, 16 * w, 32 * ks, lane);
; #pragma unroll
;                 for (int mt = 0; mt < 8; ++mt) { const bf16x8 pf = ldrow(Pc, RSQ, 16 * mt, 32 * ks, lane); X[mt] = mfma16(pf, qf, X[mt]); } }
;             __syncthreads();
	v_mfma_f32_16x16x32_bf16 v[34:37], v[134:137], v[130:133], v[34:37]
	ds_read_b128 v[134:137], v207 offset:42432
	s_waitcnt lgkmcnt(0)
	v_mfma_f32_16x16x32_bf16 v[42:45], v[134:137], v[130:133], v[42:45]
	ds_read_b128 v[134:137], v207 offset:50880
	s_waitcnt lgkmcnt(0)
	v_mfma_f32_16x16x32_bf16 v[46:49], v[134:137], v[130:133], v[46:49]
	ds_read_b128 v[134:137], v207 offset:59328
	s_waitcnt lgkmcnt(0)
	v_mfma_f32_16x16x32_bf16 v[6:9], v[134:137], v[130:133], v[6:9]
	ds_read_b128 v[130:133], v208 offset:256
	ds_read_b128 v[134:137], v207 offset:256
	s_waitcnt lgkmcnt(0)
	v_mfma_f32_16x16x32_bf16 v[14:17], v[134:137], v[130:133], v[14:17]
	ds_read_b128 v[134:137], v207 offset:8704
	s_waitcnt lgkmcnt(0)
	v_mfma_f32_16x16x32_bf16 v[18:21], v[134:137], v[130:133], v[18:21]
	ds_read_b128 v[134:137], v207 offset:17152
	s_waitcnt lgkmcnt(0)
	v_mfma_f32_16x16x32_bf16 v[26:29], v[134:137], v[130:133], v[26:29]
	ds_read_b128 v[134:137], v207 offset:25600
	s_waitcnt lgkmcnt(0)
	v_mfma_f32_16x16x32_bf16 v[30:33], v[134:137], v[130:133], v[30:33]
	ds_read_b128 v[134:137], v207 offset:34048
	s_waitcnt lgkmcnt(0)
	v_mfma_f32_16x16x32_bf16 v[34:37], v[134:137], v[130:133], v[34:37]
	ds_read_b128 v[134:137], v207 offset:42496
	s_waitcnt lgkmcnt(0)
	v_mfma_f32_16x16x32_bf16 v[42:45], v[134:137], v[130:133], v[42:45]
	ds_read_b128 v[134:137], v207 offset:50944
	s_waitcnt lgkmcnt(0)
	v_mfma_f32_16x16x32_bf16 v[46:49], v[134:137], v[130:133], v[46:49]
	ds_read_b128 v[134:137], v207 offset:59392
	s_waitcnt lgkmcnt(0)
	v_mfma_f32_16x16x32_bf16 v[6:9], v[134:137], v[130:133], v[6:9]
	ds_read_b128 v[130:133], v208 offset:320
	ds_read_b128 v[134:137], v207 offset:320
	s_waitcnt lgkmcnt(0)
	v_mfma_f32_16x16x32_bf16 v[14:17], v[134:137], v[130:133], v[14:17]
	ds_read_b128 v[134:137], v207 offset:8768
	s_waitcnt lgkmcnt(0)
	v_mfma_f32_16x16x32_bf16 v[18:21], v[134:137], v[130:133], v[18:21]
	ds_read_b128 v[134:137], v207 offset:17216
	s_waitcnt lgkmcnt(0)
	v_mfma_f32_16x16x32_bf16 v[26:29], v[134:137], v[130:133], v[26:29]
	ds_read_b128 v[134:137], v207 offset:25664
	s_waitcnt lgkmcnt(0)
	v_mfma_f32_16x16x32_bf16 v[30:33], v[134:137], v[130:133], v[30:33]
	ds_read_b128 v[134:137], v207 offset:34112
	s_waitcnt lgkmcnt(0)
	v_mfma_f32_16x16x32_bf16 v[34:37], v[134:137], v[130:133], v[34:37]
	ds_read_b128 v[134:137], v207 offset:42560
	s_waitcnt lgkmcnt(0)
	v_mfma_f32_16x16x32_bf16 v[42:45], v[134:137], v[130:133], v[42:45]
	ds_read_b128 v[134:137], v207 offset:51008
	s_waitcnt lgkmcnt(0)
	v_mfma_f32_16x16x32_bf16 v[46:49], v[134:137], v[130:133], v[46:49]
	ds_read_b128 v[134:137], v207 offset:59456
	s_waitcnt lgkmcnt(0)
	v_mfma_f32_16x16x32_bf16 v[6:9], v[134:137], v[130:133], v[6:9]
	ds_read_b128 v[130:133], v208 offset:384
	ds_read_b128 v[134:137], v207 offset:384
	s_waitcnt lgkmcnt(0)
	v_mfma_f32_16x16x32_bf16 v[14:17], v[134:137], v[130:133], v[14:17]
	ds_read_b128 v[134:137], v207 offset:8832
	s_waitcnt lgkmcnt(0)
	v_mfma_f32_16x16x32_bf16 v[18:21], v[134:137], v[130:133], v[18:21]
	ds_read_b128 v[134:137], v207 offset:17280
	s_waitcnt lgkmcnt(0)
	v_mfma_f32_16x16x32_bf16 v[26:29], v[134:137], v[130:133], v[26:29]
	ds_read_b128 v[134:137], v207 offset:25728
	s_waitcnt lgkmcnt(0)
	v_mfma_f32_16x16x32_bf16 v[30:33], v[134:137], v[130:133], v[30:33]
	ds_read_b128 v[134:137], v207 offset:34176
	s_waitcnt lgkmcnt(0)
	v_mfma_f32_16x16x32_bf16 v[34:37], v[134:137], v[130:133], v[34:37]
	ds_read_b128 v[134:137], v207 offset:42624
	s_waitcnt lgkmcnt(0)
	v_mfma_f32_16x16x32_bf16 v[42:45], v[134:137], v[130:133], v[42:45]
	ds_read_b128 v[134:137], v207 offset:51072
	s_waitcnt lgkmcnt(0)
	v_mfma_f32_16x16x32_bf16 v[46:49], v[134:137], v[130:133], v[46:49]
	ds_read_b128 v[134:137], v207 offset:59520
	s_waitcnt lgkmcnt(0)
	v_mfma_f32_16x16x32_bf16 v[130:133], v[134:137], v[130:133], v[6:9]
	ds_read_b128 v[134:137], v208 offset:448
	s_nop 1
	ds_read_b128 v[6:9], v207 offset:448
	s_waitcnt lgkmcnt(0)
	v_mfma_f32_16x16x32_bf16 v[6:9], v[6:9], v[134:137], v[14:17]
	s_nop 2
	ds_read_b128 v[14:17], v207 offset:8896
	s_waitcnt lgkmcnt(0)
	v_mfma_f32_16x16x32_bf16 v[14:17], v[14:17], v[134:137], v[18:21]
	s_nop 2
	ds_read_b128 v[18:21], v207 offset:17344
	s_waitcnt lgkmcnt(0)
	v_mfma_f32_16x16x32_bf16 v[18:21], v[18:21], v[134:137], v[26:29]
	s_nop 2
	ds_read_b128 v[26:29], v207 offset:25792
	s_waitcnt lgkmcnt(0)
	v_mfma_f32_16x16x32_bf16 v[26:29], v[26:29], v[134:137], v[30:33]
	s_nop 2
	ds_read_b128 v[30:33], v207 offset:34240
	s_waitcnt lgkmcnt(0)
	v_mfma_f32_16x16x32_bf16 v[30:33], v[30:33], v[134:137], v[34:37]
	s_nop 2
	ds_read_b128 v[34:37], v207 offset:42688
	s_waitcnt lgkmcnt(0)
	v_mfma_f32_16x16x32_bf16 v[34:37], v[34:37], v[134:137], v[42:45]
	s_nop 2
	ds_read_b128 v[42:45], v207 offset:51136
	s_waitcnt lgkmcnt(0)
	v_mfma_f32_16x16x32_bf16 v[42:45], v[42:45], v[134:137], v[46:49]
	s_nop 2
	ds_read_b128 v[46:49], v207 offset:59584
	s_waitcnt lgkmcnt(0)
	s_barrier
; __device__ __forceinline__ f32x4 mfma16(bf16x8 a, bf16x8 b, f32x4 c) { return __builtin_amdgcn_mfma_f32_16x16x32_bf16(a, b, c, 0, 0, 0); }
; __device__ __forceinline__ void ret_apply_unit(LAS unsigned char* lds, const bf16* P, const bf16* PREV, bf16* BR, const float* dec, int u, int tid) {
;     ...
;             tile_store<128, 32>(Pc, RSQ, pr, tid);
;             if (dir * 2 + eh < 3) { const int nq = dir * 2 + eh + 1; tile_load<128, 32>(pr, PREV + ((size_t)n * 8 + h * 2 + (nq >> 1)) * 65536 + (size_t)(nq & 1) * 128 * 256, 256, tid); }
;             else {
; #pragma unroll
;                 for (int mt = 0; mt < 16; ++mt) gw[mt] = *(const u32x2*)(P + tok * INC + C_RG + h * 256 + 16 * mt + 4 * g); }
;             __syncthreads();
; #pragma unroll
;             for (int ks = 0; ks < 8; ++ks) { const bf16x8 qf = ldrow(Qt, RSQ, 16 * w, 32 * ks, lane);
; #pragma unroll
;                 for (int mt = 0; mt < 8; ++mt) { const bf16x8 pf = ldrow(Pc, RSQ, 16 * mt, 32 * ks, lane); X[mt] = mfma16(pf, qf, X[mt]); } }
;             __syncthreads();
	s_waitcnt vmcnt(7)
	ds_write_b128 v163, v[98:101]
	s_waitcnt vmcnt(6)
	ds_write_b128 v209, v[102:105]
	s_waitcnt vmcnt(5)
	ds_write_b128 v210, v[106:109]
	s_waitcnt vmcnt(4)
	ds_write_b128 v211, v[110:113]
	s_waitcnt vmcnt(3)
	ds_write_b128 v212, v[114:117]
	s_waitcnt vmcnt(2)
	ds_write_b128 v213, v[118:121]
	s_waitcnt vmcnt(1)
	ds_write_b128 v214, v[122:125]
	s_waitcnt vmcnt(0)
	ds_write_b128 v215, v[126:129]
	v_lshl_add_u64 v[98:99], s[12:13], 0, v[164:165]
	v_lshl_add_u64 v[98:99], v[98:99], 0, v[166:167]
	v_mfma_f32_16x16x32_bf16 v[46:49], v[46:49], v[134:137], v[130:133]
	s_nop 2
	global_load_dwordx4 v[130:133], v[98:99], off
	v_lshl_add_u64 v[98:99], s[12:13], 0, v[168:169]
	v_lshl_add_u64 v[98:99], v[98:99], 0, v[170:171]
	global_load_dwordx4 v[134:137], v[98:99], off
	v_lshl_add_u64 v[98:99], s[12:13], 0, v[172:173]
	v_lshl_add_u64 v[98:99], v[98:99], 0, v[174:175]
	global_load_dwordx4 v[138:141], v[98:99], off
	v_lshl_add_u64 v[98:99], s[12:13], 0, v[176:177]
	v_lshl_add_u64 v[98:99], v[98:99], 0, v[178:179]
	global_load_dwordx4 v[142:145], v[98:99], off
	v_lshl_add_u64 v[98:99], s[12:13], 0, v[180:181]
	v_lshl_add_u64 v[98:99], v[98:99], 0, v[182:183]
	global_load_dwordx4 v[146:149], v[98:99], off
	v_lshl_add_u64 v[98:99], s[12:13], 0, v[184:185]
	v_lshl_add_u64 v[98:99], v[98:99], 0, v[186:187]
	global_load_dwordx4 v[150:153], v[98:99], off
	v_lshl_add_u64 v[98:99], s[12:13], 0, v[188:189]
	v_lshl_add_u64 v[98:99], v[98:99], 0, v[190:191]
	global_load_dwordx4 v[154:157], v[98:99], off
	v_lshl_add_u64 v[98:99], s[12:13], 0, v[192:193]
	v_lshl_add_u64 v[98:99], v[98:99], 0, v[194:195]
	global_load_dwordx4 v[158:161], v[98:99], off
	s_waitcnt lgkmcnt(0)
	s_barrier
	ds_read_b128 v[98:101], v208
	ds_read_b128 v[102:105], v207
	ds_read_b128 v[106:109], v207 offset:8448
	ds_read_b128 v[110:113], v207 offset:16896
	ds_read_b128 v[114:117], v207 offset:25344
	ds_read_b128 v[118:121], v207 offset:33792
	ds_read_b128 v[122:125], v207 offset:42240
	ds_read_b128 v[126:129], v207 offset:50688
	ds_read_b128 v[200:203], v207 offset:59136
	s_waitcnt lgkmcnt(7)
	v_mfma_f32_16x16x32_bf16 v[102:105], v[102:105], v[98:101], 0
	s_add_u32 s12, s24, 0x30000
	s_addc_u32 s13, s25, 0
	s_lshl_b32 s26, s19, 1
	s_waitcnt lgkmcnt(6)
	v_mfma_f32_16x16x32_bf16 v[106:109], v[106:109], v[98:101], 0
	s_add_i32 s18, s18, s3
	s_waitcnt lgkmcnt(5)
	v_mfma_f32_16x16x32_bf16 v[110:113], v[110:113], v[98:101], 0
	s_waitcnt lgkmcnt(4)
	v_mfma_f32_16x16x32_bf16 v[114:117], v[114:117], v[98:101], 0
	s_waitcnt lgkmcnt(3)
	v_mfma_f32_16x16x32_bf16 v[118:121], v[118:121], v[98:101], 0
	s_waitcnt lgkmcnt(2)
	v_mfma_f32_16x16x32_bf16 v[122:125], v[122:125], v[98:101], 0
	s_waitcnt lgkmcnt(1)
	v_mfma_f32_16x16x32_bf16 v[126:129], v[126:129], v[98:101], 0
	s_waitcnt lgkmcnt(0)
	v_mfma_f32_16x16x32_bf16 v[98:101], v[200:203], v[98:101], 0
	ds_read_b128 v[200:203], v208 offset:64
	ds_read_b128 v[218:221], v207 offset:64
	s_waitcnt lgkmcnt(0)
	v_mfma_f32_16x16x32_bf16 v[102:105], v[218:221], v[200:203], v[102:105]
	ds_read_b128 v[218:221], v207 offset:8512
	s_waitcnt lgkmcnt(0)
	v_mfma_f32_16x16x32_bf16 v[106:109], v[218:221], v[200:203], v[106:109]
	ds_read_b128 v[218:221], v207 offset:16960
	s_waitcnt lgkmcnt(0)
	v_mfma_f32_16x16x32_bf16 v[110:113], v[218:221], v[200:203], v[110:113]
	ds_read_b128 v[218:221], v207 offset:25408
	s_waitcnt lgkmcnt(0)
	v_mfma_f32_16x16x32_bf16 v[114:117], v[218:221], v[200:203], v[114:117]
	ds_read_b128 v[218:221], v207 offset:33856
	s_waitcnt lgkmcnt(0)
	v_mfma_f32_16x16x32_bf16 v[118:121], v[218:221], v[200:203], v[118:121]
	ds_read_b128 v[218:221], v207 offset:42304
	s_waitcnt lgkmcnt(0)
	v_mfma_f32_16x16x32_bf16 v[122:125], v[218:221], v[200:203], v[122:125]
	ds_read_b128 v[218:221], v207 offset:50752
	s_waitcnt lgkmcnt(0)
	v_mfma_f32_16x16x32_bf16 v[126:129], v[218:221], v[200:203], v[126:129]
	ds_read_b128 v[218:221], v207 offset:59200
	s_waitcnt lgkmcnt(0)
	v_mfma_f32_16x16x32_bf16 v[98:101], v[218:221], v[200:203], v[98:101]
	ds_read_b128 v[200:203], v208 offset:128
	ds_read_b128 v[218:221], v207 offset:128
	s_waitcnt lgkmcnt(0)
	v_mfma_f32_16x16x32_bf16 v[102:105], v[218:221], v[200:203], v[102:105]
	ds_read_b128 v[218:221], v207 offset:8576
	s_waitcnt lgkmcnt(0)
	v_mfma_f32_16x16x32_bf16 v[106:109], v[218:221], v[200:203], v[106:109]
	ds_read_b128 v[218:221], v207 offset:17024
	s_waitcnt lgkmcnt(0)
	v_mfma_f32_16x16x32_bf16 v[110:113], v[218:221], v[200:203], v[110:113]
	ds_read_b128 v[218:221], v207 offset:25472
	s_waitcnt lgkmcnt(0)
	v_mfma_f32_16x16x32_bf16 v[114:117], v[218:221], v[200:203], v[114:117]
	ds_read_b128 v[218:221], v207 offset:33920
	s_waitcnt lgkmcnt(0)
	v_mfma_f32_16x16x32_bf16 v[118:121], v[218:221], v[200:203], v[118:121]
	ds_read_b128 v[218:221], v207 offset:42368
	s_waitcnt lgkmcnt(0)
	v_mfma_f32_16x16x32_bf16 v[122:125], v[218:221], v[200:203], v[122:125]
	ds_read_b128 v[218:221], v207 offset:50816
	s_waitcnt lgkmcnt(0)
	v_mfma_f32_16x16x32_bf16 v[126:129], v[218:221], v[200:203], v[126:129]
	ds_read_b128 v[218:221], v207 offset:59264
	s_waitcnt lgkmcnt(0)
	v_mfma_f32_16x16x32_bf16 v[98:101], v[218:221], v[200:203], v[98:101]
	ds_read_b128 v[200:203], v208 offset:192
	ds_read_b128 v[218:221], v207 offset:192
	s_waitcnt lgkmcnt(0)
	v_mfma_f32_16x16x32_bf16 v[102:105], v[218:221], v[200:203], v[102:105]
	ds_read_b128 v[218:221], v207 offset:8640
	s_waitcnt lgkmcnt(0)
	v_mfma_f32_16x16x32_bf16 v[106:109], v[218:221], v[200:203], v[106:109]
	ds_read_b128 v[218:221], v207 offset:17088
	s_waitcnt lgkmcnt(0)
	v_mfma_f32_16x16x32_bf16 v[110:113], v[218:221], v[200:203], v[110:113]
	ds_read_b128 v[218:221], v207 offset:25536
	s_waitcnt lgkmcnt(0)
; __device__ __forceinline__ f32x4 mfma16(bf16x8 a, bf16x8 b, f32x4 c) { return __builtin_amdgcn_mfma_f32_16x16x32_bf16(a, b, c, 0, 0, 0); }
; __device__ __forceinline__ void ret_apply_unit(LAS unsigned char* lds, const bf16* P, const bf16* PREV, bf16* BR, const float* dec, int u, int tid) {
;     ...
;             for (int ks = 0; ks < 8; ++ks) { const bf16x8 qf = ldrow(Qt, RSQ, 16 * w, 32 * ks, lane);
; #pragma unroll
;                 for (int mt = 0; mt < 8; ++mt) { const bf16x8 pf = ldrow(Pc, RSQ, 16 * mt, 32 * ks, lane); X[mt] = mfma16(pf, qf, X[mt]); } }
;             __syncthreads();
	v_mfma_f32_16x16x32_bf16 v[114:117], v[218:221], v[200:203], v[114:117]
	ds_read_b128 v[218:221], v207 offset:33984
	s_waitcnt lgkmcnt(0)
	v_mfma_f32_16x16x32_bf16 v[118:121], v[218:221], v[200:203], v[118:121]
	ds_read_b128 v[218:221], v207 offset:42432
	s_waitcnt lgkmcnt(0)
	v_mfma_f32_16x16x32_bf16 v[122:125], v[218:221], v[200:203], v[122:125]
	ds_read_b128 v[218:221], v207 offset:50880
	s_waitcnt lgkmcnt(0)
	v_mfma_f32_16x16x32_bf16 v[126:129], v[218:221], v[200:203], v[126:129]
	ds_read_b128 v[218:221], v207 offset:59328
	s_waitcnt lgkmcnt(0)
	v_mfma_f32_16x16x32_bf16 v[98:101], v[218:221], v[200:203], v[98:101]
	ds_read_b128 v[200:203], v208 offset:256
	ds_read_b128 v[218:221], v207 offset:256
	s_waitcnt lgkmcnt(0)
	v_mfma_f32_16x16x32_bf16 v[102:105], v[218:221], v[200:203], v[102:105]
	ds_read_b128 v[218:221], v207 offset:8704
	s_waitcnt lgkmcnt(0)
	v_mfma_f32_16x16x32_bf16 v[106:109], v[218:221], v[200:203], v[106:109]
	ds_read_b128 v[218:221], v207 offset:17152
	s_waitcnt lgkmcnt(0)
	v_mfma_f32_16x16x32_bf16 v[110:113], v[218:221], v[200:203], v[110:113]
	ds_read_b128 v[218:221], v207 offset:25600
	s_waitcnt lgkmcnt(0)
	v_mfma_f32_16x16x32_bf16 v[114:117], v[218:221], v[200:203], v[114:117]
	ds_read_b128 v[218:221], v207 offset:34048
	s_waitcnt lgkmcnt(0)
	v_mfma_f32_16x16x32_bf16 v[118:121], v[218:221], v[200:203], v[118:121]
	ds_read_b128 v[218:221], v207 offset:42496
	s_waitcnt lgkmcnt(0)
	v_mfma_f32_16x16x32_bf16 v[122:125], v[218:221], v[200:203], v[122:125]
	ds_read_b128 v[218:221], v207 offset:50944
	s_waitcnt lgkmcnt(0)
	v_mfma_f32_16x16x32_bf16 v[126:129], v[218:221], v[200:203], v[126:129]
	ds_read_b128 v[218:221], v207 offset:59392
	s_waitcnt lgkmcnt(0)
	v_mfma_f32_16x16x32_bf16 v[98:101], v[218:221], v[200:203], v[98:101]
	ds_read_b128 v[200:203], v208 offset:320
	ds_read_b128 v[218:221], v207 offset:320
	s_waitcnt lgkmcnt(0)
	v_mfma_f32_16x16x32_bf16 v[102:105], v[218:221], v[200:203], v[102:105]
	ds_read_b128 v[218:221], v207 offset:8768
	s_waitcnt lgkmcnt(0)
	v_mfma_f32_16x16x32_bf16 v[106:109], v[218:221], v[200:203], v[106:109]
	ds_read_b128 v[218:221], v207 offset:17216
	s_waitcnt lgkmcnt(0)
	v_mfma_f32_16x16x32_bf16 v[110:113], v[218:221], v[200:203], v[110:113]
	ds_read_b128 v[218:221], v207 offset:25664
	s_waitcnt lgkmcnt(0)
	v_mfma_f32_16x16x32_bf16 v[114:117], v[218:221], v[200:203], v[114:117]
	ds_read_b128 v[218:221], v207 offset:34112
	s_waitcnt lgkmcnt(0)
	v_mfma_f32_16x16x32_bf16 v[118:121], v[218:221], v[200:203], v[118:121]
	ds_read_b128 v[218:221], v207 offset:42560
	s_waitcnt lgkmcnt(0)
	v_mfma_f32_16x16x32_bf16 v[122:125], v[218:221], v[200:203], v[122:125]
	ds_read_b128 v[218:221], v207 offset:51008
	s_waitcnt lgkmcnt(0)
	v_mfma_f32_16x16x32_bf16 v[126:129], v[218:221], v[200:203], v[126:129]
	ds_read_b128 v[218:221], v207 offset:59456
	s_waitcnt lgkmcnt(0)
	v_mfma_f32_16x16x32_bf16 v[98:101], v[218:221], v[200:203], v[98:101]
	ds_read_b128 v[200:203], v208 offset:384
	ds_read_b128 v[218:221], v207 offset:384
	s_waitcnt lgkmcnt(0)
	v_mfma_f32_16x16x32_bf16 v[102:105], v[218:221], v[200:203], v[102:105]
	ds_read_b128 v[218:221], v207 offset:8832
	s_waitcnt lgkmcnt(0)
	v_mfma_f32_16x16x32_bf16 v[106:109], v[218:221], v[200:203], v[106:109]
	ds_read_b128 v[218:221], v207 offset:17280
	s_waitcnt lgkmcnt(0)
	v_mfma_f32_16x16x32_bf16 v[110:113], v[218:221], v[200:203], v[110:113]
	ds_read_b128 v[218:221], v207 offset:25728
	s_waitcnt lgkmcnt(0)
	v_mfma_f32_16x16x32_bf16 v[114:117], v[218:221], v[200:203], v[114:117]
	ds_read_b128 v[218:221], v207 offset:34176
	s_waitcnt lgkmcnt(0)
	v_mfma_f32_16x16x32_bf16 v[118:121], v[218:221], v[200:203], v[118:121]
	ds_read_b128 v[218:221], v207 offset:42624
	s_waitcnt lgkmcnt(0)
	v_mfma_f32_16x16x32_bf16 v[122:125], v[218:221], v[200:203], v[122:125]
	ds_read_b128 v[218:221], v207 offset:51072
	s_waitcnt lgkmcnt(0)
	v_mfma_f32_16x16x32_bf16 v[126:129], v[218:221], v[200:203], v[126:129]
	ds_read_b128 v[218:221], v207 offset:59520
	s_waitcnt lgkmcnt(0)
	v_mfma_f32_16x16x32_bf16 v[200:203], v[218:221], v[200:203], v[98:101]
	ds_read_b128 v[218:221], v208 offset:448
	s_nop 1
	ds_read_b128 v[98:101], v207 offset:448
	s_waitcnt lgkmcnt(0)
	v_mfma_f32_16x16x32_bf16 v[98:101], v[98:101], v[218:221], v[102:105]
	s_nop 2
	ds_read_b128 v[102:105], v207 offset:8896
	s_waitcnt lgkmcnt(0)
	v_mfma_f32_16x16x32_bf16 v[102:105], v[102:105], v[218:221], v[106:109]
	s_nop 2
	ds_read_b128 v[106:109], v207 offset:17344
	s_waitcnt lgkmcnt(0)
	v_mfma_f32_16x16x32_bf16 v[106:109], v[106:109], v[218:221], v[110:113]
	s_nop 2
	ds_read_b128 v[110:113], v207 offset:25792
	s_waitcnt lgkmcnt(0)
	v_mfma_f32_16x16x32_bf16 v[110:113], v[110:113], v[218:221], v[114:117]
	s_nop 2
	ds_read_b128 v[114:117], v207 offset:34240
	s_waitcnt lgkmcnt(0)
	v_mfma_f32_16x16x32_bf16 v[114:117], v[114:117], v[218:221], v[118:121]
	s_nop 2
	ds_read_b128 v[118:121], v207 offset:42688
	s_waitcnt lgkmcnt(0)
	v_mfma_f32_16x16x32_bf16 v[118:121], v[118:121], v[218:221], v[122:125]
	s_nop 2
	ds_read_b128 v[122:125], v207 offset:51136
	s_waitcnt lgkmcnt(0)
	v_mfma_f32_16x16x32_bf16 v[122:125], v[122:125], v[218:221], v[126:129]
	s_nop 2
	ds_read_b128 v[126:129], v207 offset:59584
	s_waitcnt lgkmcnt(0)
	s_barrier
; __device__ __forceinline__ f32x4 mfma16(bf16x8 a, bf16x8 b, f32x4 c) { return __builtin_amdgcn_mfma_f32_16x16x32_bf16(a, b, c, 0, 0, 0); }
; __device__ __forceinline__ void ret_apply_unit(LAS unsigned char* lds, const bf16* P, const bf16* PREV, bf16* BR, const float* dec, int u, int tid) {
;     ...
;             tile_store<128, 32>(Pc, RSQ, pr, tid);
;             if (dir * 2 + eh < 3) { const int nq = dir * 2 + eh + 1; tile_load<128, 32>(pr, PREV + ((size_t)n * 8 + h * 2 + (nq >> 1)) * 65536 + (size_t)(nq & 1) * 128 * 256, 256, tid); }
;             else {
; #pragma unroll
;                 for (int mt = 0; mt < 16; ++mt) gw[mt] = *(const u32x2*)(P + tok * INC + C_RG + h * 256 + 16 * mt + 4 * g); }
;             __syncthreads();
; #pragma unroll
;             for (int ks = 0; ks < 8; ++ks) { const bf16x8 qf = ldrow(Qt, RSQ, 16 * w, 32 * ks, lane);
; #pragma unroll
;                 for (int mt = 0; mt < 8; ++mt) { const bf16x8 pf = ldrow(Pc, RSQ, 16 * mt, 32 * ks, lane); X[mt] = mfma16(pf, qf, X[mt]); } }
;             __syncthreads();
	s_waitcnt vmcnt(7)
	ds_write_b128 v163, v[130:133]
	s_waitcnt vmcnt(6)
	ds_write_b128 v209, v[134:137]
	s_waitcnt vmcnt(5)
	ds_write_b128 v210, v[138:141]
	s_waitcnt vmcnt(4)
	ds_write_b128 v211, v[142:145]
	s_waitcnt vmcnt(3)
	ds_write_b128 v212, v[146:149]
	s_waitcnt vmcnt(2)
	ds_write_b128 v213, v[150:153]
	s_waitcnt vmcnt(1)
	ds_write_b128 v214, v[154:157]
	s_waitcnt vmcnt(0)
	ds_write_b128 v215, v[158:161]
	v_lshl_add_u64 v[130:131], s[12:13], 0, v[164:165]
	v_lshl_add_u64 v[134:135], s[12:13], 0, v[168:169]
	v_lshl_add_u64 v[138:139], s[12:13], 0, v[172:173]
	v_lshl_add_u64 v[142:143], s[12:13], 0, v[176:177]
	v_lshl_add_u64 v[146:147], s[12:13], 0, v[180:181]
	v_lshl_add_u64 v[150:151], s[12:13], 0, v[184:185]
	v_lshl_add_u64 v[154:155], s[12:13], 0, v[188:189]
	v_lshl_add_u64 v[158:159], s[12:13], 0, v[192:193]
	v_lshl_add_u64 v[130:131], v[130:131], 0, v[166:167]
	v_lshl_add_u64 v[134:135], v[134:135], 0, v[170:171]
	v_lshl_add_u64 v[138:139], v[138:139], 0, v[174:175]
	v_lshl_add_u64 v[142:143], v[142:143], 0, v[178:179]
	v_lshl_add_u64 v[146:147], v[146:147], 0, v[182:183]
	v_lshl_add_u64 v[150:151], v[150:151], 0, v[186:187]
	v_lshl_add_u64 v[154:155], v[154:155], 0, v[190:191]
	v_lshl_add_u64 v[158:159], v[158:159], 0, v[194:195]
	v_mfma_f32_16x16x32_bf16 v[126:129], v[126:129], v[218:221], v[200:203]
	global_load_dwordx4 v[130:133], v[130:131], off
	s_lshl_b64 s[12:13], s[22:23], 7
	global_load_dwordx4 v[134:137], v[134:135], off
	s_cmpk_gt_i32 s18, 0xff
	global_load_dwordx4 v[138:141], v[138:139], off
	s_nop 0
	global_load_dwordx4 v[142:145], v[142:143], off
	s_nop 0
	global_load_dwordx4 v[146:149], v[146:147], off
	s_nop 0
	global_load_dwordx4 v[150:153], v[150:151], off
	s_nop 0
	global_load_dwordx4 v[154:157], v[154:155], off
	s_nop 0
	global_load_dwordx4 v[158:161], v[158:159], off
	s_waitcnt lgkmcnt(0)
	s_barrier
	ds_read_b128 v[164:167], v208
	ds_read_b128 v[168:171], v207
	ds_read_b128 v[172:175], v207 offset:8448
	ds_read_b128 v[176:179], v207 offset:16896
	ds_read_b128 v[180:183], v207 offset:25344
	ds_read_b128 v[184:187], v207 offset:33792
	ds_read_b128 v[188:191], v207 offset:42240
	ds_read_b128 v[192:195], v207 offset:50688
	ds_read_b128 v[200:203], v207 offset:59136
	s_waitcnt lgkmcnt(7)
	v_mfma_f32_16x16x32_bf16 v[168:171], v[168:171], v[164:167], 0
	s_waitcnt lgkmcnt(6)
	v_mfma_f32_16x16x32_bf16 v[172:175], v[172:175], v[164:167], 0
	s_waitcnt lgkmcnt(5)
	v_mfma_f32_16x16x32_bf16 v[176:179], v[176:179], v[164:167], 0
	s_waitcnt lgkmcnt(4)
	v_mfma_f32_16x16x32_bf16 v[180:183], v[180:183], v[164:167], 0
	s_waitcnt lgkmcnt(3)
	v_mfma_f32_16x16x32_bf16 v[184:187], v[184:187], v[164:167], 0
	s_waitcnt lgkmcnt(2)
	v_mfma_f32_16x16x32_bf16 v[188:191], v[188:191], v[164:167], 0
	s_waitcnt lgkmcnt(1)
	v_mfma_f32_16x16x32_bf16 v[192:195], v[192:195], v[164:167], 0
	s_waitcnt lgkmcnt(0)
	v_mfma_f32_16x16x32_bf16 v[164:167], v[200:203], v[164:167], 0
	ds_read_b128 v[200:203], v208 offset:64
	ds_read_b128 v[218:221], v207 offset:64
	s_waitcnt lgkmcnt(0)
	v_mfma_f32_16x16x32_bf16 v[168:171], v[218:221], v[200:203], v[168:171]
	ds_read_b128 v[218:221], v207 offset:8512
	s_waitcnt lgkmcnt(0)
	v_mfma_f32_16x16x32_bf16 v[172:175], v[218:221], v[200:203], v[172:175]
	ds_read_b128 v[218:221], v207 offset:16960
	s_waitcnt lgkmcnt(0)
	v_mfma_f32_16x16x32_bf16 v[176:179], v[218:221], v[200:203], v[176:179]
	ds_read_b128 v[218:221], v207 offset:25408
	s_waitcnt lgkmcnt(0)
	v_mfma_f32_16x16x32_bf16 v[180:183], v[218:221], v[200:203], v[180:183]
	ds_read_b128 v[218:221], v207 offset:33856
	s_waitcnt lgkmcnt(0)
	v_mfma_f32_16x16x32_bf16 v[184:187], v[218:221], v[200:203], v[184:187]
	ds_read_b128 v[218:221], v207 offset:42304
	s_waitcnt lgkmcnt(0)
	v_mfma_f32_16x16x32_bf16 v[188:191], v[218:221], v[200:203], v[188:191]
	ds_read_b128 v[218:221], v207 offset:50752
	s_waitcnt lgkmcnt(0)
	v_mfma_f32_16x16x32_bf16 v[192:195], v[218:221], v[200:203], v[192:195]
	ds_read_b128 v[218:221], v207 offset:59200
	s_waitcnt lgkmcnt(0)
	v_mfma_f32_16x16x32_bf16 v[164:167], v[218:221], v[200:203], v[164:167]
	ds_read_b128 v[200:203], v208 offset:128
	ds_read_b128 v[218:221], v207 offset:128
	s_waitcnt lgkmcnt(0)
	v_mfma_f32_16x16x32_bf16 v[168:171], v[218:221], v[200:203], v[168:171]
	ds_read_b128 v[218:221], v207 offset:8576
	s_waitcnt lgkmcnt(0)
	v_mfma_f32_16x16x32_bf16 v[172:175], v[218:221], v[200:203], v[172:175]
	ds_read_b128 v[218:221], v207 offset:17024
	s_waitcnt lgkmcnt(0)
	v_mfma_f32_16x16x32_bf16 v[176:179], v[218:221], v[200:203], v[176:179]
	ds_read_b128 v[218:221], v207 offset:25472
	s_waitcnt lgkmcnt(0)
	v_mfma_f32_16x16x32_bf16 v[180:183], v[218:221], v[200:203], v[180:183]
	ds_read_b128 v[218:221], v207 offset:33920
	s_waitcnt lgkmcnt(0)
	v_mfma_f32_16x16x32_bf16 v[184:187], v[218:221], v[200:203], v[184:187]
	ds_read_b128 v[218:221], v207 offset:42368
	s_waitcnt lgkmcnt(0)
	v_mfma_f32_16x16x32_bf16 v[188:191], v[218:221], v[200:203], v[188:191]
	ds_read_b128 v[218:221], v207 offset:50816
	s_waitcnt lgkmcnt(0)
	v_mfma_f32_16x16x32_bf16 v[192:195], v[218:221], v[200:203], v[192:195]
	ds_read_b128 v[218:221], v207 offset:59264
	s_waitcnt lgkmcnt(0)
	v_mfma_f32_16x16x32_bf16 v[164:167], v[218:221], v[200:203], v[164:167]
	ds_read_b128 v[200:203], v208 offset:192
	ds_read_b128 v[218:221], v207 offset:192
	s_waitcnt lgkmcnt(0)
	v_mfma_f32_16x16x32_bf16 v[168:171], v[218:221], v[200:203], v[168:171]
	ds_read_b128 v[218:221], v207 offset:8640
	s_waitcnt lgkmcnt(0)
	v_mfma_f32_16x16x32_bf16 v[172:175], v[218:221], v[200:203], v[172:175]
	ds_read_b128 v[218:221], v207 offset:17088
	s_waitcnt lgkmcnt(0)
; __device__ __forceinline__ f32x4 mfma16(bf16x8 a, bf16x8 b, f32x4 c) { return __builtin_amdgcn_mfma_f32_16x16x32_bf16(a, b, c, 0, 0, 0); }
; __device__ __forceinline__ void ret_apply_unit(LAS unsigned char* lds, const bf16* P, const bf16* PREV, bf16* BR, const float* dec, int u, int tid) {
;     ...
;             for (int ks = 0; ks < 8; ++ks) { const bf16x8 qf = ldrow(Qt, RSQ, 16 * w, 32 * ks, lane);
; #pragma unroll
;                 for (int mt = 0; mt < 8; ++mt) { const bf16x8 pf = ldrow(Pc, RSQ, 16 * mt, 32 * ks, lane); X[mt] = mfma16(pf, qf, X[mt]); } }
;             __syncthreads();
	v_mfma_f32_16x16x32_bf16 v[176:179], v[218:221], v[200:203], v[176:179]
	ds_read_b128 v[218:221], v207 offset:25536
	s_waitcnt lgkmcnt(0)
	v_mfma_f32_16x16x32_bf16 v[180:183], v[218:221], v[200:203], v[180:183]
	ds_read_b128 v[218:221], v207 offset:33984
	s_waitcnt lgkmcnt(0)
	v_mfma_f32_16x16x32_bf16 v[184:187], v[218:221], v[200:203], v[184:187]
	ds_read_b128 v[218:221], v207 offset:42432
	s_waitcnt lgkmcnt(0)
	v_mfma_f32_16x16x32_bf16 v[188:191], v[218:221], v[200:203], v[188:191]
	ds_read_b128 v[218:221], v207 offset:50880
	s_waitcnt lgkmcnt(0)
	v_mfma_f32_16x16x32_bf16 v[192:195], v[218:221], v[200:203], v[192:195]
	ds_read_b128 v[218:221], v207 offset:59328
	s_waitcnt lgkmcnt(0)
	v_mfma_f32_16x16x32_bf16 v[164:167], v[218:221], v[200:203], v[164:167]
	ds_read_b128 v[200:203], v208 offset:256
	ds_read_b128 v[218:221], v207 offset:256
	s_waitcnt lgkmcnt(0)
	v_mfma_f32_16x16x32_bf16 v[168:171], v[218:221], v[200:203], v[168:171]
	ds_read_b128 v[218:221], v207 offset:8704
	s_waitcnt lgkmcnt(0)
	v_mfma_f32_16x16x32_bf16 v[172:175], v[218:221], v[200:203], v[172:175]
	ds_read_b128 v[218:221], v207 offset:17152
	s_waitcnt lgkmcnt(0)
	v_mfma_f32_16x16x32_bf16 v[176:179], v[218:221], v[200:203], v[176:179]
	ds_read_b128 v[218:221], v207 offset:25600
	s_waitcnt lgkmcnt(0)
	v_mfma_f32_16x16x32_bf16 v[180:183], v[218:221], v[200:203], v[180:183]
	ds_read_b128 v[218:221], v207 offset:34048
	s_waitcnt lgkmcnt(0)
	v_mfma_f32_16x16x32_bf16 v[184:187], v[218:221], v[200:203], v[184:187]
	ds_read_b128 v[218:221], v207 offset:42496
	s_waitcnt lgkmcnt(0)
	v_mfma_f32_16x16x32_bf16 v[188:191], v[218:221], v[200:203], v[188:191]
	ds_read_b128 v[218:221], v207 offset:50944
	s_waitcnt lgkmcnt(0)
	v_mfma_f32_16x16x32_bf16 v[192:195], v[218:221], v[200:203], v[192:195]
	ds_read_b128 v[218:221], v207 offset:59392
	s_waitcnt lgkmcnt(0)
	v_mfma_f32_16x16x32_bf16 v[164:167], v[218:221], v[200:203], v[164:167]
	ds_read_b128 v[200:203], v208 offset:320
	ds_read_b128 v[218:221], v207 offset:320
	s_waitcnt lgkmcnt(0)
	v_mfma_f32_16x16x32_bf16 v[168:171], v[218:221], v[200:203], v[168:171]
	ds_read_b128 v[218:221], v207 offset:8768
	s_waitcnt lgkmcnt(0)
	v_mfma_f32_16x16x32_bf16 v[172:175], v[218:221], v[200:203], v[172:175]
	ds_read_b128 v[218:221], v207 offset:17216
	s_waitcnt lgkmcnt(0)
	v_mfma_f32_16x16x32_bf16 v[176:179], v[218:221], v[200:203], v[176:179]
	ds_read_b128 v[218:221], v207 offset:25664
	s_waitcnt lgkmcnt(0)
	v_mfma_f32_16x16x32_bf16 v[180:183], v[218:221], v[200:203], v[180:183]
	ds_read_b128 v[218:221], v207 offset:34112
	s_waitcnt lgkmcnt(0)
	v_mfma_f32_16x16x32_bf16 v[184:187], v[218:221], v[200:203], v[184:187]
	ds_read_b128 v[218:221], v207 offset:42560
	s_waitcnt lgkmcnt(0)
	v_mfma_f32_16x16x32_bf16 v[188:191], v[218:221], v[200:203], v[188:191]
	ds_read_b128 v[218:221], v207 offset:51008
	s_waitcnt lgkmcnt(0)
	v_mfma_f32_16x16x32_bf16 v[192:195], v[218:221], v[200:203], v[192:195]
	ds_read_b128 v[218:221], v207 offset:59456
	s_waitcnt lgkmcnt(0)
	v_mfma_f32_16x16x32_bf16 v[164:167], v[218:221], v[200:203], v[164:167]
	ds_read_b128 v[200:203], v208 offset:384
	ds_read_b128 v[218:221], v207 offset:384
	s_waitcnt lgkmcnt(0)
	v_mfma_f32_16x16x32_bf16 v[168:171], v[218:221], v[200:203], v[168:171]
	ds_read_b128 v[218:221], v207 offset:8832
	s_waitcnt lgkmcnt(0)
	v_mfma_f32_16x16x32_bf16 v[172:175], v[218:221], v[200:203], v[172:175]
	ds_read_b128 v[218:221], v207 offset:17280
	s_waitcnt lgkmcnt(0)
	v_mfma_f32_16x16x32_bf16 v[176:179], v[218:221], v[200:203], v[176:179]
	ds_read_b128 v[218:221], v207 offset:25728
	s_waitcnt lgkmcnt(0)
	v_mfma_f32_16x16x32_bf16 v[180:183], v[218:221], v[200:203], v[180:183]
	ds_read_b128 v[218:221], v207 offset:34176
	s_waitcnt lgkmcnt(0)
	v_mfma_f32_16x16x32_bf16 v[184:187], v[218:221], v[200:203], v[184:187]
	ds_read_b128 v[218:221], v207 offset:42624
	s_waitcnt lgkmcnt(0)
	v_mfma_f32_16x16x32_bf16 v[188:191], v[218:221], v[200:203], v[188:191]
	ds_read_b128 v[218:221], v207 offset:51072
	s_waitcnt lgkmcnt(0)
	v_mfma_f32_16x16x32_bf16 v[192:195], v[218:221], v[200:203], v[192:195]
	ds_read_b128 v[218:221], v207 offset:59520
	s_waitcnt lgkmcnt(0)
	v_mfma_f32_16x16x32_bf16 v[164:167], v[218:221], v[200:203], v[164:167]
	ds_read_b128 v[200:203], v208 offset:448
	ds_read_b128 v[218:221], v207 offset:448
	s_waitcnt lgkmcnt(0)
	v_mfma_f32_16x16x32_bf16 v[168:171], v[218:221], v[200:203], v[168:171]
	ds_read_b128 v[218:221], v207 offset:8896
	s_waitcnt lgkmcnt(0)
	v_mfma_f32_16x16x32_bf16 v[172:175], v[218:221], v[200:203], v[172:175]
	ds_read_b128 v[218:221], v207 offset:17344
	s_waitcnt lgkmcnt(0)
	v_mfma_f32_16x16x32_bf16 v[176:179], v[218:221], v[200:203], v[176:179]
	ds_read_b128 v[218:221], v207 offset:25792
	s_waitcnt lgkmcnt(0)
	v_mfma_f32_16x16x32_bf16 v[180:183], v[218:221], v[200:203], v[180:183]
	ds_read_b128 v[218:221], v207 offset:34240
	s_waitcnt lgkmcnt(0)
	v_mfma_f32_16x16x32_bf16 v[184:187], v[218:221], v[200:203], v[184:187]
	ds_read_b128 v[218:221], v207 offset:42688
	s_waitcnt lgkmcnt(0)
	v_mfma_f32_16x16x32_bf16 v[188:191], v[218:221], v[200:203], v[188:191]
	ds_read_b128 v[218:221], v207 offset:51136
	s_waitcnt lgkmcnt(0)
	v_mfma_f32_16x16x32_bf16 v[192:195], v[218:221], v[200:203], v[192:195]
	ds_read_b128 v[218:221], v207 offset:59584
	s_waitcnt lgkmcnt(0)
	s_barrier
; __device__ __forceinline__ f32x4 mfma16(bf16x8 a, bf16x8 b, f32x4 c) { return __builtin_amdgcn_mfma_f32_16x16x32_bf16(a, b, c, 0, 0, 0); }
; __device__ __forceinline__ void ret_apply_unit(LAS unsigned char* lds, const bf16* P, const bf16* PREV, bf16* BR, const float* dec, int u, int tid) {
;     ...
;         const float qd = __builtin_amdgcn_exp2f(dir == 0 ? (float)(a + 1) * lgf2 : (float)(128 - a) * lgb2);
; #pragma unroll
;         for (int eh = 0; eh < 2; ++eh) {
;             f32x4 X[8];
; #pragma unroll
;             for (int mt = 0; mt < 8; ++mt) X[mt] = (f32x4){0.f, 0.f, 0.f, 0.f};
;             tile_store<128, 32>(Pc, RSQ, pr, tid);
;             if (dir * 2 + eh < 3) { const int nq = dir * 2 + eh + 1; tile_load<128, 32>(pr, PREV + ((size_t)n * 8 + h * 2 + (nq >> 1)) * 65536 + (size_t)(nq & 1) * 128 * 256, 256, tid); }
;             else {
; #pragma unroll
;                 for (int mt = 0; mt < 16; ++mt) gw[mt] = *(const u32x2*)(P + tok * INC + C_RG + h * 256 + 16 * mt + 4 * g); }
;             __syncthreads();
; #pragma unroll
;             for (int ks = 0; ks < 8; ++ks) { const bf16x8 qf = ldrow(Qt, RSQ, 16 * w, 32 * ks, lane);
; #pragma unroll
;                 for (int mt = 0; mt < 8; ++mt) { const bf16x8 pf = ldrow(Pc, RSQ, 16 * mt, 32 * ks, lane); X[mt] = mfma16(pf, qf, X[mt]); } }
;             __syncthreads();
; #pragma unroll
;             for (int mt = 0; mt < 8; ++mt) acc[8 * eh + mt] = acc[8 * eh + mt] + X[mt] * qd;
	s_waitcnt vmcnt(7)
	ds_write_b128 v163, v[130:133]
	s_waitcnt vmcnt(6)
	ds_write_b128 v209, v[134:137]
	s_waitcnt vmcnt(5)
	ds_write_b128 v210, v[138:141]
	s_waitcnt vmcnt(4)
	ds_write_b128 v211, v[142:145]
	s_waitcnt vmcnt(3)
	ds_write_b128 v212, v[146:149]
	s_waitcnt vmcnt(2)
	ds_write_b128 v213, v[150:153]
	s_waitcnt vmcnt(1)
	ds_write_b128 v214, v[154:157]
	s_waitcnt vmcnt(0)
	ds_write_b128 v215, v[158:161]
	v_ashrrev_i32_e32 v163, 31, v162
	v_lshl_add_u64 v[160:161], s[12:13], 0, v[162:163]
	v_add_u32_e32 v163, 1, v162
	v_cvt_f32_i32_e32 v163, v163
	v_mfma_f32_16x16x32_bf16 v[200:203], v[218:221], v[200:203], v[164:167]
	v_mov_b64_e32 v[130:131], s[0:1]
	v_mad_u64_u32 v[130:131], s[12:13], v160, s94, v[130:131]
	v_mul_f32_e32 v163, v216, v163
	v_exp_f32_e32 v166, v163
	v_mad_i32_i24 v131, v161, s94, v131
	v_lshl_add_u64 v[130:131], v[130:131], 0, s[26:27]
	v_lshl_add_u64 v[164:165], v[130:131], 0, v[0:1]
	v_pk_fma_f32 v[46:47], v[166:167], v[46:47], v[62:63] op_sel_hi:[0,1,1]
	v_sub_u32_e32 v62, 0x80, v162
	v_cvt_f32_i32_e32 v62, v62
	s_mov_b64 s[12:13], 0x1800
	v_lshl_add_u64 v[158:159], v[164:165], 0, s[12:13]
	v_add_co_u32_e32 v164, vcc, s65, v164
	v_mul_f32_e32 v62, v217, v62
	v_exp_f32_e32 v62, v62
	v_addc_co_u32_e32 v165, vcc, 0, v165, vcc
	v_pk_fma_f32 v[4:5], v[166:167], v[8:9], v[4:5] op_sel_hi:[0,1,1]
	v_pk_fma_f32 v[2:3], v[166:167], v[6:7], v[2:3] op_sel_hi:[0,1,1]
	global_load_dwordx2 v[130:131], v[158:159], off offset:480
	global_load_dwordx2 v[132:133], v[158:159], off offset:448
	global_load_dwordx2 v[134:135], v[158:159], off offset:416
	global_load_dwordx2 v[136:137], v[158:159], off offset:384
	global_load_dwordx2 v[138:139], v[158:159], off offset:352
	global_load_dwordx2 v[140:141], v[158:159], off offset:320
	global_load_dwordx2 v[142:143], v[158:159], off offset:288
	global_load_dwordx2 v[144:145], v[158:159], off offset:256
	global_load_dwordx2 v[146:147], v[158:159], off offset:224
	global_load_dwordx2 v[148:149], v[158:159], off offset:192
	global_load_dwordx2 v[150:151], v[158:159], off offset:160
	global_load_dwordx2 v[152:153], v[158:159], off offset:128
	global_load_dwordx2 v[154:155], v[158:159], off offset:96
	global_load_dwordx2 v[156:157], v[158:159], off offset:64
	s_nop 0
	global_load_dwordx2 v[158:159], v[158:159], off offset:32
	v_pk_fma_f32 v[48:49], v[166:167], v[48:49], v[64:65] op_sel_hi:[0,1,1]
	global_load_dwordx2 v[164:165], v[164:165], off offset:2048
	v_pk_fma_f32 v[44:45], v[166:167], v[44:45], v[60:61] op_sel_hi:[0,1,1]
	v_pk_fma_f32 v[42:43], v[166:167], v[42:43], v[58:59] op_sel_hi:[0,1,1]
	v_pk_fma_f32 v[36:37], v[166:167], v[36:37], v[56:57] op_sel_hi:[0,1,1]
	v_pk_fma_f32 v[34:35], v[166:167], v[34:35], v[54:55] op_sel_hi:[0,1,1]
	v_pk_fma_f32 v[32:33], v[166:167], v[32:33], v[52:53] op_sel_hi:[0,1,1]
	v_pk_fma_f32 v[30:31], v[166:167], v[30:31], v[50:51] op_sel_hi:[0,1,1]
	v_pk_fma_f32 v[28:29], v[166:167], v[28:29], v[40:41] op_sel_hi:[0,1,1]
	v_pk_fma_f32 v[26:27], v[166:167], v[26:27], v[38:39] op_sel_hi:[0,1,1]
	v_pk_fma_f32 v[20:21], v[166:167], v[20:21], v[24:25] op_sel_hi:[0,1,1]
	v_pk_fma_f32 v[18:19], v[166:167], v[18:19], v[22:23] op_sel_hi:[0,1,1]
	v_pk_fma_f32 v[12:13], v[166:167], v[16:17], v[12:13] op_sel_hi:[0,1,1]
	v_pk_fma_f32 v[10:11], v[166:167], v[14:15], v[10:11] op_sel_hi:[0,1,1]
	v_pk_fma_f32 v[8:9], v[62:63], v[170:171], v[4:5] op_sel_hi:[0,1,1]
	v_pk_fma_f32 v[6:7], v[62:63], v[168:169], v[2:3] op_sel_hi:[0,1,1]
	v_pk_fma_f32 v[14:15], v[166:167], v[128:129], v[96:97] op_sel_hi:[0,1,1]
	v_pk_fma_f32 v[16:17], v[166:167], v[126:127], v[94:95] op_sel_hi:[0,1,1]
	v_pk_fma_f32 v[22:23], v[166:167], v[124:125], v[92:93] op_sel_hi:[0,1,1]
	v_pk_fma_f32 v[24:25], v[166:167], v[122:123], v[90:91] op_sel_hi:[0,1,1]
	v_pk_fma_f32 v[38:39], v[166:167], v[120:121], v[88:89] op_sel_hi:[0,1,1]
	v_pk_fma_f32 v[40:41], v[166:167], v[118:119], v[86:87] op_sel_hi:[0,1,1]
	v_pk_fma_f32 v[50:51], v[166:167], v[116:117], v[84:85] op_sel_hi:[0,1,1]
	v_pk_fma_f32 v[52:53], v[166:167], v[114:115], v[82:83] op_sel_hi:[0,1,1]
	v_pk_fma_f32 v[54:55], v[166:167], v[112:113], v[80:81] op_sel_hi:[0,1,1]
	v_pk_fma_f32 v[56:57], v[166:167], v[110:111], v[78:79] op_sel_hi:[0,1,1]
	v_pk_fma_f32 v[58:59], v[166:167], v[108:109], v[76:77] op_sel_hi:[0,1,1]
	v_pk_fma_f32 v[60:61], v[166:167], v[106:107], v[74:75] op_sel_hi:[0,1,1]
	v_pk_fma_f32 v[64:65], v[166:167], v[104:105], v[72:73] op_sel_hi:[0,1,1]
	v_pk_fma_f32 v[70:71], v[166:167], v[102:103], v[70:71] op_sel_hi:[0,1,1]
	v_pk_fma_f32 v[68:69], v[166:167], v[100:101], v[68:69] op_sel_hi:[0,1,1]
	v_pk_fma_f32 v[66:67], v[166:167], v[98:99], v[66:67] op_sel_hi:[0,1,1]
	s_waitcnt lgkmcnt(0)
	s_barrier
; __device__ __forceinline__ f32x4 mfma16(bf16x8 a, bf16x8 b, f32x4 c) { return __builtin_amdgcn_mfma_f32_16x16x32_bf16(a, b, c, 0, 0, 0); }
; __device__ __forceinline__ void ret_apply_unit(LAS unsigned char* lds, const bf16* P, const bf16* PREV, bf16* BR, const float* dec, int u, int tid) {
;     ...
;             for (int ks = 0; ks < 8; ++ks) { const bf16x8 qf = ldrow(Qt, RSQ, 16 * w, 32 * ks, lane);
; #pragma unroll
;                 for (int mt = 0; mt < 8; ++mt) { const bf16x8 pf = ldrow(Pc, RSQ, 16 * mt, 32 * ks, lane); X[mt] = mfma16(pf, qf, X[mt]); } }
;             __syncthreads();
; #pragma unroll
;             for (int mt = 0; mt < 8; ++mt) acc[8 * eh + mt] = acc[8 * eh + mt] + X[mt] * qd;
	ds_read_b128 v[2:5], v208
	ds_read_b128 v[72:75], v207
	ds_read_b128 v[76:79], v207 offset:8448
	ds_read_b128 v[80:83], v207 offset:16896
	ds_read_b128 v[84:87], v207 offset:25344
	ds_read_b128 v[88:91], v207 offset:33792
	ds_read_b128 v[92:95], v207 offset:42240
	ds_read_b128 v[96:99], v207 offset:50688
	ds_read_b128 v[100:103], v207 offset:59136
	s_waitcnt lgkmcnt(7)
	v_mfma_f32_16x16x32_bf16 v[72:75], v[72:75], v[2:5], 0
	v_fma_f32 v12, v62, v174, v12
	v_fma_f32 v13, v62, v175, v13
	v_pk_fma_f32 v[10:11], v[62:63], v[172:173], v[10:11] op_sel_hi:[0,1,1]
	v_pk_fma_f32 v[28:29], v[62:63], v[182:183], v[28:29] op_sel_hi:[0,1,1]
	s_waitcnt lgkmcnt(6)
	v_mfma_f32_16x16x32_bf16 v[76:79], v[76:79], v[2:5], 0
	v_fma_f32 v26, v62, v180, v26
	v_fma_f32 v27, v62, v181, v27
	v_pk_fma_f32 v[20:21], v[62:63], v[178:179], v[20:21] op_sel_hi:[0,1,1]
	v_pk_fma_f32 v[18:19], v[62:63], v[176:177], v[18:19] op_sel_hi:[0,1,1]
	s_waitcnt lgkmcnt(5)
	v_mfma_f32_16x16x32_bf16 v[80:83], v[80:83], v[2:5], 0
	v_fma_f32 v48, v62, v202, v48
	v_fma_f32 v49, v62, v203, v49
	v_pk_fma_f32 v[46:47], v[62:63], v[200:201], v[46:47] op_sel_hi:[0,1,1]
	v_pk_fma_f32 v[44:45], v[62:63], v[194:195], v[44:45] op_sel_hi:[0,1,1]
	s_waitcnt lgkmcnt(4)
	v_mfma_f32_16x16x32_bf16 v[84:87], v[84:87], v[2:5], 0
	v_fma_f32 v42, v62, v192, v42
	v_fma_f32 v43, v62, v193, v43
	v_pk_fma_f32 v[36:37], v[62:63], v[190:191], v[36:37] op_sel_hi:[0,1,1]
	v_pk_fma_f32 v[34:35], v[62:63], v[188:189], v[34:35] op_sel_hi:[0,1,1]
	s_waitcnt lgkmcnt(3)
	v_mfma_f32_16x16x32_bf16 v[88:91], v[88:91], v[2:5], 0
	v_fma_f32 v32, v62, v186, v32
	v_fma_f32 v33, v62, v187, v33
	v_pk_fma_f32 v[30:31], v[62:63], v[184:185], v[30:31] op_sel_hi:[0,1,1]
	s_waitcnt lgkmcnt(2)
	v_mfma_f32_16x16x32_bf16 v[92:95], v[92:95], v[2:5], 0
	s_waitcnt lgkmcnt(1)
	v_mfma_f32_16x16x32_bf16 v[96:99], v[96:99], v[2:5], 0
	s_waitcnt lgkmcnt(0)
	v_mfma_f32_16x16x32_bf16 v[2:5], v[100:103], v[2:5], 0
	ds_read_b128 v[100:103], v208 offset:64
	ds_read_b128 v[104:107], v207 offset:64
	s_waitcnt lgkmcnt(0)
	v_mfma_f32_16x16x32_bf16 v[72:75], v[104:107], v[100:103], v[72:75]
	ds_read_b128 v[104:107], v207 offset:8512
	s_waitcnt lgkmcnt(0)
	v_mfma_f32_16x16x32_bf16 v[76:79], v[104:107], v[100:103], v[76:79]
	ds_read_b128 v[104:107], v207 offset:16960
	s_waitcnt lgkmcnt(0)
	v_mfma_f32_16x16x32_bf16 v[80:83], v[104:107], v[100:103], v[80:83]
	ds_read_b128 v[104:107], v207 offset:25408
	s_waitcnt lgkmcnt(0)
	v_mfma_f32_16x16x32_bf16 v[84:87], v[104:107], v[100:103], v[84:87]
	ds_read_b128 v[104:107], v207 offset:33856
	s_waitcnt lgkmcnt(0)
	v_mfma_f32_16x16x32_bf16 v[88:91], v[104:107], v[100:103], v[88:91]
	ds_read_b128 v[104:107], v207 offset:42304
	s_waitcnt lgkmcnt(0)
	v_mfma_f32_16x16x32_bf16 v[92:95], v[104:107], v[100:103], v[92:95]
	ds_read_b128 v[104:107], v207 offset:50752
	s_waitcnt lgkmcnt(0)
	v_mfma_f32_16x16x32_bf16 v[96:99], v[104:107], v[100:103], v[96:99]
	ds_read_b128 v[104:107], v207 offset:59200
	s_waitcnt lgkmcnt(0)
	v_mfma_f32_16x16x32_bf16 v[2:5], v[104:107], v[100:103], v[2:5]
	ds_read_b128 v[100:103], v208 offset:128
	ds_read_b128 v[104:107], v207 offset:128
	s_waitcnt lgkmcnt(0)
	v_mfma_f32_16x16x32_bf16 v[72:75], v[104:107], v[100:103], v[72:75]
	ds_read_b128 v[104:107], v207 offset:8576
	s_waitcnt lgkmcnt(0)
	v_mfma_f32_16x16x32_bf16 v[76:79], v[104:107], v[100:103], v[76:79]
	ds_read_b128 v[104:107], v207 offset:17024
	s_waitcnt lgkmcnt(0)
	v_mfma_f32_16x16x32_bf16 v[80:83], v[104:107], v[100:103], v[80:83]
	ds_read_b128 v[104:107], v207 offset:25472
	s_waitcnt lgkmcnt(0)
	v_mfma_f32_16x16x32_bf16 v[84:87], v[104:107], v[100:103], v[84:87]
	ds_read_b128 v[104:107], v207 offset:33920
	s_waitcnt lgkmcnt(0)
	v_mfma_f32_16x16x32_bf16 v[88:91], v[104:107], v[100:103], v[88:91]
	ds_read_b128 v[104:107], v207 offset:42368
	s_waitcnt lgkmcnt(0)
	v_mfma_f32_16x16x32_bf16 v[92:95], v[104:107], v[100:103], v[92:95]
	ds_read_b128 v[104:107], v207 offset:50816
	s_waitcnt lgkmcnt(0)
	v_mfma_f32_16x16x32_bf16 v[96:99], v[104:107], v[100:103], v[96:99]
	ds_read_b128 v[104:107], v207 offset:59264
	s_waitcnt lgkmcnt(0)
	v_mfma_f32_16x16x32_bf16 v[2:5], v[104:107], v[100:103], v[2:5]
	ds_read_b128 v[100:103], v208 offset:192
	ds_read_b128 v[104:107], v207 offset:192
	s_waitcnt lgkmcnt(0)
	v_mfma_f32_16x16x32_bf16 v[72:75], v[104:107], v[100:103], v[72:75]
	ds_read_b128 v[104:107], v207 offset:8640
	s_waitcnt lgkmcnt(0)
	v_mfma_f32_16x16x32_bf16 v[76:79], v[104:107], v[100:103], v[76:79]
	ds_read_b128 v[104:107], v207 offset:17088
	s_waitcnt lgkmcnt(0)
	v_mfma_f32_16x16x32_bf16 v[80:83], v[104:107], v[100:103], v[80:83]
	ds_read_b128 v[104:107], v207 offset:25536
	s_waitcnt lgkmcnt(0)
	v_mfma_f32_16x16x32_bf16 v[84:87], v[104:107], v[100:103], v[84:87]
	ds_read_b128 v[104:107], v207 offset:33984
	s_waitcnt lgkmcnt(0)
	v_mfma_f32_16x16x32_bf16 v[88:91], v[104:107], v[100:103], v[88:91]
	ds_read_b128 v[104:107], v207 offset:42432
	s_waitcnt lgkmcnt(0)
	v_mfma_f32_16x16x32_bf16 v[92:95], v[104:107], v[100:103], v[92:95]
	ds_read_b128 v[104:107], v207 offset:50880
	s_waitcnt lgkmcnt(0)
	v_mfma_f32_16x16x32_bf16 v[96:99], v[104:107], v[100:103], v[96:99]
	ds_read_b128 v[104:107], v207 offset:59328
	s_waitcnt lgkmcnt(0)
	v_mfma_f32_16x16x32_bf16 v[2:5], v[104:107], v[100:103], v[2:5]
	ds_read_b128 v[100:103], v208 offset:256
	ds_read_b128 v[104:107], v207 offset:256
	s_waitcnt lgkmcnt(0)
	v_mfma_f32_16x16x32_bf16 v[72:75], v[104:107], v[100:103], v[72:75]
	ds_read_b128 v[104:107], v207 offset:8704
	s_waitcnt lgkmcnt(0)
	v_mfma_f32_16x16x32_bf16 v[76:79], v[104:107], v[100:103], v[76:79]
	ds_read_b128 v[104:107], v207 offset:17152
	s_waitcnt lgkmcnt(0)
; __device__ __forceinline__ f32x4 mfma16(bf16x8 a, bf16x8 b, f32x4 c) { return __builtin_amdgcn_mfma_f32_16x16x32_bf16(a, b, c, 0, 0, 0); }
; __device__ __forceinline__ void ret_apply_unit(LAS unsigned char* lds, const bf16* P, const bf16* PREV, bf16* BR, const float* dec, int u, int tid) {
;     ...
;             for (int ks = 0; ks < 8; ++ks) { const bf16x8 qf = ldrow(Qt, RSQ, 16 * w, 32 * ks, lane);
; #pragma unroll
;                 for (int mt = 0; mt < 8; ++mt) { const bf16x8 pf = ldrow(Pc, RSQ, 16 * mt, 32 * ks, lane); X[mt] = mfma16(pf, qf, X[mt]); } }
;             __syncthreads();
; #pragma unroll
;             for (int mt = 0; mt < 8; ++mt) acc[8 * eh + mt] = acc[8 * eh + mt] + X[mt] * qd;
	v_mfma_f32_16x16x32_bf16 v[80:83], v[104:107], v[100:103], v[80:83]
	ds_read_b128 v[104:107], v207 offset:25600
	s_waitcnt lgkmcnt(0)
	v_mfma_f32_16x16x32_bf16 v[84:87], v[104:107], v[100:103], v[84:87]
	ds_read_b128 v[104:107], v207 offset:34048
	s_waitcnt lgkmcnt(0)
	v_mfma_f32_16x16x32_bf16 v[88:91], v[104:107], v[100:103], v[88:91]
	ds_read_b128 v[104:107], v207 offset:42496
	s_waitcnt lgkmcnt(0)
	v_mfma_f32_16x16x32_bf16 v[92:95], v[104:107], v[100:103], v[92:95]
	ds_read_b128 v[104:107], v207 offset:50944
	s_waitcnt lgkmcnt(0)
	v_mfma_f32_16x16x32_bf16 v[96:99], v[104:107], v[100:103], v[96:99]
	ds_read_b128 v[104:107], v207 offset:59392
	s_waitcnt lgkmcnt(0)
	v_mfma_f32_16x16x32_bf16 v[2:5], v[104:107], v[100:103], v[2:5]
	ds_read_b128 v[100:103], v208 offset:320
	ds_read_b128 v[104:107], v207 offset:320
	s_waitcnt lgkmcnt(0)
	v_mfma_f32_16x16x32_bf16 v[72:75], v[104:107], v[100:103], v[72:75]
	ds_read_b128 v[104:107], v207 offset:8768
	s_waitcnt lgkmcnt(0)
	v_mfma_f32_16x16x32_bf16 v[76:79], v[104:107], v[100:103], v[76:79]
	ds_read_b128 v[104:107], v207 offset:17216
	s_waitcnt lgkmcnt(0)
	v_mfma_f32_16x16x32_bf16 v[80:83], v[104:107], v[100:103], v[80:83]
	ds_read_b128 v[104:107], v207 offset:25664
	s_waitcnt lgkmcnt(0)
	v_mfma_f32_16x16x32_bf16 v[84:87], v[104:107], v[100:103], v[84:87]
	ds_read_b128 v[104:107], v207 offset:34112
	s_waitcnt lgkmcnt(0)
	v_mfma_f32_16x16x32_bf16 v[88:91], v[104:107], v[100:103], v[88:91]
	ds_read_b128 v[104:107], v207 offset:42560
	s_waitcnt lgkmcnt(0)
	v_mfma_f32_16x16x32_bf16 v[92:95], v[104:107], v[100:103], v[92:95]
	ds_read_b128 v[104:107], v207 offset:51008
	s_waitcnt lgkmcnt(0)
	v_mfma_f32_16x16x32_bf16 v[96:99], v[104:107], v[100:103], v[96:99]
	ds_read_b128 v[104:107], v207 offset:59456
	s_waitcnt lgkmcnt(0)
	v_mfma_f32_16x16x32_bf16 v[2:5], v[104:107], v[100:103], v[2:5]
	ds_read_b128 v[100:103], v208 offset:384
	ds_read_b128 v[104:107], v207 offset:384
	s_waitcnt lgkmcnt(0)
	v_mfma_f32_16x16x32_bf16 v[72:75], v[104:107], v[100:103], v[72:75]
	ds_read_b128 v[104:107], v207 offset:8832
	s_waitcnt lgkmcnt(0)
	v_mfma_f32_16x16x32_bf16 v[76:79], v[104:107], v[100:103], v[76:79]
	ds_read_b128 v[104:107], v207 offset:17280
	s_waitcnt lgkmcnt(0)
	v_mfma_f32_16x16x32_bf16 v[80:83], v[104:107], v[100:103], v[80:83]
	ds_read_b128 v[104:107], v207 offset:25728
	s_waitcnt lgkmcnt(0)
	v_mfma_f32_16x16x32_bf16 v[84:87], v[104:107], v[100:103], v[84:87]
	ds_read_b128 v[104:107], v207 offset:34176
	s_waitcnt lgkmcnt(0)
	v_mfma_f32_16x16x32_bf16 v[88:91], v[104:107], v[100:103], v[88:91]
	ds_read_b128 v[104:107], v207 offset:42624
	s_waitcnt lgkmcnt(0)
	v_mfma_f32_16x16x32_bf16 v[92:95], v[104:107], v[100:103], v[92:95]
	ds_read_b128 v[104:107], v207 offset:51072
	s_waitcnt lgkmcnt(0)
	v_mfma_f32_16x16x32_bf16 v[96:99], v[104:107], v[100:103], v[96:99]
	ds_read_b128 v[104:107], v207 offset:59520
	s_waitcnt lgkmcnt(0)
	v_mfma_f32_16x16x32_bf16 v[2:5], v[104:107], v[100:103], v[2:5]
	ds_read_b128 v[100:103], v208 offset:448
	ds_read_b128 v[104:107], v207 offset:448
	s_waitcnt lgkmcnt(0)
	v_mfma_f32_16x16x32_bf16 v[72:75], v[104:107], v[100:103], v[72:75]
	ds_read_b128 v[104:107], v207 offset:8896
	s_waitcnt lgkmcnt(0)
	v_mfma_f32_16x16x32_bf16 v[76:79], v[104:107], v[100:103], v[76:79]
	ds_read_b128 v[104:107], v207 offset:17344
	s_nop 3
	v_pk_fma_f32 v[74:75], v[62:63], v[74:75], v[68:69] op_sel_hi:[0,1,1]
	v_pk_fma_f32 v[72:73], v[62:63], v[72:73], v[66:67] op_sel_hi:[0,1,1]
	s_waitcnt lgkmcnt(0)
	v_mfma_f32_16x16x32_bf16 v[80:83], v[104:107], v[100:103], v[80:83]
	ds_read_b128 v[104:107], v207 offset:25792
	v_pk_fma_f32 v[68:69], v[62:63], v[78:79], v[64:65] op_sel_hi:[0,1,1]
	v_pk_fma_f32 v[66:67], v[62:63], v[76:77], v[70:71] op_sel_hi:[0,1,1]
	s_waitcnt lgkmcnt(0)
	v_mfma_f32_16x16x32_bf16 v[84:87], v[104:107], v[100:103], v[84:87]
	ds_read_b128 v[104:107], v207 offset:34240
	s_nop 1
	v_pk_fma_f32 v[64:65], v[62:63], v[82:83], v[58:59] op_sel_hi:[0,1,1]
	v_pk_fma_f32 v[60:61], v[62:63], v[80:81], v[60:61] op_sel_hi:[0,1,1]
	s_waitcnt lgkmcnt(0)
	v_mfma_f32_16x16x32_bf16 v[88:91], v[104:107], v[100:103], v[88:91]
	ds_read_b128 v[104:107], v207 offset:42688
	v_pk_fma_f32 v[58:59], v[62:63], v[86:87], v[54:55] op_sel_hi:[0,1,1]
	v_pk_fma_f32 v[56:57], v[62:63], v[84:85], v[56:57] op_sel_hi:[0,1,1]
	s_waitcnt lgkmcnt(0)
	v_mfma_f32_16x16x32_bf16 v[92:95], v[104:107], v[100:103], v[92:95]
	ds_read_b128 v[104:107], v207 offset:51136
	s_nop 1
	v_pk_fma_f32 v[54:55], v[62:63], v[90:91], v[50:51] op_sel_hi:[0,1,1]
	v_pk_fma_f32 v[52:53], v[62:63], v[88:89], v[52:53] op_sel_hi:[0,1,1]
	s_waitcnt lgkmcnt(0)
	v_mfma_f32_16x16x32_bf16 v[96:99], v[104:107], v[100:103], v[96:99]
	ds_read_b128 v[104:107], v207 offset:59584
	v_pk_fma_f32 v[50:51], v[62:63], v[94:95], v[38:39] op_sel_hi:[0,1,1]
	v_pk_fma_f32 v[40:41], v[62:63], v[92:93], v[40:41] op_sel_hi:[0,1,1]
	s_waitcnt lgkmcnt(0)
; __device__ __forceinline__ float shx(float v, int o, int lane) { return __int_as_float(__builtin_amdgcn_ds_bpermute((lane ^ o) << 2, __float_as_int(v))); }
; __device__ __forceinline__ void ret_apply_unit(LAS unsigned char* lds, const bf16* P, const bf16* PREV, bf16* BR, const float* dec, int u, int tid) {
;     ...
;             for (int mt = 0; mt < 8; ++mt) acc[8 * eh + mt] = acc[8 * eh + mt] + X[mt] * qd;
;         }
;     }
;     float sm = 0.f;
; #pragma unroll
;     for (int mt = 0; mt < 16; ++mt) sm += (acc[mt][0] + acc[mt][1]) + (acc[mt][2] + acc[mt][3]);
;     sm += shx(sm, 16, lane); sm += shx(sm, 32, lane);
;     const float mean = sm * (1.f / 256.f); float sq = 0.f;
; #pragma unroll
;     for (int mt = 0; mt < 16; ++mt) { const f32x4 d = acc[mt] - mean; sq += (d[0] * d[0] + d[1] * d[1]) + (d[2] * d[2] + d[3] * d[3]); }
;     sq += shx(sq, 16, lane); sq += shx(sq, 32, lane);
	v_mfma_f32_16x16x32_bf16 v[2:5], v[104:107], v[100:103], v[2:5]
	s_nop 2
	v_fma_f32 v38, v62, v98, v22
	v_fma_f32 v39, v62, v99, v23
	v_pk_fma_f32 v[22:23], v[62:63], v[96:97], v[24:25] op_sel_hi:[0,1,1]
	v_mov_b32_e32 v24, v10
	s_nop 0
	v_pk_fma_f32 v[4:5], v[62:63], v[4:5], v[14:15] op_sel_hi:[0,1,1]
	v_pk_fma_f32 v[2:3], v[62:63], v[2:3], v[16:17] op_sel_hi:[0,1,1]
	v_pk_mov_b32 v[14:15], v[6:7], v[8:9] op_sel:[1,0]
	v_mov_b32_e32 v16, v6
	v_mov_b32_e32 v17, v9
	v_pk_add_f32 v[14:15], v[14:15], v[16:17]
	v_pk_mov_b32 v[16:17], v[10:11], v[12:13] op_sel:[1,0]
	v_mov_b32_e32 v25, v13
	v_pk_add_f32 v[16:17], v[16:17], v[24:25]
	v_add_f32_e32 v14, v14, v15
	v_pk_add_f32 v[16:17], v[16:17], v[16:17] op_sel:[0,1] op_sel_hi:[1,0]
	v_add_f32_e32 v14, 0, v14
	v_add_f32_e32 v24, v18, v19
	v_add_f32_e32 v62, v20, v21
	v_mov_b32_e32 v15, v26
	v_mov_b32_e32 v17, v27
	v_mov_b32_e32 v25, v28
	v_mov_b32_e32 v63, v29
	v_pk_add_f32 v[14:15], v[14:15], v[16:17]
	v_pk_add_f32 v[16:17], v[24:25], v[62:63]
	v_mov_b32_e32 v24, v30
	v_pk_add_f32 v[14:15], v[14:15], v[16:17]
	v_pk_mov_b32 v[16:17], v[30:31], v[32:33] op_sel:[1,0]
	v_mov_b32_e32 v25, v33
	v_pk_add_f32 v[16:17], v[16:17], v[24:25]
	v_pk_add_f32 v[14:15], v[14:15], v[14:15] op_sel:[0,1] op_sel_hi:[1,0]
	v_pk_add_f32 v[16:17], v[16:17], v[16:17] op_sel:[0,1] op_sel_hi:[1,0]
	v_add_f32_e32 v24, v34, v35
	v_add_f32_e32 v62, v36, v37
	v_mov_b32_e32 v15, v42
	v_mov_b32_e32 v17, v43
	v_mov_b32_e32 v25, v44
	v_mov_b32_e32 v63, v45
	v_pk_add_f32 v[14:15], v[14:15], v[16:17]
	v_pk_add_f32 v[16:17], v[24:25], v[62:63]
	v_mov_b32_e32 v24, v46
	v_pk_add_f32 v[14:15], v[14:15], v[16:17]
	v_pk_mov_b32 v[16:17], v[46:47], v[48:49] op_sel:[1,0]
	v_mov_b32_e32 v25, v49
	v_pk_add_f32 v[16:17], v[16:17], v[24:25]
	v_pk_add_f32 v[14:15], v[14:15], v[14:15] op_sel:[0,1] op_sel_hi:[1,0]
	v_pk_add_f32 v[16:17], v[16:17], v[16:17] op_sel:[0,1] op_sel_hi:[1,0]
	v_add_f32_e32 v24, v72, v73
	v_add_f32_e32 v62, v74, v75
	v_mov_b32_e32 v15, v66
	v_mov_b32_e32 v17, v67
	v_mov_b32_e32 v25, v68
	v_mov_b32_e32 v63, v69
	v_pk_add_f32 v[14:15], v[14:15], v[16:17]
	v_pk_add_f32 v[16:17], v[24:25], v[62:63]
	v_mov_b32_e32 v24, v60
	v_pk_add_f32 v[14:15], v[14:15], v[16:17]
	v_pk_mov_b32 v[16:17], v[60:61], v[64:65] op_sel:[1,0]
	v_mov_b32_e32 v25, v65
	v_pk_add_f32 v[16:17], v[16:17], v[24:25]
	v_pk_add_f32 v[14:15], v[14:15], v[14:15] op_sel:[0,1] op_sel_hi:[1,0]
	v_pk_add_f32 v[16:17], v[16:17], v[16:17] op_sel:[0,1] op_sel_hi:[1,0]
	v_add_f32_e32 v24, v56, v57
	v_add_f32_e32 v62, v58, v59
	v_mov_b32_e32 v15, v52
	v_mov_b32_e32 v17, v53
	v_mov_b32_e32 v25, v54
	v_mov_b32_e32 v63, v55
	v_pk_add_f32 v[14:15], v[14:15], v[16:17]
	v_pk_add_f32 v[16:17], v[24:25], v[62:63]
	v_mov_b32_e32 v24, v40
	v_pk_add_f32 v[14:15], v[14:15], v[16:17]
	v_pk_mov_b32 v[16:17], v[40:41], v[50:51] op_sel:[1,0]
	v_mov_b32_e32 v25, v51
	v_pk_add_f32 v[16:17], v[16:17], v[24:25]
	v_pk_add_f32 v[14:15], v[14:15], v[14:15] op_sel:[0,1] op_sel_hi:[1,0]
	v_pk_add_f32 v[16:17], v[16:17], v[16:17] op_sel:[0,1] op_sel_hi:[1,0]
	v_add_f32_e32 v24, v22, v23
	v_add_f32_e32 v62, v38, v39
	v_mov_b32_e32 v15, v2
	v_mov_b32_e32 v17, v3
	v_mov_b32_e32 v25, v4
	v_mov_b32_e32 v63, v5
	v_pk_add_f32 v[14:15], v[14:15], v[16:17]
	v_pk_add_f32 v[16:17], v[24:25], v[62:63]
	s_nop 0
	v_pk_add_f32 v[14:15], v[14:15], v[16:17]
	s_barrier
	v_add_f32_e32 v14, v14, v15
	v_lshlrev_b32_e32 v15, 2, v206
	v_xor_b32_e32 v70, 64, v15
	ds_bpermute_b32 v16, v70, v14
	v_xor_b32_e32 v71, 0x80, v15
	s_waitcnt lgkmcnt(0)
	v_add_f32_e32 v14, v14, v16
	ds_bpermute_b32 v15, v71, v14
	s_waitcnt lgkmcnt(0)
	v_add_f32_e32 v76, v14, v15
	v_fmamk_f32 v7, v76, 0xbb800000, v7
	v_fmac_f32_e32 v6, 0xbb800000, v76
	v_fmamk_f32 v9, v76, 0xbb800000, v9
	v_fmac_f32_e32 v8, 0xbb800000, v76
	v_pk_mul_f32 v[14:15], v[8:9], v[8:9]
	v_pk_mul_f32 v[16:17], v[6:7], v[6:7]
	v_fmamk_f32 v11, v76, 0xbb800000, v11
	v_pk_mov_b32 v[24:25], v[16:17], v[14:15] op_sel:[1,0]
	v_mov_b32_e32 v17, v15
	v_pk_add_f32 v[14:15], v[24:25], v[16:17]
	v_fmac_f32_e32 v10, 0xbb800000, v76
	v_fmamk_f32 v13, v76, 0xbb800000, v13
	v_fmac_f32_e32 v12, 0xbb800000, v76
	v_pk_add_f32 v[14:15], v[14:15], v[14:15] op_sel_hi:[0,1]
	v_pk_mul_f32 v[16:17], v[12:13], v[12:13]
	v_pk_mul_f32 v[24:25], v[10:11], v[10:11]
	v_fmac_f32_e32 v18, 0xbb800000, v76
	v_pk_mov_b32 v[62:63], v[24:25], v[16:17] op_sel:[1,0]
	v_mov_b32_e32 v25, v17
	v_fmamk_f32 v19, v76, 0xbb800000, v19
	v_fmac_f32_e32 v20, 0xbb800000, v76
	v_mul_f32_e32 v14, v18, v18
	v_pk_add_f32 v[16:17], v[62:63], v[24:25]
	v_fmamk_f32 v21, v76, 0xbb800000, v21
	v_pk_fma_f32 v[24:25], v[18:19], v[18:19], v[14:15] op_sel_hi:[1,1,0]
	v_mul_f32_e32 v14, v20, v20
	v_pk_add_f32 v[16:17], v[16:17], v[16:17] op_sel_hi:[0,1]
	v_pk_fma_f32 v[62:63], v[20:21], v[20:21], v[14:15] op_sel_hi:[1,1,0]
	v_fmamk_f32 v29, v76, 0xbb800000, v29
	v_fmac_f32_e32 v28, 0xbb800000, v76
	v_fmamk_f32 v27, v76, 0xbb800000, v27
	v_fmac_f32_e32 v26, 0xbb800000, v76
	v_mul_f32_e32 v24, v26, v26
	v_mul_f32_e32 v62, v27, v27
	v_mul_f32_e32 v14, v28, v28
	v_mul_f32_e32 v16, v29, v29
	v_pk_add_f32 v[24:25], v[24:25], v[62:63]
	v_pk_add_f32 v[14:15], v[14:15], v[16:17]
	v_fmamk_f32 v31, v76, 0xbb800000, v31
	v_pk_add_f32 v[14:15], v[24:25], v[14:15]
	v_fmac_f32_e32 v30, 0xbb800000, v76
	v_fmamk_f32 v33, v76, 0xbb800000, v33
	v_fmac_f32_e32 v32, 0xbb800000, v76
	v_pk_add_f32 v[14:15], v[14:15], v[14:15] op_sel_hi:[0,1]
	v_pk_mul_f32 v[16:17], v[32:33], v[32:33]
	v_pk_mul_f32 v[24:25], v[30:31], v[30:31]
	v_fmac_f32_e32 v34, 0xbb800000, v76
	v_pk_mov_b32 v[62:63], v[24:25], v[16:17] op_sel:[1,0]
	v_mov_b32_e32 v25, v17
; __device__ __forceinline__ unsigned pk2(float lo, float hi) { return pg8::cvt_pk_bf16(lo, hi); }
; __device__ __forceinline__ float bflo(unsigned w) { return __uint_as_float(w << 16); }
; __device__ __forceinline__ float bfhi(unsigned w) { return __uint_as_float(w & 0xffff0000u); }
; __device__ __forceinline__ float shx(float v, int o, int lane) { return __int_as_float(__builtin_amdgcn_ds_bpermute((lane ^ o) << 2, __float_as_int(v))); }
; __device__ __forceinline__ void ret_apply_unit(LAS unsigned char* lds, const bf16* P, const bf16* PREV, bf16* BR, const float* dec, int u, int tid) {
;     ...
;     float sm = 0.f;
; #pragma unroll
;     for (int mt = 0; mt < 16; ++mt) sm += (acc[mt][0] + acc[mt][1]) + (acc[mt][2] + acc[mt][3]);
;     sm += shx(sm, 16, lane); sm += shx(sm, 32, lane);
;     const float mean = sm * (1.f / 256.f); float sq = 0.f;
; #pragma unroll
;     for (int mt = 0; mt < 16; ++mt) { const f32x4 d = acc[mt] - mean; sq += (d[0] * d[0] + d[1] * d[1]) + (d[2] * d[2] + d[3] * d[3]); }
;     sq += shx(sq, 16, lane); sq += shx(sq, 32, lane);
;     const float rstd = 1.f / sqrtf(sq * (1.f / 256.f) + LN_EPS);
; #pragma unroll
;     for (int mt = 0; mt < 16; ++mt) { const int e = 16 * mt + 4 * g;
;         const f32x4 d = (acc[mt] - mean) * rstd;
;         u32x2 o; o.x = pk2(d[0] * bflo(gw[mt].x), d[1] * bfhi(gw[mt].x)); o.y = pk2(d[2] * bflo(gw[mt].y), d[3] * bfhi(gw[mt].y));
	v_fmamk_f32 v35, v76, 0xbb800000, v35
	v_fmac_f32_e32 v36, 0xbb800000, v76
	v_mul_f32_e32 v14, v34, v34
	v_pk_add_f32 v[16:17], v[62:63], v[24:25]
	v_fmamk_f32 v37, v76, 0xbb800000, v37
	v_pk_fma_f32 v[24:25], v[34:35], v[34:35], v[14:15] op_sel_hi:[1,1,0]
	v_mul_f32_e32 v14, v36, v36
	v_pk_add_f32 v[16:17], v[16:17], v[16:17] op_sel_hi:[0,1]
	v_pk_fma_f32 v[62:63], v[36:37], v[36:37], v[14:15] op_sel_hi:[1,1,0]
	v_fmamk_f32 v45, v76, 0xbb800000, v45
	v_fmac_f32_e32 v44, 0xbb800000, v76
	v_fmamk_f32 v43, v76, 0xbb800000, v43
	v_fmac_f32_e32 v42, 0xbb800000, v76
	v_mul_f32_e32 v24, v42, v42
	v_mul_f32_e32 v62, v43, v43
	v_mul_f32_e32 v16, v44, v44
	v_mul_f32_e32 v14, v45, v45
	v_pk_add_f32 v[24:25], v[24:25], v[62:63]
	v_pk_add_f32 v[14:15], v[16:17], v[14:15]
	v_fmamk_f32 v47, v76, 0xbb800000, v47
	v_pk_add_f32 v[14:15], v[24:25], v[14:15]
	v_fmac_f32_e32 v46, 0xbb800000, v76
	v_fmamk_f32 v49, v76, 0xbb800000, v49
	v_fmac_f32_e32 v48, 0xbb800000, v76
	v_pk_add_f32 v[14:15], v[14:15], v[14:15] op_sel_hi:[0,1]
	v_pk_mul_f32 v[16:17], v[48:49], v[48:49]
	v_pk_mul_f32 v[24:25], v[46:47], v[46:47]
	v_fmac_f32_e32 v72, 0xbb800000, v76
	v_pk_mov_b32 v[62:63], v[24:25], v[16:17] op_sel:[1,0]
	v_mov_b32_e32 v25, v17
	v_fmamk_f32 v73, v76, 0xbb800000, v73
	v_fmac_f32_e32 v74, 0xbb800000, v76
	v_mul_f32_e32 v14, v72, v72
	v_pk_add_f32 v[16:17], v[62:63], v[24:25]
	v_fmamk_f32 v75, v76, 0xbb800000, v75
	v_pk_fma_f32 v[24:25], v[72:73], v[72:73], v[14:15] op_sel_hi:[1,1,0]
	v_mul_f32_e32 v14, v74, v74
	v_pk_add_f32 v[16:17], v[16:17], v[16:17] op_sel_hi:[0,1]
	v_pk_fma_f32 v[62:63], v[74:75], v[74:75], v[14:15] op_sel_hi:[1,1,0]
	v_fmamk_f32 v69, v76, 0xbb800000, v69
	v_fmac_f32_e32 v68, 0xbb800000, v76
	v_fmamk_f32 v67, v76, 0xbb800000, v67
	v_fmac_f32_e32 v66, 0xbb800000, v76
	v_mul_f32_e32 v24, v66, v66
	v_mul_f32_e32 v62, v67, v67
	v_mul_f32_e32 v16, v68, v68
	v_mul_f32_e32 v14, v69, v69
	v_pk_add_f32 v[24:25], v[24:25], v[62:63]
	v_pk_add_f32 v[14:15], v[16:17], v[14:15]
	v_fmamk_f32 v61, v76, 0xbb800000, v61
	v_pk_add_f32 v[14:15], v[24:25], v[14:15]
	v_fmac_f32_e32 v60, 0xbb800000, v76
	v_fmamk_f32 v65, v76, 0xbb800000, v65
	v_fmac_f32_e32 v64, 0xbb800000, v76
	v_pk_add_f32 v[14:15], v[14:15], v[14:15] op_sel_hi:[0,1]
	v_pk_mul_f32 v[16:17], v[64:65], v[64:65]
	v_pk_mul_f32 v[24:25], v[60:61], v[60:61]
	v_fmac_f32_e32 v56, 0xbb800000, v76
	v_pk_mov_b32 v[62:63], v[24:25], v[16:17] op_sel:[1,0]
	v_mov_b32_e32 v25, v17
	v_fmamk_f32 v57, v76, 0xbb800000, v57
	v_fmac_f32_e32 v58, 0xbb800000, v76
	v_mul_f32_e32 v14, v56, v56
	v_pk_add_f32 v[16:17], v[62:63], v[24:25]
	v_fmamk_f32 v59, v76, 0xbb800000, v59
	v_pk_fma_f32 v[24:25], v[56:57], v[56:57], v[14:15] op_sel_hi:[1,1,0]
	v_mul_f32_e32 v14, v58, v58
	v_pk_add_f32 v[16:17], v[16:17], v[16:17] op_sel_hi:[0,1]
	v_pk_fma_f32 v[62:63], v[58:59], v[58:59], v[14:15] op_sel_hi:[1,1,0]
	v_fmamk_f32 v55, v76, 0xbb800000, v55
	v_fmac_f32_e32 v54, 0xbb800000, v76
	v_fmamk_f32 v53, v76, 0xbb800000, v53
	v_fmac_f32_e32 v52, 0xbb800000, v76
	v_mul_f32_e32 v24, v52, v52
	v_mul_f32_e32 v62, v53, v53
	v_mul_f32_e32 v16, v54, v54
	v_mul_f32_e32 v14, v55, v55
	v_pk_add_f32 v[24:25], v[24:25], v[62:63]
	v_pk_add_f32 v[14:15], v[16:17], v[14:15]
	v_fmamk_f32 v41, v76, 0xbb800000, v41
	v_pk_add_f32 v[14:15], v[24:25], v[14:15]
	v_fmac_f32_e32 v40, 0xbb800000, v76
	v_fmamk_f32 v51, v76, 0xbb800000, v51
	v_fmac_f32_e32 v50, 0xbb800000, v76
	v_pk_add_f32 v[14:15], v[14:15], v[14:15] op_sel_hi:[0,1]
	v_pk_mul_f32 v[16:17], v[50:51], v[50:51]
	v_pk_mul_f32 v[24:25], v[40:41], v[40:41]
	v_fmac_f32_e32 v22, 0xbb800000, v76
	v_pk_mov_b32 v[62:63], v[24:25], v[16:17] op_sel:[1,0]
	v_mov_b32_e32 v25, v17
	v_fmamk_f32 v23, v76, 0xbb800000, v23
	v_fmac_f32_e32 v38, 0xbb800000, v76
	v_mul_f32_e32 v14, v22, v22
	v_pk_add_f32 v[16:17], v[62:63], v[24:25]
	v_fmamk_f32 v39, v76, 0xbb800000, v39
	v_pk_fma_f32 v[24:25], v[22:23], v[22:23], v[14:15] op_sel_hi:[1,1,0]
	v_mul_f32_e32 v14, v38, v38
	v_pk_add_f32 v[16:17], v[16:17], v[16:17] op_sel_hi:[0,1]
	v_pk_fma_f32 v[62:63], v[38:39], v[38:39], v[14:15] op_sel_hi:[1,1,0]
	v_fmamk_f32 v5, v76, 0xbb800000, v5
	v_fmac_f32_e32 v4, 0xbb800000, v76
	v_fmamk_f32 v3, v76, 0xbb800000, v3
	v_fmac_f32_e32 v2, 0xbb800000, v76
	v_mul_f32_e32 v24, v2, v2
	v_mul_f32_e32 v62, v3, v3
	v_mul_f32_e32 v16, v4, v4
	v_mul_f32_e32 v14, v5, v5
	v_pk_add_f32 v[24:25], v[24:25], v[62:63]
	v_pk_add_f32 v[14:15], v[16:17], v[14:15]
	s_nop 0
	v_pk_add_f32 v[14:15], v[24:25], v[14:15]
	s_nop 0
	v_add_f32_e32 v14, v14, v15
	ds_bpermute_b32 v15, v70, v14
	s_waitcnt lgkmcnt(0)
	v_add_f32_e32 v14, v14, v15
	ds_bpermute_b32 v15, v71, v14
	s_waitcnt lgkmcnt(0)
	v_add_f32_e32 v14, v14, v15
	v_fmamk_f32 v14, v14, 0x3b800000, v228
	v_cmp_gt_f32_e32 vcc, s9, v14
	v_mul_f32_e32 v15, 0x4f800000, v14
	s_movk_i32 s9, 0x1800
	v_cndmask_b32_e32 v14, v14, v15, vcc
	v_sqrt_f32_e32 v15, v14
	s_nop 0
	v_add_u32_e32 v16, -1, v15
	v_fma_f32 v17, -v16, v15, v14
	v_cmp_ge_f32_e64 s[36:37], 0, v17
	v_add_u32_e32 v17, 1, v15
	s_nop 0
	v_cndmask_b32_e64 v16, v15, v16, s[36:37]
	v_fma_f32 v15, -v17, v15, v14
	v_cmp_lt_f32_e64 s[36:37], 0, v15
	s_nop 1
	v_cndmask_b32_e64 v15, v16, v17, s[36:37]
	v_mul_f32_e32 v16, 0x37800000, v15
	v_cndmask_b32_e32 v15, v15, v16, vcc
	v_cmp_class_f32_e32 vcc, v14, v205
	s_nop 1
	v_cndmask_b32_e32 v14, v15, v14, vcc
	v_div_scale_f32 v15, s[12:13], v14, v14, 1.0
	v_rcp_f32_e32 v16, v15
	s_nop 0
	v_fma_f32 v17, -v15, v16, 1.0
	v_fmac_f32_e32 v16, v17, v16
	v_div_scale_f32 v17, vcc, 1.0, v14, 1.0
	v_mul_f32_e32 v24, v17, v16
	v_fma_f32 v25, -v15, v24, v17
	v_fmac_f32_e32 v24, v25, v16
	v_fma_f32 v15, -v15, v24, v17
	v_div_fmas_f32 v15, v15, v16, v24
	v_div_fixup_f32 v14, v15, v14, 1.0
	v_pk_mul_f32 v[6:7], v[6:7], v[14:15] op_sel_hi:[1,0]
	s_waitcnt vmcnt(0)
; __device__ __forceinline__ unsigned pk2(float lo, float hi) { return pg8::cvt_pk_bf16(lo, hi); }
; __device__ __forceinline__ float bflo(unsigned w) { return __uint_as_float(w << 16); }
; __device__ __forceinline__ float bfhi(unsigned w) { return __uint_as_float(w & 0xffff0000u); }
; __device__ __forceinline__ void ret_apply_unit(LAS unsigned char* lds, const bf16* P, const bf16* PREV, bf16* BR, const float* dec, int u, int tid) {
;     ...
; #pragma unroll
;     for (int mt = 0; mt < 16; ++mt) { const int e = 16 * mt + 4 * g;
;         const f32x4 d = (acc[mt] - mean) * rstd;
;         u32x2 o; o.x = pk2(d[0] * bflo(gw[mt].x), d[1] * bfhi(gw[mt].x)); o.y = pk2(d[2] * bflo(gw[mt].y), d[3] * bfhi(gw[mt].y));
;         *(u32x2*)(BR + tok * 3072 + h * 256 + e) = o; }
	v_lshlrev_b32_e32 v24, 16, v164
	v_and_b32_e32 v25, 0xffff0000, v164
	v_pk_mul_f32 v[6:7], v[6:7], v[24:25]
	v_mov_b64_e32 v[16:17], s[4:5]
	v_pk_mul_f32 v[8:9], v[8:9], v[14:15] op_sel_hi:[1,0]
	v_cvt_pk_bf16_f32 v24, v6, v7
	v_lshlrev_b32_e32 v6, 16, v165
	v_and_b32_e32 v7, 0xffff0000, v165
	v_mad_u64_u32 v[16:17], s[12:13], v160, s9, v[16:17]
	v_pk_mul_f32 v[6:7], v[8:9], v[6:7]
	v_pk_mul_f32 v[8:9], v[12:13], v[14:15] op_sel_hi:[1,0]
	v_pk_mul_f32 v[10:11], v[10:11], v[14:15] op_sel_hi:[1,0]
	v_lshlrev_b32_e32 v12, 16, v158
	v_and_b32_e32 v13, 0xffff0000, v158
	v_mad_i32_i24 v17, v161, s9, v17
	v_pk_mul_f32 v[10:11], v[10:11], v[12:13]
	v_lshlrev_b32_e32 v12, 16, v159
	v_and_b32_e32 v13, 0xffff0000, v159
	v_lshl_add_u64 v[16:17], v[16:17], 0, s[26:27]
	v_pk_mul_f32 v[8:9], v[8:9], v[12:13]
	v_cvt_pk_bf16_f32 v25, v6, v7
	v_lshl_add_u64 v[6:7], v[16:17], 0, v[0:1]
	v_cvt_pk_bf16_f32 v10, v10, v11
	v_cvt_pk_bf16_f32 v11, v8, v9
	global_store_dwordx2 v[6:7], v[10:11], off offset:32
	v_pk_mul_f32 v[10:11], v[18:19], v[14:15] op_sel_hi:[1,0]
	v_lshlrev_b32_e32 v12, 16, v156
	v_and_b32_e32 v13, 0xffff0000, v156
	v_pk_mul_f32 v[8:9], v[20:21], v[14:15] op_sel_hi:[1,0]
	v_pk_mul_f32 v[10:11], v[10:11], v[12:13]
	v_lshlrev_b32_e32 v12, 16, v157
	v_and_b32_e32 v13, 0xffff0000, v157
	v_pk_mul_f32 v[8:9], v[8:9], v[12:13]
	v_cvt_pk_bf16_f32 v10, v10, v11
	v_cvt_pk_bf16_f32 v11, v8, v9
	global_store_dwordx2 v[6:7], v[10:11], off offset:64
	v_pk_mul_f32 v[10:11], v[26:27], v[14:15] op_sel_hi:[1,0]
	v_lshlrev_b32_e32 v12, 16, v154
	v_and_b32_e32 v13, 0xffff0000, v154
	v_pk_mul_f32 v[8:9], v[28:29], v[14:15] op_sel_hi:[1,0]
	v_pk_mul_f32 v[10:11], v[10:11], v[12:13]
	v_lshlrev_b32_e32 v12, 16, v155
	v_and_b32_e32 v13, 0xffff0000, v155
	v_pk_mul_f32 v[8:9], v[8:9], v[12:13]
	v_cvt_pk_bf16_f32 v10, v10, v11
	v_cvt_pk_bf16_f32 v11, v8, v9
	global_store_dwordx2 v[6:7], v[10:11], off offset:96
	v_pk_mul_f32 v[10:11], v[30:31], v[14:15] op_sel_hi:[1,0]
	v_lshlrev_b32_e32 v12, 16, v152
	v_and_b32_e32 v13, 0xffff0000, v152
	v_pk_mul_f32 v[8:9], v[32:33], v[14:15] op_sel_hi:[1,0]
	v_pk_mul_f32 v[10:11], v[10:11], v[12:13]
	v_lshlrev_b32_e32 v12, 16, v153
	v_and_b32_e32 v13, 0xffff0000, v153
	v_pk_mul_f32 v[8:9], v[8:9], v[12:13]
	v_cvt_pk_bf16_f32 v10, v10, v11
	v_cvt_pk_bf16_f32 v11, v8, v9
	global_store_dwordx2 v[6:7], v[10:11], off offset:128
	v_pk_mul_f32 v[10:11], v[34:35], v[14:15] op_sel_hi:[1,0]
	v_lshlrev_b32_e32 v12, 16, v150
	v_and_b32_e32 v13, 0xffff0000, v150
	v_pk_mul_f32 v[8:9], v[36:37], v[14:15] op_sel_hi:[1,0]
	v_pk_mul_f32 v[10:11], v[10:11], v[12:13]
	v_lshlrev_b32_e32 v12, 16, v151
	v_and_b32_e32 v13, 0xffff0000, v151
	v_pk_mul_f32 v[8:9], v[8:9], v[12:13]
	v_cvt_pk_bf16_f32 v10, v10, v11
	v_cvt_pk_bf16_f32 v11, v8, v9
	global_store_dwordx2 v[6:7], v[10:11], off offset:160
	v_pk_mul_f32 v[10:11], v[42:43], v[14:15] op_sel_hi:[1,0]
	v_lshlrev_b32_e32 v12, 16, v148
	v_and_b32_e32 v13, 0xffff0000, v148
	v_pk_mul_f32 v[8:9], v[44:45], v[14:15] op_sel_hi:[1,0]
	v_pk_mul_f32 v[10:11], v[10:11], v[12:13]
	v_lshlrev_b32_e32 v12, 16, v149
	v_and_b32_e32 v13, 0xffff0000, v149
	v_pk_mul_f32 v[8:9], v[8:9], v[12:13]
	v_cvt_pk_bf16_f32 v10, v10, v11
	v_cvt_pk_bf16_f32 v11, v8, v9
	global_store_dwordx2 v[6:7], v[10:11], off offset:192
	v_pk_mul_f32 v[10:11], v[46:47], v[14:15] op_sel_hi:[1,0]
	v_lshlrev_b32_e32 v12, 16, v146
	v_and_b32_e32 v13, 0xffff0000, v146
	v_pk_mul_f32 v[8:9], v[48:49], v[14:15] op_sel_hi:[1,0]
	v_pk_mul_f32 v[10:11], v[10:11], v[12:13]
	v_lshlrev_b32_e32 v12, 16, v147
	v_and_b32_e32 v13, 0xffff0000, v147
	v_pk_mul_f32 v[8:9], v[8:9], v[12:13]
	v_cvt_pk_bf16_f32 v10, v10, v11
	v_cvt_pk_bf16_f32 v11, v8, v9
	global_store_dwordx2 v[6:7], v[10:11], off offset:224
; __device__ __forceinline__ unsigned pk2(float lo, float hi) { return pg8::cvt_pk_bf16(lo, hi); }
; __device__ __forceinline__ float bflo(unsigned w) { return __uint_as_float(w << 16); }
; __device__ __forceinline__ float bfhi(unsigned w) { return __uint_as_float(w & 0xffff0000u); }
; __device__ __forceinline__ void ret_apply_unit(LAS unsigned char* lds, const bf16* P, const bf16* PREV, bf16* BR, const float* dec, int u, int tid) {
;     ...
; #pragma unroll
;     for (int mt = 0; mt < 16; ++mt) { const int e = 16 * mt + 4 * g;
;         const f32x4 d = (acc[mt] - mean) * rstd;
;         u32x2 o; o.x = pk2(d[0] * bflo(gw[mt].x), d[1] * bfhi(gw[mt].x)); o.y = pk2(d[2] * bflo(gw[mt].y), d[3] * bfhi(gw[mt].y));
;         *(u32x2*)(BR + tok * 3072 + h * 256 + e) = o; }
;     __syncthreads();
	v_pk_mul_f32 v[10:11], v[72:73], v[14:15] op_sel_hi:[1,0]
	v_lshlrev_b32_e32 v12, 16, v144
	v_and_b32_e32 v13, 0xffff0000, v144
	v_pk_mul_f32 v[8:9], v[74:75], v[14:15] op_sel_hi:[1,0]
	v_pk_mul_f32 v[10:11], v[10:11], v[12:13]
	v_lshlrev_b32_e32 v12, 16, v145
	v_and_b32_e32 v13, 0xffff0000, v145
	v_pk_mul_f32 v[8:9], v[8:9], v[12:13]
	v_cvt_pk_bf16_f32 v10, v10, v11
	v_cvt_pk_bf16_f32 v11, v8, v9
	global_store_dwordx2 v[6:7], v[10:11], off offset:256
	v_pk_mul_f32 v[10:11], v[66:67], v[14:15] op_sel_hi:[1,0]
	v_lshlrev_b32_e32 v12, 16, v142
	v_and_b32_e32 v13, 0xffff0000, v142
	v_pk_mul_f32 v[8:9], v[68:69], v[14:15] op_sel_hi:[1,0]
	v_pk_mul_f32 v[10:11], v[10:11], v[12:13]
	v_lshlrev_b32_e32 v12, 16, v143
	v_and_b32_e32 v13, 0xffff0000, v143
	v_pk_mul_f32 v[8:9], v[8:9], v[12:13]
	v_cvt_pk_bf16_f32 v10, v10, v11
	v_cvt_pk_bf16_f32 v11, v8, v9
	global_store_dwordx2 v[6:7], v[10:11], off offset:288
	v_pk_mul_f32 v[10:11], v[60:61], v[14:15] op_sel_hi:[1,0]
	v_lshlrev_b32_e32 v12, 16, v140
	v_and_b32_e32 v13, 0xffff0000, v140
	v_pk_mul_f32 v[8:9], v[64:65], v[14:15] op_sel_hi:[1,0]
	v_pk_mul_f32 v[10:11], v[10:11], v[12:13]
	v_lshlrev_b32_e32 v12, 16, v141
	v_and_b32_e32 v13, 0xffff0000, v141
	v_pk_mul_f32 v[8:9], v[8:9], v[12:13]
	v_cvt_pk_bf16_f32 v10, v10, v11
	v_cvt_pk_bf16_f32 v11, v8, v9
	global_store_dwordx2 v[6:7], v[10:11], off offset:320
	v_pk_mul_f32 v[10:11], v[56:57], v[14:15] op_sel_hi:[1,0]
	v_lshlrev_b32_e32 v12, 16, v138
	v_and_b32_e32 v13, 0xffff0000, v138
	v_pk_mul_f32 v[8:9], v[58:59], v[14:15] op_sel_hi:[1,0]
	v_pk_mul_f32 v[10:11], v[10:11], v[12:13]
	v_lshlrev_b32_e32 v12, 16, v139
	v_and_b32_e32 v13, 0xffff0000, v139
	v_pk_mul_f32 v[8:9], v[8:9], v[12:13]
	v_cvt_pk_bf16_f32 v10, v10, v11
	v_cvt_pk_bf16_f32 v11, v8, v9
	global_store_dwordx2 v[6:7], v[10:11], off offset:352
	v_pk_mul_f32 v[10:11], v[52:53], v[14:15] op_sel_hi:[1,0]
	v_lshlrev_b32_e32 v12, 16, v136
	v_and_b32_e32 v13, 0xffff0000, v136
	v_pk_mul_f32 v[8:9], v[54:55], v[14:15] op_sel_hi:[1,0]
	v_pk_mul_f32 v[10:11], v[10:11], v[12:13]
	v_lshlrev_b32_e32 v12, 16, v137
	v_and_b32_e32 v13, 0xffff0000, v137
	v_pk_mul_f32 v[8:9], v[8:9], v[12:13]
	v_cvt_pk_bf16_f32 v10, v10, v11
	v_cvt_pk_bf16_f32 v11, v8, v9
	global_store_dwordx2 v[6:7], v[10:11], off offset:384
	v_pk_mul_f32 v[10:11], v[40:41], v[14:15] op_sel_hi:[1,0]
	v_lshlrev_b32_e32 v12, 16, v134
	v_and_b32_e32 v13, 0xffff0000, v134
	v_pk_mul_f32 v[8:9], v[50:51], v[14:15] op_sel_hi:[1,0]
	v_pk_mul_f32 v[10:11], v[10:11], v[12:13]
	v_lshlrev_b32_e32 v12, 16, v135
	v_and_b32_e32 v13, 0xffff0000, v135
	v_pk_mul_f32 v[8:9], v[8:9], v[12:13]
	v_cvt_pk_bf16_f32 v10, v10, v11
	v_cvt_pk_bf16_f32 v11, v8, v9
	global_store_dwordx2 v[6:7], v[10:11], off offset:416
	v_pk_mul_f32 v[10:11], v[22:23], v[14:15] op_sel_hi:[1,0]
	v_lshlrev_b32_e32 v12, 16, v132
	v_and_b32_e32 v13, 0xffff0000, v132
	v_pk_mul_f32 v[8:9], v[38:39], v[14:15] op_sel_hi:[1,0]
	v_pk_mul_f32 v[10:11], v[10:11], v[12:13]
	v_lshlrev_b32_e32 v12, 16, v133
	v_and_b32_e32 v13, 0xffff0000, v133
	v_pk_mul_f32 v[8:9], v[8:9], v[12:13]
	v_cvt_pk_bf16_f32 v10, v10, v11
	v_cvt_pk_bf16_f32 v11, v8, v9
	v_pk_mul_f32 v[2:3], v[2:3], v[14:15] op_sel_hi:[1,0]
	v_lshlrev_b32_e32 v8, 16, v130
	v_and_b32_e32 v9, 0xffff0000, v130
	v_pk_mul_f32 v[4:5], v[4:5], v[14:15] op_sel_hi:[1,0]
	v_pk_mul_f32 v[2:3], v[2:3], v[8:9]
	v_lshlrev_b32_e32 v8, 16, v131
	v_and_b32_e32 v9, 0xffff0000, v131
	v_pk_mul_f32 v[4:5], v[4:5], v[8:9]
	v_cvt_pk_bf16_f32 v2, v2, v3
	v_cvt_pk_bf16_f32 v3, v4, v5
	global_store_dwordx2 v[6:7], v[24:25], off
	global_store_dwordx2 v[6:7], v[10:11], off offset:448
	global_store_dwordx2 v[6:7], v[2:3], off offset:480
	s_barrier
	s_cbranch_scc1 .LBB0_970

; #define PG8_STAGE(bufoff, gbase, voff) do { const int so_ = (int)(unsigned)((const char*)(gbase) - base_##voff); _Pragma("unroll") for (int _i = 0; _i < 2; ++_i) \
;         __builtin_amdgcn_raw_ptr_buffer_load_lds(rs_##voff, (PG8_LAS unsigned*)(lds + (bufoff) + ldsw + _i * 8192), 16, (int)(voff)[_i], so_, 0, 0); } while (0)
; #define PG8_LDA(dst, b, h) do { _Pragma("unroll") for (int m = 0; m < 4; ++m) _Pragma("unroll") for (int k = 0; k < 2; ++k) dst[m][k] = *(const PG8_LAS bf16x8*)(lds + PG8_SA(b, h) + aoff + m * 2048 + k * 1024); } while (0)
; #define PG8_LDB(dst, b, h) do { _Pragma("unroll") for (int n = 0; n < 2; ++n) _Pragma("unroll") for (int k = 0; k < 2; ++k) dst[n][k] = *(const PG8_LAS bf16x8*)(lds + PG8_SB(b, h) + boff + n * 2048 + k * 1024); } while (0)
; #define PG8_MMA(ai, bj, At, Bt) do { __builtin_amdgcn_s_setprio(1); _Pragma("unroll") for (int m = 0; m < 4; ++m) _Pragma("unroll") for (int n = 0; n < 2; ++n) _Pragma("unroll") for (int k = 0; k < 2; ++k) \
;         acc[ai][bj][m][n] = __builtin_amdgcn_mfma_f32_16x16x32_bf16(Bt[n][k], At[m][k], acc[ai][bj][m][n], 0, 0, 0); __builtin_amdgcn_s_setprio(0); } while (0)
; template <class Epi, class Sched, bool ALIGN_EPI = false, bool SP2 = false>
; __device__ __forceinline__ void gemm_phase(PG8_LAS unsigned char* lds, const Gemm g, const Sched& S, const Epi& E, int tid_in) {
;     ...
;             PG8_LDB(B0, 0, 0); PG8_LDB(B1, 0, 1); PG8_SCHED; PG8_LDA(At, 0, 0); PG8_STAGE(PG8_SA(1, 1), a1 + hstepA, voffA);
;             PG8_WAIT_V(8); PG8_WAIT_L(0); PG8_BAR; PG8_MMA(0, 0, At, B0); PG8_MMA(0, 1, At, B1); PG8_BAR; PG8_SCHED;
;             PG8_LDA(At, 0, 1); PG8_STAGE(PG8_SB(0, 0), b2, voffB); PG8_STAGE(PG8_SB(0, 1), b2 + hstepB, voffB); PG8_STAGE(PG8_SA(0, 0), a2, voffA);
;             PG8_WAIT_V(8); PG8_WAIT_L(0); PG8_BAR; PG8_MMA(1, 0, At, B0); PG8_MMA(1, 1, At, B1); PG8_BAR; PG8_SCHED;
;             PG8_LDB(B0, 1, 0); PG8_LDB(B1, 1, 1); PG8_SCHED; PG8_LDA(At, 1, 0); PG8_STAGE(PG8_SA(0, 1), a2 + hstepA, voffA);
;             PG8_WAIT_V(8); PG8_WAIT_L(0); PG8_BAR; PG8_MMA(0, 0, At, B0); PG8_MMA(0, 1, At, B1); PG8_BAR; PG8_SCHED;
;             PG8_LDA(At, 1, 1); PG8_STAGE(PG8_SB(1, 0), b3, voffB); PG8_STAGE(PG8_SB(1, 1), b3 + hstepB, voffB); PG8_STAGE(PG8_SA(1, 0), a3, voffA);
;             PG8_WAIT_V(8); PG8_WAIT_L(0); PG8_BAR; PG8_MMA(1, 0, At, B0); PG8_MMA(1, 1, At, B1); PG8_BAR; PG8_SCHED;
.LBB0_1037:
	v_add_u32_e32 v0, 0x10000, v236
	ds_read_b128 v[132:135], v0
	ds_read_b128 v[136:139], v0 offset:1024
	ds_read_b128 v[140:143], v0 offset:2048
	ds_read_b128 v[144:147], v0 offset:3072
	v_add_u32_e32 v0, 0x14000, v236
	ds_read_b128 v[148:151], v0
	ds_read_b128 v[152:155], v0 offset:1024
	ds_read_b128 v[156:159], v0 offset:2048
	ds_read_b128 v[160:163], v0 offset:3072
	s_add_u32 s16, s12, 0x100
	s_addc_u32 s17, s13, 0
	s_sub_i32 s12, s12, s4
	s_add_i32 s12, s12, 0xc0080
	s_cmp_eq_u32 s38, 12
	s_cselect_b32 s13, s24, s16
	s_mov_b32 m0, s76
	ds_read_b128 v[164:167], v237
	ds_read_b128 v[168:171], v237 offset:1024
	ds_read_b128 v[172:175], v237 offset:2048
	ds_read_b128 v[176:179], v237 offset:3072
	ds_read_b128 v[180:183], v237 offset:4096
	ds_read_b128 v[184:187], v237 offset:5120
	ds_read_b128 v[188:191], v237 offset:6144
	ds_read_b128 v[192:195], v237 offset:7168
	buffer_load_dwordx4 v220, s[4:7], s12 offen lds
	s_mov_b32 m0, s77
	s_nop 0
	buffer_load_dwordx4 v222, s[4:7], s12 offen lds
	s_waitcnt vmcnt(8)
	s_waitcnt lgkmcnt(0)
	s_barrier
	s_setprio 1
	s_waitcnt lgkmcnt(0)
	v_mfma_f32_16x16x32_bf16 v[128:131], v[132:135], v[164:167], v[128:131]
	v_mfma_f32_16x16x32_bf16 v[124:127], v[140:143], v[164:167], v[124:127]
	v_mfma_f32_16x16x32_bf16 v[116:119], v[140:143], v[172:175], v[116:119]
	v_mfma_f32_16x16x32_bf16 v[120:123], v[132:135], v[172:175], v[120:123]
	v_mfma_f32_16x16x32_bf16 v[112:115], v[132:135], v[180:183], v[112:115]
	v_mfma_f32_16x16x32_bf16 v[108:111], v[140:143], v[180:183], v[108:111]
	v_mfma_f32_16x16x32_bf16 v[100:103], v[140:143], v[188:191], v[100:103]
	v_mfma_f32_16x16x32_bf16 v[104:107], v[132:135], v[188:191], v[104:107]
	v_mfma_f32_16x16x32_bf16 v[128:131], v[136:139], v[168:171], v[128:131]
	v_mfma_f32_16x16x32_bf16 v[124:127], v[144:147], v[168:171], v[124:127]
	v_mfma_f32_16x16x32_bf16 v[116:119], v[144:147], v[176:179], v[116:119]
	v_mfma_f32_16x16x32_bf16 v[120:123], v[136:139], v[176:179], v[120:123]
	v_mfma_f32_16x16x32_bf16 v[112:115], v[136:139], v[184:187], v[112:115]
	v_mfma_f32_16x16x32_bf16 v[108:111], v[144:147], v[184:187], v[108:111]
	v_mfma_f32_16x16x32_bf16 v[100:103], v[144:147], v[192:195], v[100:103]
	v_mfma_f32_16x16x32_bf16 v[104:107], v[136:139], v[192:195], v[104:107]
	s_setprio 0
	s_setprio 1
	v_mfma_f32_16x16x32_bf16 v[96:99], v[148:151], v[164:167], v[96:99]
	v_mfma_f32_16x16x32_bf16 v[92:95], v[156:159], v[164:167], v[92:95]
	v_mfma_f32_16x16x32_bf16 v[84:87], v[156:159], v[172:175], v[84:87]
	v_mfma_f32_16x16x32_bf16 v[88:91], v[148:151], v[172:175], v[88:91]
	v_mfma_f32_16x16x32_bf16 v[80:83], v[148:151], v[180:183], v[80:83]
	v_mfma_f32_16x16x32_bf16 v[76:79], v[156:159], v[180:183], v[76:79]
	v_mfma_f32_16x16x32_bf16 v[68:71], v[156:159], v[188:191], v[68:71]
	v_mfma_f32_16x16x32_bf16 v[72:75], v[148:151], v[188:191], v[72:75]
	v_mfma_f32_16x16x32_bf16 v[96:99], v[152:155], v[168:171], v[96:99]
	v_mfma_f32_16x16x32_bf16 v[92:95], v[160:163], v[168:171], v[92:95]
	v_mfma_f32_16x16x32_bf16 v[84:87], v[160:163], v[176:179], v[84:87]
	v_mfma_f32_16x16x32_bf16 v[88:91], v[152:155], v[176:179], v[88:91]
	v_mfma_f32_16x16x32_bf16 v[80:83], v[152:155], v[184:187], v[80:83]
	v_mfma_f32_16x16x32_bf16 v[76:79], v[160:163], v[184:187], v[76:79]
	v_mfma_f32_16x16x32_bf16 v[68:71], v[160:163], v[192:195], v[68:71]
	v_mfma_f32_16x16x32_bf16 v[72:75], v[152:155], v[192:195], v[72:75]
	s_setprio 0
	s_barrier
	s_cselect_b32 s12, s18, s19
	s_mov_b32 m0, s26
	s_mov_b32 s46, s6
	s_mov_b32 s47, s7
	s_sub_i32 s12, s12, s44
	ds_read_b128 v[164:167], v237 offset:16384
	ds_read_b128 v[168:171], v237 offset:17408
	ds_read_b128 v[172:175], v237 offset:18432
	ds_read_b128 v[176:179], v237 offset:19456
	ds_read_b128 v[180:183], v237 offset:20480
	ds_read_b128 v[184:187], v237 offset:21504
	ds_read_b128 v[188:191], v237 offset:22528
	ds_read_b128 v[192:195], v237 offset:23552
	buffer_load_dwordx4 v221, s[44:47], s12 offen lds
	s_mov_b32 m0, s53
	s_add_i32 s39, s12, 0x40000
	buffer_load_dwordx4 v223, s[44:47], s12 offen lds
	s_mov_b32 m0, s60
	s_sub_i32 s13, s13, s4
	buffer_load_dwordx4 v221, s[44:47], s39 offen lds
	s_mov_b32 m0, s61
	s_nop 0
	buffer_load_dwordx4 v223, s[44:47], s39 offen lds
	s_mov_b32 m0, s21
	s_nop 0
	buffer_load_dwordx4 v220, s[4:7], s13 offen lds
	s_mov_b32 m0, s62
	s_nop 0
	buffer_load_dwordx4 v222, s[4:7], s13 offen lds
	s_waitcnt vmcnt(8)
	s_waitcnt lgkmcnt(0)
	s_barrier
	s_setprio 1
	s_waitcnt lgkmcnt(0)
	v_mfma_f32_16x16x32_bf16 v[64:67], v[132:135], v[164:167], v[64:67]
	v_mfma_f32_16x16x32_bf16 v[60:63], v[140:143], v[164:167], v[60:63]
	v_mfma_f32_16x16x32_bf16 v[52:55], v[140:143], v[172:175], v[52:55]
	v_mfma_f32_16x16x32_bf16 v[56:59], v[132:135], v[172:175], v[56:59]
	v_mfma_f32_16x16x32_bf16 v[48:51], v[132:135], v[180:183], v[48:51]
	v_mfma_f32_16x16x32_bf16 v[44:47], v[140:143], v[180:183], v[44:47]
	v_mfma_f32_16x16x32_bf16 v[36:39], v[140:143], v[188:191], v[36:39]
	v_mfma_f32_16x16x32_bf16 v[40:43], v[132:135], v[188:191], v[40:43]
	v_mfma_f32_16x16x32_bf16 v[64:67], v[136:139], v[168:171], v[64:67]
	v_mfma_f32_16x16x32_bf16 v[60:63], v[144:147], v[168:171], v[60:63]
	v_mfma_f32_16x16x32_bf16 v[52:55], v[144:147], v[176:179], v[52:55]
	v_mfma_f32_16x16x32_bf16 v[56:59], v[136:139], v[176:179], v[56:59]
	v_mfma_f32_16x16x32_bf16 v[48:51], v[136:139], v[184:187], v[48:51]
	v_mfma_f32_16x16x32_bf16 v[44:47], v[144:147], v[184:187], v[44:47]
	v_mfma_f32_16x16x32_bf16 v[36:39], v[144:147], v[192:195], v[36:39]
	v_mfma_f32_16x16x32_bf16 v[40:43], v[136:139], v[192:195], v[40:43]
	s_setprio 0
	s_setprio 1
	v_mfma_f32_16x16x32_bf16 v[32:35], v[148:151], v[164:167], v[32:35]
	v_mfma_f32_16x16x32_bf16 v[28:31], v[156:159], v[164:167], v[28:31]
	v_mfma_f32_16x16x32_bf16 v[20:23], v[156:159], v[172:175], v[20:23]
	v_mfma_f32_16x16x32_bf16 v[24:27], v[148:151], v[172:175], v[24:27]
	v_mfma_f32_16x16x32_bf16 v[16:19], v[148:151], v[180:183], v[16:19]
	v_mfma_f32_16x16x32_bf16 v[12:15], v[156:159], v[180:183], v[12:15]
	v_mfma_f32_16x16x32_bf16 v[2:5], v[156:159], v[188:191], v[4:7]
	v_mfma_f32_16x16x32_bf16 v[8:11], v[148:151], v[188:191], v[8:11]
	v_mfma_f32_16x16x32_bf16 v[32:35], v[152:155], v[168:171], v[32:35]
	v_mfma_f32_16x16x32_bf16 v[28:31], v[160:163], v[168:171], v[28:31]
	v_mfma_f32_16x16x32_bf16 v[20:23], v[160:163], v[176:179], v[20:23]
	v_mfma_f32_16x16x32_bf16 v[24:27], v[152:155], v[176:179], v[24:27]
	v_mfma_f32_16x16x32_bf16 v[16:19], v[152:155], v[184:187], v[16:19]
	v_mfma_f32_16x16x32_bf16 v[12:15], v[160:163], v[184:187], v[12:15]
	v_mfma_f32_16x16x32_bf16 v[2:5], v[160:163], v[192:195], v[2:5]
	v_mfma_f32_16x16x32_bf16 v[8:11], v[152:155], v[192:195], v[8:11]
	s_setprio 0
	s_barrier
; #define PG8_STAGE(bufoff, gbase, voff) do { const int so_ = (int)(unsigned)((const char*)(gbase) - base_##voff); _Pragma("unroll") for (int _i = 0; _i < 2; ++_i) \
;         __builtin_amdgcn_raw_ptr_buffer_load_lds(rs_##voff, (PG8_LAS unsigned*)(lds + (bufoff) + ldsw + _i * 8192), 16, (int)(voff)[_i], so_, 0, 0); } while (0)
; #define PG8_LDA(dst, b, h) do { _Pragma("unroll") for (int m = 0; m < 4; ++m) _Pragma("unroll") for (int k = 0; k < 2; ++k) dst[m][k] = *(const PG8_LAS bf16x8*)(lds + PG8_SA(b, h) + aoff + m * 2048 + k * 1024); } while (0)
; #define PG8_LDB(dst, b, h) do { _Pragma("unroll") for (int n = 0; n < 2; ++n) _Pragma("unroll") for (int k = 0; k < 2; ++k) dst[n][k] = *(const PG8_LAS bf16x8*)(lds + PG8_SB(b, h) + boff + n * 2048 + k * 1024); } while (0)
; #define PG8_MMA(ai, bj, At, Bt) do { __builtin_amdgcn_s_setprio(1); _Pragma("unroll") for (int m = 0; m < 4; ++m) _Pragma("unroll") for (int n = 0; n < 2; ++n) _Pragma("unroll") for (int k = 0; k < 2; ++k) \
;         acc[ai][bj][m][n] = __builtin_amdgcn_mfma_f32_16x16x32_bf16(Bt[n][k], At[m][k], acc[ai][bj][m][n], 0, 0, 0); __builtin_amdgcn_s_setprio(0); } while (0)
; template <class Epi, class Sched, bool ALIGN_EPI = false, bool SP2 = false>
; __device__ __forceinline__ void gemm_phase(PG8_LAS unsigned char* lds, const Gemm g, const Sched& S, const Epi& E, int tid_in) {
;     ...
;             PG8_LDB(B0, 0, 0); PG8_LDB(B1, 0, 1); PG8_SCHED; PG8_LDA(At, 0, 0); PG8_STAGE(PG8_SA(1, 1), a1 + hstepA, voffA);
;             PG8_WAIT_V(8); PG8_WAIT_L(0); PG8_BAR; PG8_MMA(0, 0, At, B0); PG8_MMA(0, 1, At, B1); PG8_BAR; PG8_SCHED;
;             PG8_LDA(At, 0, 1); PG8_STAGE(PG8_SB(0, 0), b2, voffB); PG8_STAGE(PG8_SB(0, 1), b2 + hstepB, voffB); PG8_STAGE(PG8_SA(0, 0), a2, voffA);
;             PG8_WAIT_V(8); PG8_WAIT_L(0); PG8_BAR; PG8_MMA(1, 0, At, B0); PG8_MMA(1, 1, At, B1); PG8_BAR; PG8_SCHED;
;             PG8_LDB(B0, 1, 0); PG8_LDB(B1, 1, 1); PG8_SCHED; PG8_LDA(At, 1, 0); PG8_STAGE(PG8_SA(0, 1), a2 + hstepA, voffA);
;             PG8_WAIT_V(8); PG8_WAIT_L(0); PG8_BAR; PG8_MMA(0, 0, At, B0); PG8_MMA(0, 1, At, B1); PG8_BAR; PG8_SCHED;
;             PG8_LDA(At, 1, 1); PG8_STAGE(PG8_SB(1, 0), b3, voffB); PG8_STAGE(PG8_SB(1, 1), b3 + hstepB, voffB); PG8_STAGE(PG8_SA(1, 0), a3, voffA);
;             PG8_WAIT_V(8); PG8_WAIT_L(0); PG8_BAR; PG8_MMA(1, 0, At, B0); PG8_MMA(1, 1, At, B1); PG8_BAR; PG8_SCHED;
	v_add_u32_e32 v0, 0x18000, v236
	ds_read_b128 v[132:135], v0
	ds_read_b128 v[136:139], v0 offset:1024
	ds_read_b128 v[140:143], v0 offset:2048
	ds_read_b128 v[144:147], v0 offset:3072
	v_add_u32_e32 v0, 0x1c000, v236
	ds_read_b128 v[148:151], v0
	ds_read_b128 v[152:155], v0 offset:1024
	ds_read_b128 v[156:159], v0 offset:2048
	ds_read_b128 v[160:163], v0 offset:3072
	s_add_i32 s39, s13, 0xc0000
	s_mov_b32 m0, s63
	ds_read_b128 v[164:167], v237 offset:32768
	ds_read_b128 v[168:171], v237 offset:33792
	ds_read_b128 v[172:175], v237 offset:34816
	ds_read_b128 v[176:179], v237 offset:35840
	ds_read_b128 v[180:183], v237 offset:36864
	ds_read_b128 v[184:187], v237 offset:37888
	ds_read_b128 v[188:191], v237 offset:38912
	ds_read_b128 v[192:195], v237 offset:39936
	buffer_load_dwordx4 v220, s[4:7], s39 offen lds
	s_mov_b32 m0, s66
	s_nop 0
	buffer_load_dwordx4 v222, s[4:7], s39 offen lds
	s_waitcnt vmcnt(8)
	s_waitcnt lgkmcnt(0)
	s_barrier
	s_setprio 1
	s_waitcnt lgkmcnt(0)
	v_mfma_f32_16x16x32_bf16 v[128:131], v[132:135], v[164:167], v[128:131]
	v_mfma_f32_16x16x32_bf16 v[124:127], v[140:143], v[164:167], v[124:127]
	v_mfma_f32_16x16x32_bf16 v[116:119], v[140:143], v[172:175], v[116:119]
	v_mfma_f32_16x16x32_bf16 v[120:123], v[132:135], v[172:175], v[120:123]
	v_mfma_f32_16x16x32_bf16 v[112:115], v[132:135], v[180:183], v[112:115]
	v_mfma_f32_16x16x32_bf16 v[108:111], v[140:143], v[180:183], v[108:111]
	v_mfma_f32_16x16x32_bf16 v[100:103], v[140:143], v[188:191], v[100:103]
	v_mfma_f32_16x16x32_bf16 v[104:107], v[132:135], v[188:191], v[104:107]
	v_mfma_f32_16x16x32_bf16 v[128:131], v[136:139], v[168:171], v[128:131]
	v_mfma_f32_16x16x32_bf16 v[124:127], v[144:147], v[168:171], v[124:127]
	v_mfma_f32_16x16x32_bf16 v[116:119], v[144:147], v[176:179], v[116:119]
	v_mfma_f32_16x16x32_bf16 v[120:123], v[136:139], v[176:179], v[120:123]
	v_mfma_f32_16x16x32_bf16 v[112:115], v[136:139], v[184:187], v[112:115]
	v_mfma_f32_16x16x32_bf16 v[108:111], v[144:147], v[184:187], v[108:111]
	v_mfma_f32_16x16x32_bf16 v[100:103], v[144:147], v[192:195], v[100:103]
	v_mfma_f32_16x16x32_bf16 v[104:107], v[136:139], v[192:195], v[104:107]
	s_setprio 0
	s_setprio 1
	v_mfma_f32_16x16x32_bf16 v[96:99], v[148:151], v[164:167], v[96:99]
	v_mfma_f32_16x16x32_bf16 v[92:95], v[156:159], v[164:167], v[92:95]
	v_mfma_f32_16x16x32_bf16 v[84:87], v[156:159], v[172:175], v[84:87]
	v_mfma_f32_16x16x32_bf16 v[88:91], v[148:151], v[172:175], v[88:91]
	v_mfma_f32_16x16x32_bf16 v[80:83], v[148:151], v[180:183], v[80:83]
	v_mfma_f32_16x16x32_bf16 v[76:79], v[156:159], v[180:183], v[76:79]
	v_mfma_f32_16x16x32_bf16 v[68:71], v[156:159], v[188:191], v[68:71]
	v_mfma_f32_16x16x32_bf16 v[72:75], v[148:151], v[188:191], v[72:75]
	v_mfma_f32_16x16x32_bf16 v[96:99], v[152:155], v[168:171], v[96:99]
	v_mfma_f32_16x16x32_bf16 v[92:95], v[160:163], v[168:171], v[92:95]
	v_mfma_f32_16x16x32_bf16 v[84:87], v[160:163], v[176:179], v[84:87]
	v_mfma_f32_16x16x32_bf16 v[88:91], v[152:155], v[176:179], v[88:91]
	v_mfma_f32_16x16x32_bf16 v[80:83], v[152:155], v[184:187], v[80:83]
	v_mfma_f32_16x16x32_bf16 v[76:79], v[160:163], v[184:187], v[76:79]
	v_mfma_f32_16x16x32_bf16 v[68:71], v[160:163], v[192:195], v[68:71]
	v_mfma_f32_16x16x32_bf16 v[72:75], v[152:155], v[192:195], v[72:75]
	s_setprio 0
	s_barrier
	s_mov_b32 m0, s69
	s_add_i32 s39, s12, 0x80
	ds_read_b128 v[164:167], v237 offset:49152
	ds_read_b128 v[168:171], v237 offset:50176
	ds_read_b128 v[172:175], v237 offset:51200
	ds_read_b128 v[176:179], v237 offset:52224
	ds_read_b128 v[180:183], v237 offset:53248
	ds_read_b128 v[184:187], v237 offset:54272
	ds_read_b128 v[188:191], v237 offset:55296
	ds_read_b128 v[192:195], v237 offset:56320
	buffer_load_dwordx4 v221, s[44:47], s39 offen lds
	s_mov_b32 m0, s71
	s_add_i32 s12, s12, 0x40080
	buffer_load_dwordx4 v223, s[44:47], s39 offen lds
	s_mov_b32 m0, s74
	s_addk_i32 s13, 0x80
	buffer_load_dwordx4 v221, s[44:47], s12 offen lds
	s_mov_b32 m0, s75
	s_nop 0
	buffer_load_dwordx4 v223, s[44:47], s12 offen lds
	s_mov_b32 m0, s72
	s_nop 0
	buffer_load_dwordx4 v220, s[4:7], s13 offen lds
	s_mov_b32 m0, s73
	s_nop 0
	buffer_load_dwordx4 v222, s[4:7], s13 offen lds
	s_waitcnt vmcnt(8)
	s_waitcnt lgkmcnt(0)
	s_barrier
	s_setprio 1
	s_waitcnt lgkmcnt(0)
	v_mfma_f32_16x16x32_bf16 v[64:67], v[132:135], v[164:167], v[64:67]
	v_mfma_f32_16x16x32_bf16 v[60:63], v[140:143], v[164:167], v[60:63]
	v_mfma_f32_16x16x32_bf16 v[52:55], v[140:143], v[172:175], v[52:55]
	v_mfma_f32_16x16x32_bf16 v[56:59], v[132:135], v[172:175], v[56:59]
	v_mfma_f32_16x16x32_bf16 v[48:51], v[132:135], v[180:183], v[48:51]
	v_mfma_f32_16x16x32_bf16 v[44:47], v[140:143], v[180:183], v[44:47]
	v_mfma_f32_16x16x32_bf16 v[36:39], v[140:143], v[188:191], v[36:39]
	v_mfma_f32_16x16x32_bf16 v[40:43], v[132:135], v[188:191], v[40:43]
	v_mfma_f32_16x16x32_bf16 v[64:67], v[136:139], v[168:171], v[64:67]
	v_mfma_f32_16x16x32_bf16 v[60:63], v[144:147], v[168:171], v[60:63]
	v_mfma_f32_16x16x32_bf16 v[52:55], v[144:147], v[176:179], v[52:55]
	v_mfma_f32_16x16x32_bf16 v[56:59], v[136:139], v[176:179], v[56:59]
	v_mfma_f32_16x16x32_bf16 v[48:51], v[136:139], v[184:187], v[48:51]
	v_mfma_f32_16x16x32_bf16 v[44:47], v[144:147], v[184:187], v[44:47]
	v_mfma_f32_16x16x32_bf16 v[36:39], v[144:147], v[192:195], v[36:39]
	v_mfma_f32_16x16x32_bf16 v[40:43], v[136:139], v[192:195], v[40:43]
	s_setprio 0
	s_setprio 1
	v_mfma_f32_16x16x32_bf16 v[32:35], v[148:151], v[164:167], v[32:35]
	v_mfma_f32_16x16x32_bf16 v[28:31], v[156:159], v[164:167], v[28:31]
	v_mfma_f32_16x16x32_bf16 v[20:23], v[156:159], v[172:175], v[20:23]
	v_mfma_f32_16x16x32_bf16 v[24:27], v[148:151], v[172:175], v[24:27]
	v_mfma_f32_16x16x32_bf16 v[16:19], v[148:151], v[180:183], v[16:19]
	v_mfma_f32_16x16x32_bf16 v[12:15], v[156:159], v[180:183], v[12:15]
	v_mfma_f32_16x16x32_bf16 v[2:5], v[156:159], v[188:191], v[2:5]
	v_mfma_f32_16x16x32_bf16 v[6:9], v[148:151], v[188:191], v[8:11]
	v_mfma_f32_16x16x32_bf16 v[32:35], v[152:155], v[168:171], v[32:35]
	v_mfma_f32_16x16x32_bf16 v[28:31], v[160:163], v[168:171], v[28:31]
	v_mfma_f32_16x16x32_bf16 v[20:23], v[160:163], v[176:179], v[20:23]
	v_mfma_f32_16x16x32_bf16 v[24:27], v[152:155], v[176:179], v[24:27]
	v_mfma_f32_16x16x32_bf16 v[16:19], v[152:155], v[184:187], v[16:19]
	v_mfma_f32_16x16x32_bf16 v[12:15], v[160:163], v[184:187], v[12:15]
	v_mfma_f32_16x16x32_bf16 v[4:7], v[160:163], v[192:195], v[2:5]
	v_mfma_f32_16x16x32_bf16 v[8:11], v[152:155], v[192:195], v[6:9]
	s_setprio 0
	s_barrier
	s_add_i32 s38, s38, 2
	s_add_u32 s19, s19, 0x100
	s_addc_u32 s23, s23, 0
	s_cmp_gt_u32 s38, 13
	s_mov_b64 s[12:13], s[16:17]
	s_cbranch_scc0 .LBB0_1037
	s_and_b64 vcc, exec, s[14:15]
	s_cbranch_vccz .LBB0_1040
	s_barrier

; #define PG8_STAGE(bufoff, gbase, voff) do { const int so_ = (int)(unsigned)((const char*)(gbase) - base_##voff); _Pragma("unroll") for (int _i = 0; _i < 2; ++_i) \
;         __builtin_amdgcn_raw_ptr_buffer_load_lds(rs_##voff, (PG8_LAS unsigned*)(lds + (bufoff) + ldsw + _i * 8192), 16, (int)(voff)[_i], so_, 0, 0); } while (0)
; #define PG8_LDA(dst, b, h) do { _Pragma("unroll") for (int m = 0; m < 4; ++m) _Pragma("unroll") for (int k = 0; k < 2; ++k) dst[m][k] = *(const PG8_LAS bf16x8*)(lds + PG8_SA(b, h) + aoff + m * 2048 + k * 1024); } while (0)
; #define PG8_LDB(dst, b, h) do { _Pragma("unroll") for (int n = 0; n < 2; ++n) _Pragma("unroll") for (int k = 0; k < 2; ++k) dst[n][k] = *(const PG8_LAS bf16x8*)(lds + PG8_SB(b, h) + boff + n * 2048 + k * 1024); } while (0)
; #define PG8_MMA(ai, bj, At, Bt) do { __builtin_amdgcn_s_setprio(1); _Pragma("unroll") for (int m = 0; m < 4; ++m) _Pragma("unroll") for (int n = 0; n < 2; ++n) _Pragma("unroll") for (int k = 0; k < 2; ++k) \
;         acc[ai][bj][m][n] = __builtin_amdgcn_mfma_f32_16x16x32_bf16(Bt[n][k], At[m][k], acc[ai][bj][m][n], 0, 0, 0); __builtin_amdgcn_s_setprio(0); } while (0)
; template <class Epi, class Sched, bool ALIGN_EPI = false, bool SP2 = false>
; __device__ __forceinline__ void gemm_phase(PG8_LAS unsigned char* lds, const Gemm g, const Sched& S, const Epi& E, int tid_in) {
;     ...
;             PG8_LDB(B0, 0, 0); PG8_LDB(B1, 0, 1); PG8_SCHED; PG8_LDA(At, 0, 0); PG8_STAGE(PG8_SA(1, 1), a1 + hstepA, voffA);
;             PG8_WAIT_V(8); PG8_WAIT_L(0); PG8_BAR; PG8_MMA(0, 0, At, B0); PG8_MMA(0, 1, At, B1); PG8_BAR; PG8_SCHED;
;             PG8_LDA(At, 0, 1); PG8_STAGE(PG8_SB(0, 0), b2, voffB); PG8_STAGE(PG8_SB(0, 1), b2 + hstepB, voffB); PG8_STAGE(PG8_SA(0, 0), a2, voffA);
;             PG8_WAIT_V(8); PG8_WAIT_L(0); PG8_BAR; PG8_MMA(1, 0, At, B0); PG8_MMA(1, 1, At, B1); PG8_BAR; PG8_SCHED;
;             PG8_LDB(B0, 1, 0); PG8_LDB(B1, 1, 1); PG8_SCHED; PG8_LDA(At, 1, 0); PG8_STAGE(PG8_SA(0, 1), a2 + hstepA, voffA);
;             PG8_WAIT_V(8); PG8_WAIT_L(0); PG8_BAR; PG8_MMA(0, 0, At, B0); PG8_MMA(0, 1, At, B1); PG8_BAR; PG8_SCHED;
;             PG8_LDA(At, 1, 1); PG8_STAGE(PG8_SB(1, 0), b3, voffB); PG8_STAGE(PG8_SB(1, 1), b3 + hstepB, voffB); PG8_STAGE(PG8_SA(1, 0), a3, voffA);
;             PG8_WAIT_V(8); PG8_WAIT_L(0); PG8_BAR; PG8_MMA(1, 0, At, B0); PG8_MMA(1, 1, At, B1); PG8_BAR; PG8_SCHED;
.LBB0_1265:
	v_add_u32_e32 v133, 0x10000, v131
	ds_read_b128 v[134:137], v133
	ds_read_b128 v[138:141], v133 offset:1024
	ds_read_b128 v[142:145], v133 offset:2048
	ds_read_b128 v[146:149], v133 offset:3072
	v_add_u32_e32 v133, 0x14000, v131
	ds_read_b128 v[150:153], v133
	ds_read_b128 v[154:157], v133 offset:1024
	ds_read_b128 v[158:161], v133 offset:2048
	ds_read_b128 v[166:169], v133 offset:3072
	s_add_i32 s42, s18, s44
	s_add_i32 s21, s14, s44
	s_add_i32 s79, s12, s44
	s_addk_i32 s42, 0xff80
	s_cmp_eq_u32 s19, 28
	s_cselect_b32 s21, s15, s21
	s_mov_b32 m0, s75
	ds_read_b128 v[170:173], v132
	ds_read_b128 v[174:177], v132 offset:1024
	ds_read_b128 v[178:181], v132 offset:2048
	ds_read_b128 v[182:185], v132 offset:3072
	ds_read_b128 v[186:189], v132 offset:4096
	ds_read_b128 v[190:193], v132 offset:5120
	ds_read_b128 v[200:203], v132 offset:6144
	ds_read_b128 v[206:209], v132 offset:7168
	buffer_load_dwordx4 v0, s[4:7], s42 offen lds
	s_mov_b32 m0, s76
	s_nop 0
	buffer_load_dwordx4 v130, s[4:7], s42 offen lds
	s_waitcnt vmcnt(8)
	s_waitcnt lgkmcnt(0)
	s_barrier
	s_setprio 1
	s_waitcnt lgkmcnt(0)
	v_mfma_f32_16x16x32_bf16 v[34:37], v[134:137], v[170:173], v[34:37]
	v_mfma_f32_16x16x32_bf16 v[18:21], v[142:145], v[170:173], v[18:21]
	v_mfma_f32_16x16x32_bf16 v[78:81], v[142:145], v[178:181], v[78:81]
	v_mfma_f32_16x16x32_bf16 v[86:89], v[134:137], v[178:181], v[86:89]
	v_mfma_f32_16x16x32_bf16 v[106:109], v[134:137], v[186:189], v[106:109]
	v_mfma_f32_16x16x32_bf16 v[102:105], v[142:145], v[186:189], v[102:105]
	v_mfma_f32_16x16x32_bf16 v[122:125], v[142:145], v[200:203], v[122:125]
	v_mfma_f32_16x16x32_bf16 v[126:129], v[134:137], v[200:203], v[126:129]
	v_mfma_f32_16x16x32_bf16 v[34:37], v[138:141], v[174:177], v[34:37]
	v_mfma_f32_16x16x32_bf16 v[18:21], v[146:149], v[174:177], v[18:21]
	v_mfma_f32_16x16x32_bf16 v[78:81], v[146:149], v[182:185], v[78:81]
	v_mfma_f32_16x16x32_bf16 v[86:89], v[138:141], v[182:185], v[86:89]
	v_mfma_f32_16x16x32_bf16 v[106:109], v[138:141], v[190:193], v[106:109]
	v_mfma_f32_16x16x32_bf16 v[102:105], v[146:149], v[190:193], v[102:105]
	v_mfma_f32_16x16x32_bf16 v[122:125], v[146:149], v[206:209], v[122:125]
	v_mfma_f32_16x16x32_bf16 v[126:129], v[138:141], v[206:209], v[126:129]
	s_setprio 0
	s_setprio 1
	v_mfma_f32_16x16x32_bf16 v[14:17], v[150:153], v[170:173], v[14:17]
	v_mfma_f32_16x16x32_bf16 v[38:41], v[158:161], v[170:173], v[38:41]
	v_mfma_f32_16x16x32_bf16 v[90:93], v[158:161], v[178:181], v[90:93]
	v_mfma_f32_16x16x32_bf16 v[74:77], v[150:153], v[178:181], v[74:77]
	v_mfma_f32_16x16x32_bf16 v[98:101], v[150:153], v[186:189], v[98:101]
	v_mfma_f32_16x16x32_bf16 v[110:113], v[158:161], v[186:189], v[110:113]
	v_mfma_f32_16x16x32_bf16 v[114:117], v[158:161], v[200:203], v[114:117]
	v_mfma_f32_16x16x32_bf16 v[118:121], v[150:153], v[200:203], v[118:121]
	v_mfma_f32_16x16x32_bf16 v[14:17], v[154:157], v[174:177], v[14:17]
	v_mfma_f32_16x16x32_bf16 v[38:41], v[166:169], v[174:177], v[38:41]
	v_mfma_f32_16x16x32_bf16 v[90:93], v[166:169], v[182:185], v[90:93]
	v_mfma_f32_16x16x32_bf16 v[74:77], v[154:157], v[182:185], v[74:77]
	v_mfma_f32_16x16x32_bf16 v[98:101], v[154:157], v[190:193], v[98:101]
	v_mfma_f32_16x16x32_bf16 v[110:113], v[166:169], v[190:193], v[110:113]
	v_mfma_f32_16x16x32_bf16 v[114:117], v[166:169], v[206:209], v[114:117]
	v_mfma_f32_16x16x32_bf16 v[118:121], v[154:157], v[206:209], v[118:121]
	s_setprio 0
	s_barrier
	s_cselect_b32 s79, s17, s79
	s_mov_b32 m0, s49
	s_mov_b32 s42, s6
	s_mov_b32 s43, s7
	s_sub_i32 s79, s79, s40
	ds_read_b128 v[170:173], v132 offset:16384
	ds_read_b128 v[174:177], v132 offset:17408
	ds_read_b128 v[178:181], v132 offset:18432
	ds_read_b128 v[182:185], v132 offset:19456
	ds_read_b128 v[186:189], v132 offset:20480
	ds_read_b128 v[190:193], v132 offset:21504
	ds_read_b128 v[200:203], v132 offset:22528
	ds_read_b128 v[206:209], v132 offset:23552
	buffer_load_dwordx4 v0, s[40:43], s79 offen lds
	s_mov_b32 m0, s60
	s_add_i32 vcc_lo, s79, 0x80000
	buffer_load_dwordx4 v130, s[40:43], s79 offen lds
	s_mov_b32 m0, s61
	s_sub_i32 s21, s21, s4
	buffer_load_dwordx4 v0, s[40:43], vcc_lo offen lds
	s_mov_b32 m0, s62
	s_nop 0
	buffer_load_dwordx4 v130, s[40:43], vcc_lo offen lds
	s_mov_b32 m0, s35
	s_nop 0
	buffer_load_dwordx4 v0, s[4:7], s21 offen lds
	s_mov_b32 m0, s63
	s_nop 0
	buffer_load_dwordx4 v130, s[4:7], s21 offen lds
	s_waitcnt vmcnt(8)
	s_waitcnt lgkmcnt(0)
	s_barrier
	s_setprio 1
	s_waitcnt lgkmcnt(0)
	v_mfma_f32_16x16x32_bf16 v[50:53], v[134:137], v[170:173], v[50:53]
	v_mfma_f32_16x16x32_bf16 v[30:33], v[142:145], v[170:173], v[30:33]
	v_mfma_f32_16x16x32_bf16 v[58:61], v[142:145], v[178:181], v[58:61]
	v_mfma_f32_16x16x32_bf16 v[62:65], v[134:137], v[178:181], v[62:65]
	v_mfma_f32_16x16x32_bf16 v[94:97], v[134:137], v[186:189], v[94:97]
	v_mfma_f32_16x16x32_bf16 v[82:85], v[142:145], v[186:189], v[82:85]
	v_mfma_f32_16x16x32_bf16 v[26:29], v[142:145], v[200:203], v[26:29]
	v_mfma_f32_16x16x32_bf16 v[46:49], v[134:137], v[200:203], v[46:49]
	v_mfma_f32_16x16x32_bf16 v[50:53], v[138:141], v[174:177], v[50:53]
	v_mfma_f32_16x16x32_bf16 v[30:33], v[146:149], v[174:177], v[30:33]
	v_mfma_f32_16x16x32_bf16 v[58:61], v[146:149], v[182:185], v[58:61]
	v_mfma_f32_16x16x32_bf16 v[62:65], v[138:141], v[182:185], v[62:65]
	v_mfma_f32_16x16x32_bf16 v[94:97], v[138:141], v[190:193], v[94:97]
	v_mfma_f32_16x16x32_bf16 v[82:85], v[146:149], v[190:193], v[82:85]
	v_mfma_f32_16x16x32_bf16 v[26:29], v[146:149], v[206:209], v[26:29]
	v_mfma_f32_16x16x32_bf16 v[46:49], v[138:141], v[206:209], v[46:49]
	s_setprio 0
	s_setprio 1
	v_mfma_f32_16x16x32_bf16 v[22:25], v[150:153], v[170:173], v[22:25]
	v_mfma_f32_16x16x32_bf16 v[10:13], v[158:161], v[170:173], v[10:13]
	v_mfma_f32_16x16x32_bf16 v[66:69], v[158:161], v[178:181], v[66:69]
	v_mfma_f32_16x16x32_bf16 v[54:57], v[150:153], v[178:181], v[54:57]
	v_mfma_f32_16x16x32_bf16 v[70:73], v[150:153], v[186:189], v[70:73]
	v_mfma_f32_16x16x32_bf16 v[42:45], v[158:161], v[186:189], v[42:45]
	v_mfma_f32_16x16x32_bf16 v[2:5], v[158:161], v[200:203], v[2:5]
	v_mfma_f32_16x16x32_bf16 v[6:9], v[150:153], v[200:203], v[6:9]
	v_mfma_f32_16x16x32_bf16 v[22:25], v[154:157], v[174:177], v[22:25]
	v_mfma_f32_16x16x32_bf16 v[10:13], v[166:169], v[174:177], v[10:13]
	v_mfma_f32_16x16x32_bf16 v[66:69], v[166:169], v[182:185], v[66:69]
	v_mfma_f32_16x16x32_bf16 v[54:57], v[154:157], v[182:185], v[54:57]
	v_mfma_f32_16x16x32_bf16 v[70:73], v[154:157], v[190:193], v[70:73]
	v_mfma_f32_16x16x32_bf16 v[42:45], v[166:169], v[190:193], v[42:45]
	v_mfma_f32_16x16x32_bf16 v[2:5], v[166:169], v[206:209], v[2:5]
	v_mfma_f32_16x16x32_bf16 v[6:9], v[154:157], v[206:209], v[6:9]
	s_setprio 0
	s_barrier
; #define PG8_STAGE(bufoff, gbase, voff) do { const int so_ = (int)(unsigned)((const char*)(gbase) - base_##voff); _Pragma("unroll") for (int _i = 0; _i < 2; ++_i) \
;         __builtin_amdgcn_raw_ptr_buffer_load_lds(rs_##voff, (PG8_LAS unsigned*)(lds + (bufoff) + ldsw + _i * 8192), 16, (int)(voff)[_i], so_, 0, 0); } while (0)
; #define PG8_LDA(dst, b, h) do { _Pragma("unroll") for (int m = 0; m < 4; ++m) _Pragma("unroll") for (int k = 0; k < 2; ++k) dst[m][k] = *(const PG8_LAS bf16x8*)(lds + PG8_SA(b, h) + aoff + m * 2048 + k * 1024); } while (0)
; #define PG8_LDB(dst, b, h) do { _Pragma("unroll") for (int n = 0; n < 2; ++n) _Pragma("unroll") for (int k = 0; k < 2; ++k) dst[n][k] = *(const PG8_LAS bf16x8*)(lds + PG8_SB(b, h) + boff + n * 2048 + k * 1024); } while (0)
; #define PG8_MMA(ai, bj, At, Bt) do { __builtin_amdgcn_s_setprio(1); _Pragma("unroll") for (int m = 0; m < 4; ++m) _Pragma("unroll") for (int n = 0; n < 2; ++n) _Pragma("unroll") for (int k = 0; k < 2; ++k) \
;         acc[ai][bj][m][n] = __builtin_amdgcn_mfma_f32_16x16x32_bf16(Bt[n][k], At[m][k], acc[ai][bj][m][n], 0, 0, 0); __builtin_amdgcn_s_setprio(0); } while (0)
; #define PG8_WAIT_V(n) asm volatile("s_waitcnt vmcnt(" #n ")" ::: "memory")
; #define PG8_BAR __builtin_amdgcn_s_barrier()
; template <class Epi, class Sched, bool ALIGN_EPI = false, bool SP2 = false>
; __device__ __forceinline__ void gemm_phase(PG8_LAS unsigned char* lds, const Gemm g, const Sched& S, const Epi& E, int tid_in) {
;     ...
;             PG8_LDB(B0, 0, 0); PG8_LDB(B1, 0, 1); PG8_SCHED; PG8_LDA(At, 0, 0); PG8_STAGE(PG8_SA(1, 1), a1 + hstepA, voffA);
;             PG8_WAIT_V(8); PG8_WAIT_L(0); PG8_BAR; PG8_MMA(0, 0, At, B0); PG8_MMA(0, 1, At, B1); PG8_BAR; PG8_SCHED;
;             PG8_LDA(At, 0, 1); PG8_STAGE(PG8_SB(0, 0), b2, voffB); PG8_STAGE(PG8_SB(0, 1), b2 + hstepB, voffB); PG8_STAGE(PG8_SA(0, 0), a2, voffA);
;             PG8_WAIT_V(8); PG8_WAIT_L(0); PG8_BAR; PG8_MMA(1, 0, At, B0); PG8_MMA(1, 1, At, B1); PG8_BAR; PG8_SCHED;
;             PG8_LDB(B0, 1, 0); PG8_LDB(B1, 1, 1); PG8_SCHED; PG8_LDA(At, 1, 0); PG8_STAGE(PG8_SA(0, 1), a2 + hstepA, voffA);
;             PG8_WAIT_V(8); PG8_WAIT_L(0); PG8_BAR; PG8_MMA(0, 0, At, B0); PG8_MMA(0, 1, At, B1); PG8_BAR; PG8_SCHED;
;             PG8_LDA(At, 1, 1); PG8_STAGE(PG8_SB(1, 0), b3, voffB); PG8_STAGE(PG8_SB(1, 1), b3 + hstepB, voffB); PG8_STAGE(PG8_SA(1, 0), a3, voffA);
	v_add_u32_e32 v133, 0x18000, v131
	ds_read_b128 v[134:137], v133
	ds_read_b128 v[138:141], v133 offset:1024
	ds_read_b128 v[142:145], v133 offset:2048
	ds_read_b128 v[146:149], v133 offset:3072
	v_add_u32_e32 v133, 0x1c000, v131
	ds_read_b128 v[150:153], v133
	ds_read_b128 v[154:157], v133 offset:1024
	ds_read_b128 v[158:161], v133 offset:2048
	ds_read_b128 v[166:169], v133 offset:3072
	s_add_i32 vcc_lo, s21, 0x80000
	s_mov_b32 m0, s66
	ds_read_b128 v[170:173], v132 offset:32768
	ds_read_b128 v[174:177], v132 offset:33792
	ds_read_b128 v[178:181], v132 offset:34816
	ds_read_b128 v[182:185], v132 offset:35840
	ds_read_b128 v[186:189], v132 offset:36864
	ds_read_b128 v[190:193], v132 offset:37888
	ds_read_b128 v[200:203], v132 offset:38912
	ds_read_b128 v[206:209], v132 offset:39936
	buffer_load_dwordx4 v0, s[4:7], vcc_lo offen lds
	s_mov_b32 m0, s67
	s_nop 0
	buffer_load_dwordx4 v130, s[4:7], vcc_lo offen lds
	s_waitcnt vmcnt(8)
	s_waitcnt lgkmcnt(0)
	s_barrier
	s_setprio 1
	s_waitcnt lgkmcnt(0)
	v_mfma_f32_16x16x32_bf16 v[34:37], v[134:137], v[170:173], v[34:37]
	v_mfma_f32_16x16x32_bf16 v[18:21], v[142:145], v[170:173], v[18:21]
	v_mfma_f32_16x16x32_bf16 v[78:81], v[142:145], v[178:181], v[78:81]
	v_mfma_f32_16x16x32_bf16 v[86:89], v[134:137], v[178:181], v[86:89]
	v_mfma_f32_16x16x32_bf16 v[106:109], v[134:137], v[186:189], v[106:109]
	v_mfma_f32_16x16x32_bf16 v[102:105], v[142:145], v[186:189], v[102:105]
	v_mfma_f32_16x16x32_bf16 v[122:125], v[142:145], v[200:203], v[122:125]
	v_mfma_f32_16x16x32_bf16 v[126:129], v[134:137], v[200:203], v[126:129]
	v_mfma_f32_16x16x32_bf16 v[34:37], v[138:141], v[174:177], v[34:37]
	v_mfma_f32_16x16x32_bf16 v[18:21], v[146:149], v[174:177], v[18:21]
	v_mfma_f32_16x16x32_bf16 v[78:81], v[146:149], v[182:185], v[78:81]
	v_mfma_f32_16x16x32_bf16 v[86:89], v[138:141], v[182:185], v[86:89]
	v_mfma_f32_16x16x32_bf16 v[106:109], v[138:141], v[190:193], v[106:109]
	v_mfma_f32_16x16x32_bf16 v[102:105], v[146:149], v[190:193], v[102:105]
	v_mfma_f32_16x16x32_bf16 v[122:125], v[146:149], v[206:209], v[122:125]
	v_mfma_f32_16x16x32_bf16 v[126:129], v[138:141], v[206:209], v[126:129]
	s_setprio 0
	s_setprio 1
	v_mfma_f32_16x16x32_bf16 v[14:17], v[150:153], v[170:173], v[14:17]
	v_mfma_f32_16x16x32_bf16 v[38:41], v[158:161], v[170:173], v[38:41]
	v_mfma_f32_16x16x32_bf16 v[90:93], v[158:161], v[178:181], v[90:93]
	v_mfma_f32_16x16x32_bf16 v[74:77], v[150:153], v[178:181], v[74:77]
	v_mfma_f32_16x16x32_bf16 v[98:101], v[150:153], v[186:189], v[98:101]
	v_mfma_f32_16x16x32_bf16 v[110:113], v[158:161], v[186:189], v[110:113]
	v_mfma_f32_16x16x32_bf16 v[114:117], v[158:161], v[200:203], v[114:117]
	v_mfma_f32_16x16x32_bf16 v[118:121], v[150:153], v[200:203], v[118:121]
	v_mfma_f32_16x16x32_bf16 v[14:17], v[154:157], v[174:177], v[14:17]
	v_mfma_f32_16x16x32_bf16 v[38:41], v[166:169], v[174:177], v[38:41]
	v_mfma_f32_16x16x32_bf16 v[90:93], v[166:169], v[182:185], v[90:93]
	v_mfma_f32_16x16x32_bf16 v[74:77], v[154:157], v[182:185], v[74:77]
	v_mfma_f32_16x16x32_bf16 v[98:101], v[154:157], v[190:193], v[98:101]
	v_mfma_f32_16x16x32_bf16 v[110:113], v[166:169], v[190:193], v[110:113]
	v_mfma_f32_16x16x32_bf16 v[114:117], v[166:169], v[206:209], v[114:117]
	v_mfma_f32_16x16x32_bf16 v[118:121], v[154:157], v[206:209], v[118:121]
	s_setprio 0
	s_barrier
	s_mov_b32 m0, s68
	s_add_i32 vcc_lo, s79, 0x80
	ds_read_b128 v[170:173], v132 offset:49152
	ds_read_b128 v[174:177], v132 offset:50176
	ds_read_b128 v[178:181], v132 offset:51200
	ds_read_b128 v[182:185], v132 offset:52224
	ds_read_b128 v[186:189], v132 offset:53248
	ds_read_b128 v[190:193], v132 offset:54272
	ds_read_b128 v[200:203], v132 offset:55296
	ds_read_b128 v[206:209], v132 offset:56320
	buffer_load_dwordx4 v0, s[40:43], vcc_lo offen lds
	s_mov_b32 m0, s69
	s_add_i32 s79, s79, 0x80080
	buffer_load_dwordx4 v130, s[40:43], vcc_lo offen lds
	s_mov_b32 m0, s73
	s_addk_i32 s21, 0x80
	buffer_load_dwordx4 v0, s[40:43], s79 offen lds
	s_mov_b32 m0, s74
	s_nop 0
	buffer_load_dwordx4 v130, s[40:43], s79 offen lds
	s_mov_b32 m0, s71
	s_nop 0
	buffer_load_dwordx4 v0, s[4:7], s21 offen lds
	s_mov_b32 m0, s72
	s_nop 0
	buffer_load_dwordx4 v130, s[4:7], s21 offen lds
	s_waitcnt vmcnt(8)
	s_waitcnt lgkmcnt(0)
	s_barrier
;     static __device__ __forceinline__ bool last_of_chain(const Unit& u) { return (u.pn >> 3) == 2; }
; #define PG8_MMA(ai, bj, At, Bt) do { __builtin_amdgcn_s_setprio(1); _Pragma("unroll") for (int m = 0; m < 4; ++m) _Pragma("unroll") for (int n = 0; n < 2; ++n) _Pragma("unroll") for (int k = 0; k < 2; ++k) \
;         acc[ai][bj][m][n] = __builtin_amdgcn_mfma_f32_16x16x32_bf16(Bt[n][k], At[m][k], acc[ai][bj][m][n], 0, 0, 0); __builtin_amdgcn_s_setprio(0); } while (0)
; #define PG8_WAIT_V(n) asm volatile("s_waitcnt vmcnt(" #n ")" ::: "memory")
; #define PG8_WAIT_L(n) asm volatile("s_waitcnt lgkmcnt(" #n ")" ::: "memory")
; #define PG8_BAR __builtin_amdgcn_s_barrier()
; #define PG8_SCHED __builtin_amdgcn_sched_barrier(0)
; template <class Epi, class Sched, bool ALIGN_EPI = false, bool SP2 = false>
; __device__ __forceinline__ void gemm_phase(PG8_LAS unsigned char* lds, const Gemm g, const Sched& S, const Epi& E, int tid_in) {
;     ...
;             PG8_WAIT_V(8); PG8_WAIT_L(0); PG8_BAR; PG8_MMA(1, 0, At, B0); PG8_MMA(1, 1, At, B1); PG8_BAR; PG8_SCHED;
;     ...
;         if (!has_next) break;
;         bool zero_acc = true; if constexpr (Epi::CHAIN) zero_acc = Epi::last_of_chain(cur);
;         if (zero_acc) {
; #pragma unroll
;         for (int a = 0; a < 2; ++a)
; #pragma unroll
;             for (int b = 0; b < 2; ++b)
; #pragma unroll
;                 for (int m = 0; m < 4; ++m)
; #pragma unroll
;                     for (int n = 0; n < 2; ++n) acc[a][b][m][n] = (f32x4){0.f, 0.f, 0.f, 0.f};
;         }
	s_setprio 1
	s_waitcnt lgkmcnt(0)
	v_mfma_f32_16x16x32_bf16 v[50:53], v[134:137], v[170:173], v[50:53]
	v_mfma_f32_16x16x32_bf16 v[30:33], v[142:145], v[170:173], v[30:33]
	v_mfma_f32_16x16x32_bf16 v[58:61], v[142:145], v[178:181], v[58:61]
	v_mfma_f32_16x16x32_bf16 v[62:65], v[134:137], v[178:181], v[62:65]
	v_mfma_f32_16x16x32_bf16 v[94:97], v[134:137], v[186:189], v[94:97]
	v_mfma_f32_16x16x32_bf16 v[82:85], v[142:145], v[186:189], v[82:85]
	v_mfma_f32_16x16x32_bf16 v[26:29], v[142:145], v[200:203], v[26:29]
	v_mfma_f32_16x16x32_bf16 v[46:49], v[134:137], v[200:203], v[46:49]
	v_mfma_f32_16x16x32_bf16 v[50:53], v[138:141], v[174:177], v[50:53]
	v_mfma_f32_16x16x32_bf16 v[30:33], v[146:149], v[174:177], v[30:33]
	v_mfma_f32_16x16x32_bf16 v[58:61], v[146:149], v[182:185], v[58:61]
	v_mfma_f32_16x16x32_bf16 v[62:65], v[138:141], v[182:185], v[62:65]
	v_mfma_f32_16x16x32_bf16 v[94:97], v[138:141], v[190:193], v[94:97]
	v_mfma_f32_16x16x32_bf16 v[82:85], v[146:149], v[190:193], v[82:85]
	v_mfma_f32_16x16x32_bf16 v[26:29], v[146:149], v[206:209], v[26:29]
	v_mfma_f32_16x16x32_bf16 v[46:49], v[138:141], v[206:209], v[46:49]
	s_setprio 0
	s_setprio 1
	v_mfma_f32_16x16x32_bf16 v[22:25], v[150:153], v[170:173], v[22:25]
	v_mfma_f32_16x16x32_bf16 v[10:13], v[158:161], v[170:173], v[10:13]
	v_mfma_f32_16x16x32_bf16 v[66:69], v[158:161], v[178:181], v[66:69]
	v_mfma_f32_16x16x32_bf16 v[54:57], v[150:153], v[178:181], v[54:57]
	v_mfma_f32_16x16x32_bf16 v[70:73], v[150:153], v[186:189], v[70:73]
	v_mfma_f32_16x16x32_bf16 v[42:45], v[158:161], v[186:189], v[42:45]
	v_mfma_f32_16x16x32_bf16 v[2:5], v[158:161], v[200:203], v[2:5]
	v_mfma_f32_16x16x32_bf16 v[6:9], v[150:153], v[200:203], v[6:9]
	v_mfma_f32_16x16x32_bf16 v[22:25], v[154:157], v[174:177], v[22:25]
	v_mfma_f32_16x16x32_bf16 v[10:13], v[166:169], v[174:177], v[10:13]
	v_mfma_f32_16x16x32_bf16 v[66:69], v[166:169], v[182:185], v[66:69]
	v_mfma_f32_16x16x32_bf16 v[54:57], v[154:157], v[182:185], v[54:57]
	v_mfma_f32_16x16x32_bf16 v[70:73], v[154:157], v[190:193], v[70:73]
	v_mfma_f32_16x16x32_bf16 v[42:45], v[166:169], v[190:193], v[42:45]
	v_mfma_f32_16x16x32_bf16 v[2:5], v[166:169], v[206:209], v[2:5]
	v_mfma_f32_16x16x32_bf16 v[6:9], v[154:157], v[206:209], v[6:9]
	s_setprio 0
	s_barrier
	s_add_i32 s19, s19, 2
	s_add_u32 s44, s44, 0x100
	s_addc_u32 s45, s45, 0
	s_cmp_gt_u32 s19, 29
	s_cbranch_scc0 .LBB0_1265
	s_andn2_b64 vcc, exec, s[38:39]
	s_cbranch_vccnz .LBB0_1257
	v_mov_b32_e32 v2, 0
	s_mov_b64 s[12:13], s[24:25]
	s_mov_b32 s10, s16
	s_mov_b32 s48, s20
	s_mov_b64 s[14:15], s[22:23]
	s_mov_b32 s13, s78
	v_mov_b32_e32 v3, v2
	v_mov_b32_e32 v4, v2
	v_mov_b32_e32 v5, v2
	v_mov_b32_e32 v6, v2
	v_mov_b32_e32 v7, v2
	v_mov_b32_e32 v8, v2
	v_mov_b32_e32 v9, v2
	v_mov_b32_e32 v42, v2
	v_mov_b32_e32 v43, v2
	v_mov_b32_e32 v44, v2
	v_mov_b32_e32 v45, v2
	v_mov_b32_e32 v70, v2
	v_mov_b32_e32 v71, v2
	v_mov_b32_e32 v72, v2
	v_mov_b32_e32 v73, v2
	v_mov_b32_e32 v66, v2
	v_mov_b32_e32 v67, v2
	v_mov_b32_e32 v68, v2
	v_mov_b32_e32 v69, v2
	v_mov_b32_e32 v54, v2
	v_mov_b32_e32 v55, v2
	v_mov_b32_e32 v56, v2
	v_mov_b32_e32 v57, v2
	v_mov_b32_e32 v10, v2
	v_mov_b32_e32 v11, v2
	v_mov_b32_e32 v12, v2
	v_mov_b32_e32 v13, v2
	v_mov_b32_e32 v22, v2
	v_mov_b32_e32 v23, v2
	v_mov_b32_e32 v24, v2
	v_mov_b32_e32 v25, v2
	v_mov_b32_e32 v26, v2
	v_mov_b32_e32 v27, v2
	v_mov_b32_e32 v28, v2
	v_mov_b32_e32 v29, v2
	v_mov_b32_e32 v46, v2
	v_mov_b32_e32 v47, v2
	v_mov_b32_e32 v48, v2
	v_mov_b32_e32 v49, v2
	v_mov_b32_e32 v82, v2
	v_mov_b32_e32 v83, v2
	v_mov_b32_e32 v84, v2
	v_mov_b32_e32 v85, v2
	v_mov_b32_e32 v94, v2
	v_mov_b32_e32 v95, v2
	v_mov_b32_e32 v96, v2
	v_mov_b32_e32 v97, v2
	v_mov_b32_e32 v58, v2
	v_mov_b32_e32 v59, v2
	v_mov_b32_e32 v60, v2
	v_mov_b32_e32 v61, v2
	v_mov_b32_e32 v62, v2
	v_mov_b32_e32 v63, v2
	v_mov_b32_e32 v64, v2
	v_mov_b32_e32 v65, v2
	v_mov_b32_e32 v30, v2
	v_mov_b32_e32 v31, v2
	v_mov_b32_e32 v32, v2
	v_mov_b32_e32 v33, v2
	v_mov_b32_e32 v50, v2
	v_mov_b32_e32 v51, v2
	v_mov_b32_e32 v52, v2
	v_mov_b32_e32 v53, v2
	v_mov_b32_e32 v114, v2
	v_mov_b32_e32 v115, v2
	v_mov_b32_e32 v116, v2
	v_mov_b32_e32 v117, v2
	v_mov_b32_e32 v118, v2
	v_mov_b32_e32 v119, v2
	v_mov_b32_e32 v120, v2
	v_mov_b32_e32 v121, v2
	v_mov_b32_e32 v110, v2
	v_mov_b32_e32 v111, v2
	v_mov_b32_e32 v112, v2
	v_mov_b32_e32 v113, v2
	v_mov_b32_e32 v98, v2
	v_mov_b32_e32 v99, v2
	v_mov_b32_e32 v100, v2
	v_mov_b32_e32 v101, v2
	v_mov_b32_e32 v90, v2
	v_mov_b32_e32 v91, v2
	v_mov_b32_e32 v92, v2
	v_mov_b32_e32 v93, v2
	v_mov_b32_e32 v74, v2
	v_mov_b32_e32 v75, v2
	v_mov_b32_e32 v76, v2
	v_mov_b32_e32 v77, v2
	v_mov_b32_e32 v38, v2
	v_mov_b32_e32 v39, v2
	v_mov_b32_e32 v40, v2
	v_mov_b32_e32 v41, v2
	v_mov_b32_e32 v14, v2
	v_mov_b32_e32 v15, v2
	v_mov_b32_e32 v16, v2
	v_mov_b32_e32 v17, v2
	v_mov_b32_e32 v122, v2
	v_mov_b32_e32 v123, v2
	v_mov_b32_e32 v124, v2
	v_mov_b32_e32 v125, v2
	v_mov_b32_e32 v126, v2
	v_mov_b32_e32 v127, v2
	v_mov_b32_e32 v128, v2
	v_mov_b32_e32 v129, v2
	v_mov_b32_e32 v102, v2
	v_mov_b32_e32 v103, v2
	v_mov_b32_e32 v104, v2
	v_mov_b32_e32 v105, v2
	v_mov_b32_e32 v106, v2
	v_mov_b32_e32 v107, v2
	v_mov_b32_e32 v108, v2
	v_mov_b32_e32 v109, v2
	v_mov_b32_e32 v78, v2
	v_mov_b32_e32 v79, v2
	v_mov_b32_e32 v80, v2
	v_mov_b32_e32 v81, v2
	v_mov_b32_e32 v86, v2
	v_mov_b32_e32 v87, v2
	v_mov_b32_e32 v88, v2
	v_mov_b32_e32 v89, v2
	v_mov_b32_e32 v18, v2
	v_mov_b32_e32 v19, v2
	v_mov_b32_e32 v20, v2
	v_mov_b32_e32 v21, v2
	v_mov_b32_e32 v34, v2
	v_mov_b32_e32 v35, v2
	v_mov_b32_e32 v36, v2
	v_mov_b32_e32 v37, v2
	s_branch .LBB0_1257

; #define PG8_STAGE(bufoff, gbase, voff) do { const int so_ = (int)(unsigned)((const char*)(gbase) - base_##voff); _Pragma("unroll") for (int _i = 0; _i < 2; ++_i) \
;         __builtin_amdgcn_raw_ptr_buffer_load_lds(rs_##voff, (PG8_LAS unsigned*)(lds + (bufoff) + ldsw + _i * 8192), 16, (int)(voff)[_i], so_, 0, 0); } while (0)
; #define PG8_LDA(dst, b, h) do { _Pragma("unroll") for (int m = 0; m < 4; ++m) _Pragma("unroll") for (int k = 0; k < 2; ++k) dst[m][k] = *(const PG8_LAS bf16x8*)(lds + PG8_SA(b, h) + aoff + m * 2048 + k * 1024); } while (0)
; #define PG8_LDB(dst, b, h) do { _Pragma("unroll") for (int n = 0; n < 2; ++n) _Pragma("unroll") for (int k = 0; k < 2; ++k) dst[n][k] = *(const PG8_LAS bf16x8*)(lds + PG8_SB(b, h) + boff + n * 2048 + k * 1024); } while (0)
; #define PG8_MMA(ai, bj, At, Bt) do { __builtin_amdgcn_s_setprio(1); _Pragma("unroll") for (int m = 0; m < 4; ++m) _Pragma("unroll") for (int n = 0; n < 2; ++n) _Pragma("unroll") for (int k = 0; k < 2; ++k) \
;         acc[ai][bj][m][n] = __builtin_amdgcn_mfma_f32_16x16x32_bf16(Bt[n][k], At[m][k], acc[ai][bj][m][n], 0, 0, 0); __builtin_amdgcn_s_setprio(0); } while (0)
; template <class Epi, class Sched, bool ALIGN_EPI = false, bool SP2 = false>
; __device__ __forceinline__ void gemm_phase(PG8_LAS unsigned char* lds, const Gemm g, const Sched& S, const Epi& E, int tid_in) {
;     ...
;             PG8_LDB(B0, 0, 0); PG8_LDB(B1, 0, 1); PG8_SCHED; PG8_LDA(At, 0, 0); PG8_STAGE(PG8_SA(1, 1), a1 + hstepA, voffA);
;             PG8_WAIT_V(8); PG8_WAIT_L(0); PG8_BAR; PG8_MMA(0, 0, At, B0); PG8_MMA(0, 1, At, B1); PG8_BAR; PG8_SCHED;
;             PG8_LDA(At, 0, 1); PG8_STAGE(PG8_SB(0, 0), b2, voffB); PG8_STAGE(PG8_SB(0, 1), b2 + hstepB, voffB); PG8_STAGE(PG8_SA(0, 0), a2, voffA);
;             PG8_WAIT_V(8); PG8_WAIT_L(0); PG8_BAR; PG8_MMA(1, 0, At, B0); PG8_MMA(1, 1, At, B1); PG8_BAR; PG8_SCHED;
;             PG8_LDB(B0, 1, 0); PG8_LDB(B1, 1, 1); PG8_SCHED; PG8_LDA(At, 1, 0); PG8_STAGE(PG8_SA(0, 1), a2 + hstepA, voffA);
;             PG8_WAIT_V(8); PG8_WAIT_L(0); PG8_BAR; PG8_MMA(0, 0, At, B0); PG8_MMA(0, 1, At, B1); PG8_BAR; PG8_SCHED;
;             PG8_LDA(At, 1, 1); PG8_STAGE(PG8_SB(1, 0), b3, voffB); PG8_STAGE(PG8_SB(1, 1), b3 + hstepB, voffB); PG8_STAGE(PG8_SA(1, 0), a3, voffA);
;             PG8_WAIT_V(8); PG8_WAIT_L(0); PG8_BAR; PG8_MMA(1, 0, At, B0); PG8_MMA(1, 1, At, B1); PG8_BAR; PG8_SCHED;
.LBB0_1514:
	v_add_u32_e32 v141, 0x10000, v139
	ds_read_b128 v[130:133], v141
	ds_read_b128 v[142:145], v141 offset:1024
	ds_read_b128 v[146:149], v141 offset:2048
	ds_read_b128 v[150:153], v141 offset:3072
	v_add_u32_e32 v141, 0x14000, v139
	ds_read_b128 v[154:157], v141
	ds_read_b128 v[158:161], v141 offset:1024
	ds_read_b128 v[162:165], v141 offset:2048
	ds_read_b128 v[166:169], v141 offset:3072
	s_add_u32 s38, s16, 0x100
	s_addc_u32 s39, s17, 0
	s_sub_i32 s16, s16, s4
	s_add_i32 s16, s16, 0x80080
	s_cmp_eq_u32 s73, 28
	s_cselect_b32 s17, s18, s38
	s_mov_b32 m0, s67
	ds_read_b128 v[170:173], v140
	ds_read_b128 v[174:177], v140 offset:1024
	ds_read_b128 v[178:181], v140 offset:2048
	ds_read_b128 v[182:185], v140 offset:3072
	ds_read_b128 v[186:189], v140 offset:4096
	ds_read_b128 v[190:193], v140 offset:5120
	ds_read_b128 v[200:203], v140 offset:6144
	ds_read_b128 v[206:209], v140 offset:7168
	buffer_load_dwordx4 v0, s[4:7], s16 offen lds
	s_mov_b32 m0, s68
	s_nop 0
	buffer_load_dwordx4 v135, s[4:7], s16 offen lds
	s_waitcnt vmcnt(8)
	s_waitcnt lgkmcnt(0)
	s_barrier
	s_setprio 1
	s_waitcnt lgkmcnt(0)
	v_mfma_f32_16x16x32_bf16 v[126:129], v[130:133], v[170:173], v[126:129]
	v_mfma_f32_16x16x32_bf16 v[122:125], v[146:149], v[170:173], v[122:125]
	v_mfma_f32_16x16x32_bf16 v[106:109], v[146:149], v[178:181], v[106:109]
	v_mfma_f32_16x16x32_bf16 v[110:113], v[130:133], v[178:181], v[110:113]
	v_mfma_f32_16x16x32_bf16 v[94:97], v[130:133], v[186:189], v[94:97]
	v_mfma_f32_16x16x32_bf16 v[90:93], v[146:149], v[186:189], v[90:93]
	v_mfma_f32_16x16x32_bf16 v[74:77], v[146:149], v[200:203], v[74:77]
	v_mfma_f32_16x16x32_bf16 v[78:81], v[130:133], v[200:203], v[78:81]
	v_mfma_f32_16x16x32_bf16 v[126:129], v[142:145], v[174:177], v[126:129]
	v_mfma_f32_16x16x32_bf16 v[122:125], v[150:153], v[174:177], v[122:125]
	v_mfma_f32_16x16x32_bf16 v[106:109], v[150:153], v[182:185], v[106:109]
	v_mfma_f32_16x16x32_bf16 v[110:113], v[142:145], v[182:185], v[110:113]
	v_mfma_f32_16x16x32_bf16 v[94:97], v[142:145], v[190:193], v[94:97]
	v_mfma_f32_16x16x32_bf16 v[90:93], v[150:153], v[190:193], v[90:93]
	v_mfma_f32_16x16x32_bf16 v[74:77], v[150:153], v[206:209], v[74:77]
	v_mfma_f32_16x16x32_bf16 v[78:81], v[142:145], v[206:209], v[78:81]
	s_setprio 0
	s_setprio 1
	v_mfma_f32_16x16x32_bf16 v[118:121], v[154:157], v[170:173], v[118:121]
	v_mfma_f32_16x16x32_bf16 v[114:117], v[162:165], v[170:173], v[114:117]
	v_mfma_f32_16x16x32_bf16 v[98:101], v[162:165], v[178:181], v[98:101]
	v_mfma_f32_16x16x32_bf16 v[102:105], v[154:157], v[178:181], v[102:105]
	v_mfma_f32_16x16x32_bf16 v[86:89], v[154:157], v[186:189], v[86:89]
	v_mfma_f32_16x16x32_bf16 v[82:85], v[162:165], v[186:189], v[82:85]
	v_mfma_f32_16x16x32_bf16 v[66:69], v[162:165], v[200:203], v[66:69]
	v_mfma_f32_16x16x32_bf16 v[70:73], v[154:157], v[200:203], v[70:73]
	v_mfma_f32_16x16x32_bf16 v[118:121], v[158:161], v[174:177], v[118:121]
	v_mfma_f32_16x16x32_bf16 v[114:117], v[166:169], v[174:177], v[114:117]
	v_mfma_f32_16x16x32_bf16 v[98:101], v[166:169], v[182:185], v[98:101]
	v_mfma_f32_16x16x32_bf16 v[102:105], v[158:161], v[182:185], v[102:105]
	v_mfma_f32_16x16x32_bf16 v[86:89], v[158:161], v[190:193], v[86:89]
	v_mfma_f32_16x16x32_bf16 v[82:85], v[166:169], v[190:193], v[82:85]
	v_mfma_f32_16x16x32_bf16 v[66:69], v[166:169], v[206:209], v[66:69]
	v_mfma_f32_16x16x32_bf16 v[70:73], v[158:161], v[206:209], v[70:73]
	s_setprio 0
	s_barrier
	s_cselect_b32 s16, s15, s19
	s_mov_b32 m0, s35
	s_mov_b32 s42, s6
	s_mov_b32 s43, s7
	s_sub_i32 s16, s16, s40
	ds_read_b128 v[170:173], v140 offset:16384
	ds_read_b128 v[174:177], v140 offset:17408
	ds_read_b128 v[178:181], v140 offset:18432
	ds_read_b128 v[182:185], v140 offset:19456
	ds_read_b128 v[186:189], v140 offset:20480
	ds_read_b128 v[190:193], v140 offset:21504
	ds_read_b128 v[200:203], v140 offset:22528
	ds_read_b128 v[206:209], v140 offset:23552
	buffer_load_dwordx4 v134, s[40:43], s16 offen lds
	s_mov_b32 m0, s44
	s_add_i32 s74, s16, 0x80000
	buffer_load_dwordx4 v136, s[40:43], s16 offen lds
	s_mov_b32 m0, s45
	s_sub_i32 s17, s17, s4
	buffer_load_dwordx4 v134, s[40:43], s74 offen lds
	s_mov_b32 m0, s46
	s_nop 0
	buffer_load_dwordx4 v136, s[40:43], s74 offen lds
	s_mov_b32 m0, s34
	s_nop 0
	buffer_load_dwordx4 v0, s[4:7], s17 offen lds
	s_mov_b32 m0, s47
	s_nop 0
	buffer_load_dwordx4 v135, s[4:7], s17 offen lds
	s_waitcnt vmcnt(8)
	s_waitcnt lgkmcnt(0)
	s_barrier
	s_setprio 1
	s_waitcnt lgkmcnt(0)
	v_mfma_f32_16x16x32_bf16 v[62:65], v[130:133], v[170:173], v[62:65]
	v_mfma_f32_16x16x32_bf16 v[58:61], v[146:149], v[170:173], v[58:61]
	v_mfma_f32_16x16x32_bf16 v[42:45], v[146:149], v[178:181], v[42:45]
	v_mfma_f32_16x16x32_bf16 v[46:49], v[130:133], v[178:181], v[46:49]
	v_mfma_f32_16x16x32_bf16 v[30:33], v[130:133], v[186:189], v[30:33]
	v_mfma_f32_16x16x32_bf16 v[26:29], v[146:149], v[186:189], v[26:29]
	v_mfma_f32_16x16x32_bf16 v[10:13], v[146:149], v[200:203], v[10:13]
	v_mfma_f32_16x16x32_bf16 v[14:17], v[130:133], v[200:203], v[14:17]
	v_mfma_f32_16x16x32_bf16 v[62:65], v[142:145], v[174:177], v[62:65]
	v_mfma_f32_16x16x32_bf16 v[58:61], v[150:153], v[174:177], v[58:61]
	v_mfma_f32_16x16x32_bf16 v[42:45], v[150:153], v[182:185], v[42:45]
	v_mfma_f32_16x16x32_bf16 v[46:49], v[142:145], v[182:185], v[46:49]
	v_mfma_f32_16x16x32_bf16 v[30:33], v[142:145], v[190:193], v[30:33]
	v_mfma_f32_16x16x32_bf16 v[26:29], v[150:153], v[190:193], v[26:29]
	v_mfma_f32_16x16x32_bf16 v[10:13], v[150:153], v[206:209], v[10:13]
	v_mfma_f32_16x16x32_bf16 v[14:17], v[142:145], v[206:209], v[14:17]
	s_setprio 0
	s_setprio 1
	v_mfma_f32_16x16x32_bf16 v[54:57], v[154:157], v[170:173], v[54:57]
	v_mfma_f32_16x16x32_bf16 v[50:53], v[162:165], v[170:173], v[50:53]
	v_mfma_f32_16x16x32_bf16 v[34:37], v[162:165], v[178:181], v[34:37]
	v_mfma_f32_16x16x32_bf16 v[38:41], v[154:157], v[178:181], v[38:41]
	v_mfma_f32_16x16x32_bf16 v[22:25], v[154:157], v[186:189], v[22:25]
	v_mfma_f32_16x16x32_bf16 v[18:21], v[162:165], v[186:189], v[18:21]
	v_mfma_f32_16x16x32_bf16 v[2:5], v[162:165], v[200:203], v[2:5]
	v_mfma_f32_16x16x32_bf16 v[6:9], v[154:157], v[200:203], v[6:9]
	v_mfma_f32_16x16x32_bf16 v[54:57], v[158:161], v[174:177], v[54:57]
	v_mfma_f32_16x16x32_bf16 v[50:53], v[166:169], v[174:177], v[50:53]
	v_mfma_f32_16x16x32_bf16 v[34:37], v[166:169], v[182:185], v[34:37]
	v_mfma_f32_16x16x32_bf16 v[38:41], v[158:161], v[182:185], v[38:41]
	v_mfma_f32_16x16x32_bf16 v[22:25], v[158:161], v[190:193], v[22:25]
	v_mfma_f32_16x16x32_bf16 v[18:21], v[166:169], v[190:193], v[18:21]
	v_mfma_f32_16x16x32_bf16 v[2:5], v[166:169], v[206:209], v[2:5]
	v_mfma_f32_16x16x32_bf16 v[6:9], v[158:161], v[206:209], v[6:9]
	s_setprio 0
	s_barrier
; template <class Epi, class Sched, bool ALIGN_EPI = false, bool SP2 = false>
; __device__ __forceinline__ void gemm_phase(PG8_LAS unsigned char* lds, const Gemm g, const Sched& S, const Epi& E, int tid_in) {
;     ...
;             PG8_LDB(B0, 0, 0); PG8_LDB(B1, 0, 1); PG8_SCHED; PG8_LDA(At, 0, 0); PG8_STAGE(PG8_SA(1, 1), a1 + hstepA, voffA);
;             PG8_WAIT_V(8); PG8_WAIT_L(0); PG8_BAR; PG8_MMA(0, 0, At, B0); PG8_MMA(0, 1, At, B1); PG8_BAR; PG8_SCHED;
;             PG8_LDA(At, 0, 1); PG8_STAGE(PG8_SB(0, 0), b2, voffB); PG8_STAGE(PG8_SB(0, 1), b2 + hstepB, voffB); PG8_STAGE(PG8_SA(0, 0), a2, voffA);
;             PG8_WAIT_V(8); PG8_WAIT_L(0); PG8_BAR; PG8_MMA(1, 0, At, B0); PG8_MMA(1, 1, At, B1); PG8_BAR; PG8_SCHED;
;             PG8_LDB(B0, 1, 0); PG8_LDB(B1, 1, 1); PG8_SCHED; PG8_LDA(At, 1, 0); PG8_STAGE(PG8_SA(0, 1), a2 + hstepA, voffA);
;             PG8_WAIT_V(8); PG8_WAIT_L(0); PG8_BAR; PG8_MMA(0, 0, At, B0); PG8_MMA(0, 1, At, B1); PG8_BAR; PG8_SCHED;
;             PG8_LDA(At, 1, 1); PG8_STAGE(PG8_SB(1, 0), b3, voffB); PG8_STAGE(PG8_SB(1, 1), b3 + hstepB, voffB); PG8_STAGE(PG8_SA(1, 0), a3, voffA);
;             PG8_WAIT_V(8); PG8_WAIT_L(0); PG8_BAR; PG8_MMA(1, 0, At, B0); PG8_MMA(1, 1, At, B1); PG8_BAR; PG8_SCHED;
;             } else {
;             PG8_LDB(B0, 0, 0); PG8_SCHED; PG8_LDA(At, 0, 0); PG8_STAGE(PG8_SA(1, 1), a1 + hstepA, voffA);
;             PG8_WAIT_L(8); PG8_BAR; PG8_WAIT_L(0); PG8_MMA(0, 0, At, B0); PG8_BAR; PG8_SCHED;
;             PG8_LDB(B1, 0, 1); PG8_STAGE(PG8_SB(0, 0), b2, voffB);
;             PG8_BAR; PG8_WAIT_L(0); PG8_MMA(0, 1, At, B1); PG8_BAR;
;             PG8_LDA(At, 0, 1); PG8_STAGE(PG8_SA(0, 0), a2, voffA);
;             PG8_BAR; PG8_WAIT_L(0); PG8_MMA(1, 0, At, B0); PG8_BAR; PG8_SCHED;
;             PG8_STAGE(PG8_SB(0, 1), b2 + hstepB, voffB);
;             PG8_WAIT_V(6); PG8_BAR; PG8_MMA(1, 1, At, B1); PG8_BAR;
;             PG8_LDB(B0, 1, 0); PG8_SCHED; PG8_LDA(At, 1, 0); PG8_STAGE(PG8_SA(0, 1), a2 + hstepA, voffA);
;             PG8_WAIT_L(8); PG8_BAR; PG8_WAIT_L(0); PG8_MMA(0, 0, At, B0); PG8_BAR; PG8_SCHED;
;             PG8_LDB(B1, 1, 1); PG8_STAGE(PG8_SB(1, 0), b3, voffB);
;             PG8_BAR; PG8_WAIT_L(0); PG8_MMA(0, 1, At, B1); PG8_BAR;
;             PG8_LDA(At, 1, 1); PG8_STAGE(PG8_SA(1, 0), a3, voffA);
;             PG8_BAR; PG8_WAIT_L(0); PG8_MMA(1, 0, At, B0); PG8_BAR; PG8_SCHED;
	v_add_u32_e32 v141, 0x18000, v139
	ds_read_b128 v[130:133], v141
	ds_read_b128 v[142:145], v141 offset:1024
	ds_read_b128 v[146:149], v141 offset:2048
	ds_read_b128 v[150:153], v141 offset:3072
	v_add_u32_e32 v141, 0x1c000, v139
	ds_read_b128 v[154:157], v141
	ds_read_b128 v[158:161], v141 offset:1024
	ds_read_b128 v[162:165], v141 offset:2048
	ds_read_b128 v[166:169], v141 offset:3072
	s_add_i32 s74, s17, 0x80000
	s_mov_b32 m0, s48
	ds_read_b128 v[170:173], v140 offset:32768
	ds_read_b128 v[174:177], v140 offset:33792
	ds_read_b128 v[178:181], v140 offset:34816
	ds_read_b128 v[182:185], v140 offset:35840
	ds_read_b128 v[186:189], v140 offset:36864
	ds_read_b128 v[190:193], v140 offset:37888
	ds_read_b128 v[200:203], v140 offset:38912
	ds_read_b128 v[206:209], v140 offset:39936
	buffer_load_dwordx4 v0, s[4:7], s74 offen lds
	s_mov_b32 m0, s49
	s_nop 0
	buffer_load_dwordx4 v135, s[4:7], s74 offen lds
	s_waitcnt vmcnt(8)
	s_waitcnt lgkmcnt(0)
	s_barrier
	s_setprio 1
	s_waitcnt lgkmcnt(0)
	v_mfma_f32_16x16x32_bf16 v[126:129], v[130:133], v[170:173], v[126:129]
	v_mfma_f32_16x16x32_bf16 v[122:125], v[146:149], v[170:173], v[122:125]
	v_mfma_f32_16x16x32_bf16 v[106:109], v[146:149], v[178:181], v[106:109]
	v_mfma_f32_16x16x32_bf16 v[110:113], v[130:133], v[178:181], v[110:113]
	v_mfma_f32_16x16x32_bf16 v[94:97], v[130:133], v[186:189], v[94:97]
	v_mfma_f32_16x16x32_bf16 v[90:93], v[146:149], v[186:189], v[90:93]
	v_mfma_f32_16x16x32_bf16 v[74:77], v[146:149], v[200:203], v[74:77]
	v_mfma_f32_16x16x32_bf16 v[78:81], v[130:133], v[200:203], v[78:81]
	v_mfma_f32_16x16x32_bf16 v[126:129], v[142:145], v[174:177], v[126:129]
	v_mfma_f32_16x16x32_bf16 v[122:125], v[150:153], v[174:177], v[122:125]
	v_mfma_f32_16x16x32_bf16 v[106:109], v[150:153], v[182:185], v[106:109]
	v_mfma_f32_16x16x32_bf16 v[110:113], v[142:145], v[182:185], v[110:113]
	v_mfma_f32_16x16x32_bf16 v[94:97], v[142:145], v[190:193], v[94:97]
	v_mfma_f32_16x16x32_bf16 v[90:93], v[150:153], v[190:193], v[90:93]
	v_mfma_f32_16x16x32_bf16 v[74:77], v[150:153], v[206:209], v[74:77]
	v_mfma_f32_16x16x32_bf16 v[78:81], v[142:145], v[206:209], v[78:81]
	s_setprio 0
	s_setprio 1
	v_mfma_f32_16x16x32_bf16 v[118:121], v[154:157], v[170:173], v[118:121]
	v_mfma_f32_16x16x32_bf16 v[114:117], v[162:165], v[170:173], v[114:117]
	v_mfma_f32_16x16x32_bf16 v[98:101], v[162:165], v[178:181], v[98:101]
	v_mfma_f32_16x16x32_bf16 v[102:105], v[154:157], v[178:181], v[102:105]
	v_mfma_f32_16x16x32_bf16 v[86:89], v[154:157], v[186:189], v[86:89]
	v_mfma_f32_16x16x32_bf16 v[82:85], v[162:165], v[186:189], v[82:85]
	v_mfma_f32_16x16x32_bf16 v[66:69], v[162:165], v[200:203], v[66:69]
	v_mfma_f32_16x16x32_bf16 v[70:73], v[154:157], v[200:203], v[70:73]
	v_mfma_f32_16x16x32_bf16 v[118:121], v[158:161], v[174:177], v[118:121]
	v_mfma_f32_16x16x32_bf16 v[114:117], v[166:169], v[174:177], v[114:117]
	v_mfma_f32_16x16x32_bf16 v[98:101], v[166:169], v[182:185], v[98:101]
	v_mfma_f32_16x16x32_bf16 v[102:105], v[158:161], v[182:185], v[102:105]
	v_mfma_f32_16x16x32_bf16 v[86:89], v[158:161], v[190:193], v[86:89]
	v_mfma_f32_16x16x32_bf16 v[82:85], v[166:169], v[190:193], v[82:85]
	v_mfma_f32_16x16x32_bf16 v[66:69], v[166:169], v[206:209], v[66:69]
	v_mfma_f32_16x16x32_bf16 v[70:73], v[158:161], v[206:209], v[70:73]
	s_setprio 0
	s_barrier
	s_mov_b32 m0, s53
	s_add_i32 s74, s16, 0x80
	ds_read_b128 v[170:173], v140 offset:49152
	ds_read_b128 v[174:177], v140 offset:50176
	ds_read_b128 v[178:181], v140 offset:51200
	ds_read_b128 v[182:185], v140 offset:52224
	ds_read_b128 v[186:189], v140 offset:53248
	ds_read_b128 v[190:193], v140 offset:54272
	ds_read_b128 v[200:203], v140 offset:55296
	ds_read_b128 v[206:209], v140 offset:56320
	buffer_load_dwordx4 v134, s[40:43], s74 offen lds
	s_mov_b32 m0, s60
	s_add_i32 s16, s16, 0x80080
	buffer_load_dwordx4 v136, s[40:43], s74 offen lds
	s_mov_b32 m0, s63
	s_addk_i32 s17, 0x80
	buffer_load_dwordx4 v134, s[40:43], s16 offen lds
	s_mov_b32 m0, s66
	s_nop 0
	buffer_load_dwordx4 v136, s[40:43], s16 offen lds
	s_mov_b32 m0, s61
	s_nop 0
	buffer_load_dwordx4 v0, s[4:7], s17 offen lds
	s_mov_b32 m0, s62
	s_nop 0
	buffer_load_dwordx4 v135, s[4:7], s17 offen lds
	s_waitcnt vmcnt(8)
	s_waitcnt lgkmcnt(0)
	s_barrier
	s_setprio 1
	s_waitcnt lgkmcnt(0)
	v_mfma_f32_16x16x32_bf16 v[62:65], v[130:133], v[170:173], v[62:65]
	v_mfma_f32_16x16x32_bf16 v[58:61], v[146:149], v[170:173], v[58:61]
	v_mfma_f32_16x16x32_bf16 v[42:45], v[146:149], v[178:181], v[42:45]
	v_mfma_f32_16x16x32_bf16 v[46:49], v[130:133], v[178:181], v[46:49]
	v_mfma_f32_16x16x32_bf16 v[30:33], v[130:133], v[186:189], v[30:33]
	v_mfma_f32_16x16x32_bf16 v[26:29], v[146:149], v[186:189], v[26:29]
	v_mfma_f32_16x16x32_bf16 v[10:13], v[146:149], v[200:203], v[10:13]
	v_mfma_f32_16x16x32_bf16 v[14:17], v[130:133], v[200:203], v[14:17]
	v_mfma_f32_16x16x32_bf16 v[62:65], v[142:145], v[174:177], v[62:65]
	v_mfma_f32_16x16x32_bf16 v[58:61], v[150:153], v[174:177], v[58:61]
	v_mfma_f32_16x16x32_bf16 v[42:45], v[150:153], v[182:185], v[42:45]
	v_mfma_f32_16x16x32_bf16 v[46:49], v[142:145], v[182:185], v[46:49]
	v_mfma_f32_16x16x32_bf16 v[30:33], v[142:145], v[190:193], v[30:33]
	v_mfma_f32_16x16x32_bf16 v[26:29], v[150:153], v[190:193], v[26:29]
	v_mfma_f32_16x16x32_bf16 v[10:13], v[150:153], v[206:209], v[10:13]
	v_mfma_f32_16x16x32_bf16 v[14:17], v[142:145], v[206:209], v[14:17]
	s_setprio 0
	s_setprio 1
	v_mfma_f32_16x16x32_bf16 v[54:57], v[154:157], v[170:173], v[54:57]
	v_mfma_f32_16x16x32_bf16 v[50:53], v[162:165], v[170:173], v[50:53]
	v_mfma_f32_16x16x32_bf16 v[34:37], v[162:165], v[178:181], v[34:37]
	v_mfma_f32_16x16x32_bf16 v[38:41], v[154:157], v[178:181], v[38:41]
	v_mfma_f32_16x16x32_bf16 v[22:25], v[154:157], v[186:189], v[22:25]
	v_mfma_f32_16x16x32_bf16 v[18:21], v[162:165], v[186:189], v[18:21]
	v_mfma_f32_16x16x32_bf16 v[2:5], v[162:165], v[200:203], v[2:5]
	v_mfma_f32_16x16x32_bf16 v[6:9], v[154:157], v[200:203], v[6:9]
	v_mfma_f32_16x16x32_bf16 v[54:57], v[158:161], v[174:177], v[54:57]
	v_mfma_f32_16x16x32_bf16 v[50:53], v[166:169], v[174:177], v[50:53]
	v_mfma_f32_16x16x32_bf16 v[34:37], v[166:169], v[182:185], v[34:37]
	v_mfma_f32_16x16x32_bf16 v[38:41], v[158:161], v[182:185], v[38:41]
	v_mfma_f32_16x16x32_bf16 v[22:25], v[158:161], v[190:193], v[22:25]
	v_mfma_f32_16x16x32_bf16 v[18:21], v[166:169], v[190:193], v[18:21]
	v_mfma_f32_16x16x32_bf16 v[2:5], v[166:169], v[206:209], v[2:5]
	v_mfma_f32_16x16x32_bf16 v[6:9], v[158:161], v[206:209], v[6:9]
	s_setprio 0
	s_barrier
	s_add_i32 s73, s73, 2
	s_add_u32 s19, s19, 0x100
	s_addc_u32 s21, s21, 0
	s_cmp_gt_u32 s73, 29
	s_mov_b64 s[16:17], s[38:39]
	s_cbranch_scc0 .LBB0_1514
	s_and_b64 vcc, exec, s[12:13]
	s_cbranch_vccz .LBB0_1517
	s_barrier

; #define PG8_STAGE(bufoff, gbase, voff) do { const int so_ = (int)(unsigned)((const char*)(gbase) - base_##voff); _Pragma("unroll") for (int _i = 0; _i < 2; ++_i) \
;         __builtin_amdgcn_raw_ptr_buffer_load_lds(rs_##voff, (PG8_LAS unsigned*)(lds + (bufoff) + ldsw + _i * 8192), 16, (int)(voff)[_i], so_, 0, 0); } while (0)
; #define PG8_LDA(dst, b, h) do { _Pragma("unroll") for (int m = 0; m < 4; ++m) _Pragma("unroll") for (int k = 0; k < 2; ++k) dst[m][k] = *(const PG8_LAS bf16x8*)(lds + PG8_SA(b, h) + aoff + m * 2048 + k * 1024); } while (0)
; #define PG8_LDB(dst, b, h) do { _Pragma("unroll") for (int n = 0; n < 2; ++n) _Pragma("unroll") for (int k = 0; k < 2; ++k) dst[n][k] = *(const PG8_LAS bf16x8*)(lds + PG8_SB(b, h) + boff + n * 2048 + k * 1024); } while (0)
; #define PG8_MMA(ai, bj, At, Bt) do { __builtin_amdgcn_s_setprio(1); _Pragma("unroll") for (int m = 0; m < 4; ++m) _Pragma("unroll") for (int n = 0; n < 2; ++n) _Pragma("unroll") for (int k = 0; k < 2; ++k) \
;         acc[ai][bj][m][n] = __builtin_amdgcn_mfma_f32_16x16x32_bf16(Bt[n][k], At[m][k], acc[ai][bj][m][n], 0, 0, 0); __builtin_amdgcn_s_setprio(0); } while (0)
; template <class Epi, class Sched, bool ALIGN_EPI = false, bool SP2 = false>
; __device__ __forceinline__ void gemm_phase(PG8_LAS unsigned char* lds, const Gemm g, const Sched& S, const Epi& E, int tid_in) {
;     ...
;             PG8_LDB(B0, 0, 0); PG8_LDB(B1, 0, 1); PG8_SCHED; PG8_LDA(At, 0, 0); PG8_STAGE(PG8_SA(1, 1), a1 + hstepA, voffA);
;             PG8_WAIT_V(8); PG8_WAIT_L(0); PG8_BAR; PG8_MMA(0, 0, At, B0); PG8_MMA(0, 1, At, B1); PG8_BAR; PG8_SCHED;
;             PG8_LDA(At, 0, 1); PG8_STAGE(PG8_SB(0, 0), b2, voffB); PG8_STAGE(PG8_SB(0, 1), b2 + hstepB, voffB); PG8_STAGE(PG8_SA(0, 0), a2, voffA);
;             PG8_WAIT_V(8); PG8_WAIT_L(0); PG8_BAR; PG8_MMA(1, 0, At, B0); PG8_MMA(1, 1, At, B1); PG8_BAR; PG8_SCHED;
;             PG8_LDB(B0, 1, 0); PG8_LDB(B1, 1, 1); PG8_SCHED; PG8_LDA(At, 1, 0); PG8_STAGE(PG8_SA(0, 1), a2 + hstepA, voffA);
;             PG8_WAIT_V(8); PG8_WAIT_L(0); PG8_BAR; PG8_MMA(0, 0, At, B0); PG8_MMA(0, 1, At, B1); PG8_BAR; PG8_SCHED;
;             PG8_LDA(At, 1, 1); PG8_STAGE(PG8_SB(1, 0), b3, voffB); PG8_STAGE(PG8_SB(1, 1), b3 + hstepB, voffB); PG8_STAGE(PG8_SA(1, 0), a3, voffA);
;             PG8_WAIT_V(8); PG8_WAIT_L(0); PG8_BAR; PG8_MMA(1, 0, At, B0); PG8_MMA(1, 1, At, B1); PG8_BAR; PG8_SCHED;
.LBB0_1584:
	v_add_u32_e32 v133, 0x10000, v131
	ds_read_b128 v[134:137], v133
	ds_read_b128 v[138:141], v133 offset:1024
	ds_read_b128 v[142:145], v133 offset:2048
	ds_read_b128 v[146:149], v133 offset:3072
	v_add_u32_e32 v133, 0x14000, v131
	ds_read_b128 v[150:153], v133
	ds_read_b128 v[154:157], v133 offset:1024
	ds_read_b128 v[158:161], v133 offset:2048
	ds_read_b128 v[166:169], v133 offset:3072
	s_add_i32 s43, s38, s22
	s_add_i32 s42, s14, s22
	s_add_i32 s76, s12, s22
	s_addk_i32 s43, 0xff80
	s_cmpk_eq_i32 s39, 0x54
	s_cselect_b32 s77, s16, s42
	s_mov_b32 m0, s68
	ds_read_b128 v[170:173], v132
	ds_read_b128 v[174:177], v132 offset:1024
	ds_read_b128 v[178:181], v132 offset:2048
	ds_read_b128 v[182:185], v132 offset:3072
	ds_read_b128 v[186:189], v132 offset:4096
	ds_read_b128 v[190:193], v132 offset:5120
	ds_read_b128 v[200:203], v132 offset:6144
	ds_read_b128 v[206:209], v132 offset:7168
	buffer_load_dwordx4 v0, s[4:7], s43 offen lds
	s_mov_b32 m0, s69
	s_nop 0
	buffer_load_dwordx4 v130, s[4:7], s43 offen lds
	s_waitcnt vmcnt(8)
	s_waitcnt lgkmcnt(0)
	s_barrier
	s_setprio 1
	s_waitcnt lgkmcnt(0)
	v_mfma_f32_16x16x32_bf16 v[22:25], v[134:137], v[170:173], v[22:25]
	v_mfma_f32_16x16x32_bf16 v[14:17], v[142:145], v[170:173], v[14:17]
	v_mfma_f32_16x16x32_bf16 v[54:57], v[142:145], v[178:181], v[54:57]
	v_mfma_f32_16x16x32_bf16 v[74:77], v[134:137], v[178:181], v[74:77]
	v_mfma_f32_16x16x32_bf16 v[106:109], v[134:137], v[186:189], v[106:109]
	v_mfma_f32_16x16x32_bf16 v[102:105], v[142:145], v[186:189], v[102:105]
	v_mfma_f32_16x16x32_bf16 v[118:121], v[142:145], v[200:203], v[118:121]
	v_mfma_f32_16x16x32_bf16 v[122:125], v[134:137], v[200:203], v[122:125]
	v_mfma_f32_16x16x32_bf16 v[22:25], v[138:141], v[174:177], v[22:25]
	v_mfma_f32_16x16x32_bf16 v[14:17], v[146:149], v[174:177], v[14:17]
	v_mfma_f32_16x16x32_bf16 v[54:57], v[146:149], v[182:185], v[54:57]
	v_mfma_f32_16x16x32_bf16 v[74:77], v[138:141], v[182:185], v[74:77]
	v_mfma_f32_16x16x32_bf16 v[106:109], v[138:141], v[190:193], v[106:109]
	v_mfma_f32_16x16x32_bf16 v[102:105], v[146:149], v[190:193], v[102:105]
	v_mfma_f32_16x16x32_bf16 v[118:121], v[146:149], v[206:209], v[118:121]
	v_mfma_f32_16x16x32_bf16 v[122:125], v[138:141], v[206:209], v[122:125]
	s_setprio 0
	s_setprio 1
	v_mfma_f32_16x16x32_bf16 v[6:9], v[150:153], v[170:173], v[6:9]
	v_mfma_f32_16x16x32_bf16 v[18:21], v[158:161], v[170:173], v[18:21]
	v_mfma_f32_16x16x32_bf16 v[78:81], v[158:161], v[178:181], v[78:81]
	v_mfma_f32_16x16x32_bf16 v[50:53], v[150:153], v[178:181], v[50:53]
	v_mfma_f32_16x16x32_bf16 v[98:101], v[150:153], v[186:189], v[98:101]
	v_mfma_f32_16x16x32_bf16 v[110:113], v[158:161], v[186:189], v[110:113]
	v_mfma_f32_16x16x32_bf16 v[126:129], v[158:161], v[200:203], v[126:129]
	v_mfma_f32_16x16x32_bf16 v[114:117], v[150:153], v[200:203], v[114:117]
	v_mfma_f32_16x16x32_bf16 v[6:9], v[154:157], v[174:177], v[6:9]
	v_mfma_f32_16x16x32_bf16 v[18:21], v[166:169], v[174:177], v[18:21]
	v_mfma_f32_16x16x32_bf16 v[78:81], v[166:169], v[182:185], v[78:81]
	v_mfma_f32_16x16x32_bf16 v[50:53], v[154:157], v[182:185], v[50:53]
	v_mfma_f32_16x16x32_bf16 v[98:101], v[154:157], v[190:193], v[98:101]
	v_mfma_f32_16x16x32_bf16 v[110:113], v[166:169], v[190:193], v[110:113]
	v_mfma_f32_16x16x32_bf16 v[126:129], v[166:169], v[206:209], v[126:129]
	v_mfma_f32_16x16x32_bf16 v[114:117], v[154:157], v[206:209], v[114:117]
	s_setprio 0
	s_barrier
	s_cselect_b32 s76, s20, s76
	s_mov_b32 m0, s26
	s_mov_b32 s42, s6
	s_mov_b32 s43, s7
	s_sub_i32 s76, s76, s40
	ds_read_b128 v[170:173], v132 offset:16384
	ds_read_b128 v[174:177], v132 offset:17408
	ds_read_b128 v[178:181], v132 offset:18432
	ds_read_b128 v[182:185], v132 offset:19456
	ds_read_b128 v[186:189], v132 offset:20480
	ds_read_b128 v[190:193], v132 offset:21504
	ds_read_b128 v[200:203], v132 offset:22528
	ds_read_b128 v[206:209], v132 offset:23552
	buffer_load_dwordx4 v0, s[40:43], s76 offen lds
	s_mov_b32 m0, s44
	s_add_i32 s78, s76, 0x160000
	buffer_load_dwordx4 v130, s[40:43], s76 offen lds
	s_mov_b32 m0, s45
	s_sub_i32 s77, s77, s4
	buffer_load_dwordx4 v0, s[40:43], s78 offen lds
	s_mov_b32 m0, s46
	s_nop 0
	buffer_load_dwordx4 v130, s[40:43], s78 offen lds
	s_mov_b32 m0, s19
	s_nop 0
	buffer_load_dwordx4 v0, s[4:7], s77 offen lds
	s_mov_b32 m0, s47
	s_nop 0
	buffer_load_dwordx4 v130, s[4:7], s77 offen lds
	s_waitcnt vmcnt(8)
	s_waitcnt lgkmcnt(0)
	s_barrier
	s_setprio 1
	s_waitcnt lgkmcnt(0)
	v_mfma_f32_16x16x32_bf16 v[62:65], v[134:137], v[170:173], v[62:65]
	v_mfma_f32_16x16x32_bf16 v[46:49], v[142:145], v[170:173], v[46:49]
	v_mfma_f32_16x16x32_bf16 v[70:73], v[142:145], v[178:181], v[70:73]
	v_mfma_f32_16x16x32_bf16 v[82:85], v[134:137], v[178:181], v[82:85]
	v_mfma_f32_16x16x32_bf16 v[94:97], v[134:137], v[186:189], v[94:97]
	v_mfma_f32_16x16x32_bf16 v[90:93], v[142:145], v[186:189], v[90:93]
	v_mfma_f32_16x16x32_bf16 v[26:29], v[142:145], v[200:203], v[26:29]
	v_mfma_f32_16x16x32_bf16 v[38:41], v[134:137], v[200:203], v[38:41]
	v_mfma_f32_16x16x32_bf16 v[62:65], v[138:141], v[174:177], v[62:65]
	v_mfma_f32_16x16x32_bf16 v[46:49], v[146:149], v[174:177], v[46:49]
	v_mfma_f32_16x16x32_bf16 v[70:73], v[146:149], v[182:185], v[70:73]
	v_mfma_f32_16x16x32_bf16 v[82:85], v[138:141], v[182:185], v[82:85]
	v_mfma_f32_16x16x32_bf16 v[94:97], v[138:141], v[190:193], v[94:97]
	v_mfma_f32_16x16x32_bf16 v[90:93], v[146:149], v[190:193], v[90:93]
	v_mfma_f32_16x16x32_bf16 v[26:29], v[146:149], v[206:209], v[26:29]
	v_mfma_f32_16x16x32_bf16 v[38:41], v[138:141], v[206:209], v[38:41]
	s_setprio 0
	s_setprio 1
	v_mfma_f32_16x16x32_bf16 v[42:45], v[150:153], v[170:173], v[42:45]
	v_mfma_f32_16x16x32_bf16 v[30:33], v[158:161], v[170:173], v[30:33]
	v_mfma_f32_16x16x32_bf16 v[86:89], v[158:161], v[178:181], v[86:89]
	v_mfma_f32_16x16x32_bf16 v[66:69], v[150:153], v[178:181], v[66:69]
	v_mfma_f32_16x16x32_bf16 v[58:61], v[150:153], v[186:189], v[58:61]
	v_mfma_f32_16x16x32_bf16 v[34:37], v[158:161], v[186:189], v[34:37]
	v_mfma_f32_16x16x32_bf16 v[2:5], v[158:161], v[200:203], v[2:5]
	v_mfma_f32_16x16x32_bf16 v[10:13], v[150:153], v[200:203], v[10:13]
	v_mfma_f32_16x16x32_bf16 v[42:45], v[154:157], v[174:177], v[42:45]
	v_mfma_f32_16x16x32_bf16 v[30:33], v[166:169], v[174:177], v[30:33]
	v_mfma_f32_16x16x32_bf16 v[86:89], v[166:169], v[182:185], v[86:89]
	v_mfma_f32_16x16x32_bf16 v[66:69], v[154:157], v[182:185], v[66:69]
	v_mfma_f32_16x16x32_bf16 v[58:61], v[154:157], v[190:193], v[58:61]
	v_mfma_f32_16x16x32_bf16 v[34:37], v[166:169], v[190:193], v[34:37]
	v_mfma_f32_16x16x32_bf16 v[2:5], v[166:169], v[206:209], v[2:5]
	v_mfma_f32_16x16x32_bf16 v[10:13], v[154:157], v[206:209], v[10:13]
	s_setprio 0
	s_barrier
; #define PG8_STAGE(bufoff, gbase, voff) do { const int so_ = (int)(unsigned)((const char*)(gbase) - base_##voff); _Pragma("unroll") for (int _i = 0; _i < 2; ++_i) \
;         __builtin_amdgcn_raw_ptr_buffer_load_lds(rs_##voff, (PG8_LAS unsigned*)(lds + (bufoff) + ldsw + _i * 8192), 16, (int)(voff)[_i], so_, 0, 0); } while (0)
; #define PG8_LDA(dst, b, h) do { _Pragma("unroll") for (int m = 0; m < 4; ++m) _Pragma("unroll") for (int k = 0; k < 2; ++k) dst[m][k] = *(const PG8_LAS bf16x8*)(lds + PG8_SA(b, h) + aoff + m * 2048 + k * 1024); } while (0)
; #define PG8_LDB(dst, b, h) do { _Pragma("unroll") for (int n = 0; n < 2; ++n) _Pragma("unroll") for (int k = 0; k < 2; ++k) dst[n][k] = *(const PG8_LAS bf16x8*)(lds + PG8_SB(b, h) + boff + n * 2048 + k * 1024); } while (0)
; #define PG8_MMA(ai, bj, At, Bt) do { __builtin_amdgcn_s_setprio(1); _Pragma("unroll") for (int m = 0; m < 4; ++m) _Pragma("unroll") for (int n = 0; n < 2; ++n) _Pragma("unroll") for (int k = 0; k < 2; ++k) \
;         acc[ai][bj][m][n] = __builtin_amdgcn_mfma_f32_16x16x32_bf16(Bt[n][k], At[m][k], acc[ai][bj][m][n], 0, 0, 0); __builtin_amdgcn_s_setprio(0); } while (0)
; #define PG8_WAIT_V(n) asm volatile("s_waitcnt vmcnt(" #n ")" ::: "memory")
; #define PG8_BAR __builtin_amdgcn_s_barrier()
; template <class Epi, class Sched, bool ALIGN_EPI = false, bool SP2 = false>
; __device__ __forceinline__ void gemm_phase(PG8_LAS unsigned char* lds, const Gemm g, const Sched& S, const Epi& E, int tid_in) {
;     ...
;             PG8_LDB(B0, 0, 0); PG8_LDB(B1, 0, 1); PG8_SCHED; PG8_LDA(At, 0, 0); PG8_STAGE(PG8_SA(1, 1), a1 + hstepA, voffA);
;             PG8_WAIT_V(8); PG8_WAIT_L(0); PG8_BAR; PG8_MMA(0, 0, At, B0); PG8_MMA(0, 1, At, B1); PG8_BAR; PG8_SCHED;
;             PG8_LDA(At, 0, 1); PG8_STAGE(PG8_SB(0, 0), b2, voffB); PG8_STAGE(PG8_SB(0, 1), b2 + hstepB, voffB); PG8_STAGE(PG8_SA(0, 0), a2, voffA);
;             PG8_WAIT_V(8); PG8_WAIT_L(0); PG8_BAR; PG8_MMA(1, 0, At, B0); PG8_MMA(1, 1, At, B1); PG8_BAR; PG8_SCHED;
;             PG8_LDB(B0, 1, 0); PG8_LDB(B1, 1, 1); PG8_SCHED; PG8_LDA(At, 1, 0); PG8_STAGE(PG8_SA(0, 1), a2 + hstepA, voffA);
;             PG8_WAIT_V(8); PG8_WAIT_L(0); PG8_BAR; PG8_MMA(0, 0, At, B0); PG8_MMA(0, 1, At, B1); PG8_BAR; PG8_SCHED;
;             PG8_LDA(At, 1, 1); PG8_STAGE(PG8_SB(1, 0), b3, voffB); PG8_STAGE(PG8_SB(1, 1), b3 + hstepB, voffB); PG8_STAGE(PG8_SA(1, 0), a3, voffA);
	v_add_u32_e32 v133, 0x18000, v131
	ds_read_b128 v[134:137], v133
	ds_read_b128 v[138:141], v133 offset:1024
	ds_read_b128 v[142:145], v133 offset:2048
	ds_read_b128 v[146:149], v133 offset:3072
	v_add_u32_e32 v133, 0x1c000, v131
	ds_read_b128 v[150:153], v133
	ds_read_b128 v[154:157], v133 offset:1024
	ds_read_b128 v[158:161], v133 offset:2048
	ds_read_b128 v[166:169], v133 offset:3072
	s_add_i32 s78, s77, 0x160000
	s_mov_b32 m0, s48
	ds_read_b128 v[170:173], v132 offset:32768
	ds_read_b128 v[174:177], v132 offset:33792
	ds_read_b128 v[178:181], v132 offset:34816
	ds_read_b128 v[182:185], v132 offset:35840
	ds_read_b128 v[186:189], v132 offset:36864
	ds_read_b128 v[190:193], v132 offset:37888
	ds_read_b128 v[200:203], v132 offset:38912
	ds_read_b128 v[206:209], v132 offset:39936
	buffer_load_dwordx4 v0, s[4:7], s78 offen lds
	s_mov_b32 m0, s49
	s_nop 0
	buffer_load_dwordx4 v130, s[4:7], s78 offen lds
	s_waitcnt vmcnt(8)
	s_waitcnt lgkmcnt(0)
	s_barrier
	s_setprio 1
	s_waitcnt lgkmcnt(0)
	v_mfma_f32_16x16x32_bf16 v[22:25], v[134:137], v[170:173], v[22:25]
	v_mfma_f32_16x16x32_bf16 v[14:17], v[142:145], v[170:173], v[14:17]
	v_mfma_f32_16x16x32_bf16 v[54:57], v[142:145], v[178:181], v[54:57]
	v_mfma_f32_16x16x32_bf16 v[74:77], v[134:137], v[178:181], v[74:77]
	v_mfma_f32_16x16x32_bf16 v[106:109], v[134:137], v[186:189], v[106:109]
	v_mfma_f32_16x16x32_bf16 v[102:105], v[142:145], v[186:189], v[102:105]
	v_mfma_f32_16x16x32_bf16 v[118:121], v[142:145], v[200:203], v[118:121]
	v_mfma_f32_16x16x32_bf16 v[122:125], v[134:137], v[200:203], v[122:125]
	v_mfma_f32_16x16x32_bf16 v[22:25], v[138:141], v[174:177], v[22:25]
	v_mfma_f32_16x16x32_bf16 v[14:17], v[146:149], v[174:177], v[14:17]
	v_mfma_f32_16x16x32_bf16 v[54:57], v[146:149], v[182:185], v[54:57]
	v_mfma_f32_16x16x32_bf16 v[74:77], v[138:141], v[182:185], v[74:77]
	v_mfma_f32_16x16x32_bf16 v[106:109], v[138:141], v[190:193], v[106:109]
	v_mfma_f32_16x16x32_bf16 v[102:105], v[146:149], v[190:193], v[102:105]
	v_mfma_f32_16x16x32_bf16 v[118:121], v[146:149], v[206:209], v[118:121]
	v_mfma_f32_16x16x32_bf16 v[122:125], v[138:141], v[206:209], v[122:125]
	s_setprio 0
	s_setprio 1
	v_mfma_f32_16x16x32_bf16 v[6:9], v[150:153], v[170:173], v[6:9]
	v_mfma_f32_16x16x32_bf16 v[18:21], v[158:161], v[170:173], v[18:21]
	v_mfma_f32_16x16x32_bf16 v[78:81], v[158:161], v[178:181], v[78:81]
	v_mfma_f32_16x16x32_bf16 v[50:53], v[150:153], v[178:181], v[50:53]
	v_mfma_f32_16x16x32_bf16 v[98:101], v[150:153], v[186:189], v[98:101]
	v_mfma_f32_16x16x32_bf16 v[110:113], v[158:161], v[186:189], v[110:113]
	v_mfma_f32_16x16x32_bf16 v[126:129], v[158:161], v[200:203], v[126:129]
	v_mfma_f32_16x16x32_bf16 v[114:117], v[150:153], v[200:203], v[114:117]
	v_mfma_f32_16x16x32_bf16 v[6:9], v[154:157], v[174:177], v[6:9]
	v_mfma_f32_16x16x32_bf16 v[18:21], v[166:169], v[174:177], v[18:21]
	v_mfma_f32_16x16x32_bf16 v[78:81], v[166:169], v[182:185], v[78:81]
	v_mfma_f32_16x16x32_bf16 v[50:53], v[154:157], v[182:185], v[50:53]
	v_mfma_f32_16x16x32_bf16 v[98:101], v[154:157], v[190:193], v[98:101]
	v_mfma_f32_16x16x32_bf16 v[110:113], v[166:169], v[190:193], v[110:113]
	v_mfma_f32_16x16x32_bf16 v[126:129], v[166:169], v[206:209], v[126:129]
	v_mfma_f32_16x16x32_bf16 v[114:117], v[154:157], v[206:209], v[114:117]
	s_setprio 0
	s_barrier
	s_mov_b32 m0, s60
	s_add_i32 s78, s76, 0x80
	ds_read_b128 v[170:173], v132 offset:49152
	ds_read_b128 v[174:177], v132 offset:50176
	ds_read_b128 v[178:181], v132 offset:51200
	ds_read_b128 v[182:185], v132 offset:52224
	ds_read_b128 v[186:189], v132 offset:53248
	ds_read_b128 v[190:193], v132 offset:54272
	ds_read_b128 v[200:203], v132 offset:55296
	ds_read_b128 v[206:209], v132 offset:56320
	buffer_load_dwordx4 v0, s[40:43], s78 offen lds
	s_mov_b32 m0, s61
	s_add_i32 s76, s76, 0x160080
	buffer_load_dwordx4 v130, s[40:43], s78 offen lds
	s_mov_b32 m0, s66
	s_addk_i32 s77, 0x80
	buffer_load_dwordx4 v0, s[40:43], s76 offen lds
	s_mov_b32 m0, s67
	s_nop 0
	buffer_load_dwordx4 v130, s[40:43], s76 offen lds
	s_mov_b32 m0, s62
	s_nop 0
	buffer_load_dwordx4 v0, s[4:7], s77 offen lds
	s_mov_b32 m0, s63
	s_nop 0
	buffer_load_dwordx4 v130, s[4:7], s77 offen lds
	s_waitcnt vmcnt(8)
	s_waitcnt lgkmcnt(0)
	s_barrier
;     static __device__ __forceinline__ bool last_of_chain(const Unit& u) { return (u.pn >> 3) == 2; }
; #define PG8_MMA(ai, bj, At, Bt) do { __builtin_amdgcn_s_setprio(1); _Pragma("unroll") for (int m = 0; m < 4; ++m) _Pragma("unroll") for (int n = 0; n < 2; ++n) _Pragma("unroll") for (int k = 0; k < 2; ++k) \
;         acc[ai][bj][m][n] = __builtin_amdgcn_mfma_f32_16x16x32_bf16(Bt[n][k], At[m][k], acc[ai][bj][m][n], 0, 0, 0); __builtin_amdgcn_s_setprio(0); } while (0)
; #define PG8_WAIT_V(n) asm volatile("s_waitcnt vmcnt(" #n ")" ::: "memory")
; #define PG8_WAIT_L(n) asm volatile("s_waitcnt lgkmcnt(" #n ")" ::: "memory")
; #define PG8_BAR __builtin_amdgcn_s_barrier()
; #define PG8_SCHED __builtin_amdgcn_sched_barrier(0)
; template <class Epi, class Sched, bool ALIGN_EPI = false, bool SP2 = false>
; __device__ __forceinline__ void gemm_phase(PG8_LAS unsigned char* lds, const Gemm g, const Sched& S, const Epi& E, int tid_in) {
;     ...
;             PG8_WAIT_V(8); PG8_WAIT_L(0); PG8_BAR; PG8_MMA(1, 0, At, B0); PG8_MMA(1, 1, At, B1); PG8_BAR; PG8_SCHED;
;     ...
;         if (!has_next) break;
;         bool zero_acc = true; if constexpr (Epi::CHAIN) zero_acc = Epi::last_of_chain(cur);
;         if (zero_acc) {
; #pragma unroll
;         for (int a = 0; a < 2; ++a)
; #pragma unroll
;             for (int b = 0; b < 2; ++b)
; #pragma unroll
;                 for (int m = 0; m < 4; ++m)
; #pragma unroll
;                     for (int n = 0; n < 2; ++n) acc[a][b][m][n] = (f32x4){0.f, 0.f, 0.f, 0.f};
;         }
	s_setprio 1
	s_waitcnt lgkmcnt(0)
	v_mfma_f32_16x16x32_bf16 v[62:65], v[134:137], v[170:173], v[62:65]
	v_mfma_f32_16x16x32_bf16 v[46:49], v[142:145], v[170:173], v[46:49]
	v_mfma_f32_16x16x32_bf16 v[70:73], v[142:145], v[178:181], v[70:73]
	v_mfma_f32_16x16x32_bf16 v[82:85], v[134:137], v[178:181], v[82:85]
	v_mfma_f32_16x16x32_bf16 v[94:97], v[134:137], v[186:189], v[94:97]
	v_mfma_f32_16x16x32_bf16 v[90:93], v[142:145], v[186:189], v[90:93]
	v_mfma_f32_16x16x32_bf16 v[26:29], v[142:145], v[200:203], v[26:29]
	v_mfma_f32_16x16x32_bf16 v[38:41], v[134:137], v[200:203], v[38:41]
	v_mfma_f32_16x16x32_bf16 v[62:65], v[138:141], v[174:177], v[62:65]
	v_mfma_f32_16x16x32_bf16 v[46:49], v[146:149], v[174:177], v[46:49]
	v_mfma_f32_16x16x32_bf16 v[70:73], v[146:149], v[182:185], v[70:73]
	v_mfma_f32_16x16x32_bf16 v[82:85], v[138:141], v[182:185], v[82:85]
	v_mfma_f32_16x16x32_bf16 v[94:97], v[138:141], v[190:193], v[94:97]
	v_mfma_f32_16x16x32_bf16 v[90:93], v[146:149], v[190:193], v[90:93]
	v_mfma_f32_16x16x32_bf16 v[26:29], v[146:149], v[206:209], v[26:29]
	v_mfma_f32_16x16x32_bf16 v[38:41], v[138:141], v[206:209], v[38:41]
	s_setprio 0
	s_setprio 1
	v_mfma_f32_16x16x32_bf16 v[42:45], v[150:153], v[170:173], v[42:45]
	v_mfma_f32_16x16x32_bf16 v[30:33], v[158:161], v[170:173], v[30:33]
	v_mfma_f32_16x16x32_bf16 v[86:89], v[158:161], v[178:181], v[86:89]
	v_mfma_f32_16x16x32_bf16 v[66:69], v[150:153], v[178:181], v[66:69]
	v_mfma_f32_16x16x32_bf16 v[58:61], v[150:153], v[186:189], v[58:61]
	v_mfma_f32_16x16x32_bf16 v[34:37], v[158:161], v[186:189], v[34:37]
	v_mfma_f32_16x16x32_bf16 v[2:5], v[158:161], v[200:203], v[2:5]
	v_mfma_f32_16x16x32_bf16 v[10:13], v[150:153], v[200:203], v[10:13]
	v_mfma_f32_16x16x32_bf16 v[42:45], v[154:157], v[174:177], v[42:45]
	v_mfma_f32_16x16x32_bf16 v[30:33], v[166:169], v[174:177], v[30:33]
	v_mfma_f32_16x16x32_bf16 v[86:89], v[166:169], v[182:185], v[86:89]
	v_mfma_f32_16x16x32_bf16 v[66:69], v[154:157], v[182:185], v[66:69]
	v_mfma_f32_16x16x32_bf16 v[58:61], v[154:157], v[190:193], v[58:61]
	v_mfma_f32_16x16x32_bf16 v[34:37], v[166:169], v[190:193], v[34:37]
	v_mfma_f32_16x16x32_bf16 v[2:5], v[166:169], v[206:209], v[2:5]
	v_mfma_f32_16x16x32_bf16 v[10:13], v[154:157], v[206:209], v[10:13]
	s_setprio 0
	s_barrier
	s_add_i32 s39, s39, 2
	s_add_u32 s22, s22, 0x100
	s_addc_u32 s23, s23, 0
	s_cmpk_gt_u32 s39, 0x55
	s_cbranch_scc0 .LBB0_1584
	s_and_b64 vcc, exec, s[36:37]
	s_cbranch_vccnz .LBB0_1572
	v_mov_b32_e32 v2, 0
	s_mov_b32 s10, s73
	s_mov_b32 s25, s74
	s_mov_b64 s[12:13], s[20:21]
	s_mov_b64 s[14:15], s[16:17]
	s_mov_b32 s72, s75
	v_mov_b32_e32 v3, v2
	v_mov_b32_e32 v4, v2
	v_mov_b32_e32 v5, v2
	v_mov_b32_e32 v10, v2
	v_mov_b32_e32 v11, v2
	v_mov_b32_e32 v12, v2
	v_mov_b32_e32 v13, v2
	v_mov_b32_e32 v34, v2
	v_mov_b32_e32 v35, v2
	v_mov_b32_e32 v36, v2
	v_mov_b32_e32 v37, v2
	v_mov_b32_e32 v58, v2
	v_mov_b32_e32 v59, v2
	v_mov_b32_e32 v60, v2
	v_mov_b32_e32 v61, v2
	v_mov_b32_e32 v86, v2
	v_mov_b32_e32 v87, v2
	v_mov_b32_e32 v88, v2
	v_mov_b32_e32 v89, v2
	v_mov_b32_e32 v66, v2
	v_mov_b32_e32 v67, v2
	v_mov_b32_e32 v68, v2
	v_mov_b32_e32 v69, v2
	v_mov_b32_e32 v30, v2
	v_mov_b32_e32 v31, v2
	v_mov_b32_e32 v32, v2
	v_mov_b32_e32 v33, v2
	v_mov_b32_e32 v42, v2
	v_mov_b32_e32 v43, v2
	v_mov_b32_e32 v44, v2
	v_mov_b32_e32 v45, v2
	v_mov_b32_e32 v26, v2
	v_mov_b32_e32 v27, v2
	v_mov_b32_e32 v28, v2
	v_mov_b32_e32 v29, v2
	v_mov_b32_e32 v38, v2
	v_mov_b32_e32 v39, v2
	v_mov_b32_e32 v40, v2
	v_mov_b32_e32 v41, v2
	v_mov_b32_e32 v90, v2
	v_mov_b32_e32 v91, v2
	v_mov_b32_e32 v92, v2
	v_mov_b32_e32 v93, v2
	v_mov_b32_e32 v94, v2
	v_mov_b32_e32 v95, v2
	v_mov_b32_e32 v96, v2
	v_mov_b32_e32 v97, v2
	v_mov_b32_e32 v70, v2
	v_mov_b32_e32 v71, v2
	v_mov_b32_e32 v72, v2
	v_mov_b32_e32 v73, v2
	v_mov_b32_e32 v82, v2
	v_mov_b32_e32 v83, v2
	v_mov_b32_e32 v84, v2
	v_mov_b32_e32 v85, v2
	v_mov_b32_e32 v46, v2
	v_mov_b32_e32 v47, v2
	v_mov_b32_e32 v48, v2
	v_mov_b32_e32 v49, v2
	v_mov_b32_e32 v62, v2
	v_mov_b32_e32 v63, v2
	v_mov_b32_e32 v64, v2
	v_mov_b32_e32 v65, v2
	v_mov_b32_e32 v126, v2
	v_mov_b32_e32 v127, v2
	v_mov_b32_e32 v128, v2
	v_mov_b32_e32 v129, v2
	v_mov_b32_e32 v114, v2
	v_mov_b32_e32 v115, v2
	v_mov_b32_e32 v116, v2
	v_mov_b32_e32 v117, v2
	v_mov_b32_e32 v110, v2
	v_mov_b32_e32 v111, v2
	v_mov_b32_e32 v112, v2
	v_mov_b32_e32 v113, v2
	v_mov_b32_e32 v98, v2
	v_mov_b32_e32 v99, v2
	v_mov_b32_e32 v100, v2
	v_mov_b32_e32 v101, v2
	v_mov_b32_e32 v78, v2
	v_mov_b32_e32 v79, v2
	v_mov_b32_e32 v80, v2
	v_mov_b32_e32 v81, v2
	v_mov_b32_e32 v50, v2
	v_mov_b32_e32 v51, v2
	v_mov_b32_e32 v52, v2
	v_mov_b32_e32 v53, v2
	v_mov_b32_e32 v18, v2
	v_mov_b32_e32 v19, v2
	v_mov_b32_e32 v20, v2
	v_mov_b32_e32 v21, v2
	v_mov_b32_e32 v6, v2
	v_mov_b32_e32 v7, v2
	v_mov_b32_e32 v8, v2
	v_mov_b32_e32 v9, v2
	v_mov_b32_e32 v118, v2
	v_mov_b32_e32 v119, v2
	v_mov_b32_e32 v120, v2
	v_mov_b32_e32 v121, v2
	v_mov_b32_e32 v122, v2
	v_mov_b32_e32 v123, v2
	v_mov_b32_e32 v124, v2
	v_mov_b32_e32 v125, v2
	v_mov_b32_e32 v102, v2
	v_mov_b32_e32 v103, v2
	v_mov_b32_e32 v104, v2
	v_mov_b32_e32 v105, v2
	v_mov_b32_e32 v106, v2
	v_mov_b32_e32 v107, v2
	v_mov_b32_e32 v108, v2
	v_mov_b32_e32 v109, v2
	v_mov_b32_e32 v54, v2
	v_mov_b32_e32 v55, v2
	v_mov_b32_e32 v56, v2
	v_mov_b32_e32 v57, v2
	v_mov_b32_e32 v74, v2
	v_mov_b32_e32 v75, v2
	v_mov_b32_e32 v76, v2
	v_mov_b32_e32 v77, v2
	v_mov_b32_e32 v14, v2
	v_mov_b32_e32 v15, v2
	v_mov_b32_e32 v16, v2
	v_mov_b32_e32 v17, v2
	v_mov_b32_e32 v22, v2
	v_mov_b32_e32 v23, v2
	v_mov_b32_e32 v24, v2
	v_mov_b32_e32 v25, v2
	s_branch .LBB0_1572
